# GEMM epilogues: row statistics loaded once per tile row by waves 0-3 and broadcast through LDS instead of 8 serialized global round trips per lane
# speedup vs baseline: 1.0358x; 1.0229x over previous
; __device__ __forceinline__ void load_row_stats(const float* sp, int row0, RowStats& r) {
; #pragma unroll
;     for (int ai = 0; ai < 2; ++ai) { asm volatile("" ::: "memory");
; #pragma unroll
;         for (int m = 0; m < 4; ++m) { const float* p = sp + (size_t)(row0 + ai * HALF + m * 16) * 8; const f32x4 a = *(const f32x4*)p, b = *(const f32x4*)(p + 4);
;             const float s1 = (a[0] + a[2]) + (b[0] + b[2]), s2 = (a[1] + a[3]) + (b[1] + b[3]); const float mu = s1 * (1.f / 1024.f); const float var = s2 * (1.f / 1024.f) - mu * mu;
;             r.mu[ai][m] = mu; r.rs[ai][m] = __builtin_amdgcn_rsqf(__builtin_fmaxf(var, 0.f) + 1e-5f); } }
;     __device__ __forceinline__ void operator()(const f32x4 (&acc)[2][2][4][2], const Unit& u, int wr, int wc, int fr_in, int fq_in) const {
;     ...
;         const int row0 = u.pm * BM + wr * 64 + fr; const int t = u.pn >> 2; bf16_t* base = O + (size_t)t * split_stride; const float sc = (t == 0) ? scale0 : 1.f;
;         const int col0 = (u.pn & 3) * BM + wc * 32 + 8 * fq, n0 = u.pn * BM + wc * 32 + 8 * fq;
;         RowStats rst; load_row_stats(sp, row0, rst); f32x4 csv[2][2], cbv[2][2];
; #pragma unroll
;         for (int bj = 0; bj < 2; ++bj)
; #pragma unroll
;             for (int n = 0; n < 2; ++n) { csv[bj][n] = *(const f32x4*)(cs + n0 + bj * HALF + 4 * n); cbv[bj][n] = *(const f32x4*)(cb + n0 + bj * HALF + 4 * n); }
.LBB0_436:
	s_lshl_b32 s8, s46, 8
	v_mov_b32_e32 v228, v183
	v_mov_b32_e32 v128, v189
	s_add_i32 s8, s8, s49
	s_nop 0
	v_add_u32_e32 v220, s8, v228
	v_ashrrev_i32_e32 v221, 31, v220
	s_cselect_b32 s99, 1, 0
	v_readfirstlane_b32 s98, v254
	v_and_b32_e32 v130, 0xffffff00, v220
	s_nop 0
	s_cmpk_lt_u32 s98, 0x100
	s_cbranch_scc0 .Lrs0_skip
	v_add_u32_e32 v130, v130, v254
	v_mov_b32_e32 v131, 0
	v_lshlrev_b64 v[130:131], 5, v[130:131]
	v_lshl_add_u64 v[134:135], s[12:13], 0, v[130:131]
	global_load_dwordx4 v[130:133], v[134:135], off offset:16
	s_nop 0
	global_load_dwordx4 v[134:137], v[134:135], off
	s_waitcnt vmcnt(0)
	v_pk_add_f32 v[130:131], v[130:131], v[132:133]
	v_pk_add_f32 v[134:135], v[134:135], v[136:137]
	s_nop 0
	v_pk_add_f32 v[130:131], v[134:135], v[130:131]
	s_nop 0
	v_pk_mul_f32 v[130:131], v[130:131], s[34:35] op_sel_hi:[1,0]
	v_lshlrev_b32_e32 v132, 3, v254
	v_add_u32_e32 v132, 0x22400, v132
	ds_write_b64 v132, v[130:131]
.Lrs0_skip:
	s_waitcnt vmcnt(0) lgkmcnt(0)
	s_barrier
	v_and_b32_e32 v132, 0xff, v220
	v_lshlrev_b32_e32 v132, 3, v132
	v_add_u32_e32 v132, 0x22400, v132
	ds_read_b64 v[216:217], v132
	ds_read_b64 v[208:209], v132 offset:128
	ds_read_b64 v[202:203], v132 offset:256
	ds_read_b64 v[196:197], v132 offset:384
	ds_read_b64 v[190:191], v132 offset:1024
	ds_read_b64 v[184:185], v132 offset:1152
	ds_read_b64 v[180:181], v132 offset:1280
	ds_read_b64 v[178:179], v132 offset:1408
	s_cmp_lg_u32 s99, 0
	s_waitcnt lgkmcnt(0)
	v_add_u32_e32 v222, 16, v220
	v_ashrrev_i32_e32 v223, 31, v222
	v_add_u32_e32 v214, 32, v220
	v_ashrrev_i32_e32 v215, 31, v214
	v_add_u32_e32 v210, 48, v220
	v_ashrrev_i32_e32 v211, 31, v210
	v_add_u32_e32 v206, 0x80, v220
	v_ashrrev_i32_e32 v207, 31, v206
	v_add_u32_e32 v200, 0x90, v220
	v_ashrrev_i32_e32 v201, 31, v200
	v_add_u32_e32 v192, 0xa0, v220
	v_ashrrev_i32_e32 v193, 31, v192
	v_add_u32_e32 v186, 0xb0, v220
	v_ashrrev_i32_e32 v187, 31, v186
	s_ashr_i32 s8, s48, 2
	s_ashr_i32 s9, s8, 31
	s_lshl_b64 s[8:9], s[8:9], 26
	s_add_u32 s50, s57, s8
	s_addc_u32 s51, s58, s9
	s_lshl_b32 s8, s48, 8
	v_lshlrev_b32_e32 v229, 3, v128
	s_or_b32 s9, s8, s56
	v_add_u32_e32 v128, s9, v229
	s_cmp_lt_u32 s48, 4
	s_cselect_b64 vcc, -1, 0
	s_and_b32 s9, s8, 0x300
	s_or_b32 s9, s9, s56
	v_add_u32_e32 v226, s9, v229
	v_cndmask_b32_e32 v224, 1.0, v219, vcc
	v_ashrrev_i32_e32 v227, 31, v226
	v_lshl_add_u64 v[226:227], v[226:227], 1, s[50:51]
	v_lshlrev_b64 v[220:221], 11, v[220:221]
	v_lshl_add_u64 v[220:221], v[226:227], 0, v[220:221]
	s_and_b32 s9, s48, -2
	s_cmp_lg_u32 s9, 4
	v_fma_f32 v129, -v216, v216, v217
	v_max_f32_e32 v129, 0, v129
	v_add_f32_e32 v129, 0x3727c5ac, v129
	v_rsq_f32_e32 v218, v129
	v_fma_f32 v129, -v208, v208, v209
	v_max_f32_e32 v129, 0, v129
	v_add_f32_e32 v129, 0x3727c5ac, v129
	v_rsq_f32_e32 v212, v129
	v_fma_f32 v129, -v202, v202, v203
	v_max_f32_e32 v129, 0, v129
	v_add_f32_e32 v129, 0x3727c5ac, v129
	v_rsq_f32_e32 v204, v129
	v_fma_f32 v129, -v196, v196, v197
	v_max_f32_e32 v129, 0, v129
	v_add_f32_e32 v129, 0x3727c5ac, v129
	v_rsq_f32_e32 v198, v129
	v_fma_f32 v129, -v190, v190, v191
	v_max_f32_e32 v129, 0, v129
	v_add_f32_e32 v129, 0x3727c5ac, v129
	v_rsq_f32_e32 v194, v129
	v_fma_f32 v129, -v184, v184, v185
	v_max_f32_e32 v129, 0, v129
	v_add_f32_e32 v129, 0x3727c5ac, v129
	v_rsq_f32_e32 v188, v129
	v_fma_f32 v129, -v180, v180, v181
	v_max_f32_e32 v129, 0, v129
	v_add_f32_e32 v129, 0x3727c5ac, v129
	v_rsq_f32_e32 v182, v129
	s_nop 0
	v_fma_f32 v129, -v178, v178, v179
	v_max_f32_e32 v129, 0, v129
	v_add_f32_e32 v129, 0x3727c5ac, v129
	v_rsq_f32_e32 v168, v129
	v_ashrrev_i32_e32 v129, 31, v128
	v_lshlrev_b64 v[128:129], 2, v[128:129]
	v_lshl_add_u64 v[132:133], s[22:23], 0, v[128:129]
	v_lshl_add_u64 v[136:137], s[24:25], 0, v[128:129]
	global_load_dwordx4 v[148:151], v[132:133], off offset:16
	global_load_dwordx4 v[156:159], v[132:133], off
	global_load_dwordx4 v[144:147], v[136:137], off offset:16
	global_load_dwordx4 v[152:155], v[136:137], off
	global_load_dwordx4 v[128:131], v[132:133], off offset:528
	global_load_dwordx4 v[140:143], v[132:133], off offset:512
	s_nop 0
	global_load_dwordx4 v[132:135], v[136:137], off offset:528
	s_nop 0
	global_load_dwordx4 v[136:139], v[136:137], off offset:512
	s_waitcnt vmcnt(6)
	v_pk_fma_f32 v[230:231], v[216:217], v[156:157], v[124:125] op_sel_hi:[0,1,1] neg_lo:[1,0,0] neg_hi:[1,0,0]
	v_pk_fma_f32 v[124:125], v[216:217], v[158:159], v[126:127] op_sel_hi:[0,1,1] neg_lo:[1,0,0] neg_hi:[1,0,0]
	s_waitcnt vmcnt(4)
	v_pk_fma_f32 v[126:127], v[218:219], v[230:231], v[152:153] op_sel_hi:[0,1,1]
	v_pk_fma_f32 v[230:231], v[216:217], v[148:149], v[120:121] op_sel_hi:[0,1,1] neg_lo:[1,0,0] neg_hi:[1,0,0]
	v_pk_fma_f32 v[124:125], v[218:219], v[124:125], v[154:155] op_sel_hi:[0,1,1]
	v_pk_fma_f32 v[120:121], v[216:217], v[150:151], v[122:123] op_sel_hi:[0,1,1] neg_lo:[1,0,0] neg_hi:[1,0,0]
	v_pk_fma_f32 v[122:123], v[218:219], v[230:231], v[144:145] op_sel_hi:[0,1,1]
	v_pk_mul_f32 v[230:231], v[224:225], v[126:127] op_sel_hi:[0,1]
	v_pk_fma_f32 v[120:121], v[218:219], v[120:121], v[146:147] op_sel_hi:[0,1,1]
	v_pk_mul_f32 v[232:233], v[224:225], v[124:125] op_sel_hi:[0,1]
	v_cvt_pk_bf16_f32 v230, v230, v231
	v_cvt_pk_bf16_f32 v231, v232, v233
	v_pk_mul_f32 v[234:235], v[224:225], v[120:121] op_sel_hi:[0,1]
	v_pk_mul_f32 v[236:237], v[224:225], v[122:123] op_sel_hi:[0,1]
	v_cvt_pk_bf16_f32 v232, v236, v237
	v_cvt_pk_bf16_f32 v233, v234, v235
	global_store_dwordx4 v[220:221], v[230:233], off
	v_pk_fma_f32 v[12:13], v[156:157], v[178:179], v[12:13] op_sel_hi:[1,0,1] neg_lo:[1,0,0] neg_hi:[1,0,0]
	s_waitcnt vmcnt(3)
; __device__ __forceinline__ unsigned cvt_pk_bf16(float lo, float hi) { unsigned r; asm("v_cvt_pk_bf16_f32 %0, %1, %2" : "=v"(r) : "v"(lo), "v"(hi)); return r; }
; __device__ __forceinline__ f32x4 ln_fix(const f32x4& a, float mu, float rs, const f32x4& cs, const f32x4& cb) { return (a - cs * mu) * rs + cb; }
;     __device__ __forceinline__ void operator()(const f32x4 (&acc)[2][2][4][2], const Unit& u, int wr, int wc, int fr_in, int fq_in) const {
;     ...
;             for (int m = 0; m < 4; ++m) { bf16_t* rowp = base + (size_t)(row0 + ai * HALF + m * 16) * 1024 + col0;
; #pragma unroll
;                 for (int bj = 0; bj < 2; ++bj) { const f32x4 v0r = ln_fix(acc[ai][bj][m][0], rst.mu[ai][m], rst.rs[ai][m], csv[bj][0], cbv[bj][0]), v1r = ln_fix(acc[ai][bj][m][1], rst.mu[ai][m], rst.rs[ai][m], csv[bj][1], cbv[bj][1]);
;                     ks[bj][0] += v0r; ks[bj][1] += v1r; const f32x4 v0 = v0r * sc, v1 = v1r * sc;
;                     u32x4 w; w.x = cvt_pk_bf16(v0[0], v0[1]); w.y = cvt_pk_bf16(v0[2], v0[3]); w.z = cvt_pk_bf16(v1[0], v1[1]); w.w = cvt_pk_bf16(v1[2], v1[3]);
;                     *(u32x4*)(rowp + bj * HALF) = w; } }
	v_pk_fma_f32 v[230:231], v[216:217], v[140:141], v[116:117] op_sel_hi:[0,1,1] neg_lo:[1,0,0] neg_hi:[1,0,0]
	v_pk_fma_f32 v[116:117], v[216:217], v[142:143], v[118:119] op_sel_hi:[0,1,1] neg_lo:[1,0,0] neg_hi:[1,0,0]
	s_waitcnt vmcnt(1)
	v_pk_fma_f32 v[118:119], v[218:219], v[230:231], v[136:137] op_sel_hi:[0,1,1]
	v_pk_fma_f32 v[230:231], v[216:217], v[128:129], v[112:113] op_sel_hi:[0,1,1] neg_lo:[1,0,0] neg_hi:[1,0,0]
	v_pk_fma_f32 v[112:113], v[216:217], v[130:131], v[114:115] op_sel_hi:[0,1,1] neg_lo:[1,0,0] neg_hi:[1,0,0]
	v_pk_fma_f32 v[114:115], v[218:219], v[230:231], v[132:133] op_sel_hi:[0,1,1]
	v_pk_fma_f32 v[116:117], v[218:219], v[116:117], v[138:139] op_sel_hi:[0,1,1]
	v_pk_fma_f32 v[112:113], v[218:219], v[112:113], v[134:135] op_sel_hi:[0,1,1]
	v_pk_mul_f32 v[230:231], v[224:225], v[118:119] op_sel_hi:[0,1]
	v_pk_mul_f32 v[232:233], v[224:225], v[114:115] op_sel_hi:[0,1]
	v_pk_mul_f32 v[216:217], v[224:225], v[116:117] op_sel_hi:[0,1]
	v_pk_mul_f32 v[234:235], v[224:225], v[112:113] op_sel_hi:[0,1]
	v_cvt_pk_bf16_f32 v230, v230, v231
	v_cvt_pk_bf16_f32 v231, v216, v217
	v_cvt_pk_bf16_f32 v232, v232, v233
	v_cvt_pk_bf16_f32 v233, v234, v235
	global_store_dwordx4 v[220:221], v[230:233], off offset:256
	v_pk_fma_f32 v[220:221], v[208:209], v[156:157], v[108:109] op_sel_hi:[0,1,1] neg_lo:[1,0,0] neg_hi:[1,0,0]
	v_pk_fma_f32 v[108:109], v[208:209], v[158:159], v[110:111] op_sel_hi:[0,1,1] neg_lo:[1,0,0] neg_hi:[1,0,0]
	v_pk_fma_f32 v[110:111], v[212:213], v[220:221], v[152:153] op_sel_hi:[0,1,1]
	v_pk_fma_f32 v[220:221], v[208:209], v[148:149], v[104:105] op_sel_hi:[0,1,1] neg_lo:[1,0,0] neg_hi:[1,0,0]
	v_lshlrev_b64 v[216:217], 11, v[222:223]
	v_pk_fma_f32 v[108:109], v[212:213], v[108:109], v[154:155] op_sel_hi:[0,1,1]
	v_pk_fma_f32 v[104:105], v[208:209], v[150:151], v[106:107] op_sel_hi:[0,1,1] neg_lo:[1,0,0] neg_hi:[1,0,0]
	v_pk_fma_f32 v[106:107], v[212:213], v[220:221], v[144:145] op_sel_hi:[0,1,1]
	v_pk_mul_f32 v[220:221], v[224:225], v[110:111] op_sel_hi:[0,1]
	v_lshl_add_u64 v[216:217], v[226:227], 0, v[216:217]
	v_pk_fma_f32 v[104:105], v[212:213], v[104:105], v[146:147] op_sel_hi:[0,1,1]
	v_pk_mul_f32 v[222:223], v[224:225], v[108:109] op_sel_hi:[0,1]
	v_cvt_pk_bf16_f32 v220, v220, v221
	v_cvt_pk_bf16_f32 v221, v222, v223
	v_pk_mul_f32 v[230:231], v[224:225], v[104:105] op_sel_hi:[0,1]
	v_pk_mul_f32 v[232:233], v[224:225], v[106:107] op_sel_hi:[0,1]
	v_cvt_pk_bf16_f32 v222, v232, v233
	v_cvt_pk_bf16_f32 v223, v230, v231
	global_store_dwordx4 v[216:217], v[220:223], off
	v_pk_fma_f32 v[12:13], v[12:13], v[168:169], v[152:153] op_sel_hi:[1,0,1]
	s_nop 0
	v_pk_fma_f32 v[220:221], v[208:209], v[140:141], v[100:101] op_sel_hi:[0,1,1] neg_lo:[1,0,0] neg_hi:[1,0,0]
	v_pk_fma_f32 v[100:101], v[208:209], v[142:143], v[102:103] op_sel_hi:[0,1,1] neg_lo:[1,0,0] neg_hi:[1,0,0]
	v_pk_fma_f32 v[100:101], v[212:213], v[100:101], v[138:139] op_sel_hi:[0,1,1]
	v_pk_fma_f32 v[102:103], v[212:213], v[220:221], v[136:137] op_sel_hi:[0,1,1]
	v_pk_fma_f32 v[220:221], v[208:209], v[128:129], v[96:97] op_sel_hi:[0,1,1] neg_lo:[1,0,0] neg_hi:[1,0,0]
	v_pk_fma_f32 v[96:97], v[208:209], v[130:131], v[98:99] op_sel_hi:[0,1,1] neg_lo:[1,0,0] neg_hi:[1,0,0]
	v_pk_fma_f32 v[98:99], v[212:213], v[220:221], v[132:133] op_sel_hi:[0,1,1]
	v_pk_mul_f32 v[208:209], v[224:225], v[100:101] op_sel_hi:[0,1]
	v_pk_mul_f32 v[220:221], v[224:225], v[102:103] op_sel_hi:[0,1]
	v_cvt_pk_bf16_f32 v220, v220, v221
	v_cvt_pk_bf16_f32 v221, v208, v209
	v_lshlrev_b64 v[208:209], 11, v[214:215]
	v_pk_fma_f32 v[214:215], v[202:203], v[156:157], v[92:93] op_sel_hi:[0,1,1] neg_lo:[1,0,0] neg_hi:[1,0,0]
	v_pk_fma_f32 v[92:93], v[202:203], v[158:159], v[94:95] op_sel_hi:[0,1,1] neg_lo:[1,0,0] neg_hi:[1,0,0]
	v_pk_fma_f32 v[94:95], v[204:205], v[214:215], v[152:153] op_sel_hi:[0,1,1]
	v_pk_fma_f32 v[214:215], v[202:203], v[148:149], v[88:89] op_sel_hi:[0,1,1] neg_lo:[1,0,0] neg_hi:[1,0,0]
	v_pk_fma_f32 v[96:97], v[212:213], v[96:97], v[134:135] op_sel_hi:[0,1,1]
	v_pk_mul_f32 v[222:223], v[224:225], v[98:99] op_sel_hi:[0,1]
	v_pk_fma_f32 v[92:93], v[204:205], v[92:93], v[154:155] op_sel_hi:[0,1,1]
	v_pk_fma_f32 v[88:89], v[202:203], v[150:151], v[90:91] op_sel_hi:[0,1,1] neg_lo:[1,0,0] neg_hi:[1,0,0]
	v_pk_fma_f32 v[90:91], v[204:205], v[214:215], v[144:145] op_sel_hi:[0,1,1]
	v_pk_mul_f32 v[214:215], v[224:225], v[94:95] op_sel_hi:[0,1]
	v_pk_mul_f32 v[230:231], v[224:225], v[96:97] op_sel_hi:[0,1]
	v_cvt_pk_bf16_f32 v222, v222, v223
	v_cvt_pk_bf16_f32 v223, v230, v231
	global_store_dwordx4 v[216:217], v[220:223], off offset:256
	v_lshl_add_u64 v[208:209], v[226:227], 0, v[208:209]
	v_pk_fma_f32 v[88:89], v[204:205], v[88:89], v[146:147] op_sel_hi:[0,1,1]
	v_pk_mul_f32 v[216:217], v[224:225], v[92:93] op_sel_hi:[0,1]
	v_cvt_pk_bf16_f32 v214, v214, v215
	v_cvt_pk_bf16_f32 v215, v216, v217
	v_pk_mul_f32 v[220:221], v[224:225], v[88:89] op_sel_hi:[0,1]
	v_pk_mul_f32 v[222:223], v[224:225], v[90:91] op_sel_hi:[0,1]
	v_cvt_pk_bf16_f32 v216, v222, v223
	v_cvt_pk_bf16_f32 v217, v220, v221
	global_store_dwordx4 v[208:209], v[214:217], off
	s_nop 1
	v_pk_fma_f32 v[214:215], v[202:203], v[140:141], v[84:85] op_sel_hi:[0,1,1] neg_lo:[1,0,0] neg_hi:[1,0,0]
	v_pk_fma_f32 v[84:85], v[202:203], v[142:143], v[86:87] op_sel_hi:[0,1,1] neg_lo:[1,0,0] neg_hi:[1,0,0]
	v_pk_fma_f32 v[86:87], v[204:205], v[214:215], v[136:137] op_sel_hi:[0,1,1]
	v_pk_fma_f32 v[214:215], v[202:203], v[128:129], v[80:81] op_sel_hi:[0,1,1] neg_lo:[1,0,0] neg_hi:[1,0,0]
	v_pk_fma_f32 v[80:81], v[202:203], v[130:131], v[82:83] op_sel_hi:[0,1,1] neg_lo:[1,0,0] neg_hi:[1,0,0]
; __device__ __forceinline__ unsigned cvt_pk_bf16(float lo, float hi) { unsigned r; asm("v_cvt_pk_bf16_f32 %0, %1, %2" : "=v"(r) : "v"(lo), "v"(hi)); return r; }
; __device__ __forceinline__ f32x4 ln_fix(const f32x4& a, float mu, float rs, const f32x4& cs, const f32x4& cb) { return (a - cs * mu) * rs + cb; }
;     __device__ __forceinline__ void operator()(const f32x4 (&acc)[2][2][4][2], const Unit& u, int wr, int wc, int fr_in, int fq_in) const {
;     ...
;             for (int m = 0; m < 4; ++m) { bf16_t* rowp = base + (size_t)(row0 + ai * HALF + m * 16) * 1024 + col0;
; #pragma unroll
;                 for (int bj = 0; bj < 2; ++bj) { const f32x4 v0r = ln_fix(acc[ai][bj][m][0], rst.mu[ai][m], rst.rs[ai][m], csv[bj][0], cbv[bj][0]), v1r = ln_fix(acc[ai][bj][m][1], rst.mu[ai][m], rst.rs[ai][m], csv[bj][1], cbv[bj][1]);
;                     ks[bj][0] += v0r; ks[bj][1] += v1r; const f32x4 v0 = v0r * sc, v1 = v1r * sc;
;                     u32x4 w; w.x = cvt_pk_bf16(v0[0], v0[1]); w.y = cvt_pk_bf16(v0[2], v0[3]); w.z = cvt_pk_bf16(v1[0], v1[1]); w.w = cvt_pk_bf16(v1[2], v1[3]);
;                     *(u32x4*)(rowp + bj * HALF) = w; } }
	v_pk_fma_f32 v[82:83], v[204:205], v[214:215], v[132:133] op_sel_hi:[0,1,1]
	v_pk_fma_f32 v[84:85], v[204:205], v[84:85], v[138:139] op_sel_hi:[0,1,1]
	v_pk_fma_f32 v[80:81], v[204:205], v[80:81], v[134:135] op_sel_hi:[0,1,1]
	v_pk_mul_f32 v[214:215], v[224:225], v[86:87] op_sel_hi:[0,1]
	v_pk_mul_f32 v[216:217], v[224:225], v[82:83] op_sel_hi:[0,1]
	v_pk_mul_f32 v[202:203], v[224:225], v[84:85] op_sel_hi:[0,1]
	v_pk_mul_f32 v[220:221], v[224:225], v[80:81] op_sel_hi:[0,1]
	v_cvt_pk_bf16_f32 v214, v214, v215
	v_cvt_pk_bf16_f32 v215, v202, v203
	v_cvt_pk_bf16_f32 v216, v216, v217
	v_cvt_pk_bf16_f32 v217, v220, v221
	global_store_dwordx4 v[208:209], v[214:217], off offset:256
	v_pk_fma_f32 v[208:209], v[196:197], v[156:157], v[76:77] op_sel_hi:[0,1,1] neg_lo:[1,0,0] neg_hi:[1,0,0]
	v_pk_fma_f32 v[76:77], v[196:197], v[158:159], v[78:79] op_sel_hi:[0,1,1] neg_lo:[1,0,0] neg_hi:[1,0,0]
	v_pk_fma_f32 v[78:79], v[198:199], v[208:209], v[152:153] op_sel_hi:[0,1,1]
	v_pk_fma_f32 v[208:209], v[196:197], v[148:149], v[72:73] op_sel_hi:[0,1,1] neg_lo:[1,0,0] neg_hi:[1,0,0]
	v_lshlrev_b64 v[202:203], 11, v[210:211]
	v_pk_fma_f32 v[76:77], v[198:199], v[76:77], v[154:155] op_sel_hi:[0,1,1]
	v_pk_fma_f32 v[72:73], v[196:197], v[150:151], v[74:75] op_sel_hi:[0,1,1] neg_lo:[1,0,0] neg_hi:[1,0,0]
	v_pk_fma_f32 v[74:75], v[198:199], v[208:209], v[144:145] op_sel_hi:[0,1,1]
	v_pk_mul_f32 v[208:209], v[224:225], v[78:79] op_sel_hi:[0,1]
	v_lshl_add_u64 v[202:203], v[226:227], 0, v[202:203]
	v_pk_fma_f32 v[72:73], v[198:199], v[72:73], v[146:147] op_sel_hi:[0,1,1]
	v_pk_mul_f32 v[210:211], v[224:225], v[76:77] op_sel_hi:[0,1]
	v_cvt_pk_bf16_f32 v208, v208, v209
	v_cvt_pk_bf16_f32 v209, v210, v211
	v_pk_mul_f32 v[214:215], v[224:225], v[72:73] op_sel_hi:[0,1]
	v_pk_mul_f32 v[216:217], v[224:225], v[74:75] op_sel_hi:[0,1]
	v_cvt_pk_bf16_f32 v210, v216, v217
	v_cvt_pk_bf16_f32 v211, v214, v215
	global_store_dwordx4 v[202:203], v[208:211], off
	s_nop 1
	v_pk_fma_f32 v[208:209], v[196:197], v[140:141], v[68:69] op_sel_hi:[0,1,1] neg_lo:[1,0,0] neg_hi:[1,0,0]
	v_pk_fma_f32 v[68:69], v[196:197], v[142:143], v[70:71] op_sel_hi:[0,1,1] neg_lo:[1,0,0] neg_hi:[1,0,0]
	v_pk_fma_f32 v[70:71], v[198:199], v[208:209], v[136:137] op_sel_hi:[0,1,1]
	v_pk_fma_f32 v[208:209], v[196:197], v[128:129], v[64:65] op_sel_hi:[0,1,1] neg_lo:[1,0,0] neg_hi:[1,0,0]
	v_pk_fma_f32 v[64:65], v[196:197], v[130:131], v[66:67] op_sel_hi:[0,1,1] neg_lo:[1,0,0] neg_hi:[1,0,0]
	v_pk_fma_f32 v[66:67], v[198:199], v[208:209], v[132:133] op_sel_hi:[0,1,1]
	v_pk_fma_f32 v[68:69], v[198:199], v[68:69], v[138:139] op_sel_hi:[0,1,1]
	v_pk_fma_f32 v[64:65], v[198:199], v[64:65], v[134:135] op_sel_hi:[0,1,1]
	v_pk_mul_f32 v[208:209], v[224:225], v[70:71] op_sel_hi:[0,1]
	v_pk_mul_f32 v[210:211], v[224:225], v[66:67] op_sel_hi:[0,1]
	v_pk_mul_f32 v[196:197], v[224:225], v[68:69] op_sel_hi:[0,1]
	v_pk_mul_f32 v[214:215], v[224:225], v[64:65] op_sel_hi:[0,1]
	v_cvt_pk_bf16_f32 v208, v208, v209
	v_cvt_pk_bf16_f32 v209, v196, v197
	v_cvt_pk_bf16_f32 v210, v210, v211
	v_cvt_pk_bf16_f32 v211, v214, v215
	global_store_dwordx4 v[202:203], v[208:211], off offset:256
	v_pk_fma_f32 v[202:203], v[190:191], v[156:157], v[60:61] op_sel_hi:[0,1,1] neg_lo:[1,0,0] neg_hi:[1,0,0]
	v_pk_fma_f32 v[60:61], v[190:191], v[158:159], v[62:63] op_sel_hi:[0,1,1] neg_lo:[1,0,0] neg_hi:[1,0,0]
	v_pk_fma_f32 v[60:61], v[60:61], v[194:195], v[154:155] op_sel_hi:[1,0,1]
	v_pk_fma_f32 v[62:63], v[202:203], v[194:195], v[152:153] op_sel_hi:[1,0,1]
	v_pk_fma_f32 v[202:203], v[190:191], v[148:149], v[56:57] op_sel_hi:[0,1,1] neg_lo:[1,0,0] neg_hi:[1,0,0]
	v_lshlrev_b64 v[196:197], 11, v[206:207]
	v_pk_fma_f32 v[56:57], v[190:191], v[150:151], v[58:59] op_sel_hi:[0,1,1] neg_lo:[1,0,0] neg_hi:[1,0,0]
	v_pk_fma_f32 v[58:59], v[202:203], v[194:195], v[144:145] op_sel_hi:[1,0,1]
	v_pk_mul_f32 v[202:203], v[224:225], v[60:61] op_sel_hi:[0,1]
	v_pk_mul_f32 v[206:207], v[224:225], v[62:63] op_sel_hi:[0,1]
	v_cvt_pk_bf16_f32 v206, v206, v207
	v_cvt_pk_bf16_f32 v207, v202, v203
	v_pk_fma_f32 v[202:203], v[190:191], v[140:141], v[52:53] op_sel_hi:[0,1,1] neg_lo:[1,0,0] neg_hi:[1,0,0]
	v_pk_fma_f32 v[56:57], v[56:57], v[194:195], v[146:147] op_sel_hi:[1,0,1]
	v_pk_mul_f32 v[208:209], v[224:225], v[58:59] op_sel_hi:[0,1]
	v_pk_fma_f32 v[52:53], v[190:191], v[142:143], v[54:55] op_sel_hi:[0,1,1] neg_lo:[1,0,0] neg_hi:[1,0,0]
	v_pk_fma_f32 v[54:55], v[194:195], v[202:203], v[136:137] op_sel_hi:[0,1,1]
	v_pk_fma_f32 v[202:203], v[190:191], v[128:129], v[48:49] op_sel_hi:[0,1,1] neg_lo:[1,0,0] neg_hi:[1,0,0]
	v_lshl_add_u64 v[196:197], v[226:227], 0, v[196:197]
	v_pk_mul_f32 v[210:211], v[224:225], v[56:57] op_sel_hi:[0,1]
	v_cvt_pk_bf16_f32 v208, v208, v209
	v_cvt_pk_bf16_f32 v209, v210, v211
	v_pk_fma_f32 v[48:49], v[190:191], v[130:131], v[50:51] op_sel_hi:[0,1,1] neg_lo:[1,0,0] neg_hi:[1,0,0]
	v_pk_fma_f32 v[50:51], v[194:195], v[202:203], v[132:133] op_sel_hi:[0,1,1]
	global_store_dwordx4 v[196:197], v[206:209], off
	v_pk_fma_f32 v[52:53], v[194:195], v[52:53], v[138:139] op_sel_hi:[0,1,1]
	v_pk_fma_f32 v[48:49], v[194:195], v[48:49], v[134:135] op_sel_hi:[0,1,1]
	v_pk_mul_f32 v[208:209], v[224:225], v[50:51] op_sel_hi:[0,1]
	v_xor_b32_e32 v159, 0x80000000, v159
	v_xor_b32_e32 v158, 0x80000000, v158
	v_pk_mul_f32 v[190:191], v[224:225], v[52:53] op_sel_hi:[0,1]
	v_pk_mul_f32 v[202:203], v[224:225], v[54:55] op_sel_hi:[0,1]
	v_pk_mul_f32 v[210:211], v[224:225], v[48:49] op_sel_hi:[0,1]
	v_cvt_pk_bf16_f32 v206, v202, v203
	v_cvt_pk_bf16_f32 v207, v190, v191
	v_cvt_pk_bf16_f32 v208, v208, v209
	v_cvt_pk_bf16_f32 v209, v210, v211
; __device__ __forceinline__ unsigned cvt_pk_bf16(float lo, float hi) { unsigned r; asm("v_cvt_pk_bf16_f32 %0, %1, %2" : "=v"(r) : "v"(lo), "v"(hi)); return r; }
; __device__ __forceinline__ f32x4 ln_fix(const f32x4& a, float mu, float rs, const f32x4& cs, const f32x4& cb) { return (a - cs * mu) * rs + cb; }
;     __device__ __forceinline__ void operator()(const f32x4 (&acc)[2][2][4][2], const Unit& u, int wr, int wc, int fr_in, int fq_in) const {
;     ...
;             for (int m = 0; m < 4; ++m) { bf16_t* rowp = base + (size_t)(row0 + ai * HALF + m * 16) * 1024 + col0;
; #pragma unroll
;                 for (int bj = 0; bj < 2; ++bj) { const f32x4 v0r = ln_fix(acc[ai][bj][m][0], rst.mu[ai][m], rst.rs[ai][m], csv[bj][0], cbv[bj][0]), v1r = ln_fix(acc[ai][bj][m][1], rst.mu[ai][m], rst.rs[ai][m], csv[bj][1], cbv[bj][1]);
;                     ks[bj][0] += v0r; ks[bj][1] += v1r; const f32x4 v0 = v0r * sc, v1 = v1r * sc;
;                     u32x4 w; w.x = cvt_pk_bf16(v0[0], v0[1]); w.y = cvt_pk_bf16(v0[2], v0[3]); w.z = cvt_pk_bf16(v1[0], v1[1]); w.w = cvt_pk_bf16(v1[2], v1[3]);
;                     *(u32x4*)(rowp + bj * HALF) = w; } }
	global_store_dwordx4 v[196:197], v[206:209], off offset:256
	v_pk_fma_f32 v[196:197], v[156:157], v[184:185], v[44:45] op_sel_hi:[1,0,1] neg_lo:[1,0,0] neg_hi:[1,0,0]
	v_pk_fma_f32 v[44:45], v[158:159], v[184:185], v[46:47] op_sel_hi:[1,0,1]
	v_pk_fma_f32 v[46:47], v[196:197], v[188:189], v[152:153] op_sel_hi:[1,0,1]
	v_pk_fma_f32 v[44:45], v[44:45], v[188:189], v[154:155] op_sel_hi:[1,0,1]
	v_pk_fma_f32 v[196:197], v[184:185], v[148:149], v[40:41] op_sel_hi:[0,1,1] neg_lo:[1,0,0] neg_hi:[1,0,0]
	v_lshlrev_b64 v[190:191], 11, v[200:201]
	v_pk_fma_f32 v[40:41], v[184:185], v[150:151], v[42:43] op_sel_hi:[0,1,1] neg_lo:[1,0,0] neg_hi:[1,0,0]
	v_pk_fma_f32 v[42:43], v[196:197], v[188:189], v[144:145] op_sel_hi:[1,0,1]
	v_pk_mul_f32 v[196:197], v[224:225], v[44:45] op_sel_hi:[0,1]
	v_pk_mul_f32 v[200:201], v[224:225], v[46:47] op_sel_hi:[0,1]
	v_cvt_pk_bf16_f32 v200, v200, v201
	v_cvt_pk_bf16_f32 v201, v196, v197
	v_pk_fma_f32 v[196:197], v[184:185], v[140:141], v[36:37] op_sel_hi:[0,1,1] neg_lo:[1,0,0] neg_hi:[1,0,0]
	v_pk_fma_f32 v[40:41], v[40:41], v[188:189], v[146:147] op_sel_hi:[1,0,1]
	v_pk_mul_f32 v[202:203], v[224:225], v[42:43] op_sel_hi:[0,1]
	v_pk_fma_f32 v[36:37], v[184:185], v[142:143], v[38:39] op_sel_hi:[0,1,1] neg_lo:[1,0,0] neg_hi:[1,0,0]
	v_pk_fma_f32 v[38:39], v[196:197], v[188:189], v[136:137] op_sel_hi:[1,0,1]
	v_pk_fma_f32 v[196:197], v[184:185], v[128:129], v[32:33] op_sel_hi:[0,1,1] neg_lo:[1,0,0] neg_hi:[1,0,0]
	v_lshl_add_u64 v[190:191], v[226:227], 0, v[190:191]
	v_pk_mul_f32 v[206:207], v[224:225], v[40:41] op_sel_hi:[0,1]
	v_cvt_pk_bf16_f32 v202, v202, v203
	v_cvt_pk_bf16_f32 v203, v206, v207
	v_pk_fma_f32 v[32:33], v[184:185], v[130:131], v[34:35] op_sel_hi:[0,1,1] neg_lo:[1,0,0] neg_hi:[1,0,0]
	v_pk_fma_f32 v[34:35], v[188:189], v[196:197], v[132:133] op_sel_hi:[0,1,1]
	global_store_dwordx4 v[190:191], v[200:203], off
	v_pk_fma_f32 v[36:37], v[36:37], v[188:189], v[138:139] op_sel_hi:[1,0,1]
	v_pk_fma_f32 v[32:33], v[188:189], v[32:33], v[134:135] op_sel_hi:[0,1,1]
	v_pk_mul_f32 v[202:203], v[224:225], v[34:35] op_sel_hi:[0,1]
	v_pk_mul_f32 v[184:185], v[224:225], v[36:37] op_sel_hi:[0,1]
	v_pk_mul_f32 v[196:197], v[224:225], v[38:39] op_sel_hi:[0,1]
	v_pk_mul_f32 v[206:207], v[224:225], v[32:33] op_sel_hi:[0,1]
	v_cvt_pk_bf16_f32 v200, v196, v197
	v_cvt_pk_bf16_f32 v201, v184, v185
	v_cvt_pk_bf16_f32 v202, v202, v203
	v_cvt_pk_bf16_f32 v203, v206, v207
	global_store_dwordx4 v[190:191], v[200:203], off offset:256
	v_pk_fma_f32 v[190:191], v[156:157], v[180:181], v[28:29] op_sel_hi:[1,0,1] neg_lo:[1,0,0] neg_hi:[1,0,0]
	v_pk_fma_f32 v[28:29], v[158:159], v[180:181], v[30:31] op_sel_hi:[1,0,1]
	v_pk_fma_f32 v[30:31], v[190:191], v[182:183], v[152:153] op_sel_hi:[1,0,1]
	v_pk_fma_f32 v[190:191], v[148:149], v[180:181], v[24:25] op_sel_hi:[1,0,1] neg_lo:[1,0,0] neg_hi:[1,0,0]
	v_xor_b32_e32 v151, 0x80000000, v151
	v_xor_b32_e32 v150, 0x80000000, v150
	v_lshlrev_b64 v[184:185], 11, v[192:193]
	v_pk_fma_f32 v[28:29], v[28:29], v[182:183], v[154:155] op_sel_hi:[1,0,1]
	v_pk_fma_f32 v[24:25], v[150:151], v[180:181], v[26:27] op_sel_hi:[1,0,1]
	v_pk_fma_f32 v[26:27], v[190:191], v[182:183], v[144:145] op_sel_hi:[1,0,1]
	v_pk_mul_f32 v[190:191], v[224:225], v[30:31] op_sel_hi:[0,1]
	v_lshl_add_u64 v[184:185], v[226:227], 0, v[184:185]
	v_pk_fma_f32 v[24:25], v[24:25], v[182:183], v[146:147] op_sel_hi:[1,0,1]
	v_pk_mul_f32 v[192:193], v[224:225], v[28:29] op_sel_hi:[0,1]
	v_cvt_pk_bf16_f32 v190, v190, v191
	v_cvt_pk_bf16_f32 v191, v192, v193
	v_pk_mul_f32 v[196:197], v[224:225], v[24:25] op_sel_hi:[0,1]
	v_pk_mul_f32 v[200:201], v[224:225], v[26:27] op_sel_hi:[0,1]
	v_cvt_pk_bf16_f32 v192, v200, v201
	v_cvt_pk_bf16_f32 v193, v196, v197
	global_store_dwordx4 v[184:185], v[190:193], off
	v_pk_fma_f32 v[14:15], v[158:159], v[178:179], v[14:15] op_sel_hi:[1,0,1]
	v_pk_fma_f32 v[148:149], v[148:149], v[178:179], v[8:9] op_sel_hi:[1,0,1] neg_lo:[1,0,0] neg_hi:[1,0,0]
	v_pk_fma_f32 v[190:191], v[180:181], v[140:141], v[20:21] op_sel_hi:[0,1,1] neg_lo:[1,0,0] neg_hi:[1,0,0]
	v_pk_fma_f32 v[20:21], v[180:181], v[142:143], v[22:23] op_sel_hi:[0,1,1] neg_lo:[1,0,0] neg_hi:[1,0,0]
	v_pk_fma_f32 v[20:21], v[20:21], v[182:183], v[138:139] op_sel_hi:[1,0,1]
	v_pk_fma_f32 v[22:23], v[190:191], v[182:183], v[136:137] op_sel_hi:[1,0,1]
	v_pk_fma_f32 v[190:191], v[180:181], v[128:129], v[16:17] op_sel_hi:[0,1,1] neg_lo:[1,0,0] neg_hi:[1,0,0]
	v_pk_fma_f32 v[140:141], v[140:141], v[178:179], v[4:5] op_sel_hi:[1,0,1] neg_lo:[1,0,0] neg_hi:[1,0,0]
; __device__ __forceinline__ unsigned cvt_pk_bf16(float lo, float hi) { unsigned r; asm("v_cvt_pk_bf16_f32 %0, %1, %2" : "=v"(r) : "v"(lo), "v"(hi)); return r; }
; __device__ __forceinline__ f32x4 ln_fix(const f32x4& a, float mu, float rs, const f32x4& cs, const f32x4& cb) { return (a - cs * mu) * rs + cb; }
;     __device__ __forceinline__ void operator()(const f32x4 (&acc)[2][2][4][2], const Unit& u, int wr, int wc, int fr_in, int fq_in) const {
;     ...
;             for (int m = 0; m < 4; ++m) { bf16_t* rowp = base + (size_t)(row0 + ai * HALF + m * 16) * 1024 + col0;
; #pragma unroll
;                 for (int bj = 0; bj < 2; ++bj) { const f32x4 v0r = ln_fix(acc[ai][bj][m][0], rst.mu[ai][m], rst.rs[ai][m], csv[bj][0], cbv[bj][0]), v1r = ln_fix(acc[ai][bj][m][1], rst.mu[ai][m], rst.rs[ai][m], csv[bj][1], cbv[bj][1]);
;                     ks[bj][0] += v0r; ks[bj][1] += v1r; const f32x4 v0 = v0r * sc, v1 = v1r * sc;
;                     u32x4 w; w.x = cvt_pk_bf16(v0[0], v0[1]); w.y = cvt_pk_bf16(v0[2], v0[3]); w.z = cvt_pk_bf16(v1[0], v1[1]); w.w = cvt_pk_bf16(v1[2], v1[3]);
;                     *(u32x4*)(rowp + bj * HALF) = w; } }
;         if (kb) {
;             const int colt = (u.pn - 4) * BM + wc * 32 + 8 * fq; const int b = u.pm >> 5, blk = u.pm & 31;
; #pragma unroll
;             for (int bj = 0; bj < 2; ++bj)
; #pragma unroll
;                 for (int n = 0; n < 2; ++n)
; #pragma unroll
;                     for (int j = 0; j < 4; ++j) { float s = ks[bj][n][j];
;                         s += __shfl_xor(s, 1); s += __shfl_xor(s, 2); s += __shfl_xor(s, 4); s += __shfl_xor(s, 8);
;                         if (fr == 0) { const int col = colt + bj * HALF + 4 * n + j; atomicAdd(kbar + ((size_t)((b * 8 + (col >> 6)) * 32 + blk)) * 64 + (col & 63), s); } }
	v_xor_b32_e32 v5, 0x80000000, v143
	v_xor_b32_e32 v4, 0x80000000, v142
	v_pk_fma_f32 v[16:17], v[180:181], v[130:131], v[18:19] op_sel_hi:[0,1,1] neg_lo:[1,0,0] neg_hi:[1,0,0]
	v_pk_fma_f32 v[18:19], v[190:191], v[182:183], v[132:133] op_sel_hi:[1,0,1]
	v_pk_mul_f32 v[180:181], v[224:225], v[20:21] op_sel_hi:[0,1]
	v_pk_mul_f32 v[190:191], v[224:225], v[22:23] op_sel_hi:[0,1]
	v_pk_fma_f32 v[4:5], v[4:5], v[178:179], v[6:7] op_sel_hi:[1,0,1]
	v_cvt_pk_bf16_f32 v190, v190, v191
	v_cvt_pk_bf16_f32 v191, v180, v181
	v_lshlrev_b64 v[180:181], 11, v[186:187]
	v_pk_fma_f32 v[14:15], v[14:15], v[168:169], v[154:155] op_sel_hi:[1,0,1]
	v_pk_fma_f32 v[8:9], v[150:151], v[178:179], v[10:11] op_sel_hi:[1,0,1]
	v_pk_fma_f32 v[4:5], v[4:5], v[168:169], v[138:139] op_sel_hi:[1,0,1]
	v_pk_fma_f32 v[6:7], v[140:141], v[168:169], v[136:137] op_sel_hi:[1,0,1]
	v_pk_fma_f32 v[128:129], v[178:179], v[128:129], v[0:1] op_sel_hi:[0,1,1] neg_lo:[1,0,0] neg_hi:[1,0,0]
	v_pk_fma_f32 v[0:1], v[178:179], v[130:131], v[2:3] op_sel_hi:[0,1,1] neg_lo:[1,0,0] neg_hi:[1,0,0]
	v_pk_fma_f32 v[16:17], v[16:17], v[182:183], v[134:135] op_sel_hi:[1,0,1]
	v_pk_mul_f32 v[192:193], v[224:225], v[18:19] op_sel_hi:[0,1]
	v_lshl_add_u64 v[180:181], v[226:227], 0, v[180:181]
	v_pk_fma_f32 v[8:9], v[8:9], v[168:169], v[146:147] op_sel_hi:[1,0,1]
	v_pk_fma_f32 v[10:11], v[148:149], v[168:169], v[144:145] op_sel_hi:[1,0,1]
	v_pk_mul_f32 v[146:147], v[224:225], v[14:15] op_sel_hi:[0,1]
	v_pk_mul_f32 v[144:145], v[224:225], v[12:13] op_sel_hi:[0,1]
	v_pk_fma_f32 v[0:1], v[0:1], v[168:169], v[134:135] op_sel_hi:[1,0,1]
	v_pk_fma_f32 v[2:3], v[128:129], v[168:169], v[132:133] op_sel_hi:[1,0,1]
	v_pk_mul_f32 v[130:131], v[224:225], v[4:5] op_sel_hi:[0,1]
	v_pk_mul_f32 v[128:129], v[224:225], v[6:7] op_sel_hi:[0,1]
	v_pk_mul_f32 v[196:197], v[224:225], v[16:17] op_sel_hi:[0,1]
	v_cvt_pk_bf16_f32 v192, v192, v193
	v_cvt_pk_bf16_f32 v193, v196, v197
	global_store_dwordx4 v[184:185], v[190:193], off offset:256
	v_pk_mul_f32 v[148:149], v[224:225], v[8:9] op_sel_hi:[0,1]
	v_pk_mul_f32 v[150:151], v[224:225], v[10:11] op_sel_hi:[0,1]
	v_cvt_pk_bf16_f32 v144, v144, v145
	v_cvt_pk_bf16_f32 v145, v146, v147
	v_cvt_pk_bf16_f32 v146, v150, v151
	v_cvt_pk_bf16_f32 v147, v148, v149
	global_store_dwordx4 v[180:181], v[144:147], off
	v_pk_mul_f32 v[132:133], v[224:225], v[0:1] op_sel_hi:[0,1]
	v_pk_mul_f32 v[134:135], v[224:225], v[2:3] op_sel_hi:[0,1]
	v_cvt_pk_bf16_f32 v128, v128, v129
	v_cvt_pk_bf16_f32 v129, v130, v131
	v_cvt_pk_bf16_f32 v130, v134, v135
	v_cvt_pk_bf16_f32 v131, v132, v133
	global_store_dwordx4 v[180:181], v[128:131], off offset:256
	s_cbranch_scc1 .LBB0_470
	v_pk_add_f32 v[126:127], v[126:127], 0 op_sel_hi:[1,0]
	s_add_i32 s8, s62, s8
	v_pk_add_f32 v[110:111], v[110:111], v[126:127]
	s_and_b32 s37, s46, 31
	v_pk_add_f32 v[94:95], v[94:95], v[110:111]
	s_nop 0
	v_pk_add_f32 v[78:79], v[78:79], v[94:95]
	s_nop 0
	v_pk_add_f32 v[62:63], v[62:63], v[78:79]
	s_nop 0
	v_pk_add_f32 v[46:47], v[62:63], v[46:47]
	v_add_u32_e32 v63, s8, v229
	v_pk_add_f32 v[30:31], v[46:47], v[30:31]
	s_ashr_i32 s8, s46, 2
	v_pk_add_f32 v[30:31], v[30:31], v[12:13]
	v_and_b32_e32 v13, 64, v225
	v_xor_b32_e32 v12, 1, v225
	v_add_u32_e32 v13, 64, v13
	v_cmp_lt_i32_e32 vcc, v12, v13
	s_and_b32 s41, s8, -8
	v_and_b32_e32 v94, 56, v63
	v_cndmask_b32_e32 v12, v225, v12, vcc
	v_lshlrev_b32_e32 v46, 2, v12
	v_xor_b32_e32 v12, 2, v225
	v_cmp_lt_i32_e32 vcc, v12, v13
	ds_bpermute_b32 v78, v46, v30
	v_lshlrev_b32_e32 v168, 2, v94
	v_cndmask_b32_e32 v12, v225, v12, vcc
	v_lshlrev_b32_e32 v47, 2, v12
	v_xor_b32_e32 v12, 4, v225
	v_cmp_lt_i32_e32 vcc, v12, v13
	s_nop 1
	v_cndmask_b32_e32 v12, v225, v12, vcc
	v_lshlrev_b32_e32 v62, 2, v12
	v_xor_b32_e32 v12, 8, v225
	v_cmp_lt_i32_e32 vcc, v12, v13
	s_waitcnt lgkmcnt(0)
	v_add_f32_e32 v13, v30, v78
	ds_bpermute_b32 v78, v47, v13
	v_cndmask_b32_e32 v12, v225, v12, vcc
	v_lshlrev_b32_e32 v30, 2, v12
	v_ashrrev_i32_e32 v12, 6, v63
	v_add_u32_e32 v12, s41, v12
	s_waitcnt lgkmcnt(0)
	v_add_f32_e32 v13, v13, v78
	ds_bpermute_b32 v78, v62, v13
	v_lshl_or_b32 v12, v12, 5, s37
	v_cmp_eq_u32_e32 vcc, 0, v228
	s_waitcnt lgkmcnt(0)
	v_add_f32_e32 v78, v13, v78
	ds_bpermute_b32 v79, v30, v78
	v_ashrrev_i32_e32 v13, 31, v12
	v_lshlrev_b64 v[12:13], 8, v[12:13]
	v_lshl_add_u64 v[12:13], s[10:11], 0, v[12:13]
	s_and_saveexec_b64 s[46:47], vcc
	s_cbranch_execz .LBB0_439
	v_lshl_add_u64 v[94:95], v[12:13], 0, v[168:169]
	s_waitcnt lgkmcnt(0)
	v_add_f32_e32 v78, v78, v79
	global_atomic_add_f32 v[94:95], v78, off

; __device__ __forceinline__ void load_row_stats(const float* sp, int row0, RowStats& r) {
; #pragma unroll
;     for (int ai = 0; ai < 2; ++ai) { asm volatile("" ::: "memory");
; #pragma unroll
;         for (int m = 0; m < 4; ++m) { const float* p = sp + (size_t)(row0 + ai * HALF + m * 16) * 8; const f32x4 a = *(const f32x4*)p, b = *(const f32x4*)(p + 4);
;             const float s1 = (a[0] + a[2]) + (b[0] + b[2]), s2 = (a[1] + a[3]) + (b[1] + b[3]); const float mu = s1 * (1.f / 1024.f); const float var = s2 * (1.f / 1024.f) - mu * mu;
;             r.mu[ai][m] = mu; r.rs[ai][m] = __builtin_amdgcn_rsqf(__builtin_fmaxf(var, 0.f) + 1e-5f); } }
;     __device__ __forceinline__ void operator()(const f32x4 (&acc)[2][2][4][2], const Unit& u, int wr, int wc, int fr_in, int fq_in) const {
;     ...
;         const int row0 = u.pm * BM + wr * 64 + fr, col0 = u.pn * BM + wc * 32 + 8 * fq;
;         float al_ = alpha, s_ = s; asm volatile("" : "+v"(al_), "+v"(s_));
;         RowStats rst;
;         if constexpr (BASE == 1) load_row_stats(sp_old, row0, rst);
;         float s1[2][4], s2[2][4];
; #pragma unroll
;         for (int ai = 0; ai < 2; ++ai)
; #pragma unroll
;             for (int m = 0; m < 4; ++m) { s1[ai][m] = 0.f; s2[ai][m] = 0.f; }
; #pragma unroll
;         for (int bj = 0; bj < 2; ++bj) { f32x4 gv[2], bv[2];
;             if constexpr (BASE == 1) {
; #pragma unroll
;                 for (int n = 0; n < 2; ++n) { gv[n] = *(const f32x4*)(lg + col0 + bj * HALF + 4 * n); bv[n] = *(const f32x4*)(lb + col0 + bj * HALF + 4 * n); } }
.LBB0_1175:
	s_lshl_b32 s11, s48, 8
	v_mov_b32_e32 v203, v177
	v_mov_b32_e32 v199, v175
	s_add_i32 s8, s11, s60
	v_mov_b32_e32 v174, 1.0
	v_add_u32_e32 v146, s8, v199
	v_ashrrev_i32_e32 v147, 31, v146
	v_mov_b32_e32 v176, 0x3fb504f3
	s_cselect_b32 s99, 1, 0
	v_readfirstlane_b32 s98, v254
	v_and_b32_e32 v128, 0xffffff00, v146
	s_nop 0
	s_cmpk_lt_u32 s98, 0x100
	s_cbranch_scc0 .Lrs1_skip
	v_add_u32_e32 v128, v128, v254
	v_mov_b32_e32 v129, 0
	v_lshlrev_b64 v[128:129], 5, v[128:129]
	v_lshl_add_u64 v[132:133], s[24:25], 0, v[128:129]
	global_load_dwordx4 v[128:131], v[132:133], off offset:16
	s_nop 0
	global_load_dwordx4 v[132:135], v[132:133], off
	s_waitcnt vmcnt(0)
	v_pk_add_f32 v[128:129], v[128:129], v[130:131]
	v_pk_add_f32 v[132:133], v[132:133], v[134:135]
	s_nop 0
	v_pk_add_f32 v[128:129], v[132:133], v[128:129]
	s_nop 0
	v_pk_mul_f32 v[128:129], v[128:129], s[40:41] op_sel_hi:[1,0]
	v_lshlrev_b32_e32 v130, 3, v254
	v_add_u32_e32 v130, 0x22400, v130
	ds_write_b64 v130, v[128:129]
.Lrs1_skip:
	s_waitcnt vmcnt(0) lgkmcnt(0)
	s_barrier
	v_and_b32_e32 v130, 0xff, v146
	v_lshlrev_b32_e32 v130, 3, v130
	v_add_u32_e32 v130, 0x22400, v130
	ds_read_b64 v[208:209], v130
	ds_read_b64 v[204:205], v130 offset:128
	ds_read_b64 v[200:201], v130 offset:256
	ds_read_b64 v[196:197], v130 offset:384
	ds_read_b64 v[192:193], v130 offset:1024
	ds_read_b64 v[188:189], v130 offset:1152
	ds_read_b64 v[184:185], v130 offset:1280
	ds_read_b64 v[180:181], v130 offset:1408
	s_cmp_lg_u32 s99, 0
	s_waitcnt lgkmcnt(0)
	v_add_u32_e32 v144, 16, v146
	v_ashrrev_i32_e32 v145, 31, v144
	v_add_u32_e32 v148, 32, v146
	v_ashrrev_i32_e32 v149, 31, v148
	v_add_u32_e32 v150, 48, v146
	v_ashrrev_i32_e32 v151, 31, v150
	v_add_u32_e32 v222, 0x80, v146
	v_ashrrev_i32_e32 v223, 31, v222
	v_add_u32_e32 v226, 0x90, v146
	v_ashrrev_i32_e32 v227, 31, v226
	v_add_u32_e32 v210, 0xa0, v146
	v_ashrrev_i32_e32 v211, 31, v210
	v_add_u32_e32 v212, 0xb0, v146
	v_ashrrev_i32_e32 v213, 31, v212
	s_lshl_b32 s8, s10, 8
	s_or_b32 s8, s8, s61
	v_lshl_add_u32 v152, v203, 3, s8
	v_ashrrev_i32_e32 v153, 31, v152
	v_lshlrev_b64 v[220:221], 1, v[152:153]
	v_lshl_add_u64 v[234:235], s[22:23], 0, v[220:221]
	v_lshlrev_b64 v[232:233], 11, v[146:147]
	v_lshl_add_u64 v[218:219], v[234:235], 0, v[232:233]
	v_lshlrev_b64 v[236:237], 11, v[144:145]
	v_lshl_add_u64 v[224:225], v[234:235], 0, v[236:237]
	v_lshlrev_b64 v[240:241], 11, v[148:149]
	v_lshl_add_u64 v[228:229], v[234:235], 0, v[240:241]
	v_lshlrev_b64 v[238:239], 11, v[150:151]
	v_lshl_add_u64 v[230:231], v[234:235], 0, v[238:239]
	s_nop 0
	v_fma_f32 v128, -v208, v208, v209
	v_max_f32_e32 v128, 0, v128
	v_add_f32_e32 v128, 0x3727c5ac, v128
	v_rsq_f32_e32 v206, v128
	s_nop 0
	v_fma_f32 v128, -v204, v204, v205
	v_max_f32_e32 v128, 0, v128
	v_add_f32_e32 v128, 0x3727c5ac, v128
	v_rsq_f32_e32 v202, v128
	s_nop 0
	v_fma_f32 v128, -v200, v200, v201
	v_max_f32_e32 v128, 0, v128
	v_add_f32_e32 v128, 0x3727c5ac, v128
	v_rsq_f32_e32 v198, v128
	s_nop 0
	v_fma_f32 v128, -v196, v196, v197
	v_max_f32_e32 v128, 0, v128
	v_add_f32_e32 v128, 0x3727c5ac, v128
	v_rsq_f32_e32 v194, v128
	s_nop 0
	v_fma_f32 v128, -v192, v192, v193
	v_max_f32_e32 v128, 0, v128
	v_add_f32_e32 v128, 0x3727c5ac, v128
	v_rsq_f32_e32 v190, v128
	s_nop 0
	v_fma_f32 v128, -v188, v188, v189
	v_max_f32_e32 v128, 0, v128
	v_add_f32_e32 v128, 0x3727c5ac, v128
	v_rsq_f32_e32 v186, v128
	s_nop 0
	v_fma_f32 v128, -v184, v184, v185
	v_max_f32_e32 v128, 0, v128
	v_add_f32_e32 v128, 0x3727c5ac, v128
	v_rsq_f32_e32 v182, v128
	s_nop 0
	v_fma_f32 v128, -v180, v180, v181
	v_max_f32_e32 v128, 0, v128
	v_add_f32_e32 v128, 0x3727c5ac, v128
	v_rsq_f32_e32 v178, v128
	v_lshlrev_b64 v[128:129], 2, v[152:153]
	v_lshl_add_u64 v[216:217], s[4:5], 0, v[128:129]
	v_lshl_add_u64 v[214:215], s[6:7], 0, v[128:129]
	global_load_dwordx4 v[128:131], v[216:217], off offset:16
	global_load_dwordx4 v[136:139], v[216:217], off
	global_load_dwordx4 v[132:135], v[214:215], off offset:16
	global_load_dwordx4 v[140:143], v[214:215], off
	global_load_dwordx4 v[152:155], v[218:219], off
	global_load_dwordx4 v[144:147], v[224:225], off
	global_load_dwordx4 v[242:245], v[228:229], off
	global_load_dwordx4 v[148:151], v[230:231], off
	s_waitcnt vmcnt(0)
; __device__ __forceinline__ unsigned cvt_pk_bf16(float lo, float hi) { unsigned r; asm("v_cvt_pk_bf16_f32 %0, %1, %2" : "=v"(r) : "v"(lo), "v"(hi)); return r; }
; __device__ __forceinline__ float bf_lo(unsigned w) { return __uint_as_float(w << 16); }
; __device__ __forceinline__ float bf_hi(unsigned w) { return __uint_as_float(w & 0xffff0000u); }
;     __device__ __forceinline__ void operator()(const f32x4 (&acc)[2][2][4][2], const Unit& u, int wr, int wc, int fr_in, int fq_in) const {
;     ...
;                 for (int m = 0; m < 4; ++m) { const size_t off = (size_t)(row0 + ai * HALF + m * 16) * 1024 + col0 + bj * HALF;
;                     if constexpr (BASE == 0) { pf[m][0] = *(const f32x4*)(basef + off); pf[m][1] = *(const f32x4*)(basef + off + 4); } else pb[m] = *(const u32x4*)(baseb + off); }
; #pragma unroll
;                 for (int m = 0; m < 4; ++m) { const size_t off = (size_t)(row0 + ai * HALF + m * 16) * 1024 + col0 + bj * HALF; f32x4 b[2];
;                     if constexpr (BASE == 0) { b[0] = pf[m][0]; b[1] = pf[m][1]; }
;                     else { const u32x4 pw = pb[m]; b[0] = (f32x4){bf_lo(pw.x), bf_hi(pw.x), bf_lo(pw.y), bf_hi(pw.y)}; b[1] = (f32x4){bf_lo(pw.z), bf_hi(pw.z), bf_lo(pw.w), bf_hi(pw.w)}; }
;                     f32x4 z[2];
; #pragma unroll
;                     for (int n = 0; n < 2; ++n) { if constexpr (BASE == 1) b[n] = (b[n] - rst.mu[ai][m]) * rst.rs[ai][m] * gv[n] + bv[n];
;                         z[n] = b[n] * al_ + acc[ai][bj][m][n] * s_; }
;                     u32x4 w; w.x = cvt_pk_bf16(z[0][0], z[0][1]); w.y = cvt_pk_bf16(z[0][2], z[0][3]); w.z = cvt_pk_bf16(z[1][0], z[1][1]); w.w = cvt_pk_bf16(z[1][2], z[1][3]);
;                     *(u32x4*)(zb + off) = w;
;                     const float r0 = bf_lo(w.x), r1 = bf_hi(w.x), r2 = bf_lo(w.y), r3 = bf_hi(w.y), r4 = bf_lo(w.z), r5 = bf_hi(w.z), r6 = bf_lo(w.w), r7 = bf_hi(w.w);
;                     s1[ai][m] += ((r0 + r1) + (r2 + r3)) + ((r4 + r5) + (r6 + r7)); s2[ai][m] += ((r0 * r0 + r1 * r1) + (r2 * r2 + r3 * r3)) + ((r4 * r4 + r5 * r5) + (r6 * r6 + r7 * r7)); }
	v_lshlrev_b32_e32 v165, 16, v152
	v_and_b32_e32 v181, 0xffff0000, v152
	v_lshlrev_b32_e32 v152, 16, v153
	v_and_b32_e32 v153, 0xffff0000, v153
	v_lshlrev_b32_e32 v185, 16, v154
	v_and_b32_e32 v189, 0xffff0000, v154
	v_lshlrev_b32_e32 v193, 16, v155
	v_and_b32_e32 v197, 0xffff0000, v155
	v_sub_f32_e32 v153, v153, v208
	v_sub_f32_e32 v152, v152, v208
	v_sub_f32_e32 v155, v181, v208
	v_sub_f32_e32 v154, v165, v208
	v_pk_mul_f32 v[154:155], v[206:207], v[154:155] op_sel_hi:[0,1]
	v_pk_mul_f32 v[152:153], v[206:207], v[152:153] op_sel_hi:[0,1]
	v_pk_fma_f32 v[152:153], v[138:139], v[152:153], v[142:143]
	v_pk_fma_f32 v[154:155], v[136:137], v[154:155], v[140:141]
	v_pk_mul_f32 v[152:153], v[176:177], v[152:153] op_sel_hi:[0,1]
	v_pk_mul_f32 v[154:155], v[176:177], v[154:155] op_sel_hi:[0,1]
	v_pk_fma_f32 v[126:127], v[126:127], v[174:175], v[152:153] op_sel_hi:[1,0,1]
	v_pk_fma_f32 v[124:125], v[124:125], v[174:175], v[154:155] op_sel_hi:[1,0,1]
	v_sub_f32_e32 v153, v197, v208
	v_sub_f32_e32 v152, v193, v208
	v_sub_f32_e32 v155, v189, v208
	v_sub_f32_e32 v154, v185, v208
	v_pk_mul_f32 v[154:155], v[206:207], v[154:155] op_sel_hi:[0,1]
	v_pk_mul_f32 v[152:153], v[206:207], v[152:153] op_sel_hi:[0,1]
	v_pk_fma_f32 v[152:153], v[130:131], v[152:153], v[134:135]
	v_pk_fma_f32 v[154:155], v[128:129], v[154:155], v[132:133]
	v_pk_mul_f32 v[152:153], v[176:177], v[152:153] op_sel_hi:[0,1]
	v_pk_mul_f32 v[154:155], v[176:177], v[154:155] op_sel_hi:[0,1]
	v_pk_fma_f32 v[152:153], v[122:123], v[174:175], v[152:153] op_sel_hi:[1,0,1]
	v_pk_fma_f32 v[122:123], v[120:121], v[174:175], v[154:155] op_sel_hi:[1,0,1]
	v_cvt_pk_bf16_f32 v120, v124, v125
	v_lshl_add_u64 v[124:125], s[22:23], 0, v[232:233]
	v_cvt_pk_bf16_f32 v121, v126, v127
	v_lshl_add_u64 v[232:233], v[124:125], 0, v[220:221]
	v_lshlrev_b32_e32 v125, 16, v144
	v_and_b32_e32 v127, 0xffff0000, v144
	v_lshlrev_b32_e32 v144, 16, v145
	v_and_b32_e32 v145, 0xffff0000, v145
	v_cvt_pk_bf16_f32 v122, v122, v123
	v_cvt_pk_bf16_f32 v123, v152, v153
	v_lshlrev_b32_e32 v153, 16, v146
	v_and_b32_e32 v155, 0xffff0000, v146
	v_lshlrev_b32_e32 v165, 16, v147
	v_and_b32_e32 v181, 0xffff0000, v147
	v_sub_f32_e32 v145, v145, v204
	v_sub_f32_e32 v144, v144, v204
	v_sub_f32_e32 v147, v127, v204
	v_sub_f32_e32 v146, v125, v204
	v_pk_mul_f32 v[146:147], v[202:203], v[146:147] op_sel_hi:[0,1]
	v_pk_mul_f32 v[144:145], v[202:203], v[144:145] op_sel_hi:[0,1]
	v_pk_fma_f32 v[144:145], v[138:139], v[144:145], v[142:143]
	v_pk_fma_f32 v[146:147], v[136:137], v[146:147], v[140:141]
	v_pk_mul_f32 v[144:145], v[176:177], v[144:145] op_sel_hi:[0,1]
	v_pk_mul_f32 v[146:147], v[176:177], v[146:147] op_sel_hi:[0,1]
	v_pk_fma_f32 v[118:119], v[118:119], v[174:175], v[144:145] op_sel_hi:[1,0,1]
	v_pk_fma_f32 v[116:117], v[116:117], v[174:175], v[146:147] op_sel_hi:[1,0,1]
	v_sub_f32_e32 v145, v181, v204
	v_sub_f32_e32 v144, v165, v204
	v_sub_f32_e32 v147, v155, v204
	v_sub_f32_e32 v146, v153, v204
	v_pk_mul_f32 v[146:147], v[202:203], v[146:147] op_sel_hi:[0,1]
	v_pk_mul_f32 v[144:145], v[202:203], v[144:145] op_sel_hi:[0,1]
	v_pk_fma_f32 v[144:145], v[130:131], v[144:145], v[134:135]
	v_pk_fma_f32 v[146:147], v[128:129], v[146:147], v[132:133]
	v_pk_mul_f32 v[144:145], v[176:177], v[144:145] op_sel_hi:[0,1]
	v_pk_mul_f32 v[146:147], v[176:177], v[146:147] op_sel_hi:[0,1]
	v_pk_fma_f32 v[144:145], v[114:115], v[174:175], v[144:145] op_sel_hi:[1,0,1]
	v_pk_fma_f32 v[114:115], v[112:113], v[174:175], v[146:147] op_sel_hi:[1,0,1]
	v_cvt_pk_bf16_f32 v113, v118, v119
	v_lshlrev_b32_e32 v125, 16, v242
	v_and_b32_e32 v127, 0xffff0000, v242
	v_lshlrev_b32_e32 v118, 16, v243
	v_and_b32_e32 v119, 0xffff0000, v243
	v_cvt_pk_bf16_f32 v114, v114, v115
	v_cvt_pk_bf16_f32 v115, v144, v145
	v_sub_f32_e32 v119, v119, v200
	v_sub_f32_e32 v118, v118, v200
	v_sub_f32_e32 v145, v127, v200
	v_sub_f32_e32 v144, v125, v200
	v_pk_mul_f32 v[144:145], v[198:199], v[144:145] op_sel_hi:[0,1]
	v_pk_mul_f32 v[118:119], v[198:199], v[118:119] op_sel_hi:[0,1]
	v_pk_fma_f32 v[118:119], v[138:139], v[118:119], v[142:143]
	v_pk_fma_f32 v[144:145], v[136:137], v[144:145], v[140:141]
	v_lshlrev_b32_e32 v146, 16, v244
	v_and_b32_e32 v147, 0xffff0000, v244
	v_lshlrev_b32_e32 v153, 16, v245
	v_and_b32_e32 v155, 0xffff0000, v245
	v_pk_mul_f32 v[144:145], v[176:177], v[144:145] op_sel_hi:[0,1]
	v_pk_mul_f32 v[118:119], v[176:177], v[118:119] op_sel_hi:[0,1]
	v_pk_fma_f32 v[110:111], v[110:111], v[174:175], v[118:119] op_sel_hi:[1,0,1]
	v_pk_fma_f32 v[108:109], v[108:109], v[174:175], v[144:145] op_sel_hi:[1,0,1]
	v_sub_f32_e32 v119, v155, v200
	v_sub_f32_e32 v118, v153, v200
	v_sub_f32_e32 v145, v147, v200
	v_sub_f32_e32 v144, v146, v200
	v_pk_mul_f32 v[144:145], v[198:199], v[144:145] op_sel_hi:[0,1]
	v_pk_mul_f32 v[118:119], v[198:199], v[118:119] op_sel_hi:[0,1]
	v_pk_fma_f32 v[118:119], v[130:131], v[118:119], v[134:135]
	v_pk_fma_f32 v[144:145], v[128:129], v[144:145], v[132:133]
	v_pk_mul_f32 v[118:119], v[176:177], v[118:119] op_sel_hi:[0,1]
	v_pk_mul_f32 v[144:145], v[176:177], v[144:145] op_sel_hi:[0,1]
	v_pk_fma_f32 v[118:119], v[106:107], v[174:175], v[118:119] op_sel_hi:[1,0,1]
	v_pk_fma_f32 v[106:107], v[104:105], v[174:175], v[144:145] op_sel_hi:[1,0,1]
	v_cvt_pk_bf16_f32 v105, v110, v111
	v_lshlrev_b32_e32 v110, 16, v149
	v_cvt_pk_bf16_f32 v106, v106, v107
	v_cvt_pk_bf16_f32 v107, v118, v119
	v_lshlrev_b32_e32 v118, 16, v148
	v_and_b32_e32 v119, 0xffff0000, v148
	v_and_b32_e32 v111, 0xffff0000, v149
	v_sub_f32_e32 v111, v111, v196
	v_sub_f32_e32 v110, v110, v196
	v_sub_f32_e32 v119, v119, v196
	v_sub_f32_e32 v118, v118, v196
; __device__ __forceinline__ unsigned cvt_pk_bf16(float lo, float hi) { unsigned r; asm("v_cvt_pk_bf16_f32 %0, %1, %2" : "=v"(r) : "v"(lo), "v"(hi)); return r; }
; __device__ __forceinline__ float bf_lo(unsigned w) { return __uint_as_float(w << 16); }
; __device__ __forceinline__ float bf_hi(unsigned w) { return __uint_as_float(w & 0xffff0000u); }
;     __device__ __forceinline__ void operator()(const f32x4 (&acc)[2][2][4][2], const Unit& u, int wr, int wc, int fr_in, int fq_in) const {
;     ...
;                 for (int m = 0; m < 4; ++m) { const size_t off = (size_t)(row0 + ai * HALF + m * 16) * 1024 + col0 + bj * HALF;
;                     if constexpr (BASE == 0) { pf[m][0] = *(const f32x4*)(basef + off); pf[m][1] = *(const f32x4*)(basef + off + 4); } else pb[m] = *(const u32x4*)(baseb + off); }
; #pragma unroll
;                 for (int m = 0; m < 4; ++m) { const size_t off = (size_t)(row0 + ai * HALF + m * 16) * 1024 + col0 + bj * HALF; f32x4 b[2];
;                     if constexpr (BASE == 0) { b[0] = pf[m][0]; b[1] = pf[m][1]; }
;                     else { const u32x4 pw = pb[m]; b[0] = (f32x4){bf_lo(pw.x), bf_hi(pw.x), bf_lo(pw.y), bf_hi(pw.y)}; b[1] = (f32x4){bf_lo(pw.z), bf_hi(pw.z), bf_lo(pw.w), bf_hi(pw.w)}; }
;                     f32x4 z[2];
; #pragma unroll
;                     for (int n = 0; n < 2; ++n) { if constexpr (BASE == 1) b[n] = (b[n] - rst.mu[ai][m]) * rst.rs[ai][m] * gv[n] + bv[n];
;                         z[n] = b[n] * al_ + acc[ai][bj][m][n] * s_; }
;                     u32x4 w; w.x = cvt_pk_bf16(z[0][0], z[0][1]); w.y = cvt_pk_bf16(z[0][2], z[0][3]); w.z = cvt_pk_bf16(z[1][0], z[1][1]); w.w = cvt_pk_bf16(z[1][2], z[1][3]);
;                     *(u32x4*)(zb + off) = w;
;                     const float r0 = bf_lo(w.x), r1 = bf_hi(w.x), r2 = bf_lo(w.y), r3 = bf_hi(w.y), r4 = bf_lo(w.z), r5 = bf_hi(w.z), r6 = bf_lo(w.w), r7 = bf_hi(w.w);
;                     s1[ai][m] += ((r0 + r1) + (r2 + r3)) + ((r4 + r5) + (r6 + r7)); s2[ai][m] += ((r0 * r0 + r1 * r1) + (r2 * r2 + r3 * r3)) + ((r4 * r4 + r5 * r5) + (r6 * r6 + r7 * r7)); }
	v_pk_mul_f32 v[118:119], v[194:195], v[118:119] op_sel_hi:[0,1]
	v_pk_mul_f32 v[110:111], v[194:195], v[110:111] op_sel_hi:[0,1]
	v_pk_fma_f32 v[110:111], v[138:139], v[110:111], v[142:143]
	v_pk_fma_f32 v[118:119], v[136:137], v[118:119], v[140:141]
	v_lshlrev_b32_e32 v125, 16, v150
	v_and_b32_e32 v127, 0xffff0000, v150
	v_lshlrev_b32_e32 v144, 16, v151
	v_and_b32_e32 v145, 0xffff0000, v151
	v_pk_mul_f32 v[118:119], v[176:177], v[118:119] op_sel_hi:[0,1]
	v_pk_mul_f32 v[110:111], v[176:177], v[110:111] op_sel_hi:[0,1]
	v_pk_fma_f32 v[102:103], v[102:103], v[174:175], v[110:111] op_sel_hi:[1,0,1]
	v_pk_fma_f32 v[100:101], v[100:101], v[174:175], v[118:119] op_sel_hi:[1,0,1]
	v_sub_f32_e32 v111, v145, v196
	v_sub_f32_e32 v110, v144, v196
	v_sub_f32_e32 v119, v127, v196
	v_sub_f32_e32 v118, v125, v196
	v_pk_mul_f32 v[118:119], v[194:195], v[118:119] op_sel_hi:[0,1]
	v_pk_mul_f32 v[110:111], v[194:195], v[110:111] op_sel_hi:[0,1]
	v_pk_fma_f32 v[110:111], v[130:131], v[110:111], v[134:135]
	v_pk_fma_f32 v[118:119], v[128:129], v[118:119], v[132:133]
	v_pk_mul_f32 v[110:111], v[176:177], v[110:111] op_sel_hi:[0,1]
	v_pk_mul_f32 v[118:119], v[176:177], v[118:119] op_sel_hi:[0,1]
	v_cvt_pk_bf16_f32 v112, v116, v117
	v_lshl_add_u64 v[116:117], s[22:23], 0, v[236:237]
	v_cvt_pk_bf16_f32 v104, v108, v109
	v_lshl_add_u64 v[108:109], s[22:23], 0, v[240:241]
	v_pk_fma_f32 v[110:111], v[98:99], v[174:175], v[110:111] op_sel_hi:[1,0,1]
	v_pk_fma_f32 v[98:99], v[96:97], v[174:175], v[118:119] op_sel_hi:[1,0,1]
	v_cvt_pk_bf16_f32 v96, v100, v101
	v_lshl_add_u64 v[100:101], s[22:23], 0, v[238:239]
	v_lshl_add_u64 v[116:117], v[116:117], 0, v[220:221]
	v_lshl_add_u64 v[108:109], v[108:109], 0, v[220:221]
	v_lshl_add_u64 v[100:101], v[100:101], 0, v[220:221]
	global_store_dwordx4 v[232:233], v[120:123], off
	global_store_dwordx4 v[116:117], v[112:115], off
	global_store_dwordx4 v[108:109], v[104:107], off
	v_cvt_pk_bf16_f32 v97, v102, v103
	v_cvt_pk_bf16_f32 v98, v98, v99
	v_cvt_pk_bf16_f32 v99, v110, v111
	global_store_dwordx4 v[100:101], v[96:99], off
	v_lshlrev_b64 v[144:145], 11, v[222:223]
	v_lshl_add_u64 v[102:103], v[234:235], 0, v[144:145]
	global_load_dwordx4 v[236:239], v[102:103], off
	v_lshlrev_b64 v[146:147], 11, v[226:227]
	v_lshl_add_u64 v[110:111], v[234:235], 0, v[146:147]
	global_load_dwordx4 v[240:243], v[110:111], off
	v_lshlrev_b64 v[150:151], 11, v[210:211]
	v_lshl_add_u64 v[148:149], v[234:235], 0, v[150:151]
	global_load_dwordx4 v[244:247], v[148:149], off
	v_lshlrev_b64 v[210:211], 11, v[212:213]
	v_lshl_add_u64 v[118:119], v[234:235], 0, v[210:211]
	global_load_dwordx4 v[248:251], v[118:119], off
	v_and_b32_e32 v154, 0xffff0000, v120
	v_lshlrev_b32_e32 v152, 16, v121
	v_and_b32_e32 v126, 0xffff0000, v122
	v_lshlrev_b32_e32 v124, 16, v123
	s_waitcnt vmcnt(0)
	v_lshlrev_b32_e32 v125, 16, v236
	v_and_b32_e32 v127, 0xffff0000, v236
	v_lshlrev_b32_e32 v153, 16, v237
	v_and_b32_e32 v155, 0xffff0000, v237
	v_sub_f32_e32 v213, v155, v192
	v_sub_f32_e32 v212, v153, v192
	v_sub_f32_e32 v223, v127, v192
	v_sub_f32_e32 v222, v125, v192
	v_pk_mul_f32 v[222:223], v[190:191], v[222:223] op_sel_hi:[0,1]
	v_pk_mul_f32 v[212:213], v[190:191], v[212:213] op_sel_hi:[0,1]
	v_pk_fma_f32 v[212:213], v[138:139], v[212:213], v[142:143]
	v_pk_fma_f32 v[222:223], v[136:137], v[222:223], v[140:141]
	v_lshlrev_b32_e32 v165, 16, v238
	v_and_b32_e32 v181, 0xffff0000, v238
	v_lshlrev_b32_e32 v185, 16, v239
	v_and_b32_e32 v189, 0xffff0000, v239
	v_pk_mul_f32 v[222:223], v[176:177], v[222:223] op_sel_hi:[0,1]
	v_pk_mul_f32 v[212:213], v[176:177], v[212:213] op_sel_hi:[0,1]
	v_pk_fma_f32 v[94:95], v[94:95], v[174:175], v[212:213] op_sel_hi:[1,0,1]
	v_pk_fma_f32 v[92:93], v[92:93], v[174:175], v[222:223] op_sel_hi:[1,0,1]
	v_sub_f32_e32 v213, v189, v192
	v_sub_f32_e32 v212, v185, v192
	v_sub_f32_e32 v223, v181, v192
	v_sub_f32_e32 v222, v165, v192
	v_pk_mul_f32 v[222:223], v[190:191], v[222:223] op_sel_hi:[0,1]
	v_pk_mul_f32 v[212:213], v[190:191], v[212:213] op_sel_hi:[0,1]
	v_pk_fma_f32 v[212:213], v[130:131], v[212:213], v[134:135]
	v_pk_fma_f32 v[222:223], v[128:129], v[222:223], v[132:133]
	v_pk_mul_f32 v[212:213], v[176:177], v[212:213] op_sel_hi:[0,1]
	v_pk_mul_f32 v[222:223], v[176:177], v[222:223] op_sel_hi:[0,1]
	v_pk_fma_f32 v[212:213], v[90:91], v[174:175], v[212:213] op_sel_hi:[1,0,1]
	v_pk_fma_f32 v[90:91], v[88:89], v[174:175], v[222:223] op_sel_hi:[1,0,1]
	v_cvt_pk_bf16_f32 v88, v92, v93
	v_lshl_add_u64 v[92:93], s[22:23], 0, v[144:145]
	v_cvt_pk_bf16_f32 v89, v94, v95
	v_lshl_add_u64 v[144:145], v[92:93], 0, v[220:221]
	v_lshlrev_b32_e32 v94, 16, v240
	v_and_b32_e32 v95, 0xffff0000, v240
	v_lshlrev_b32_e32 v92, 16, v241
	v_and_b32_e32 v93, 0xffff0000, v241
	v_sub_f32_e32 v93, v93, v188
	v_sub_f32_e32 v92, v92, v188
	v_sub_f32_e32 v95, v95, v188
	v_sub_f32_e32 v94, v94, v188
	v_pk_mul_f32 v[94:95], v[186:187], v[94:95] op_sel_hi:[0,1]
	v_pk_mul_f32 v[92:93], v[186:187], v[92:93] op_sel_hi:[0,1]
	v_pk_fma_f32 v[92:93], v[138:139], v[92:93], v[142:143]
	v_pk_fma_f32 v[94:95], v[136:137], v[94:95], v[140:141]
	v_lshlrev_b32_e32 v125, 16, v242
	v_and_b32_e32 v127, 0xffff0000, v242
	v_lshlrev_b32_e32 v153, 16, v243
	v_and_b32_e32 v155, 0xffff0000, v243
	v_pk_mul_f32 v[94:95], v[176:177], v[94:95] op_sel_hi:[0,1]
	v_pk_mul_f32 v[92:93], v[176:177], v[92:93] op_sel_hi:[0,1]
	v_pk_fma_f32 v[86:87], v[86:87], v[174:175], v[92:93] op_sel_hi:[1,0,1]
	v_pk_fma_f32 v[84:85], v[84:85], v[174:175], v[94:95] op_sel_hi:[1,0,1]
	v_sub_f32_e32 v93, v155, v188
	v_sub_f32_e32 v92, v153, v188
	v_sub_f32_e32 v95, v127, v188
	v_sub_f32_e32 v94, v125, v188
; __device__ __forceinline__ unsigned cvt_pk_bf16(float lo, float hi) { unsigned r; asm("v_cvt_pk_bf16_f32 %0, %1, %2" : "=v"(r) : "v"(lo), "v"(hi)); return r; }
; __device__ __forceinline__ float bf_lo(unsigned w) { return __uint_as_float(w << 16); }
; __device__ __forceinline__ float bf_hi(unsigned w) { return __uint_as_float(w & 0xffff0000u); }
;     __device__ __forceinline__ void operator()(const f32x4 (&acc)[2][2][4][2], const Unit& u, int wr, int wc, int fr_in, int fq_in) const {
;     ...
;                 for (int m = 0; m < 4; ++m) { const size_t off = (size_t)(row0 + ai * HALF + m * 16) * 1024 + col0 + bj * HALF;
;                     if constexpr (BASE == 0) { pf[m][0] = *(const f32x4*)(basef + off); pf[m][1] = *(const f32x4*)(basef + off + 4); } else pb[m] = *(const u32x4*)(baseb + off); }
; #pragma unroll
;                 for (int m = 0; m < 4; ++m) { const size_t off = (size_t)(row0 + ai * HALF + m * 16) * 1024 + col0 + bj * HALF; f32x4 b[2];
;                     if constexpr (BASE == 0) { b[0] = pf[m][0]; b[1] = pf[m][1]; }
;                     else { const u32x4 pw = pb[m]; b[0] = (f32x4){bf_lo(pw.x), bf_hi(pw.x), bf_lo(pw.y), bf_hi(pw.y)}; b[1] = (f32x4){bf_lo(pw.z), bf_hi(pw.z), bf_lo(pw.w), bf_hi(pw.w)}; }
;                     f32x4 z[2];
; #pragma unroll
;                     for (int n = 0; n < 2; ++n) { if constexpr (BASE == 1) b[n] = (b[n] - rst.mu[ai][m]) * rst.rs[ai][m] * gv[n] + bv[n];
;                         z[n] = b[n] * al_ + acc[ai][bj][m][n] * s_; }
;                     u32x4 w; w.x = cvt_pk_bf16(z[0][0], z[0][1]); w.y = cvt_pk_bf16(z[0][2], z[0][3]); w.z = cvt_pk_bf16(z[1][0], z[1][1]); w.w = cvt_pk_bf16(z[1][2], z[1][3]);
;                     *(u32x4*)(zb + off) = w;
;                     const float r0 = bf_lo(w.x), r1 = bf_hi(w.x), r2 = bf_lo(w.y), r3 = bf_hi(w.y), r4 = bf_lo(w.z), r5 = bf_hi(w.z), r6 = bf_lo(w.w), r7 = bf_hi(w.w);
;                     s1[ai][m] += ((r0 + r1) + (r2 + r3)) + ((r4 + r5) + (r6 + r7)); s2[ai][m] += ((r0 * r0 + r1 * r1) + (r2 * r2 + r3 * r3)) + ((r4 * r4 + r5 * r5) + (r6 * r6 + r7 * r7)); }
	v_pk_mul_f32 v[94:95], v[186:187], v[94:95] op_sel_hi:[0,1]
	v_pk_mul_f32 v[92:93], v[186:187], v[92:93] op_sel_hi:[0,1]
	v_pk_fma_f32 v[92:93], v[130:131], v[92:93], v[134:135]
	v_pk_fma_f32 v[94:95], v[128:129], v[94:95], v[132:133]
	v_pk_mul_f32 v[92:93], v[176:177], v[92:93] op_sel_hi:[0,1]
	v_pk_mul_f32 v[94:95], v[176:177], v[94:95] op_sel_hi:[0,1]
	v_pk_fma_f32 v[92:93], v[82:83], v[174:175], v[92:93] op_sel_hi:[1,0,1]
	v_pk_fma_f32 v[82:83], v[80:81], v[174:175], v[94:95] op_sel_hi:[1,0,1]
	v_cvt_pk_bf16_f32 v80, v84, v85
	v_lshl_add_u64 v[84:85], s[22:23], 0, v[146:147]
	v_cvt_pk_bf16_f32 v81, v86, v87
	v_lshl_add_u64 v[146:147], v[84:85], 0, v[220:221]
	v_lshlrev_b32_e32 v86, 16, v244
	v_and_b32_e32 v87, 0xffff0000, v244
	v_lshlrev_b32_e32 v84, 16, v245
	v_and_b32_e32 v85, 0xffff0000, v245
	v_sub_f32_e32 v85, v85, v184
	v_sub_f32_e32 v84, v84, v184
	v_sub_f32_e32 v87, v87, v184
	v_sub_f32_e32 v86, v86, v184
	v_pk_mul_f32 v[86:87], v[182:183], v[86:87] op_sel_hi:[0,1]
	v_pk_mul_f32 v[84:85], v[182:183], v[84:85] op_sel_hi:[0,1]
	v_pk_fma_f32 v[84:85], v[138:139], v[84:85], v[142:143]
	v_pk_fma_f32 v[86:87], v[136:137], v[86:87], v[140:141]
	v_cvt_pk_bf16_f32 v82, v82, v83
	v_cvt_pk_bf16_f32 v83, v92, v93
	v_lshlrev_b32_e32 v92, 16, v246
	v_and_b32_e32 v93, 0xffff0000, v246
	v_lshlrev_b32_e32 v94, 16, v247
	v_and_b32_e32 v95, 0xffff0000, v247
	v_pk_mul_f32 v[86:87], v[176:177], v[86:87] op_sel_hi:[0,1]
	v_pk_mul_f32 v[84:85], v[176:177], v[84:85] op_sel_hi:[0,1]
	v_pk_fma_f32 v[78:79], v[78:79], v[174:175], v[84:85] op_sel_hi:[1,0,1]
	v_pk_fma_f32 v[76:77], v[76:77], v[174:175], v[86:87] op_sel_hi:[1,0,1]
	v_sub_f32_e32 v85, v95, v184
	v_sub_f32_e32 v84, v94, v184
	v_sub_f32_e32 v87, v93, v184
	v_sub_f32_e32 v86, v92, v184
	v_pk_mul_f32 v[86:87], v[182:183], v[86:87] op_sel_hi:[0,1]
	v_pk_mul_f32 v[84:85], v[182:183], v[84:85] op_sel_hi:[0,1]
	v_pk_fma_f32 v[84:85], v[130:131], v[84:85], v[134:135]
	v_pk_fma_f32 v[86:87], v[128:129], v[86:87], v[132:133]
	v_pk_mul_f32 v[84:85], v[176:177], v[84:85] op_sel_hi:[0,1]
	v_pk_mul_f32 v[86:87], v[176:177], v[86:87] op_sel_hi:[0,1]
	v_pk_fma_f32 v[84:85], v[74:75], v[174:175], v[84:85] op_sel_hi:[1,0,1]
	v_pk_fma_f32 v[74:75], v[72:73], v[174:175], v[86:87] op_sel_hi:[1,0,1]
	v_cvt_pk_bf16_f32 v72, v76, v77
	v_lshl_add_u64 v[76:77], s[22:23], 0, v[150:151]
	v_cvt_pk_bf16_f32 v73, v78, v79
	v_lshl_add_u64 v[150:151], v[76:77], 0, v[220:221]
	v_lshlrev_b32_e32 v78, 16, v248
	v_and_b32_e32 v79, 0xffff0000, v248
	v_lshlrev_b32_e32 v76, 16, v249
	v_and_b32_e32 v77, 0xffff0000, v249
	v_sub_f32_e32 v77, v77, v180
	v_sub_f32_e32 v76, v76, v180
	v_sub_f32_e32 v79, v79, v180
	v_sub_f32_e32 v78, v78, v180
	v_pk_mul_f32 v[78:79], v[178:179], v[78:79] op_sel_hi:[0,1]
	v_pk_mul_f32 v[76:77], v[178:179], v[76:77] op_sel_hi:[0,1]
	v_pk_fma_f32 v[76:77], v[138:139], v[76:77], v[142:143]
	v_pk_fma_f32 v[78:79], v[136:137], v[78:79], v[140:141]
	v_cvt_pk_bf16_f32 v74, v74, v75
	v_cvt_pk_bf16_f32 v75, v84, v85
	v_lshlrev_b32_e32 v84, 16, v250
	v_and_b32_e32 v85, 0xffff0000, v250
	v_lshlrev_b32_e32 v86, 16, v251
	v_and_b32_e32 v87, 0xffff0000, v251
	v_pk_mul_f32 v[78:79], v[176:177], v[78:79] op_sel_hi:[0,1]
	v_pk_mul_f32 v[76:77], v[176:177], v[76:77] op_sel_hi:[0,1]
	v_pk_fma_f32 v[70:71], v[70:71], v[174:175], v[76:77] op_sel_hi:[1,0,1]
	v_pk_fma_f32 v[68:69], v[68:69], v[174:175], v[78:79] op_sel_hi:[1,0,1]
	v_sub_f32_e32 v77, v87, v180
	v_sub_f32_e32 v76, v86, v180
	v_sub_f32_e32 v79, v85, v180
	v_sub_f32_e32 v78, v84, v180
	v_pk_mul_f32 v[78:79], v[178:179], v[78:79] op_sel_hi:[0,1]
	v_pk_mul_f32 v[76:77], v[178:179], v[76:77] op_sel_hi:[0,1]
	v_pk_fma_f32 v[76:77], v[130:131], v[76:77], v[134:135]
	v_pk_fma_f32 v[78:79], v[128:129], v[78:79], v[132:133]
	v_pk_mul_f32 v[76:77], v[176:177], v[76:77] op_sel_hi:[0,1]
	v_pk_mul_f32 v[78:79], v[176:177], v[78:79] op_sel_hi:[0,1]
	v_pk_fma_f32 v[76:77], v[66:67], v[174:175], v[76:77] op_sel_hi:[1,0,1]
	v_pk_fma_f32 v[66:67], v[64:65], v[174:175], v[78:79] op_sel_hi:[1,0,1]
	v_cvt_pk_bf16_f32 v64, v68, v69
	v_lshl_add_u64 v[68:69], s[22:23], 0, v[210:211]
	v_lshl_add_u64 v[128:129], v[68:69], 0, v[220:221]
	v_cvt_pk_bf16_f32 v90, v90, v91
	v_cvt_pk_bf16_f32 v91, v212, v213
	global_store_dwordx4 v[144:145], v[88:91], off
	global_store_dwordx4 v[146:147], v[80:83], off
	global_store_dwordx4 v[150:151], v[72:75], off
	v_cvt_pk_bf16_f32 v65, v70, v71
	v_cvt_pk_bf16_f32 v66, v66, v67
	v_cvt_pk_bf16_f32 v67, v76, v77
	global_store_dwordx4 v[128:129], v[64:67], off
	global_load_dwordx4 v[68:71], v[216:217], off offset:528
	global_load_dwordx4 v[84:87], v[216:217], off offset:512
	global_load_dwordx4 v[76:79], v[214:215], off offset:528
	global_load_dwordx4 v[92:95], v[214:215], off offset:512
	global_load_dwordx4 v[130:133], v[218:219], off offset:256
	global_load_dwordx4 v[134:137], v[224:225], off offset:256
	global_load_dwordx4 v[138:141], v[228:229], off offset:256
	global_load_dwordx4 v[210:213], v[230:231], off offset:256
	s_waitcnt vmcnt(0)
; __device__ __forceinline__ unsigned cvt_pk_bf16(float lo, float hi) { unsigned r; asm("v_cvt_pk_bf16_f32 %0, %1, %2" : "=v"(r) : "v"(lo), "v"(hi)); return r; }
; __device__ __forceinline__ float bf_lo(unsigned w) { return __uint_as_float(w << 16); }
; __device__ __forceinline__ float bf_hi(unsigned w) { return __uint_as_float(w & 0xffff0000u); }
;     __device__ __forceinline__ void operator()(const f32x4 (&acc)[2][2][4][2], const Unit& u, int wr, int wc, int fr_in, int fq_in) const {
;     ...
;                 for (int m = 0; m < 4; ++m) { const size_t off = (size_t)(row0 + ai * HALF + m * 16) * 1024 + col0 + bj * HALF;
;                     if constexpr (BASE == 0) { pf[m][0] = *(const f32x4*)(basef + off); pf[m][1] = *(const f32x4*)(basef + off + 4); } else pb[m] = *(const u32x4*)(baseb + off); }
; #pragma unroll
;                 for (int m = 0; m < 4; ++m) { const size_t off = (size_t)(row0 + ai * HALF + m * 16) * 1024 + col0 + bj * HALF; f32x4 b[2];
;                     if constexpr (BASE == 0) { b[0] = pf[m][0]; b[1] = pf[m][1]; }
;                     else { const u32x4 pw = pb[m]; b[0] = (f32x4){bf_lo(pw.x), bf_hi(pw.x), bf_lo(pw.y), bf_hi(pw.y)}; b[1] = (f32x4){bf_lo(pw.z), bf_hi(pw.z), bf_lo(pw.w), bf_hi(pw.w)}; }
;                     f32x4 z[2];
; #pragma unroll
;                     for (int n = 0; n < 2; ++n) { if constexpr (BASE == 1) b[n] = (b[n] - rst.mu[ai][m]) * rst.rs[ai][m] * gv[n] + bv[n];
;                         z[n] = b[n] * al_ + acc[ai][bj][m][n] * s_; }
;                     u32x4 w; w.x = cvt_pk_bf16(z[0][0], z[0][1]); w.y = cvt_pk_bf16(z[0][2], z[0][3]); w.z = cvt_pk_bf16(z[1][0], z[1][1]); w.w = cvt_pk_bf16(z[1][2], z[1][3]);
;                     *(u32x4*)(zb + off) = w;
;                     const float r0 = bf_lo(w.x), r1 = bf_hi(w.x), r2 = bf_lo(w.y), r3 = bf_hi(w.y), r4 = bf_lo(w.z), r5 = bf_hi(w.z), r6 = bf_lo(w.w), r7 = bf_hi(w.w);
;                     s1[ai][m] += ((r0 + r1) + (r2 + r3)) + ((r4 + r5) + (r6 + r7)); s2[ai][m] += ((r0 * r0 + r1 * r1) + (r2 * r2 + r3 * r3)) + ((r4 * r4 + r5 * r5) + (r6 * r6 + r7 * r7)); }
	v_lshlrev_b32_e32 v125, 16, v130
	v_and_b32_e32 v127, 0xffff0000, v130
	v_lshlrev_b32_e32 v130, 16, v131
	v_and_b32_e32 v131, 0xffff0000, v131
	v_lshlrev_b32_e32 v142, 16, v132
	v_and_b32_e32 v143, 0xffff0000, v132
	v_lshlrev_b32_e32 v153, 16, v133
	v_and_b32_e32 v155, 0xffff0000, v133
	v_sub_f32_e32 v131, v131, v208
	v_sub_f32_e32 v130, v130, v208
	v_sub_f32_e32 v133, v127, v208
	v_sub_f32_e32 v132, v125, v208
	v_pk_mul_f32 v[132:133], v[206:207], v[132:133] op_sel_hi:[0,1]
	v_pk_mul_f32 v[130:131], v[206:207], v[130:131] op_sel_hi:[0,1]
	v_pk_fma_f32 v[130:131], v[86:87], v[130:131], v[94:95]
	v_pk_fma_f32 v[132:133], v[84:85], v[132:133], v[92:93]
	v_pk_mul_f32 v[130:131], v[176:177], v[130:131] op_sel_hi:[0,1]
	v_pk_mul_f32 v[132:133], v[176:177], v[132:133] op_sel_hi:[0,1]
	v_pk_fma_f32 v[62:63], v[62:63], v[174:175], v[130:131] op_sel_hi:[1,0,1]
	v_pk_fma_f32 v[60:61], v[60:61], v[174:175], v[132:133] op_sel_hi:[1,0,1]
	v_sub_f32_e32 v131, v155, v208
	v_sub_f32_e32 v130, v153, v208
	v_sub_f32_e32 v133, v143, v208
	v_sub_f32_e32 v132, v142, v208
	v_pk_mul_f32 v[132:133], v[206:207], v[132:133] op_sel_hi:[0,1]
	v_pk_mul_f32 v[130:131], v[206:207], v[130:131] op_sel_hi:[0,1]
	v_pk_fma_f32 v[130:131], v[70:71], v[130:131], v[78:79]
	v_pk_fma_f32 v[132:133], v[68:69], v[132:133], v[76:77]
	v_pk_mul_f32 v[130:131], v[176:177], v[130:131] op_sel_hi:[0,1]
	v_pk_mul_f32 v[132:133], v[176:177], v[132:133] op_sel_hi:[0,1]
	v_pk_fma_f32 v[130:131], v[58:59], v[174:175], v[130:131] op_sel_hi:[1,0,1]
	v_pk_fma_f32 v[58:59], v[56:57], v[174:175], v[132:133] op_sel_hi:[1,0,1]
	v_cvt_pk_bf16_f32 v57, v62, v63
	v_cvt_pk_bf16_f32 v56, v60, v61
	v_and_b32_e32 v125, 0xffff0000, v134
	v_cvt_pk_bf16_f32 v58, v58, v59
	v_cvt_pk_bf16_f32 v59, v130, v131
	global_store_dwordx4 v[232:233], v[56:59], off offset:256
	v_and_b32_e32 v63, 0xffff0000, v59
	v_and_b32_e32 v62, 0xffff0000, v58
	v_lshlrev_b32_e32 v61, 16, v59
	v_lshlrev_b32_e32 v60, 16, v58
	v_pk_mul_f32 v[58:59], v[62:63], v[62:63]
	v_lshlrev_b32_e32 v127, 16, v135
	v_pk_fma_f32 v[58:59], v[60:61], v[60:61], v[58:59]
	v_and_b32_e32 v130, 0xffff0000, v135
	v_pk_add_f32 v[58:59], v[58:59], v[58:59] op_sel_hi:[0,1]
	v_lshlrev_b32_e32 v58, 16, v134
	v_sub_f32_e32 v131, v130, v204
	v_sub_f32_e32 v130, v127, v204
	v_sub_f32_e32 v133, v125, v204
	v_sub_f32_e32 v132, v58, v204
	v_pk_mul_f32 v[132:133], v[202:203], v[132:133] op_sel_hi:[0,1]
	v_pk_mul_f32 v[130:131], v[202:203], v[130:131] op_sel_hi:[0,1]
	v_pk_fma_f32 v[130:131], v[86:87], v[130:131], v[94:95]
	v_pk_fma_f32 v[132:133], v[84:85], v[132:133], v[92:93]
	v_lshlrev_b32_e32 v134, 16, v136
	v_and_b32_e32 v135, 0xffff0000, v136
	v_lshlrev_b32_e32 v136, 16, v137
	v_and_b32_e32 v137, 0xffff0000, v137
	v_pk_mul_f32 v[132:133], v[176:177], v[132:133] op_sel_hi:[0,1]
	v_pk_mul_f32 v[130:131], v[176:177], v[130:131] op_sel_hi:[0,1]
	v_pk_fma_f32 v[54:55], v[54:55], v[174:175], v[130:131] op_sel_hi:[1,0,1]
	v_pk_fma_f32 v[52:53], v[52:53], v[174:175], v[132:133] op_sel_hi:[1,0,1]
	v_sub_f32_e32 v131, v137, v204
	v_sub_f32_e32 v130, v136, v204
	v_sub_f32_e32 v133, v135, v204
	v_sub_f32_e32 v132, v134, v204
	v_pk_mul_f32 v[132:133], v[202:203], v[132:133] op_sel_hi:[0,1]
	v_pk_mul_f32 v[130:131], v[202:203], v[130:131] op_sel_hi:[0,1]
	v_pk_fma_f32 v[130:131], v[70:71], v[130:131], v[78:79]
	v_pk_fma_f32 v[132:133], v[68:69], v[132:133], v[76:77]
	v_pk_mul_f32 v[130:131], v[176:177], v[130:131] op_sel_hi:[0,1]
	v_pk_mul_f32 v[132:133], v[176:177], v[132:133] op_sel_hi:[0,1]
	v_pk_fma_f32 v[130:131], v[50:51], v[174:175], v[130:131] op_sel_hi:[1,0,1]
	v_pk_fma_f32 v[50:51], v[48:49], v[174:175], v[132:133] op_sel_hi:[1,0,1]
	v_cvt_pk_bf16_f32 v48, v52, v53
	v_cvt_pk_bf16_f32 v49, v54, v55
	v_lshlrev_b32_e32 v54, 16, v138
	v_and_b32_e32 v55, 0xffff0000, v138
	v_lshlrev_b32_e32 v52, 16, v139
	v_and_b32_e32 v53, 0xffff0000, v139
	v_sub_f32_e32 v53, v53, v200
	v_sub_f32_e32 v52, v52, v200
	v_sub_f32_e32 v55, v55, v200
	v_sub_f32_e32 v54, v54, v200
	v_pk_mul_f32 v[54:55], v[198:199], v[54:55] op_sel_hi:[0,1]
	v_pk_mul_f32 v[52:53], v[198:199], v[52:53] op_sel_hi:[0,1]
	v_pk_fma_f32 v[52:53], v[86:87], v[52:53], v[94:95]
	v_pk_fma_f32 v[54:55], v[84:85], v[54:55], v[92:93]
	v_cvt_pk_bf16_f32 v50, v50, v51
	v_cvt_pk_bf16_f32 v51, v130, v131
	global_store_dwordx4 v[116:117], v[48:51], off offset:256
	v_lshlrev_b32_e32 v58, 16, v140
	v_and_b32_e32 v116, 0xffff0000, v140
	v_lshlrev_b32_e32 v117, 16, v141
	v_and_b32_e32 v125, 0xffff0000, v141
	v_pk_mul_f32 v[54:55], v[176:177], v[54:55] op_sel_hi:[0,1]
	v_pk_mul_f32 v[52:53], v[176:177], v[52:53] op_sel_hi:[0,1]
	v_pk_fma_f32 v[46:47], v[46:47], v[174:175], v[52:53] op_sel_hi:[1,0,1]
	v_pk_fma_f32 v[44:45], v[44:45], v[174:175], v[54:55] op_sel_hi:[1,0,1]
	v_sub_f32_e32 v53, v125, v200
	v_sub_f32_e32 v52, v117, v200
	v_sub_f32_e32 v55, v116, v200
	v_sub_f32_e32 v54, v58, v200
	v_pk_mul_f32 v[54:55], v[198:199], v[54:55] op_sel_hi:[0,1]
	v_pk_mul_f32 v[52:53], v[198:199], v[52:53] op_sel_hi:[0,1]
	v_pk_fma_f32 v[52:53], v[70:71], v[52:53], v[78:79]
	v_pk_fma_f32 v[54:55], v[68:69], v[54:55], v[76:77]
	v_pk_mul_f32 v[52:53], v[176:177], v[52:53] op_sel_hi:[0,1]
	v_pk_mul_f32 v[54:55], v[176:177], v[54:55] op_sel_hi:[0,1]
	v_pk_fma_f32 v[52:53], v[42:43], v[174:175], v[52:53] op_sel_hi:[1,0,1]
	v_pk_fma_f32 v[42:43], v[40:41], v[174:175], v[54:55] op_sel_hi:[1,0,1]
	v_cvt_pk_bf16_f32 v40, v44, v45
	v_cvt_pk_bf16_f32 v41, v46, v47
	v_lshlrev_b32_e32 v46, 16, v210
	v_and_b32_e32 v47, 0xffff0000, v210
	v_lshlrev_b32_e32 v44, 16, v211
	v_and_b32_e32 v45, 0xffff0000, v211
	v_sub_f32_e32 v45, v45, v196
	v_sub_f32_e32 v44, v44, v196
; __device__ __forceinline__ unsigned cvt_pk_bf16(float lo, float hi) { unsigned r; asm("v_cvt_pk_bf16_f32 %0, %1, %2" : "=v"(r) : "v"(lo), "v"(hi)); return r; }
; __device__ __forceinline__ float bf_lo(unsigned w) { return __uint_as_float(w << 16); }
; __device__ __forceinline__ float bf_hi(unsigned w) { return __uint_as_float(w & 0xffff0000u); }
;     __device__ __forceinline__ void operator()(const f32x4 (&acc)[2][2][4][2], const Unit& u, int wr, int wc, int fr_in, int fq_in) const {
;     ...
;                 for (int m = 0; m < 4; ++m) { const size_t off = (size_t)(row0 + ai * HALF + m * 16) * 1024 + col0 + bj * HALF; f32x4 b[2];
;                     if constexpr (BASE == 0) { b[0] = pf[m][0]; b[1] = pf[m][1]; }
;                     else { const u32x4 pw = pb[m]; b[0] = (f32x4){bf_lo(pw.x), bf_hi(pw.x), bf_lo(pw.y), bf_hi(pw.y)}; b[1] = (f32x4){bf_lo(pw.z), bf_hi(pw.z), bf_lo(pw.w), bf_hi(pw.w)}; }
;                     f32x4 z[2];
; #pragma unroll
;                     for (int n = 0; n < 2; ++n) { if constexpr (BASE == 1) b[n] = (b[n] - rst.mu[ai][m]) * rst.rs[ai][m] * gv[n] + bv[n];
;                         z[n] = b[n] * al_ + acc[ai][bj][m][n] * s_; }
;                     u32x4 w; w.x = cvt_pk_bf16(z[0][0], z[0][1]); w.y = cvt_pk_bf16(z[0][2], z[0][3]); w.z = cvt_pk_bf16(z[1][0], z[1][1]); w.w = cvt_pk_bf16(z[1][2], z[1][3]);
;                     *(u32x4*)(zb + off) = w;
;                     const float r0 = bf_lo(w.x), r1 = bf_hi(w.x), r2 = bf_lo(w.y), r3 = bf_hi(w.y), r4 = bf_lo(w.z), r5 = bf_hi(w.z), r6 = bf_lo(w.w), r7 = bf_hi(w.w);
;                     s1[ai][m] += ((r0 + r1) + (r2 + r3)) + ((r4 + r5) + (r6 + r7)); s2[ai][m] += ((r0 * r0 + r1 * r1) + (r2 * r2 + r3 * r3)) + ((r4 * r4 + r5 * r5) + (r6 * r6 + r7 * r7)); }
	v_sub_f32_e32 v47, v47, v196
	v_sub_f32_e32 v46, v46, v196
	v_pk_mul_f32 v[46:47], v[194:195], v[46:47] op_sel_hi:[0,1]
	v_pk_mul_f32 v[44:45], v[194:195], v[44:45] op_sel_hi:[0,1]
	v_pk_fma_f32 v[44:45], v[86:87], v[44:45], v[94:95]
	v_pk_fma_f32 v[46:47], v[84:85], v[46:47], v[92:93]
	v_cvt_pk_bf16_f32 v42, v42, v43
	v_cvt_pk_bf16_f32 v43, v52, v53
	v_lshlrev_b32_e32 v52, 16, v212
	v_and_b32_e32 v53, 0xffff0000, v212
	v_lshlrev_b32_e32 v54, 16, v213
	v_and_b32_e32 v55, 0xffff0000, v213
	v_pk_mul_f32 v[46:47], v[176:177], v[46:47] op_sel_hi:[0,1]
	v_pk_mul_f32 v[44:45], v[176:177], v[44:45] op_sel_hi:[0,1]
	v_pk_fma_f32 v[38:39], v[38:39], v[174:175], v[44:45] op_sel_hi:[1,0,1]
	v_pk_fma_f32 v[36:37], v[36:37], v[174:175], v[46:47] op_sel_hi:[1,0,1]
	v_sub_f32_e32 v45, v55, v196
	v_sub_f32_e32 v44, v54, v196
	v_sub_f32_e32 v47, v53, v196
	v_sub_f32_e32 v46, v52, v196
	v_pk_mul_f32 v[46:47], v[194:195], v[46:47] op_sel_hi:[0,1]
	v_pk_mul_f32 v[44:45], v[194:195], v[44:45] op_sel_hi:[0,1]
	v_pk_fma_f32 v[44:45], v[70:71], v[44:45], v[78:79]
	v_pk_fma_f32 v[46:47], v[68:69], v[46:47], v[76:77]
	v_pk_mul_f32 v[44:45], v[176:177], v[44:45] op_sel_hi:[0,1]
	v_pk_mul_f32 v[46:47], v[176:177], v[46:47] op_sel_hi:[0,1]
	v_pk_fma_f32 v[44:45], v[34:35], v[174:175], v[44:45] op_sel_hi:[1,0,1]
	v_pk_fma_f32 v[34:35], v[32:33], v[174:175], v[46:47] op_sel_hi:[1,0,1]
	global_store_dwordx4 v[108:109], v[40:43], off offset:256
	v_cvt_pk_bf16_f32 v32, v36, v37
	v_cvt_pk_bf16_f32 v33, v38, v39
	v_cvt_pk_bf16_f32 v34, v34, v35
	v_cvt_pk_bf16_f32 v35, v44, v45
	global_store_dwordx4 v[100:101], v[32:35], off offset:256
	global_load_dwordx4 v[36:39], v[102:103], off offset:256
	global_load_dwordx4 v[44:47], v[110:111], off offset:256
	global_load_dwordx4 v[52:55], v[148:149], off offset:256
	s_nop 0
	global_load_dwordx4 v[100:103], v[118:119], off offset:256
	v_mov_b32_e32 v165, v59
	s_waitcnt vmcnt(0)
	v_lshlrev_b32_e32 v58, 16, v36
	v_and_b32_e32 v108, 0xffff0000, v36
	v_lshlrev_b32_e32 v36, 16, v37
	v_and_b32_e32 v37, 0xffff0000, v37
	v_lshlrev_b32_e32 v109, 16, v38
	v_and_b32_e32 v110, 0xffff0000, v38
	v_lshlrev_b32_e32 v111, 16, v39
	v_and_b32_e32 v116, 0xffff0000, v39
	v_sub_f32_e32 v37, v37, v192
	v_sub_f32_e32 v36, v36, v192
	v_sub_f32_e32 v39, v108, v192
	v_sub_f32_e32 v38, v58, v192
	v_pk_mul_f32 v[38:39], v[190:191], v[38:39] op_sel_hi:[0,1]
	v_pk_mul_f32 v[36:37], v[190:191], v[36:37] op_sel_hi:[0,1]
	v_pk_fma_f32 v[36:37], v[86:87], v[36:37], v[94:95]
	v_pk_fma_f32 v[38:39], v[84:85], v[38:39], v[92:93]
	v_pk_mul_f32 v[36:37], v[176:177], v[36:37] op_sel_hi:[0,1]
	v_pk_mul_f32 v[38:39], v[176:177], v[38:39] op_sel_hi:[0,1]
	v_pk_fma_f32 v[30:31], v[30:31], v[174:175], v[36:37] op_sel_hi:[1,0,1]
	v_pk_fma_f32 v[28:29], v[28:29], v[174:175], v[38:39] op_sel_hi:[1,0,1]
	v_sub_f32_e32 v37, v116, v192
	v_sub_f32_e32 v36, v111, v192
	v_sub_f32_e32 v39, v110, v192
	v_sub_f32_e32 v38, v109, v192
	v_pk_mul_f32 v[38:39], v[190:191], v[38:39] op_sel_hi:[0,1]
	v_pk_mul_f32 v[36:37], v[190:191], v[36:37] op_sel_hi:[0,1]
	v_pk_fma_f32 v[36:37], v[70:71], v[36:37], v[78:79]
	v_pk_fma_f32 v[38:39], v[68:69], v[38:39], v[76:77]
	v_pk_mul_f32 v[36:37], v[176:177], v[36:37] op_sel_hi:[0,1]
	v_pk_mul_f32 v[38:39], v[176:177], v[38:39] op_sel_hi:[0,1]
	v_pk_fma_f32 v[36:37], v[26:27], v[174:175], v[36:37] op_sel_hi:[1,0,1]
	v_pk_fma_f32 v[26:27], v[24:25], v[174:175], v[38:39] op_sel_hi:[1,0,1]
	v_cvt_pk_bf16_f32 v24, v28, v29
	v_cvt_pk_bf16_f32 v25, v30, v31
	v_lshlrev_b32_e32 v30, 16, v44
	v_and_b32_e32 v31, 0xffff0000, v44
	v_lshlrev_b32_e32 v28, 16, v45
	v_and_b32_e32 v29, 0xffff0000, v45
	v_sub_f32_e32 v29, v29, v188
	v_sub_f32_e32 v28, v28, v188
	v_sub_f32_e32 v31, v31, v188
	v_sub_f32_e32 v30, v30, v188
	v_pk_mul_f32 v[30:31], v[186:187], v[30:31] op_sel_hi:[0,1]
	v_pk_mul_f32 v[28:29], v[186:187], v[28:29] op_sel_hi:[0,1]
	v_pk_fma_f32 v[28:29], v[86:87], v[28:29], v[94:95]
	v_pk_fma_f32 v[30:31], v[84:85], v[30:31], v[92:93]
	v_cvt_pk_bf16_f32 v26, v26, v27
	v_cvt_pk_bf16_f32 v27, v36, v37
	v_lshlrev_b32_e32 v36, 16, v46
	v_and_b32_e32 v37, 0xffff0000, v46
	v_lshlrev_b32_e32 v38, 16, v47
	v_and_b32_e32 v39, 0xffff0000, v47
	v_pk_mul_f32 v[30:31], v[176:177], v[30:31] op_sel_hi:[0,1]
	v_pk_mul_f32 v[28:29], v[176:177], v[28:29] op_sel_hi:[0,1]
	v_pk_fma_f32 v[22:23], v[22:23], v[174:175], v[28:29] op_sel_hi:[1,0,1]
	v_pk_fma_f32 v[20:21], v[20:21], v[174:175], v[30:31] op_sel_hi:[1,0,1]
	v_sub_f32_e32 v29, v39, v188
	v_sub_f32_e32 v28, v38, v188
	v_sub_f32_e32 v31, v37, v188
	v_sub_f32_e32 v30, v36, v188
	v_pk_mul_f32 v[30:31], v[186:187], v[30:31] op_sel_hi:[0,1]
	v_pk_mul_f32 v[28:29], v[186:187], v[28:29] op_sel_hi:[0,1]
	v_pk_fma_f32 v[28:29], v[70:71], v[28:29], v[78:79]
	v_pk_fma_f32 v[30:31], v[68:69], v[30:31], v[76:77]
	v_pk_mul_f32 v[28:29], v[176:177], v[28:29] op_sel_hi:[0,1]
	v_pk_mul_f32 v[30:31], v[176:177], v[30:31] op_sel_hi:[0,1]
	v_pk_fma_f32 v[28:29], v[18:19], v[174:175], v[28:29] op_sel_hi:[1,0,1]
	v_pk_fma_f32 v[18:19], v[16:17], v[174:175], v[30:31] op_sel_hi:[1,0,1]
	v_cvt_pk_bf16_f32 v16, v20, v21
	v_cvt_pk_bf16_f32 v17, v22, v23
	v_lshlrev_b32_e32 v22, 16, v52
	v_and_b32_e32 v23, 0xffff0000, v52
	v_lshlrev_b32_e32 v20, 16, v53
	v_and_b32_e32 v21, 0xffff0000, v53
	v_sub_f32_e32 v21, v21, v184
	v_sub_f32_e32 v20, v20, v184
	v_sub_f32_e32 v23, v23, v184
	v_sub_f32_e32 v22, v22, v184
	v_pk_mul_f32 v[22:23], v[182:183], v[22:23] op_sel_hi:[0,1]
	v_pk_mul_f32 v[20:21], v[182:183], v[20:21] op_sel_hi:[0,1]
	v_pk_fma_f32 v[20:21], v[86:87], v[20:21], v[94:95]
	v_pk_fma_f32 v[22:23], v[84:85], v[22:23], v[92:93]
	v_cvt_pk_bf16_f32 v18, v18, v19
; __device__ __forceinline__ unsigned cvt_pk_bf16(float lo, float hi) { unsigned r; asm("v_cvt_pk_bf16_f32 %0, %1, %2" : "=v"(r) : "v"(lo), "v"(hi)); return r; }
; __device__ __forceinline__ float bf_lo(unsigned w) { return __uint_as_float(w << 16); }
; __device__ __forceinline__ float bf_hi(unsigned w) { return __uint_as_float(w & 0xffff0000u); }
; __device__ __forceinline__ void emit_row_stats(float (&s1)[2][4], float (&s2)[2][4], float* sp_new, const Unit& u, int wr, int wc, int fr, int fq, PG8_LAS unsigned char* xl) {
;     ...
;         for (int m = 0; m < 4; ++m) { float a = s1[ai][m], b = s2[ai][m]; a += __shfl_xor(a, 16); b += __shfl_xor(b, 16); a += __shfl_xor(a, 32); b += __shfl_xor(b, 32);
;             if (fq == 0) P[(ai * HALF + wr * 64 + m * 16 + fr) * 4 + wc] = (f32x2v){a, b}; }
;     __device__ __forceinline__ void operator()(const f32x4 (&acc)[2][2][4][2], const Unit& u, int wr, int wc, int fr_in, int fq_in) const {
;     ...
;                 for (int m = 0; m < 4; ++m) { const size_t off = (size_t)(row0 + ai * HALF + m * 16) * 1024 + col0 + bj * HALF; f32x4 b[2];
;                     if constexpr (BASE == 0) { b[0] = pf[m][0]; b[1] = pf[m][1]; }
;                     else { const u32x4 pw = pb[m]; b[0] = (f32x4){bf_lo(pw.x), bf_hi(pw.x), bf_lo(pw.y), bf_hi(pw.y)}; b[1] = (f32x4){bf_lo(pw.z), bf_hi(pw.z), bf_lo(pw.w), bf_hi(pw.w)}; }
;                     f32x4 z[2];
; #pragma unroll
;                     for (int n = 0; n < 2; ++n) { if constexpr (BASE == 1) b[n] = (b[n] - rst.mu[ai][m]) * rst.rs[ai][m] * gv[n] + bv[n];
;                         z[n] = b[n] * al_ + acc[ai][bj][m][n] * s_; }
;                     u32x4 w; w.x = cvt_pk_bf16(z[0][0], z[0][1]); w.y = cvt_pk_bf16(z[0][2], z[0][3]); w.z = cvt_pk_bf16(z[1][0], z[1][1]); w.w = cvt_pk_bf16(z[1][2], z[1][3]);
;                     *(u32x4*)(zb + off) = w;
;                     const float r0 = bf_lo(w.x), r1 = bf_hi(w.x), r2 = bf_lo(w.y), r3 = bf_hi(w.y), r4 = bf_lo(w.z), r5 = bf_hi(w.z), r6 = bf_lo(w.w), r7 = bf_hi(w.w);
;                     s1[ai][m] += ((r0 + r1) + (r2 + r3)) + ((r4 + r5) + (r6 + r7)); s2[ai][m] += ((r0 * r0 + r1 * r1) + (r2 * r2 + r3 * r3)) + ((r4 * r4 + r5 * r5) + (r6 * r6 + r7 * r7)); }
	v_cvt_pk_bf16_f32 v19, v28, v29
	v_lshlrev_b32_e32 v28, 16, v54
	v_and_b32_e32 v29, 0xffff0000, v54
	v_lshlrev_b32_e32 v30, 16, v55
	v_and_b32_e32 v31, 0xffff0000, v55
	v_pk_mul_f32 v[22:23], v[176:177], v[22:23] op_sel_hi:[0,1]
	v_pk_mul_f32 v[20:21], v[176:177], v[20:21] op_sel_hi:[0,1]
	v_pk_fma_f32 v[14:15], v[14:15], v[174:175], v[20:21] op_sel_hi:[1,0,1]
	v_pk_fma_f32 v[12:13], v[12:13], v[174:175], v[22:23] op_sel_hi:[1,0,1]
	v_sub_f32_e32 v21, v31, v184
	v_sub_f32_e32 v20, v30, v184
	v_sub_f32_e32 v23, v29, v184
	v_sub_f32_e32 v22, v28, v184
	v_pk_mul_f32 v[22:23], v[182:183], v[22:23] op_sel_hi:[0,1]
	v_pk_mul_f32 v[20:21], v[182:183], v[20:21] op_sel_hi:[0,1]
	v_pk_fma_f32 v[20:21], v[70:71], v[20:21], v[78:79]
	v_pk_fma_f32 v[22:23], v[68:69], v[22:23], v[76:77]
	v_pk_mul_f32 v[20:21], v[176:177], v[20:21] op_sel_hi:[0,1]
	v_pk_mul_f32 v[22:23], v[176:177], v[22:23] op_sel_hi:[0,1]
	v_pk_fma_f32 v[20:21], v[10:11], v[174:175], v[20:21] op_sel_hi:[1,0,1]
	v_pk_fma_f32 v[10:11], v[8:9], v[174:175], v[22:23] op_sel_hi:[1,0,1]
	v_cvt_pk_bf16_f32 v8, v12, v13
	v_cvt_pk_bf16_f32 v9, v14, v15
	v_lshlrev_b32_e32 v14, 16, v100
	v_and_b32_e32 v15, 0xffff0000, v100
	v_lshlrev_b32_e32 v12, 16, v101
	v_and_b32_e32 v13, 0xffff0000, v101
	v_sub_f32_e32 v13, v13, v180
	v_sub_f32_e32 v12, v12, v180
	v_sub_f32_e32 v15, v15, v180
	v_sub_f32_e32 v14, v14, v180
	v_pk_mul_f32 v[14:15], v[178:179], v[14:15] op_sel_hi:[0,1]
	v_pk_mul_f32 v[12:13], v[178:179], v[12:13] op_sel_hi:[0,1]
	v_pk_fma_f32 v[12:13], v[86:87], v[12:13], v[94:95]
	v_pk_fma_f32 v[14:15], v[84:85], v[14:15], v[92:93]
	v_cvt_pk_bf16_f32 v10, v10, v11
	v_cvt_pk_bf16_f32 v11, v20, v21
	v_lshlrev_b32_e32 v20, 16, v102
	v_and_b32_e32 v21, 0xffff0000, v102
	v_lshlrev_b32_e32 v22, 16, v103
	v_and_b32_e32 v23, 0xffff0000, v103
	v_pk_mul_f32 v[14:15], v[176:177], v[14:15] op_sel_hi:[0,1]
	v_pk_mul_f32 v[12:13], v[176:177], v[12:13] op_sel_hi:[0,1]
	v_pk_fma_f32 v[6:7], v[6:7], v[174:175], v[12:13] op_sel_hi:[1,0,1]
	v_pk_fma_f32 v[4:5], v[4:5], v[174:175], v[14:15] op_sel_hi:[1,0,1]
	v_sub_f32_e32 v13, v23, v180
	v_sub_f32_e32 v12, v22, v180
	v_sub_f32_e32 v15, v21, v180
	v_sub_f32_e32 v14, v20, v180
	v_pk_mul_f32 v[14:15], v[178:179], v[14:15] op_sel_hi:[0,1]
	v_pk_mul_f32 v[12:13], v[178:179], v[12:13] op_sel_hi:[0,1]
	v_pk_fma_f32 v[12:13], v[70:71], v[12:13], v[78:79]
	v_pk_fma_f32 v[14:15], v[68:69], v[14:15], v[76:77]
	v_pk_mul_f32 v[12:13], v[176:177], v[12:13] op_sel_hi:[0,1]
	v_pk_mul_f32 v[14:15], v[176:177], v[14:15] op_sel_hi:[0,1]
	v_pk_fma_f32 v[12:13], v[2:3], v[174:175], v[12:13] op_sel_hi:[1,0,1]
	v_pk_fma_f32 v[2:3], v[0:1], v[174:175], v[14:15] op_sel_hi:[1,0,1]
	v_cvt_pk_bf16_f32 v0, v4, v5
	v_and_b32_e32 v5, 64, v195
	v_xor_b32_e32 v4, 16, v195
	v_add_u32_e32 v5, 64, v5
	v_cmp_lt_i32_e32 vcc, v4, v5
	v_cvt_pk_bf16_f32 v2, v2, v3
	v_cvt_pk_bf16_f32 v3, v12, v13
	v_cvt_pk_bf16_f32 v1, v6, v7
	v_and_b32_e32 v21, 0xffff0000, v56
	v_and_b32_e32 v20, 0xffff0000, v121
	v_cndmask_b32_e32 v4, v195, v4, vcc
	v_lshlrev_b32_e32 v13, 2, v4
	v_xor_b32_e32 v4, 32, v195
	v_cmp_lt_i32_e32 vcc, v4, v5
	v_lshlrev_b32_e32 v5, 16, v56
	v_mov_b32_e32 v155, v5
	v_cndmask_b32_e32 v4, v195, v4, vcc
	v_lshlrev_b32_e32 v12, 2, v4
	v_lshlrev_b32_e32 v4, 16, v120
	v_pk_mul_f32 v[6:7], v[4:5], v[4:5]
	v_pk_mul_f32 v[14:15], v[154:155], v[154:155]
	v_mov_b32_e32 v153, v21
	v_pk_mov_b32 v[54:55], v[4:5], v[6:7] op_sel:[1,0]
	v_pk_add_f32 v[4:5], v[4:5], v[154:155]
	v_pk_mul_f32 v[22:23], v[152:153], v[152:153]
	v_pk_mul_f32 v[28:29], v[20:21], v[20:21]
	v_lshlrev_b32_e32 v30, 16, v122
	v_lshlrev_b32_e32 v31, 16, v57
	v_and_b32_e32 v45, 0xffff0000, v57
	v_and_b32_e32 v44, 0xffff0000, v123
	v_pk_mov_b32 v[14:15], v[20:21], v[14:15] op_sel:[1,0]
	v_mov_b32_e32 v5, v7
	v_pk_add_f32 v[6:7], v[20:21], v[152:153]
	v_mov_b32_e32 v127, v31
	v_mov_b32_e32 v125, v45
	v_pk_add_f32 v[14:15], v[54:55], v[14:15]
	v_pk_mov_b32 v[22:23], v[30:31], v[22:23] op_sel:[1,0]
	v_pk_mov_b32 v[54:55], v[44:45], v[28:29] op_sel:[1,0]
	v_mov_b32_e32 v7, v29
	v_pk_mul_f32 v[36:37], v[30:31], v[30:31]
	v_pk_mul_f32 v[38:39], v[126:127], v[126:127]
	v_pk_mul_f32 v[46:47], v[124:125], v[124:125]
	v_pk_mul_f32 v[52:53], v[44:45], v[44:45]
	v_pk_add_f32 v[22:23], v[22:23], v[54:55]
	v_pk_add_f32 v[4:5], v[4:5], v[6:7]
	v_pk_add_f32 v[6:7], v[30:31], v[126:127]
	v_pk_add_f32 v[20:21], v[44:45], v[124:125]
	v_pk_add_f32 v[14:15], v[14:15], v[22:23]
	v_mov_b32_e32 v22, v60
	v_mov_b32_e32 v23, v36
	v_mov_b32_e32 v54, v62
	v_mov_b32_e32 v55, v38
	v_pk_mov_b32 v[38:39], v[60:61], v[46:47] op_sel:[1,0]
	v_pk_mov_b32 v[46:47], v[62:63], v[52:53] op_sel:[1,0]
	v_mov_b32_e32 v7, v37
	v_mov_b32_e32 v21, v53
	v_pk_add_f32 v[22:23], v[22:23], v[54:55]
	v_pk_add_f32 v[38:39], v[38:39], v[46:47]
	v_pk_add_f32 v[6:7], v[6:7], v[20:21]
	v_pk_add_f32 v[22:23], v[22:23], v[38:39]
	v_pk_add_f32 v[4:5], v[4:5], v[6:7]
	v_pk_add_f32 v[14:15], v[14:15], v[22:23]
	v_pk_add_f32 v[4:5], v[4:5], v[164:165]
	global_store_dwordx4 v[144:145], v[24:27], off offset:256
	v_pk_add_f32 v[4:5], v[14:15], v[4:5]
	ds_bpermute_b32 v6, v13, v4
	ds_bpermute_b32 v7, v13, v5
	global_store_dwordx4 v[146:147], v[16:19], off offset:256
	global_store_dwordx4 v[150:151], v[8:11], off offset:256
	global_store_dwordx4 v[128:129], v[0:3], off offset:256
	s_waitcnt lgkmcnt(0)
	v_pk_add_f32 v[4:5], v[4:5], v[6:7]
	ds_bpermute_b32 v6, v12, v4
	ds_bpermute_b32 v7, v12, v5
	v_cmp_eq_u32_e32 vcc, 0, v203
	v_lshl_add_u32 v14, v199, 5, s66
	s_and_saveexec_b64 s[8:9], vcc
	s_cbranch_execz .LBB0_1177
	s_waitcnt lgkmcnt(0)
	v_pk_add_f32 v[4:5], v[4:5], v[6:7]
	ds_write_b64 v14, v[4:5]

; __device__ __forceinline__ float fast_sigmoid(float v) { return __builtin_amdgcn_rcpf(1.0f + __builtin_amdgcn_exp2f(-1.4426950408889634f * v)); }
; __device__ __forceinline__ f32x4 ln_fix(const f32x4& a, float mu, float rs, const f32x4& cs, const f32x4& cb) { return (a - cs * mu) * rs + cb; }
; __device__ __forceinline__ void load_row_stats(const float* sp, int row0, RowStats& r) {
; #pragma unroll
;     for (int ai = 0; ai < 2; ++ai) { asm volatile("" ::: "memory");
; #pragma unroll
;         for (int m = 0; m < 4; ++m) { const float* p = sp + (size_t)(row0 + ai * HALF + m * 16) * 8; const f32x4 a = *(const f32x4*)p, b = *(const f32x4*)(p + 4);
;             const float s1 = (a[0] + a[2]) + (b[0] + b[2]), s2 = (a[1] + a[3]) + (b[1] + b[3]); const float mu = s1 * (1.f / 1024.f); const float var = s2 * (1.f / 1024.f) - mu * mu;
;             r.mu[ai][m] = mu; r.rs[ai][m] = __builtin_amdgcn_rsqf(__builtin_fmaxf(var, 0.f) + 1e-5f); } }
;     __device__ __forceinline__ void operator()(const f32x4 (&acc)[2][2][4][2], const Unit& u, int wr, int wc, int fr_in, int fq_in) const {
;     ...
;         const int row0 = u.pm * BM + wr * 64 + fr, n0 = u.pn * BM + wc * 32 + 8 * fq; const int kt = u.pn * 2 + (wc >> 1), cin = (wc & 1) * 32 + 8 * fq;
;         RowStats rst; f32x4 csv[2][2], cbv[2][2];
;         if constexpr (LN) { load_row_stats(sp, row0, rst);
; #pragma unroll
;             for (int bj = 0; bj < 2; ++bj)
; #pragma unroll
;                 for (int n = 0; n < 2; ++n) { csv[bj][n] = *(const f32x4*)(cs + n0 + bj * HALF + 4 * n); cbv[bj][n] = *(const f32x4*)(cb + n0 + bj * HALF + 4 * n); } }
; #pragma unroll
;         for (int ai = 0; ai < 2; ++ai)
; #pragma unroll
;             for (int m = 0; m < 4; ++m) { bf16_t* rowp = H + ((size_t)kt * mrows + (row0 + ai * HALF + m * 16)) * 64 + cin;
;                 float h[8];
; #pragma unroll
;                 for (int n = 0; n < 2; ++n) { f32x4 g = acc[ai][0][m][n], uu = acc[ai][1][m][n];
;                     if constexpr (LN) { g = ln_fix(g, rst.mu[ai][m], rst.rs[ai][m], csv[0][n], cbv[0][n]); uu = ln_fix(uu, rst.mu[ai][m], rst.rs[ai][m], csv[1][n], cbv[1][n]); }
; #pragma unroll
;                     for (int j = 0; j < 4; ++j) h[4 * n + j] = g[j] * fast_sigmoid(g[j]) * uu[j]; }
.LBB0_1260:
	s_lshl_b32 s35, s44, 8
	v_mov_b32_e32 v112, v185
	v_mov_b32_e32 v113, v179
	s_add_i32 s35, s35, s54
	s_andn2_b64 vcc, exec, s[38:39]
	v_add_u32_e32 v192, s35, v113
	v_ashrrev_i32_e32 v193, 31, v192
	s_cselect_b32 s99, 1, 0
	v_readfirstlane_b32 s98, v254
	v_and_b32_e32 v114, 0xffffff00, v192
	s_nop 0
	s_cmpk_lt_u32 s98, 0x100
	s_cbranch_scc0 .Lrs2_skip
	v_add_u32_e32 v114, v114, v254
	v_mov_b32_e32 v115, 0
	v_lshlrev_b64 v[114:115], 5, v[114:115]
	v_lshl_add_u64 v[118:119], s[10:11], 0, v[114:115]
	global_load_dwordx4 v[114:117], v[118:119], off offset:16
	s_nop 0
	global_load_dwordx4 v[128:131], v[118:119], off
	s_waitcnt vmcnt(0)
	v_pk_add_f32 v[114:115], v[114:115], v[116:117]
	v_pk_add_f32 v[118:119], v[128:129], v[130:131]
	s_nop 0
	v_pk_add_f32 v[114:115], v[118:119], v[114:115]
	s_nop 0
	v_pk_mul_f32 v[114:115], v[114:115], s[30:31] op_sel_hi:[1,0]
	v_lshlrev_b32_e32 v116, 3, v254
	v_add_u32_e32 v116, 0x22400, v116
	ds_write_b64 v116, v[114:115]
.Lrs2_skip:
	s_waitcnt vmcnt(0) lgkmcnt(0)
	s_barrier
	v_and_b32_e32 v116, 0xff, v192
	v_lshlrev_b32_e32 v116, 3, v116
	v_add_u32_e32 v116, 0x22400, v116
	ds_read_b64 v[226:227], v116
	ds_read_b64 v[220:221], v116 offset:128
	ds_read_b64 v[214:215], v116 offset:256
	ds_read_b64 v[200:201], v116 offset:384
	ds_read_b64 v[194:195], v116 offset:1024
	ds_read_b64 v[186:187], v116 offset:1152
	ds_read_b64 v[180:181], v116 offset:1280
	ds_read_b64 v[176:177], v116 offset:1408
	s_cmp_lg_u32 s99, 0
	s_waitcnt lgkmcnt(0)
	v_add_u32_e32 v224, 16, v192
	v_ashrrev_i32_e32 v225, 31, v224
	v_add_u32_e32 v218, 32, v192
	v_ashrrev_i32_e32 v219, 31, v218
	v_add_u32_e32 v212, 48, v192
	v_ashrrev_i32_e32 v213, 31, v212
	v_add_u32_e32 v204, 0x80, v192
	v_ashrrev_i32_e32 v205, 31, v204
	v_add_u32_e32 v196, 0x90, v192
	v_ashrrev_i32_e32 v197, 31, v196
	v_add_u32_e32 v188, 0xa0, v192
	v_ashrrev_i32_e32 v189, 31, v188
	v_add_u32_e32 v182, 0xb0, v192
	v_ashrrev_i32_e32 v183, 31, v182
	s_lshl_b32 s35, s45, 8
	s_or_b32 s35, s35, s55
	v_lshlrev_b32_e32 v206, 3, v112
	v_add_u32_e32 v112, s35, v206
	s_lshl_b32 s35, s45, 1
	s_or_b32 s44, s35, s59
	s_ashr_i32 s45, s44, 31
	s_lshl_b64 s[44:45], s[44:45], 15
	v_lshl_add_u64 v[192:193], s[44:45], 0, v[192:193]
	v_lshlrev_b64 v[192:193], 7, v[192:193]
	v_add_u32_e32 v230, s60, v206
	v_lshl_add_u64 v[232:233], s[6:7], 0, v[192:193]
	v_mov_b32_e32 v192, v144
	v_mov_b32_e32 v193, v140
	v_mov_b32_e32 v140, v145
	v_ashrrev_i32_e32 v231, 31, v230
	v_fma_f32 v113, -v226, v226, v227
	v_max_f32_e32 v113, 0, v113
	v_add_f32_e32 v113, 0x3727c5ac, v113
	v_rsq_f32_e32 v228, v113
	v_fma_f32 v113, -v220, v220, v221
	v_max_f32_e32 v113, 0, v113
	v_add_f32_e32 v113, 0x3727c5ac, v113
	v_rsq_f32_e32 v222, v113
	v_fma_f32 v113, -v214, v214, v215
	v_max_f32_e32 v113, 0, v113
	v_add_f32_e32 v113, 0x3727c5ac, v113
	v_rsq_f32_e32 v216, v113
	v_fma_f32 v113, -v200, v200, v201
	v_max_f32_e32 v113, 0, v113
	v_add_f32_e32 v113, 0x3727c5ac, v113
	v_rsq_f32_e32 v202, v113
	v_fma_f32 v113, -v194, v194, v195
	v_max_f32_e32 v113, 0, v113
	v_add_f32_e32 v113, 0x3727c5ac, v113
	v_rsq_f32_e32 v198, v113
	v_fma_f32 v113, -v186, v186, v187
	v_max_f32_e32 v113, 0, v113
	v_add_f32_e32 v113, 0x3727c5ac, v113
	v_rsq_f32_e32 v190, v113
	v_fma_f32 v113, -v180, v180, v181
	v_max_f32_e32 v113, 0, v113
	v_add_f32_e32 v113, 0x3727c5ac, v113
	v_rsq_f32_e32 v184, v113
	s_nop 0
	v_fma_f32 v113, -v176, v176, v177
	v_max_f32_e32 v113, 0, v113
	v_add_f32_e32 v113, 0x3727c5ac, v113
	v_rsq_f32_e32 v178, v113
	v_ashrrev_i32_e32 v113, 31, v112
	v_lshlrev_b64 v[112:113], 2, v[112:113]
	v_lshl_add_u64 v[136:137], s[12:13], 0, v[112:113]
	v_lshl_add_u64 v[156:157], s[22:23], 0, v[112:113]
	global_load_dwordx4 v[112:115], v[136:137], off offset:16
	global_load_dwordx4 v[128:131], v[136:137], off
	global_load_dwordx4 v[116:119], v[156:157], off offset:16
	global_load_dwordx4 v[132:135], v[156:157], off
	global_load_dwordx4 v[148:151], v[136:137], off offset:528
	s_nop 0
	global_load_dwordx4 v[136:139], v[136:137], off offset:512
	s_nop 0
	global_load_dwordx4 v[152:155], v[156:157], off offset:528
	s_nop 0
	global_load_dwordx4 v[156:159], v[156:157], off offset:512
	s_waitcnt vmcnt(0)
	v_mov_b32_e32 v207, v128
	v_mov_b32_e32 v211, v131
	v_mov_b32_e32 v206, v136
	v_pk_fma_f32 v[208:209], v[226:227], v[206:207], v[192:193] op_sel_hi:[0,1,1] neg_lo:[1,0,0] neg_hi:[1,0,0]
	v_mov_b32_e32 v192, v156
	v_mov_b32_e32 v193, v132
	v_pk_fma_f32 v[208:209], v[228:229], v[208:209], v[192:193] op_sel_hi:[0,1,1]
	v_mul_f32_e32 v132, 0xbfb8aa3b, v209
	v_exp_f32_e32 v132, v132
	v_mov_b32_e32 v156, v138
	v_mov_b32_e32 v210, v139
	v_add_f32_e32 v132, 1.0, v132
	v_rcp_f32_e32 v132, v132
	s_nop 0
	v_mul_f32_e32 v132, v209, v132
	v_mul_f32_e32 v223, v208, v132
	v_mov_b32_e32 v208, v137
	v_mov_b32_e32 v209, v129
	v_pk_fma_f32 v[140:141], v[226:227], v[208:209], v[140:141] op_sel_hi:[0,1,1] neg_lo:[1,0,0] neg_hi:[1,0,0]
	v_mov_b32_e32 v132, v157
	v_pk_fma_f32 v[140:141], v[228:229], v[140:141], v[132:133] op_sel_hi:[0,1,1]
	v_mul_f32_e32 v144, 0xbfb8aa3b, v141
	v_exp_f32_e32 v144, v144
	v_mov_b32_e32 v157, v130
	v_add_f32_e32 v144, 1.0, v144
	v_rcp_f32_e32 v144, v144
	s_nop 0
	v_mul_f32_e32 v141, v141, v144
	v_mul_f32_e32 v229, v140, v141
	v_mov_b32_e32 v140, v146
	v_mov_b32_e32 v141, v142
	v_pk_fma_f32 v[144:145], v[226:227], v[156:157], v[140:141] op_sel_hi:[0,1,1] neg_lo:[1,0,0] neg_hi:[1,0,0]
	v_mov_b32_e32 v140, v158
	v_mov_b32_e32 v141, v134
	v_pk_fma_f32 v[144:145], v[228:229], v[144:145], v[140:141] op_sel_hi:[0,1,1]
	v_mul_f32_e32 v134, 0xbfb8aa3b, v145
	v_exp_f32_e32 v134, v134
	v_mov_b32_e32 v142, v147
; __device__ __forceinline__ unsigned cvt_pk_bf16(float lo, float hi) { unsigned r; asm("v_cvt_pk_bf16_f32 %0, %1, %2" : "=v"(r) : "v"(lo), "v"(hi)); return r; }
; __device__ __forceinline__ f32x4 ln_fix(const f32x4& a, float mu, float rs, const f32x4& cs, const f32x4& cb) { return (a - cs * mu) * rs + cb; }
; __device__ __forceinline__ float fast_sigmoid(float v) { return __builtin_amdgcn_rcpf(1.0f + __builtin_amdgcn_exp2f(-1.4426950408889634f * v)); }
;     __device__ __forceinline__ void operator()(const f32x4 (&acc)[2][2][4][2], const Unit& u, int wr, int wc, int fr_in, int fq_in) const {
;     ...
;         for (int ai = 0; ai < 2; ++ai)
; #pragma unroll
;             for (int m = 0; m < 4; ++m) { bf16_t* rowp = H + ((size_t)kt * mrows + (row0 + ai * HALF + m * 16)) * 64 + cin;
;                 float h[8];
; #pragma unroll
;                 for (int n = 0; n < 2; ++n) { f32x4 g = acc[ai][0][m][n], uu = acc[ai][1][m][n];
;                     if constexpr (LN) { g = ln_fix(g, rst.mu[ai][m], rst.rs[ai][m], csv[0][n], cbv[0][n]); uu = ln_fix(uu, rst.mu[ai][m], rst.rs[ai][m], csv[1][n], cbv[1][n]); }
; #pragma unroll
;                     for (int j = 0; j < 4; ++j) h[4 * n + j] = g[j] * fast_sigmoid(g[j]) * uu[j]; }
;                 u32x4 w; w.x = cvt_pk_bf16(h[0], h[1]); w.y = cvt_pk_bf16(h[2], h[3]); w.z = cvt_pk_bf16(h[4], h[5]); w.w = cvt_pk_bf16(h[6], h[7]);
;                 *(u32x4*)rowp = w; }
	v_pk_fma_f32 v[142:143], v[226:227], v[210:211], v[142:143] op_sel_hi:[0,1,1] neg_lo:[1,0,0] neg_hi:[1,0,0]
	v_add_f32_e32 v134, 1.0, v134
	v_rcp_f32_e32 v134, v134
	s_nop 0
	v_mul_f32_e32 v134, v145, v134
	v_mul_f32_e32 v158, v144, v134
	v_mov_b32_e32 v134, v159
	v_pk_fma_f32 v[142:143], v[228:229], v[142:143], v[134:135] op_sel_hi:[0,1,1]
	v_mul_f32_e32 v144, 0xbfb8aa3b, v143
	v_exp_f32_e32 v144, v144
	v_mov_b32_e32 v145, v120
	v_mov_b32_e32 v120, v125
	v_mov_b32_e32 v125, v122
	v_add_f32_e32 v144, 1.0, v144
	v_rcp_f32_e32 v144, v144
	v_mov_b32_e32 v122, v127
	v_mul_f32_e32 v143, v143, v144
	v_mul_f32_e32 v159, v142, v143
	v_mov_b32_e32 v142, v148
	v_mov_b32_e32 v143, v112
	v_mov_b32_e32 v144, v124
	v_pk_fma_f32 v[146:147], v[226:227], v[142:143], v[144:145] op_sel_hi:[0,1,1] neg_lo:[1,0,0] neg_hi:[1,0,0]
	v_mov_b32_e32 v144, v152
	v_mov_b32_e32 v145, v116
	v_pk_fma_f32 v[146:147], v[228:229], v[146:147], v[144:145] op_sel_hi:[0,1,1]
	v_mul_f32_e32 v112, 0xbfb8aa3b, v147
	v_exp_f32_e32 v112, v112
	v_mov_b32_e32 v116, v153
	v_add_f32_e32 v112, 1.0, v112
	v_rcp_f32_e32 v112, v112
	s_nop 0
	v_mul_f32_e32 v112, v147, v112
	v_mul_f32_e32 v148, v146, v112
	v_mov_b32_e32 v112, v149
	v_pk_fma_f32 v[120:121], v[226:227], v[112:113], v[120:121] op_sel_hi:[0,1,1] neg_lo:[1,0,0] neg_hi:[1,0,0]
	v_pk_fma_f32 v[120:121], v[228:229], v[120:121], v[116:117] op_sel_hi:[0,1,1]
	v_mul_f32_e32 v124, 0xbfb8aa3b, v121
	v_exp_f32_e32 v124, v124
	s_nop 0
	v_add_f32_e32 v124, 1.0, v124
	v_rcp_f32_e32 v124, v124
	s_nop 0
	v_mul_f32_e32 v121, v121, v124
	v_mul_f32_e32 v149, v120, v121
	v_mov_b32_e32 v120, v150
	v_mov_b32_e32 v121, v114
	v_mov_b32_e32 v124, v126
	v_pk_fma_f32 v[146:147], v[226:227], v[120:121], v[124:125] op_sel_hi:[0,1,1] neg_lo:[1,0,0] neg_hi:[1,0,0]
	v_mov_b32_e32 v124, v154
	v_mov_b32_e32 v125, v118
	v_pk_fma_f32 v[146:147], v[228:229], v[146:147], v[124:125] op_sel_hi:[0,1,1]
	v_mul_f32_e32 v114, 0xbfb8aa3b, v147
	v_exp_f32_e32 v114, v114
	v_mov_b32_e32 v118, v155
	v_cvt_pk_bf16_f32 v148, v148, v149
	v_add_f32_e32 v114, 1.0, v114
	v_rcp_f32_e32 v114, v114
	s_nop 0
	v_mul_f32_e32 v114, v147, v114
	v_mul_f32_e32 v150, v146, v114
	v_mov_b32_e32 v114, v151
	v_pk_fma_f32 v[122:123], v[226:227], v[114:115], v[122:123] op_sel_hi:[0,1,1] neg_lo:[1,0,0] neg_hi:[1,0,0]
	v_pk_fma_f32 v[122:123], v[228:229], v[122:123], v[118:119] op_sel_hi:[0,1,1]
	v_mul_f32_e32 v126, 0xbfb8aa3b, v123
	v_exp_f32_e32 v126, v126
	v_cvt_pk_bf16_f32 v146, v223, v229
	v_cvt_pk_bf16_f32 v147, v158, v159
	s_nop 0
	v_add_f32_e32 v126, 1.0, v126
	v_rcp_f32_e32 v126, v126
	s_nop 0
	v_mul_f32_e32 v123, v123, v126
	v_mul_f32_e32 v151, v122, v123
	v_lshlrev_b64 v[122:123], 1, v[230:231]
	v_lshl_add_u64 v[126:127], v[232:233], 0, v[122:123]
	v_cvt_pk_bf16_f32 v149, v150, v151
	global_store_dwordx4 v[126:127], v[146:149], off
	v_lshl_add_u64 v[126:127], s[44:45], 0, v[224:225]
	v_lshlrev_b64 v[126:127], 7, v[126:127]
	v_mov_b32_e32 v146, v108
	v_mov_b32_e32 v147, v104
	v_pk_fma_f32 v[146:147], v[220:221], v[206:207], v[146:147] op_sel_hi:[0,1,1] neg_lo:[1,0,0] neg_hi:[1,0,0]
	v_pk_fma_f32 v[146:147], v[222:223], v[146:147], v[192:193] op_sel_hi:[0,1,1]
	v_mul_f32_e32 v104, 0xbfb8aa3b, v147
	v_exp_f32_e32 v104, v104
	v_lshl_add_u64 v[126:127], s[6:7], 0, v[126:127]
	v_add_f32_e32 v104, 1.0, v104
	v_rcp_f32_e32 v104, v104
	s_nop 0
	v_mul_f32_e32 v104, v147, v104
	v_mul_f32_e32 v108, v146, v104
	v_mov_b32_e32 v104, v109
	v_pk_fma_f32 v[104:105], v[220:221], v[208:209], v[104:105] op_sel_hi:[0,1,1] neg_lo:[1,0,0] neg_hi:[1,0,0]
	v_pk_fma_f32 v[104:105], v[222:223], v[104:105], v[132:133] op_sel_hi:[0,1,1]
	v_mul_f32_e32 v109, 0xbfb8aa3b, v105
	v_exp_f32_e32 v109, v109
	s_nop 0
	v_add_f32_e32 v109, 1.0, v109
	v_rcp_f32_e32 v109, v109
	s_nop 0
	v_mul_f32_e32 v105, v105, v109
	v_mul_f32_e32 v109, v104, v105
	v_mov_b32_e32 v104, v110
	v_mov_b32_e32 v105, v106
	v_pk_fma_f32 v[104:105], v[220:221], v[156:157], v[104:105] op_sel_hi:[0,1,1] neg_lo:[1,0,0] neg_hi:[1,0,0]
	v_pk_fma_f32 v[104:105], v[222:223], v[104:105], v[140:141] op_sel_hi:[0,1,1]
	v_mul_f32_e32 v106, 0xbfb8aa3b, v105
	v_exp_f32_e32 v106, v106
	s_nop 0
	v_add_f32_e32 v106, 1.0, v106
	v_rcp_f32_e32 v106, v106
	s_nop 0
	v_mul_f32_e32 v105, v105, v106
	v_mov_b32_e32 v106, v111
	v_mul_f32_e32 v110, v104, v105
	v_pk_fma_f32 v[104:105], v[220:221], v[210:211], v[106:107] op_sel_hi:[0,1,1] neg_lo:[1,0,0] neg_hi:[1,0,0]
	v_pk_fma_f32 v[104:105], v[222:223], v[104:105], v[134:135] op_sel_hi:[0,1,1]
	v_mul_f32_e32 v106, 0xbfb8aa3b, v105
	v_exp_f32_e32 v106, v106
	s_nop 0
	v_add_f32_e32 v106, 1.0, v106
	v_rcp_f32_e32 v106, v106
	s_nop 0
	v_mul_f32_e32 v105, v105, v106
	v_mul_f32_e32 v106, v104, v105
	v_mov_b32_e32 v104, v100
	v_mov_b32_e32 v105, v96
	v_pk_fma_f32 v[104:105], v[220:221], v[142:143], v[104:105] op_sel_hi:[0,1,1] neg_lo:[1,0,0] neg_hi:[1,0,0]
	v_pk_fma_f32 v[104:105], v[222:223], v[104:105], v[144:145] op_sel_hi:[0,1,1]
	v_mul_f32_e32 v96, 0xbfb8aa3b, v105
	v_exp_f32_e32 v96, v96
	s_nop 0
	v_add_f32_e32 v96, 1.0, v96
	v_rcp_f32_e32 v96, v96
	s_nop 0
	v_mul_f32_e32 v96, v105, v96
	v_mul_f32_e32 v104, v104, v96
	v_mov_b32_e32 v96, v101
	v_pk_fma_f32 v[96:97], v[220:221], v[112:113], v[96:97] op_sel_hi:[0,1,1] neg_lo:[1,0,0] neg_hi:[1,0,0]
	v_pk_fma_f32 v[96:97], v[222:223], v[96:97], v[116:117] op_sel_hi:[0,1,1]
	v_mul_f32_e32 v100, 0xbfb8aa3b, v97
	v_exp_f32_e32 v100, v100
	s_nop 0
	v_add_f32_e32 v100, 1.0, v100
	v_rcp_f32_e32 v100, v100
	s_nop 0
	v_mul_f32_e32 v97, v97, v100
	v_mul_f32_e32 v105, v96, v97
	v_mov_b32_e32 v96, v102
	v_mov_b32_e32 v97, v98
	v_pk_fma_f32 v[96:97], v[220:221], v[120:121], v[96:97] op_sel_hi:[0,1,1] neg_lo:[1,0,0] neg_hi:[1,0,0]
; __device__ __forceinline__ unsigned cvt_pk_bf16(float lo, float hi) { unsigned r; asm("v_cvt_pk_bf16_f32 %0, %1, %2" : "=v"(r) : "v"(lo), "v"(hi)); return r; }
; __device__ __forceinline__ f32x4 ln_fix(const f32x4& a, float mu, float rs, const f32x4& cs, const f32x4& cb) { return (a - cs * mu) * rs + cb; }
; __device__ __forceinline__ float fast_sigmoid(float v) { return __builtin_amdgcn_rcpf(1.0f + __builtin_amdgcn_exp2f(-1.4426950408889634f * v)); }
;     __device__ __forceinline__ void operator()(const f32x4 (&acc)[2][2][4][2], const Unit& u, int wr, int wc, int fr_in, int fq_in) const {
;     ...
;         for (int ai = 0; ai < 2; ++ai)
; #pragma unroll
;             for (int m = 0; m < 4; ++m) { bf16_t* rowp = H + ((size_t)kt * mrows + (row0 + ai * HALF + m * 16)) * 64 + cin;
;                 float h[8];
; #pragma unroll
;                 for (int n = 0; n < 2; ++n) { f32x4 g = acc[ai][0][m][n], uu = acc[ai][1][m][n];
;                     if constexpr (LN) { g = ln_fix(g, rst.mu[ai][m], rst.rs[ai][m], csv[0][n], cbv[0][n]); uu = ln_fix(uu, rst.mu[ai][m], rst.rs[ai][m], csv[1][n], cbv[1][n]); }
; #pragma unroll
;                     for (int j = 0; j < 4; ++j) h[4 * n + j] = g[j] * fast_sigmoid(g[j]) * uu[j]; }
;                 u32x4 w; w.x = cvt_pk_bf16(h[0], h[1]); w.y = cvt_pk_bf16(h[2], h[3]); w.z = cvt_pk_bf16(h[4], h[5]); w.w = cvt_pk_bf16(h[6], h[7]);
;                 *(u32x4*)rowp = w; }
	v_pk_fma_f32 v[96:97], v[222:223], v[96:97], v[124:125] op_sel_hi:[0,1,1]
	v_mul_f32_e32 v98, 0xbfb8aa3b, v97
	v_exp_f32_e32 v98, v98
	v_lshl_add_u64 v[100:101], v[126:127], 0, v[122:123]
	v_add_f32_e32 v98, 1.0, v98
	v_rcp_f32_e32 v98, v98
	s_nop 0
	v_mul_f32_e32 v97, v97, v98
	v_mov_b32_e32 v98, v103
	v_mul_f32_e32 v102, v96, v97
	v_pk_fma_f32 v[96:97], v[220:221], v[114:115], v[98:99] op_sel_hi:[0,1,1] neg_lo:[1,0,0] neg_hi:[1,0,0]
	v_pk_fma_f32 v[96:97], v[222:223], v[96:97], v[118:119] op_sel_hi:[0,1,1]
	v_mul_f32_e32 v98, 0xbfb8aa3b, v97
	v_exp_f32_e32 v98, v98
	s_nop 0
	v_add_f32_e32 v98, 1.0, v98
	v_rcp_f32_e32 v98, v98
	s_nop 0
	v_mul_f32_e32 v97, v97, v98
	v_mul_f32_e32 v99, v96, v97
	v_cvt_pk_bf16_f32 v98, v104, v105
	v_cvt_pk_bf16_f32 v99, v102, v99
	v_cvt_pk_bf16_f32 v96, v108, v109
	v_cvt_pk_bf16_f32 v97, v110, v106
	global_store_dwordx4 v[100:101], v[96:99], off
	s_nop 1
	v_mov_b32_e32 v98, v92
	v_mov_b32_e32 v99, v88
	v_pk_fma_f32 v[98:99], v[214:215], v[206:207], v[98:99] op_sel_hi:[0,1,1] neg_lo:[1,0,0] neg_hi:[1,0,0]
	v_pk_fma_f32 v[98:99], v[216:217], v[98:99], v[192:193] op_sel_hi:[0,1,1]
	v_mul_f32_e32 v88, 0xbfb8aa3b, v99
	v_exp_f32_e32 v88, v88
	v_lshl_add_u64 v[96:97], s[44:45], 0, v[218:219]
	v_lshlrev_b64 v[96:97], 7, v[96:97]
	v_lshl_add_u64 v[96:97], s[6:7], 0, v[96:97]
	v_add_f32_e32 v88, 1.0, v88
	v_rcp_f32_e32 v88, v88
	s_nop 0
	v_mul_f32_e32 v88, v99, v88
	v_mul_f32_e32 v92, v98, v88
	v_mov_b32_e32 v88, v93
	v_pk_fma_f32 v[88:89], v[214:215], v[208:209], v[88:89] op_sel_hi:[0,1,1] neg_lo:[1,0,0] neg_hi:[1,0,0]
	v_pk_fma_f32 v[88:89], v[216:217], v[88:89], v[132:133] op_sel_hi:[0,1,1]
	v_mul_f32_e32 v93, 0xbfb8aa3b, v89
	v_exp_f32_e32 v93, v93
	s_nop 0
	v_add_f32_e32 v93, 1.0, v93
	v_rcp_f32_e32 v93, v93
	s_nop 0
	v_mul_f32_e32 v89, v89, v93
	v_mul_f32_e32 v93, v88, v89
	v_mov_b32_e32 v88, v94
	v_mov_b32_e32 v89, v90
	v_pk_fma_f32 v[88:89], v[214:215], v[156:157], v[88:89] op_sel_hi:[0,1,1] neg_lo:[1,0,0] neg_hi:[1,0,0]
	v_pk_fma_f32 v[88:89], v[216:217], v[88:89], v[140:141] op_sel_hi:[0,1,1]
	v_mul_f32_e32 v90, 0xbfb8aa3b, v89
	v_exp_f32_e32 v90, v90
	s_nop 0
	v_add_f32_e32 v90, 1.0, v90
	v_rcp_f32_e32 v90, v90
	s_nop 0
	v_mul_f32_e32 v89, v89, v90
	v_mov_b32_e32 v90, v95
	v_mul_f32_e32 v94, v88, v89
	v_pk_fma_f32 v[88:89], v[214:215], v[210:211], v[90:91] op_sel_hi:[0,1,1] neg_lo:[1,0,0] neg_hi:[1,0,0]
	v_pk_fma_f32 v[88:89], v[216:217], v[88:89], v[134:135] op_sel_hi:[0,1,1]
	v_mul_f32_e32 v90, 0xbfb8aa3b, v89
	v_exp_f32_e32 v90, v90
	s_nop 0
	v_add_f32_e32 v90, 1.0, v90
	v_rcp_f32_e32 v90, v90
	s_nop 0
	v_mul_f32_e32 v89, v89, v90
	v_mul_f32_e32 v90, v88, v89
	v_mov_b32_e32 v88, v84
	v_mov_b32_e32 v89, v80
	v_pk_fma_f32 v[88:89], v[214:215], v[142:143], v[88:89] op_sel_hi:[0,1,1] neg_lo:[1,0,0] neg_hi:[1,0,0]
	v_pk_fma_f32 v[88:89], v[216:217], v[88:89], v[144:145] op_sel_hi:[0,1,1]
	v_mul_f32_e32 v80, 0xbfb8aa3b, v89
	v_exp_f32_e32 v80, v80
	s_nop 0
	v_add_f32_e32 v80, 1.0, v80
	v_rcp_f32_e32 v80, v80
	s_nop 0
	v_mul_f32_e32 v80, v89, v80
	v_mul_f32_e32 v88, v88, v80
	v_mov_b32_e32 v80, v85
	v_pk_fma_f32 v[80:81], v[214:215], v[112:113], v[80:81] op_sel_hi:[0,1,1] neg_lo:[1,0,0] neg_hi:[1,0,0]
	v_pk_fma_f32 v[80:81], v[216:217], v[80:81], v[116:117] op_sel_hi:[0,1,1]
	v_mul_f32_e32 v84, 0xbfb8aa3b, v81
	v_exp_f32_e32 v84, v84
	s_nop 0
	v_add_f32_e32 v84, 1.0, v84
	v_rcp_f32_e32 v84, v84
	s_nop 0
	v_mul_f32_e32 v81, v81, v84
	v_mul_f32_e32 v89, v80, v81
	v_mov_b32_e32 v80, v86
	v_mov_b32_e32 v81, v82
	v_pk_fma_f32 v[80:81], v[214:215], v[120:121], v[80:81] op_sel_hi:[0,1,1] neg_lo:[1,0,0] neg_hi:[1,0,0]
	v_pk_fma_f32 v[80:81], v[216:217], v[80:81], v[124:125] op_sel_hi:[0,1,1]
	v_mul_f32_e32 v82, 0xbfb8aa3b, v81
	v_exp_f32_e32 v82, v82
	v_lshl_add_u64 v[84:85], v[96:97], 0, v[122:123]
	v_add_f32_e32 v82, 1.0, v82
	v_rcp_f32_e32 v82, v82
	s_nop 0
	v_mul_f32_e32 v81, v81, v82
	v_mov_b32_e32 v82, v87
	v_mul_f32_e32 v86, v80, v81
	v_pk_fma_f32 v[80:81], v[214:215], v[114:115], v[82:83] op_sel_hi:[0,1,1] neg_lo:[1,0,0] neg_hi:[1,0,0]
	v_pk_fma_f32 v[80:81], v[216:217], v[80:81], v[118:119] op_sel_hi:[0,1,1]
	v_mul_f32_e32 v82, 0xbfb8aa3b, v81
	v_exp_f32_e32 v82, v82
	s_nop 0
	v_add_f32_e32 v82, 1.0, v82
	v_rcp_f32_e32 v82, v82
	s_nop 0
	v_mul_f32_e32 v81, v81, v82
	v_mul_f32_e32 v83, v80, v81
	v_cvt_pk_bf16_f32 v82, v88, v89
	v_cvt_pk_bf16_f32 v83, v86, v83
	v_cvt_pk_bf16_f32 v80, v92, v93
	v_cvt_pk_bf16_f32 v81, v94, v90
	global_store_dwordx4 v[84:85], v[80:83], off
	s_nop 1
	v_mov_b32_e32 v82, v76
	v_mov_b32_e32 v83, v72
	v_pk_fma_f32 v[82:83], v[200:201], v[206:207], v[82:83] op_sel_hi:[0,1,1] neg_lo:[1,0,0] neg_hi:[1,0,0]
	v_pk_fma_f32 v[82:83], v[202:203], v[82:83], v[192:193] op_sel_hi:[0,1,1]
	v_mul_f32_e32 v72, 0xbfb8aa3b, v83
	v_exp_f32_e32 v72, v72
	v_lshl_add_u64 v[80:81], s[44:45], 0, v[212:213]
	v_lshlrev_b64 v[80:81], 7, v[80:81]
	v_lshl_add_u64 v[80:81], s[6:7], 0, v[80:81]
	v_add_f32_e32 v72, 1.0, v72
	v_rcp_f32_e32 v72, v72
	s_nop 0
	v_mul_f32_e32 v72, v83, v72
	v_mul_f32_e32 v76, v82, v72
	v_mov_b32_e32 v72, v77
	v_pk_fma_f32 v[72:73], v[200:201], v[208:209], v[72:73] op_sel_hi:[0,1,1] neg_lo:[1,0,0] neg_hi:[1,0,0]
	v_pk_fma_f32 v[72:73], v[202:203], v[72:73], v[132:133] op_sel_hi:[0,1,1]
	v_mul_f32_e32 v77, 0xbfb8aa3b, v73
	v_exp_f32_e32 v77, v77
	s_nop 0
	v_add_f32_e32 v77, 1.0, v77
	v_rcp_f32_e32 v77, v77
	s_nop 0
	v_mul_f32_e32 v73, v73, v77
	v_mul_f32_e32 v77, v72, v73
	v_mov_b32_e32 v72, v78
	v_mov_b32_e32 v73, v74
	v_pk_fma_f32 v[72:73], v[200:201], v[156:157], v[72:73] op_sel_hi:[0,1,1] neg_lo:[1,0,0] neg_hi:[1,0,0]
	v_pk_fma_f32 v[72:73], v[202:203], v[72:73], v[140:141] op_sel_hi:[0,1,1]
; __device__ __forceinline__ unsigned cvt_pk_bf16(float lo, float hi) { unsigned r; asm("v_cvt_pk_bf16_f32 %0, %1, %2" : "=v"(r) : "v"(lo), "v"(hi)); return r; }
; __device__ __forceinline__ f32x4 ln_fix(const f32x4& a, float mu, float rs, const f32x4& cs, const f32x4& cb) { return (a - cs * mu) * rs + cb; }
; __device__ __forceinline__ float fast_sigmoid(float v) { return __builtin_amdgcn_rcpf(1.0f + __builtin_amdgcn_exp2f(-1.4426950408889634f * v)); }
;     __device__ __forceinline__ void operator()(const f32x4 (&acc)[2][2][4][2], const Unit& u, int wr, int wc, int fr_in, int fq_in) const {
;     ...
;         for (int ai = 0; ai < 2; ++ai)
; #pragma unroll
;             for (int m = 0; m < 4; ++m) { bf16_t* rowp = H + ((size_t)kt * mrows + (row0 + ai * HALF + m * 16)) * 64 + cin;
;                 float h[8];
; #pragma unroll
;                 for (int n = 0; n < 2; ++n) { f32x4 g = acc[ai][0][m][n], uu = acc[ai][1][m][n];
;                     if constexpr (LN) { g = ln_fix(g, rst.mu[ai][m], rst.rs[ai][m], csv[0][n], cbv[0][n]); uu = ln_fix(uu, rst.mu[ai][m], rst.rs[ai][m], csv[1][n], cbv[1][n]); }
; #pragma unroll
;                     for (int j = 0; j < 4; ++j) h[4 * n + j] = g[j] * fast_sigmoid(g[j]) * uu[j]; }
;                 u32x4 w; w.x = cvt_pk_bf16(h[0], h[1]); w.y = cvt_pk_bf16(h[2], h[3]); w.z = cvt_pk_bf16(h[4], h[5]); w.w = cvt_pk_bf16(h[6], h[7]);
;                 *(u32x4*)rowp = w; }
	v_mul_f32_e32 v74, 0xbfb8aa3b, v73
	v_exp_f32_e32 v74, v74
	s_nop 0
	v_add_f32_e32 v74, 1.0, v74
	v_rcp_f32_e32 v74, v74
	s_nop 0
	v_mul_f32_e32 v73, v73, v74
	v_mov_b32_e32 v74, v79
	v_mul_f32_e32 v78, v72, v73
	v_pk_fma_f32 v[72:73], v[200:201], v[210:211], v[74:75] op_sel_hi:[0,1,1] neg_lo:[1,0,0] neg_hi:[1,0,0]
	v_pk_fma_f32 v[72:73], v[202:203], v[72:73], v[134:135] op_sel_hi:[0,1,1]
	v_mul_f32_e32 v74, 0xbfb8aa3b, v73
	v_exp_f32_e32 v74, v74
	s_nop 0
	v_add_f32_e32 v74, 1.0, v74
	v_rcp_f32_e32 v74, v74
	s_nop 0
	v_mul_f32_e32 v73, v73, v74
	v_mul_f32_e32 v74, v72, v73
	v_mov_b32_e32 v72, v68
	v_mov_b32_e32 v73, v64
	v_pk_fma_f32 v[72:73], v[200:201], v[142:143], v[72:73] op_sel_hi:[0,1,1] neg_lo:[1,0,0] neg_hi:[1,0,0]
	v_pk_fma_f32 v[72:73], v[202:203], v[72:73], v[144:145] op_sel_hi:[0,1,1]
	v_mul_f32_e32 v64, 0xbfb8aa3b, v73
	v_exp_f32_e32 v64, v64
	s_nop 0
	v_add_f32_e32 v64, 1.0, v64
	v_rcp_f32_e32 v64, v64
	s_nop 0
	v_mul_f32_e32 v64, v73, v64
	v_mul_f32_e32 v72, v72, v64
	v_mov_b32_e32 v64, v69
	v_pk_fma_f32 v[64:65], v[200:201], v[112:113], v[64:65] op_sel_hi:[0,1,1] neg_lo:[1,0,0] neg_hi:[1,0,0]
	v_pk_fma_f32 v[64:65], v[202:203], v[64:65], v[116:117] op_sel_hi:[0,1,1]
	v_mul_f32_e32 v68, 0xbfb8aa3b, v65
	v_exp_f32_e32 v68, v68
	s_nop 0
	v_add_f32_e32 v68, 1.0, v68
	v_rcp_f32_e32 v68, v68
	s_nop 0
	v_mul_f32_e32 v65, v65, v68
	v_mul_f32_e32 v73, v64, v65
	v_mov_b32_e32 v64, v70
	v_mov_b32_e32 v65, v66
	v_pk_fma_f32 v[64:65], v[200:201], v[120:121], v[64:65] op_sel_hi:[0,1,1] neg_lo:[1,0,0] neg_hi:[1,0,0]
	v_pk_fma_f32 v[64:65], v[202:203], v[64:65], v[124:125] op_sel_hi:[0,1,1]
	v_mul_f32_e32 v66, 0xbfb8aa3b, v65
	v_exp_f32_e32 v66, v66
	v_lshl_add_u64 v[68:69], v[80:81], 0, v[122:123]
	v_add_f32_e32 v66, 1.0, v66
	v_rcp_f32_e32 v66, v66
	s_nop 0
	v_mul_f32_e32 v65, v65, v66
	v_mov_b32_e32 v66, v71
	v_mul_f32_e32 v70, v64, v65
	v_pk_fma_f32 v[64:65], v[200:201], v[114:115], v[66:67] op_sel_hi:[0,1,1] neg_lo:[1,0,0] neg_hi:[1,0,0]
	v_pk_fma_f32 v[64:65], v[202:203], v[64:65], v[118:119] op_sel_hi:[0,1,1]
	v_mul_f32_e32 v66, 0xbfb8aa3b, v65
	v_exp_f32_e32 v66, v66
	s_nop 0
	v_add_f32_e32 v66, 1.0, v66
	v_rcp_f32_e32 v66, v66
	s_nop 0
	v_mul_f32_e32 v65, v65, v66
	v_mul_f32_e32 v67, v64, v65
	v_cvt_pk_bf16_f32 v66, v72, v73
	v_cvt_pk_bf16_f32 v67, v70, v67
	v_cvt_pk_bf16_f32 v64, v76, v77
	v_cvt_pk_bf16_f32 v65, v78, v74
	global_store_dwordx4 v[68:69], v[64:67], off
	s_nop 1
	v_mov_b32_e32 v66, v60
	v_mov_b32_e32 v67, v56
	v_pk_fma_f32 v[66:67], v[194:195], v[206:207], v[66:67] op_sel_hi:[0,1,1] neg_lo:[1,0,0] neg_hi:[1,0,0]
	v_pk_fma_f32 v[66:67], v[198:199], v[66:67], v[192:193] op_sel_hi:[0,1,1]
	v_mul_f32_e32 v56, 0xbfb8aa3b, v67
	v_exp_f32_e32 v56, v56
	v_lshl_add_u64 v[64:65], s[44:45], 0, v[204:205]
	v_lshlrev_b64 v[64:65], 7, v[64:65]
	v_lshl_add_u64 v[64:65], s[6:7], 0, v[64:65]
	v_add_f32_e32 v56, 1.0, v56
	v_rcp_f32_e32 v56, v56
	s_nop 0
	v_mul_f32_e32 v56, v67, v56
	v_mul_f32_e32 v60, v66, v56
	v_mov_b32_e32 v56, v61
	v_pk_fma_f32 v[56:57], v[194:195], v[208:209], v[56:57] op_sel_hi:[0,1,1] neg_lo:[1,0,0] neg_hi:[1,0,0]
	v_pk_fma_f32 v[56:57], v[198:199], v[56:57], v[132:133] op_sel_hi:[0,1,1]
	v_mul_f32_e32 v61, 0xbfb8aa3b, v57
	v_exp_f32_e32 v61, v61
	s_nop 0
	v_add_f32_e32 v61, 1.0, v61
	v_rcp_f32_e32 v61, v61
	s_nop 0
	v_mul_f32_e32 v57, v57, v61
	v_mul_f32_e32 v61, v56, v57
	v_mov_b32_e32 v56, v62
	v_mov_b32_e32 v57, v58
	v_pk_fma_f32 v[56:57], v[194:195], v[156:157], v[56:57] op_sel_hi:[0,1,1] neg_lo:[1,0,0] neg_hi:[1,0,0]
	v_pk_fma_f32 v[56:57], v[198:199], v[56:57], v[140:141] op_sel_hi:[0,1,1]
	v_mul_f32_e32 v58, 0xbfb8aa3b, v57
	v_exp_f32_e32 v58, v58
	s_nop 0
	v_add_f32_e32 v58, 1.0, v58
	v_rcp_f32_e32 v58, v58
	s_nop 0
	v_mul_f32_e32 v57, v57, v58
	v_mov_b32_e32 v58, v63
	v_mul_f32_e32 v62, v56, v57
	v_pk_fma_f32 v[56:57], v[194:195], v[210:211], v[58:59] op_sel_hi:[0,1,1] neg_lo:[1,0,0] neg_hi:[1,0,0]
	v_pk_fma_f32 v[56:57], v[198:199], v[56:57], v[134:135] op_sel_hi:[0,1,1]
	v_mul_f32_e32 v58, 0xbfb8aa3b, v57
	v_exp_f32_e32 v58, v58
	s_nop 0
	v_add_f32_e32 v58, 1.0, v58
	v_rcp_f32_e32 v58, v58
	s_nop 0
	v_mul_f32_e32 v57, v57, v58
	v_mul_f32_e32 v58, v56, v57
	v_mov_b32_e32 v56, v52
	v_mov_b32_e32 v57, v48
	v_pk_fma_f32 v[56:57], v[194:195], v[142:143], v[56:57] op_sel_hi:[0,1,1] neg_lo:[1,0,0] neg_hi:[1,0,0]
	v_pk_fma_f32 v[56:57], v[198:199], v[56:57], v[144:145] op_sel_hi:[0,1,1]
	v_mul_f32_e32 v48, 0xbfb8aa3b, v57
	v_exp_f32_e32 v48, v48
	s_nop 0
	v_add_f32_e32 v48, 1.0, v48
	v_rcp_f32_e32 v48, v48
	s_nop 0
	v_mul_f32_e32 v48, v57, v48
	v_mul_f32_e32 v56, v56, v48
	v_mov_b32_e32 v48, v53
	v_pk_fma_f32 v[48:49], v[194:195], v[112:113], v[48:49] op_sel_hi:[0,1,1] neg_lo:[1,0,0] neg_hi:[1,0,0]
	v_pk_fma_f32 v[48:49], v[198:199], v[48:49], v[116:117] op_sel_hi:[0,1,1]
	v_mul_f32_e32 v52, 0xbfb8aa3b, v49
	v_exp_f32_e32 v52, v52
	s_nop 0
	v_add_f32_e32 v52, 1.0, v52
	v_rcp_f32_e32 v52, v52
	s_nop 0
	v_mul_f32_e32 v49, v49, v52
	v_mul_f32_e32 v57, v48, v49
	v_mov_b32_e32 v48, v54
	v_mov_b32_e32 v49, v50
	v_pk_fma_f32 v[48:49], v[194:195], v[120:121], v[48:49] op_sel_hi:[0,1,1] neg_lo:[1,0,0] neg_hi:[1,0,0]
	v_pk_fma_f32 v[48:49], v[198:199], v[48:49], v[124:125] op_sel_hi:[0,1,1]
	v_mul_f32_e32 v50, 0xbfb8aa3b, v49
	v_exp_f32_e32 v50, v50
	v_lshl_add_u64 v[52:53], v[64:65], 0, v[122:123]
	v_add_f32_e32 v50, 1.0, v50
	v_rcp_f32_e32 v50, v50
	s_nop 0
	v_mul_f32_e32 v49, v49, v50
	v_mov_b32_e32 v50, v55
	v_mul_f32_e32 v54, v48, v49
	v_pk_fma_f32 v[48:49], v[194:195], v[114:115], v[50:51] op_sel_hi:[0,1,1] neg_lo:[1,0,0] neg_hi:[1,0,0]
	v_pk_fma_f32 v[48:49], v[198:199], v[48:49], v[118:119] op_sel_hi:[0,1,1]
; __device__ __forceinline__ unsigned cvt_pk_bf16(float lo, float hi) { unsigned r; asm("v_cvt_pk_bf16_f32 %0, %1, %2" : "=v"(r) : "v"(lo), "v"(hi)); return r; }
; __device__ __forceinline__ f32x4 ln_fix(const f32x4& a, float mu, float rs, const f32x4& cs, const f32x4& cb) { return (a - cs * mu) * rs + cb; }
; __device__ __forceinline__ float fast_sigmoid(float v) { return __builtin_amdgcn_rcpf(1.0f + __builtin_amdgcn_exp2f(-1.4426950408889634f * v)); }
;     __device__ __forceinline__ void operator()(const f32x4 (&acc)[2][2][4][2], const Unit& u, int wr, int wc, int fr_in, int fq_in) const {
;     ...
;         for (int ai = 0; ai < 2; ++ai)
; #pragma unroll
;             for (int m = 0; m < 4; ++m) { bf16_t* rowp = H + ((size_t)kt * mrows + (row0 + ai * HALF + m * 16)) * 64 + cin;
;                 float h[8];
; #pragma unroll
;                 for (int n = 0; n < 2; ++n) { f32x4 g = acc[ai][0][m][n], uu = acc[ai][1][m][n];
;                     if constexpr (LN) { g = ln_fix(g, rst.mu[ai][m], rst.rs[ai][m], csv[0][n], cbv[0][n]); uu = ln_fix(uu, rst.mu[ai][m], rst.rs[ai][m], csv[1][n], cbv[1][n]); }
; #pragma unroll
;                     for (int j = 0; j < 4; ++j) h[4 * n + j] = g[j] * fast_sigmoid(g[j]) * uu[j]; }
;                 u32x4 w; w.x = cvt_pk_bf16(h[0], h[1]); w.y = cvt_pk_bf16(h[2], h[3]); w.z = cvt_pk_bf16(h[4], h[5]); w.w = cvt_pk_bf16(h[6], h[7]);
;                 *(u32x4*)rowp = w; }
	v_mul_f32_e32 v50, 0xbfb8aa3b, v49
	v_exp_f32_e32 v50, v50
	s_nop 0
	v_add_f32_e32 v50, 1.0, v50
	v_rcp_f32_e32 v50, v50
	s_nop 0
	v_mul_f32_e32 v49, v49, v50
	v_mul_f32_e32 v51, v48, v49
	v_cvt_pk_bf16_f32 v50, v56, v57
	v_cvt_pk_bf16_f32 v51, v54, v51
	v_cvt_pk_bf16_f32 v48, v60, v61
	v_cvt_pk_bf16_f32 v49, v62, v58
	global_store_dwordx4 v[52:53], v[48:51], off
	s_nop 1
	v_mov_b32_e32 v50, v44
	v_mov_b32_e32 v51, v40
	v_pk_fma_f32 v[50:51], v[186:187], v[206:207], v[50:51] op_sel_hi:[0,1,1] neg_lo:[1,0,0] neg_hi:[1,0,0]
	v_pk_fma_f32 v[50:51], v[190:191], v[50:51], v[192:193] op_sel_hi:[0,1,1]
	v_mul_f32_e32 v40, 0xbfb8aa3b, v51
	v_exp_f32_e32 v40, v40
	v_lshl_add_u64 v[48:49], s[44:45], 0, v[196:197]
	v_lshlrev_b64 v[48:49], 7, v[48:49]
	v_lshl_add_u64 v[48:49], s[6:7], 0, v[48:49]
	v_add_f32_e32 v40, 1.0, v40
	v_rcp_f32_e32 v40, v40
	s_nop 0
	v_mul_f32_e32 v40, v51, v40
	v_mul_f32_e32 v44, v50, v40
	v_mov_b32_e32 v40, v45
	v_pk_fma_f32 v[40:41], v[186:187], v[208:209], v[40:41] op_sel_hi:[0,1,1] neg_lo:[1,0,0] neg_hi:[1,0,0]
	v_pk_fma_f32 v[40:41], v[190:191], v[40:41], v[132:133] op_sel_hi:[0,1,1]
	v_mul_f32_e32 v45, 0xbfb8aa3b, v41
	v_exp_f32_e32 v45, v45
	s_nop 0
	v_add_f32_e32 v45, 1.0, v45
	v_rcp_f32_e32 v45, v45
	s_nop 0
	v_mul_f32_e32 v41, v41, v45
	v_mul_f32_e32 v45, v40, v41
	v_mov_b32_e32 v40, v46
	v_mov_b32_e32 v41, v42
	v_pk_fma_f32 v[40:41], v[186:187], v[156:157], v[40:41] op_sel_hi:[0,1,1] neg_lo:[1,0,0] neg_hi:[1,0,0]
	v_pk_fma_f32 v[40:41], v[190:191], v[40:41], v[140:141] op_sel_hi:[0,1,1]
	v_mul_f32_e32 v42, 0xbfb8aa3b, v41
	v_exp_f32_e32 v42, v42
	s_nop 0
	v_add_f32_e32 v42, 1.0, v42
	v_rcp_f32_e32 v42, v42
	s_nop 0
	v_mul_f32_e32 v41, v41, v42
	v_mov_b32_e32 v42, v47
	v_mul_f32_e32 v46, v40, v41
	v_pk_fma_f32 v[40:41], v[186:187], v[210:211], v[42:43] op_sel_hi:[0,1,1] neg_lo:[1,0,0] neg_hi:[1,0,0]
	v_pk_fma_f32 v[40:41], v[190:191], v[40:41], v[134:135] op_sel_hi:[0,1,1]
	v_mul_f32_e32 v42, 0xbfb8aa3b, v41
	v_exp_f32_e32 v42, v42
	s_nop 0
	v_add_f32_e32 v42, 1.0, v42
	v_rcp_f32_e32 v42, v42
	s_nop 0
	v_mul_f32_e32 v41, v41, v42
	v_mul_f32_e32 v42, v40, v41
	v_mov_b32_e32 v40, v36
	v_mov_b32_e32 v41, v32
	v_pk_fma_f32 v[40:41], v[186:187], v[142:143], v[40:41] op_sel_hi:[0,1,1] neg_lo:[1,0,0] neg_hi:[1,0,0]
	v_pk_fma_f32 v[40:41], v[190:191], v[40:41], v[144:145] op_sel_hi:[0,1,1]
	v_mul_f32_e32 v32, 0xbfb8aa3b, v41
	v_exp_f32_e32 v32, v32
	s_nop 0
	v_add_f32_e32 v32, 1.0, v32
	v_rcp_f32_e32 v32, v32
	s_nop 0
	v_mul_f32_e32 v32, v41, v32
	v_mul_f32_e32 v40, v40, v32
	v_mov_b32_e32 v32, v37
	v_pk_fma_f32 v[32:33], v[186:187], v[112:113], v[32:33] op_sel_hi:[0,1,1] neg_lo:[1,0,0] neg_hi:[1,0,0]
	v_pk_fma_f32 v[32:33], v[190:191], v[32:33], v[116:117] op_sel_hi:[0,1,1]
	v_mul_f32_e32 v36, 0xbfb8aa3b, v33
	v_exp_f32_e32 v36, v36
	s_nop 0
	v_add_f32_e32 v36, 1.0, v36
	v_rcp_f32_e32 v36, v36
	s_nop 0
	v_mul_f32_e32 v33, v33, v36
	v_mul_f32_e32 v41, v32, v33
	v_mov_b32_e32 v32, v38
	v_mov_b32_e32 v33, v34
	v_pk_fma_f32 v[32:33], v[186:187], v[120:121], v[32:33] op_sel_hi:[0,1,1] neg_lo:[1,0,0] neg_hi:[1,0,0]
	v_pk_fma_f32 v[32:33], v[190:191], v[32:33], v[124:125] op_sel_hi:[0,1,1]
	v_mul_f32_e32 v34, 0xbfb8aa3b, v33
	v_exp_f32_e32 v34, v34
	v_lshl_add_u64 v[36:37], v[48:49], 0, v[122:123]
	v_add_f32_e32 v34, 1.0, v34
	v_rcp_f32_e32 v34, v34
	s_nop 0
	v_mul_f32_e32 v33, v33, v34
	v_mov_b32_e32 v34, v39
	v_mul_f32_e32 v38, v32, v33
	v_pk_fma_f32 v[32:33], v[186:187], v[114:115], v[34:35] op_sel_hi:[0,1,1] neg_lo:[1,0,0] neg_hi:[1,0,0]
	v_pk_fma_f32 v[32:33], v[190:191], v[32:33], v[118:119] op_sel_hi:[0,1,1]
	v_mul_f32_e32 v34, 0xbfb8aa3b, v33
	v_exp_f32_e32 v34, v34
	s_nop 0
	v_add_f32_e32 v34, 1.0, v34
	v_rcp_f32_e32 v34, v34
	s_nop 0
	v_mul_f32_e32 v33, v33, v34
	v_mul_f32_e32 v35, v32, v33
	v_cvt_pk_bf16_f32 v34, v40, v41
	v_cvt_pk_bf16_f32 v35, v38, v35
	v_cvt_pk_bf16_f32 v32, v44, v45
	v_cvt_pk_bf16_f32 v33, v46, v42
	global_store_dwordx4 v[36:37], v[32:35], off
	s_nop 1
	v_mov_b32_e32 v34, v28
	v_mov_b32_e32 v35, v24
	v_pk_fma_f32 v[34:35], v[180:181], v[206:207], v[34:35] op_sel_hi:[0,1,1] neg_lo:[1,0,0] neg_hi:[1,0,0]
	v_pk_fma_f32 v[34:35], v[184:185], v[34:35], v[192:193] op_sel_hi:[0,1,1]
	v_mul_f32_e32 v24, 0xbfb8aa3b, v35
	v_exp_f32_e32 v24, v24
	v_lshl_add_u64 v[32:33], s[44:45], 0, v[188:189]
	v_lshlrev_b64 v[32:33], 7, v[32:33]
	v_lshl_add_u64 v[32:33], s[6:7], 0, v[32:33]
	v_add_f32_e32 v24, 1.0, v24
	v_rcp_f32_e32 v24, v24
	s_nop 0
	v_mul_f32_e32 v24, v35, v24
	v_mul_f32_e32 v28, v34, v24
	v_mov_b32_e32 v24, v29
	v_pk_fma_f32 v[24:25], v[180:181], v[208:209], v[24:25] op_sel_hi:[0,1,1] neg_lo:[1,0,0] neg_hi:[1,0,0]
	v_pk_fma_f32 v[24:25], v[184:185], v[24:25], v[132:133] op_sel_hi:[0,1,1]
	v_mul_f32_e32 v29, 0xbfb8aa3b, v25
	v_exp_f32_e32 v29, v29
	s_nop 0
	v_add_f32_e32 v29, 1.0, v29
	v_rcp_f32_e32 v29, v29
	s_nop 0
	v_mul_f32_e32 v25, v25, v29
	v_mul_f32_e32 v29, v24, v25
	v_mov_b32_e32 v24, v30
	v_mov_b32_e32 v25, v26
	v_pk_fma_f32 v[24:25], v[180:181], v[156:157], v[24:25] op_sel_hi:[0,1,1] neg_lo:[1,0,0] neg_hi:[1,0,0]
	v_pk_fma_f32 v[24:25], v[184:185], v[24:25], v[140:141] op_sel_hi:[0,1,1]
	v_mul_f32_e32 v26, 0xbfb8aa3b, v25
	v_exp_f32_e32 v26, v26
	s_nop 0
	v_add_f32_e32 v26, 1.0, v26
	v_rcp_f32_e32 v26, v26
	s_nop 0
	v_mul_f32_e32 v25, v25, v26
	v_mov_b32_e32 v26, v31
	v_mul_f32_e32 v30, v24, v25
	v_pk_fma_f32 v[24:25], v[180:181], v[210:211], v[26:27] op_sel_hi:[0,1,1] neg_lo:[1,0,0] neg_hi:[1,0,0]
	v_pk_fma_f32 v[24:25], v[184:185], v[24:25], v[134:135] op_sel_hi:[0,1,1]
	v_mul_f32_e32 v26, 0xbfb8aa3b, v25
	v_exp_f32_e32 v26, v26
	s_nop 0
	v_add_f32_e32 v26, 1.0, v26
	v_rcp_f32_e32 v26, v26
; __device__ __forceinline__ unsigned cvt_pk_bf16(float lo, float hi) { unsigned r; asm("v_cvt_pk_bf16_f32 %0, %1, %2" : "=v"(r) : "v"(lo), "v"(hi)); return r; }
; __device__ __forceinline__ float fast_sigmoid(float v) { return __builtin_amdgcn_rcpf(1.0f + __builtin_amdgcn_exp2f(-1.4426950408889634f * v)); }
; __device__ __forceinline__ f32x4 ln_fix(const f32x4& a, float mu, float rs, const f32x4& cs, const f32x4& cb) { return (a - cs * mu) * rs + cb; }
;     __device__ __forceinline__ void operator()(const f32x4 (&acc)[2][2][4][2], const Unit& u, int wr, int wc, int fr_in, int fq_in) const {
;     ...
;         for (int ai = 0; ai < 2; ++ai)
; #pragma unroll
;             for (int m = 0; m < 4; ++m) { bf16_t* rowp = H + ((size_t)kt * mrows + (row0 + ai * HALF + m * 16)) * 64 + cin;
;                 float h[8];
; #pragma unroll
;                 for (int n = 0; n < 2; ++n) { f32x4 g = acc[ai][0][m][n], uu = acc[ai][1][m][n];
;                     if constexpr (LN) { g = ln_fix(g, rst.mu[ai][m], rst.rs[ai][m], csv[0][n], cbv[0][n]); uu = ln_fix(uu, rst.mu[ai][m], rst.rs[ai][m], csv[1][n], cbv[1][n]); }
; #pragma unroll
;                     for (int j = 0; j < 4; ++j) h[4 * n + j] = g[j] * fast_sigmoid(g[j]) * uu[j]; }
;                 u32x4 w; w.x = cvt_pk_bf16(h[0], h[1]); w.y = cvt_pk_bf16(h[2], h[3]); w.z = cvt_pk_bf16(h[4], h[5]); w.w = cvt_pk_bf16(h[6], h[7]);
;                 *(u32x4*)rowp = w; }
	s_nop 0
	v_mul_f32_e32 v25, v25, v26
	v_mul_f32_e32 v26, v24, v25
	v_mov_b32_e32 v24, v20
	v_mov_b32_e32 v25, v16
	v_pk_fma_f32 v[24:25], v[180:181], v[142:143], v[24:25] op_sel_hi:[0,1,1] neg_lo:[1,0,0] neg_hi:[1,0,0]
	v_pk_fma_f32 v[24:25], v[184:185], v[24:25], v[144:145] op_sel_hi:[0,1,1]
	v_mul_f32_e32 v16, 0xbfb8aa3b, v25
	v_exp_f32_e32 v16, v16
	s_nop 0
	v_add_f32_e32 v16, 1.0, v16
	v_rcp_f32_e32 v16, v16
	s_nop 0
	v_mul_f32_e32 v16, v25, v16
	v_mul_f32_e32 v24, v24, v16
	v_mov_b32_e32 v16, v21
	v_pk_fma_f32 v[16:17], v[180:181], v[112:113], v[16:17] op_sel_hi:[0,1,1] neg_lo:[1,0,0] neg_hi:[1,0,0]
	v_pk_fma_f32 v[16:17], v[184:185], v[16:17], v[116:117] op_sel_hi:[0,1,1]
	v_mul_f32_e32 v20, 0xbfb8aa3b, v17
	v_exp_f32_e32 v20, v20
	s_nop 0
	v_add_f32_e32 v20, 1.0, v20
	v_rcp_f32_e32 v20, v20
	s_nop 0
	v_mul_f32_e32 v17, v17, v20
	v_mul_f32_e32 v25, v16, v17
	v_mov_b32_e32 v16, v22
	v_mov_b32_e32 v17, v18
	v_pk_fma_f32 v[16:17], v[180:181], v[120:121], v[16:17] op_sel_hi:[0,1,1] neg_lo:[1,0,0] neg_hi:[1,0,0]
	v_pk_fma_f32 v[16:17], v[184:185], v[16:17], v[124:125] op_sel_hi:[0,1,1]
	v_mul_f32_e32 v18, 0xbfb8aa3b, v17
	v_exp_f32_e32 v18, v18
	v_lshl_add_u64 v[20:21], v[32:33], 0, v[122:123]
	v_add_f32_e32 v18, 1.0, v18
	v_rcp_f32_e32 v18, v18
	s_nop 0
	v_mul_f32_e32 v17, v17, v18
	v_mov_b32_e32 v18, v23
	v_mul_f32_e32 v22, v16, v17
	v_pk_fma_f32 v[16:17], v[180:181], v[114:115], v[18:19] op_sel_hi:[0,1,1] neg_lo:[1,0,0] neg_hi:[1,0,0]
	v_pk_fma_f32 v[16:17], v[184:185], v[16:17], v[118:119] op_sel_hi:[0,1,1]
	v_mul_f32_e32 v18, 0xbfb8aa3b, v17
	v_exp_f32_e32 v18, v18
	v_mov_b32_e32 v23, v8
	v_add_f32_e32 v18, 1.0, v18
	v_rcp_f32_e32 v18, v18
	s_nop 0
	v_mul_f32_e32 v17, v17, v18
	v_mul_f32_e32 v19, v16, v17
	v_cvt_pk_bf16_f32 v18, v24, v25
	v_cvt_pk_bf16_f32 v19, v22, v19
	v_cvt_pk_bf16_f32 v16, v28, v29
	v_cvt_pk_bf16_f32 v17, v30, v26
	global_store_dwordx4 v[20:21], v[16:19], off
	v_mov_b32_e32 v20, v136
	v_mov_b32_e32 v21, v176
	v_mov_b32_e32 v18, v176
	v_mov_b32_e32 v19, v128
	v_mov_b32_e32 v22, v12
	v_pk_fma_f32 v[18:19], v[18:19], v[20:21], v[22:23] neg_lo:[1,0,0] neg_hi:[1,0,0]
	v_mov_b32_e32 v128, v176
	v_pk_fma_f32 v[18:19], v[18:19], v[178:179], v[192:193] op_sel_hi:[1,0,1]
	v_lshl_add_u64 v[16:17], s[44:45], 0, v[182:183]
	v_mul_f32_e32 v8, 0xbfb8aa3b, v19
	v_exp_f32_e32 v8, v8
	v_lshlrev_b64 v[16:17], 7, v[16:17]
	v_lshl_add_u64 v[16:17], s[6:7], 0, v[16:17]
	s_mov_b64 s[44:45], -1
	v_add_f32_e32 v8, 1.0, v8
	v_rcp_f32_e32 v8, v8
	s_nop 0
	v_mul_f32_e32 v8, v19, v8
	v_mul_f32_e32 v20, v18, v8
	v_pk_mov_b32 v[18:19], v[136:137], v[176:177] op_sel:[1,0]
	v_mov_b32_e32 v8, v13
	v_pk_fma_f32 v[8:9], v[128:129], v[18:19], v[8:9] neg_lo:[1,0,0] neg_hi:[1,0,0]
	v_mov_b32_e32 v13, v176
	v_pk_fma_f32 v[8:9], v[8:9], v[178:179], v[132:133] op_sel_hi:[1,0,1]
	v_mov_b32_e32 v18, v14
	v_mul_f32_e32 v12, 0xbfb8aa3b, v9
	v_exp_f32_e32 v12, v12
	v_mov_b32_e32 v19, v10
	v_add_f32_e32 v12, 1.0, v12
	v_rcp_f32_e32 v12, v12
	s_nop 0
	v_mul_f32_e32 v9, v9, v12
	v_mul_f32_e32 v21, v8, v9
	v_mov_b32_e32 v8, v176
	v_mov_b32_e32 v9, v130
	v_mov_b32_e32 v12, v138
	v_pk_fma_f32 v[8:9], v[8:9], v[12:13], v[18:19] neg_lo:[1,0,0] neg_hi:[1,0,0]
	v_mov_b32_e32 v130, v176
	v_pk_fma_f32 v[8:9], v[8:9], v[178:179], v[140:141] op_sel_hi:[1,0,1]
	s_nop 0
	v_mul_f32_e32 v10, 0xbfb8aa3b, v9
	v_exp_f32_e32 v10, v10
	s_nop 0
	v_add_f32_e32 v10, 1.0, v10
	v_rcp_f32_e32 v10, v10
	s_nop 0
	v_mul_f32_e32 v9, v9, v10
	v_mul_f32_e32 v12, v8, v9
	v_pk_mov_b32 v[8:9], v[138:139], v[176:177] op_sel:[1,0]
	v_mov_b32_e32 v10, v15
	v_pk_fma_f32 v[8:9], v[130:131], v[8:9], v[10:11] neg_lo:[1,0,0] neg_hi:[1,0,0]
	s_nop 0
	v_pk_fma_f32 v[8:9], v[8:9], v[178:179], v[134:135] op_sel_hi:[1,0,1]
	s_nop 0
	v_mul_f32_e32 v10, 0xbfb8aa3b, v9
	v_exp_f32_e32 v10, v10
	s_nop 0
	v_add_f32_e32 v10, 1.0, v10
	v_rcp_f32_e32 v10, v10
	s_nop 0
	v_mul_f32_e32 v9, v9, v10
	v_mul_f32_e32 v10, v8, v9
	v_mov_b32_e32 v8, v0
	v_mov_b32_e32 v9, v4
	v_pk_fma_f32 v[8:9], v[176:177], v[142:143], v[8:9] op_sel_hi:[0,1,1] neg_lo:[1,0,0] neg_hi:[1,0,0]
	v_pk_fma_f32 v[8:9], v[178:179], v[8:9], v[144:145] op_sel_hi:[0,1,1]
	v_mul_f32_e32 v0, 0xbfb8aa3b, v9
	v_exp_f32_e32 v0, v0
	v_mov_b32_e32 v4, v1
	v_add_f32_e32 v0, 1.0, v0
	v_rcp_f32_e32 v0, v0
	s_nop 0
	v_mul_f32_e32 v0, v9, v0
	v_mul_f32_e32 v8, v8, v0
	v_pk_fma_f32 v[0:1], v[176:177], v[112:113], v[4:5] op_sel_hi:[0,1,1] neg_lo:[1,0,0] neg_hi:[1,0,0]
	v_pk_fma_f32 v[0:1], v[178:179], v[0:1], v[116:117] op_sel_hi:[0,1,1]
	v_mul_f32_e32 v4, 0xbfb8aa3b, v1
	v_exp_f32_e32 v4, v4
	s_nop 0
	v_add_f32_e32 v4, 1.0, v4
	v_rcp_f32_e32 v4, v4
	s_nop 0
	v_mul_f32_e32 v1, v1, v4
	v_mul_f32_e32 v9, v0, v1
	v_mov_b32_e32 v0, v2
	v_mov_b32_e32 v1, v6
	v_pk_fma_f32 v[0:1], v[176:177], v[120:121], v[0:1] op_sel_hi:[0,1,1] neg_lo:[1,0,0] neg_hi:[1,0,0]
	v_pk_fma_f32 v[0:1], v[178:179], v[0:1], v[124:125] op_sel_hi:[0,1,1]
	v_mul_f32_e32 v2, 0xbfb8aa3b, v1
	v_exp_f32_e32 v2, v2
	v_mov_b32_e32 v6, v3
	v_lshl_add_u64 v[4:5], v[16:17], 0, v[122:123]
	v_add_f32_e32 v2, 1.0, v2
	v_rcp_f32_e32 v2, v2
	s_nop 0
	v_mul_f32_e32 v1, v1, v2
	v_mul_f32_e32 v11, v0, v1
	v_pk_fma_f32 v[0:1], v[176:177], v[114:115], v[6:7] op_sel_hi:[0,1,1] neg_lo:[1,0,0] neg_hi:[1,0,0]
	v_pk_fma_f32 v[0:1], v[178:179], v[0:1], v[118:119] op_sel_hi:[0,1,1]
	v_mul_f32_e32 v2, 0xbfb8aa3b, v1
	v_exp_f32_e32 v2, v2
	s_nop 0
	v_add_f32_e32 v2, 1.0, v2
	v_rcp_f32_e32 v2, v2
	s_nop 0
	v_mul_f32_e32 v1, v1, v2
	v_mul_f32_e32 v3, v0, v1
	v_cvt_pk_bf16_f32 v0, v20, v21
	v_cvt_pk_bf16_f32 v1, v12, v10
	v_cvt_pk_bf16_f32 v2, v8, v9
	v_cvt_pk_bf16_f32 v3, v11, v3
	global_store_dwordx4 v[4:5], v[0:3], off
	s_cbranch_vccnz .LBB0_1252
	s_andn2_b64 vcc, exec, s[4:5]
	s_cbranch_vccnz .LBB0_1251
	s_barrier
	s_branch .LBB0_1251

; __device__ __forceinline__ void load_row_stats(const float* sp, int row0, RowStats& r) {
; #pragma unroll
;     for (int ai = 0; ai < 2; ++ai) { asm volatile("" ::: "memory");
; #pragma unroll
;         for (int m = 0; m < 4; ++m) { const float* p = sp + (size_t)(row0 + ai * HALF + m * 16) * 8; const f32x4 a = *(const f32x4*)p, b = *(const f32x4*)(p + 4);
;             const float s1 = (a[0] + a[2]) + (b[0] + b[2]), s2 = (a[1] + a[3]) + (b[1] + b[3]); const float mu = s1 * (1.f / 1024.f); const float var = s2 * (1.f / 1024.f) - mu * mu;
;             r.mu[ai][m] = mu; r.rs[ai][m] = __builtin_amdgcn_rsqf(__builtin_fmaxf(var, 0.f) + 1e-5f); } }
;     __device__ __forceinline__ void operator()(const f32x4 (&acc)[2][2][4][2], const Unit& u, int wr, int wc, int fr_in, int fq_in) const {
;     ...
;         const int row0 = u.pm * BM + wr * 64 + fr, col0 = u.pn * BM + wc * 32 + 8 * fq;
;         float al_ = alpha, s_ = s; asm volatile("" : "+v"(al_), "+v"(s_));
;         RowStats rst;
;         if constexpr (BASE == 1) load_row_stats(sp_old, row0, rst);
;         float s1[2][4], s2[2][4];
; #pragma unroll
;         for (int ai = 0; ai < 2; ++ai)
; #pragma unroll
;             for (int m = 0; m < 4; ++m) { s1[ai][m] = 0.f; s2[ai][m] = 0.f; }
; #pragma unroll
;         for (int bj = 0; bj < 2; ++bj) { f32x4 gv[2], bv[2];
;             if constexpr (BASE == 1) {
; #pragma unroll
;                 for (int n = 0; n < 2; ++n) { gv[n] = *(const f32x4*)(lg + col0 + bj * HALF + 4 * n); bv[n] = *(const f32x4*)(lb + col0 + bj * HALF + 4 * n); } }
; #pragma unroll
;             for (int ai = 0; ai < 2; ++ai) {
;                 f32x4 pf[4][2]; u32x4 pb[4];
; #pragma unroll
;                 for (int m = 0; m < 4; ++m) { const size_t off = (size_t)(row0 + ai * HALF + m * 16) * 1024 + col0 + bj * HALF;
;                     if constexpr (BASE == 0) { pf[m][0] = *(const f32x4*)(basef + off); pf[m][1] = *(const f32x4*)(basef + off + 4); } else pb[m] = *(const u32x4*)(baseb + off); }
.LBB0_1365:
	s_lshl_b32 s11, s46, 8
	v_mov_b32_e32 v199, v175
	v_mov_b32_e32 v203, v177
	s_add_i32 s8, s11, s60
	v_mov_b32_e32 v176, 0x3fb504f3
	v_add_u32_e32 v146, s8, v199
	v_ashrrev_i32_e32 v147, 31, v146
	v_mov_b32_e32 v174, 0.5
	s_cselect_b32 s99, 1, 0
	v_readfirstlane_b32 s98, v254
	v_and_b32_e32 v128, 0xffffff00, v146
	s_nop 0
	s_cmpk_lt_u32 s98, 0x100
	s_cbranch_scc0 .Lrs3_skip
	v_add_u32_e32 v128, v128, v254
	v_mov_b32_e32 v129, 0
	v_lshlrev_b64 v[128:129], 5, v[128:129]
	v_lshl_add_u64 v[132:133], s[22:23], 0, v[128:129]
	global_load_dwordx4 v[128:131], v[132:133], off offset:16
	s_nop 0
	global_load_dwordx4 v[132:135], v[132:133], off
	s_waitcnt vmcnt(0)
	v_pk_add_f32 v[128:129], v[128:129], v[130:131]
	v_pk_add_f32 v[132:133], v[132:133], v[134:135]
	s_nop 0
	v_pk_add_f32 v[128:129], v[132:133], v[128:129]
	s_nop 0
	v_pk_mul_f32 v[128:129], v[128:129], s[34:35] op_sel_hi:[1,0]
	v_lshlrev_b32_e32 v130, 3, v254
	v_add_u32_e32 v130, 0x22400, v130
	ds_write_b64 v130, v[128:129]
.Lrs3_skip:
	s_waitcnt vmcnt(0) lgkmcnt(0)
	s_barrier
	v_and_b32_e32 v130, 0xff, v146
	v_lshlrev_b32_e32 v130, 3, v130
	v_add_u32_e32 v130, 0x22400, v130
	ds_read_b64 v[208:209], v130
	ds_read_b64 v[204:205], v130 offset:128
	ds_read_b64 v[200:201], v130 offset:256
	ds_read_b64 v[196:197], v130 offset:384
	ds_read_b64 v[192:193], v130 offset:1024
	ds_read_b64 v[188:189], v130 offset:1152
	ds_read_b64 v[184:185], v130 offset:1280
	ds_read_b64 v[180:181], v130 offset:1408
	s_cmp_lg_u32 s99, 0
	s_waitcnt lgkmcnt(0)
	v_add_u32_e32 v144, 16, v146
	v_ashrrev_i32_e32 v145, 31, v144
	v_add_u32_e32 v148, 32, v146
	v_ashrrev_i32_e32 v149, 31, v148
	v_add_u32_e32 v150, 48, v146
	v_ashrrev_i32_e32 v151, 31, v150
	v_add_u32_e32 v222, 0x80, v146
	v_ashrrev_i32_e32 v223, 31, v222
	v_add_u32_e32 v226, 0x90, v146
	v_ashrrev_i32_e32 v227, 31, v226
	v_add_u32_e32 v210, 0xa0, v146
	v_ashrrev_i32_e32 v211, 31, v210
	v_add_u32_e32 v212, 0xb0, v146
	v_ashrrev_i32_e32 v213, 31, v212
	s_lshl_b32 s8, s10, 8
	s_or_b32 s8, s8, s61
	v_lshl_add_u32 v152, v203, 3, s8
	v_ashrrev_i32_e32 v153, 31, v152
	v_lshlrev_b64 v[220:221], 1, v[152:153]
	v_lshl_add_u64 v[234:235], s[26:27], 0, v[220:221]
	v_lshlrev_b64 v[232:233], 11, v[146:147]
	v_lshl_add_u64 v[218:219], v[234:235], 0, v[232:233]
	v_lshlrev_b64 v[236:237], 11, v[144:145]
	v_lshl_add_u64 v[224:225], v[234:235], 0, v[236:237]
	v_lshlrev_b64 v[240:241], 11, v[148:149]
	v_lshl_add_u64 v[228:229], v[234:235], 0, v[240:241]
	v_lshlrev_b64 v[238:239], 11, v[150:151]
	v_lshl_add_u64 v[230:231], v[234:235], 0, v[238:239]
	s_nop 0
	v_fma_f32 v128, -v208, v208, v209
	v_max_f32_e32 v128, 0, v128
	v_add_f32_e32 v128, 0x3727c5ac, v128
	v_rsq_f32_e32 v206, v128
	s_nop 0
	v_fma_f32 v128, -v204, v204, v205
	v_max_f32_e32 v128, 0, v128
	v_add_f32_e32 v128, 0x3727c5ac, v128
	v_rsq_f32_e32 v202, v128
	s_nop 0
	v_fma_f32 v128, -v200, v200, v201
	v_max_f32_e32 v128, 0, v128
	v_add_f32_e32 v128, 0x3727c5ac, v128
	v_rsq_f32_e32 v198, v128
	s_nop 0
	v_fma_f32 v128, -v196, v196, v197
	v_max_f32_e32 v128, 0, v128
	v_add_f32_e32 v128, 0x3727c5ac, v128
	v_rsq_f32_e32 v194, v128
	s_nop 0
	v_fma_f32 v128, -v192, v192, v193
	v_max_f32_e32 v128, 0, v128
	v_add_f32_e32 v128, 0x3727c5ac, v128
	v_rsq_f32_e32 v190, v128
	s_nop 0
	v_fma_f32 v128, -v188, v188, v189
	v_max_f32_e32 v128, 0, v128
	v_add_f32_e32 v128, 0x3727c5ac, v128
	v_rsq_f32_e32 v186, v128
	s_nop 0
	v_fma_f32 v128, -v184, v184, v185
	v_max_f32_e32 v128, 0, v128
	v_add_f32_e32 v128, 0x3727c5ac, v128
	v_rsq_f32_e32 v182, v128
	s_nop 0
	v_fma_f32 v128, -v180, v180, v181
	v_max_f32_e32 v128, 0, v128
	v_add_f32_e32 v128, 0x3727c5ac, v128
	v_rsq_f32_e32 v178, v128
	v_lshlrev_b64 v[128:129], 2, v[152:153]
	v_lshl_add_u64 v[216:217], s[4:5], 0, v[128:129]
	v_lshl_add_u64 v[214:215], s[6:7], 0, v[128:129]
	global_load_dwordx4 v[128:131], v[216:217], off offset:16
	global_load_dwordx4 v[136:139], v[216:217], off
	global_load_dwordx4 v[132:135], v[214:215], off offset:16
	global_load_dwordx4 v[140:143], v[214:215], off
	global_load_dwordx4 v[152:155], v[218:219], off
	global_load_dwordx4 v[144:147], v[224:225], off
	global_load_dwordx4 v[242:245], v[228:229], off
	global_load_dwordx4 v[148:151], v[230:231], off
	s_waitcnt vmcnt(0)
; __device__ __forceinline__ unsigned cvt_pk_bf16(float lo, float hi) { unsigned r; asm("v_cvt_pk_bf16_f32 %0, %1, %2" : "=v"(r) : "v"(lo), "v"(hi)); return r; }
; __device__ __forceinline__ float bf_lo(unsigned w) { return __uint_as_float(w << 16); }
; __device__ __forceinline__ float bf_hi(unsigned w) { return __uint_as_float(w & 0xffff0000u); }
;     __device__ __forceinline__ void operator()(const f32x4 (&acc)[2][2][4][2], const Unit& u, int wr, int wc, int fr_in, int fq_in) const {
;     ...
;                 for (int m = 0; m < 4; ++m) { const size_t off = (size_t)(row0 + ai * HALF + m * 16) * 1024 + col0 + bj * HALF;
;                     if constexpr (BASE == 0) { pf[m][0] = *(const f32x4*)(basef + off); pf[m][1] = *(const f32x4*)(basef + off + 4); } else pb[m] = *(const u32x4*)(baseb + off); }
; #pragma unroll
;                 for (int m = 0; m < 4; ++m) { const size_t off = (size_t)(row0 + ai * HALF + m * 16) * 1024 + col0 + bj * HALF; f32x4 b[2];
;                     if constexpr (BASE == 0) { b[0] = pf[m][0]; b[1] = pf[m][1]; }
;                     else { const u32x4 pw = pb[m]; b[0] = (f32x4){bf_lo(pw.x), bf_hi(pw.x), bf_lo(pw.y), bf_hi(pw.y)}; b[1] = (f32x4){bf_lo(pw.z), bf_hi(pw.z), bf_lo(pw.w), bf_hi(pw.w)}; }
;                     f32x4 z[2];
; #pragma unroll
;                     for (int n = 0; n < 2; ++n) { if constexpr (BASE == 1) b[n] = (b[n] - rst.mu[ai][m]) * rst.rs[ai][m] * gv[n] + bv[n];
;                         z[n] = b[n] * al_ + acc[ai][bj][m][n] * s_; }
;                     u32x4 w; w.x = cvt_pk_bf16(z[0][0], z[0][1]); w.y = cvt_pk_bf16(z[0][2], z[0][3]); w.z = cvt_pk_bf16(z[1][0], z[1][1]); w.w = cvt_pk_bf16(z[1][2], z[1][3]);
;                     *(u32x4*)(zb + off) = w;
;                     const float r0 = bf_lo(w.x), r1 = bf_hi(w.x), r2 = bf_lo(w.y), r3 = bf_hi(w.y), r4 = bf_lo(w.z), r5 = bf_hi(w.z), r6 = bf_lo(w.w), r7 = bf_hi(w.w);
;                     s1[ai][m] += ((r0 + r1) + (r2 + r3)) + ((r4 + r5) + (r6 + r7)); s2[ai][m] += ((r0 * r0 + r1 * r1) + (r2 * r2 + r3 * r3)) + ((r4 * r4 + r5 * r5) + (r6 * r6 + r7 * r7)); }
	v_lshlrev_b32_e32 v165, 16, v152
	v_and_b32_e32 v181, 0xffff0000, v152
	v_lshlrev_b32_e32 v152, 16, v153
	v_and_b32_e32 v153, 0xffff0000, v153
	v_lshlrev_b32_e32 v185, 16, v154
	v_and_b32_e32 v189, 0xffff0000, v154
	v_lshlrev_b32_e32 v193, 16, v155
	v_and_b32_e32 v197, 0xffff0000, v155
	v_sub_f32_e32 v153, v153, v208
	v_sub_f32_e32 v152, v152, v208
	v_sub_f32_e32 v155, v181, v208
	v_sub_f32_e32 v154, v165, v208
	v_pk_mul_f32 v[154:155], v[206:207], v[154:155] op_sel_hi:[0,1]
	v_pk_mul_f32 v[152:153], v[206:207], v[152:153] op_sel_hi:[0,1]
	v_pk_fma_f32 v[152:153], v[138:139], v[152:153], v[142:143]
	v_pk_fma_f32 v[154:155], v[136:137], v[154:155], v[140:141]
	v_pk_mul_f32 v[152:153], v[176:177], v[152:153] op_sel_hi:[0,1]
	v_pk_mul_f32 v[154:155], v[176:177], v[154:155] op_sel_hi:[0,1]
	v_pk_fma_f32 v[126:127], v[126:127], v[174:175], v[152:153] op_sel_hi:[1,0,1]
	v_pk_fma_f32 v[124:125], v[124:125], v[174:175], v[154:155] op_sel_hi:[1,0,1]
	v_sub_f32_e32 v153, v197, v208
	v_sub_f32_e32 v152, v193, v208
	v_sub_f32_e32 v155, v189, v208
	v_sub_f32_e32 v154, v185, v208
	v_pk_mul_f32 v[154:155], v[206:207], v[154:155] op_sel_hi:[0,1]
	v_pk_mul_f32 v[152:153], v[206:207], v[152:153] op_sel_hi:[0,1]
	v_pk_fma_f32 v[152:153], v[130:131], v[152:153], v[134:135]
	v_pk_fma_f32 v[154:155], v[128:129], v[154:155], v[132:133]
	v_pk_mul_f32 v[152:153], v[176:177], v[152:153] op_sel_hi:[0,1]
	v_pk_mul_f32 v[154:155], v[176:177], v[154:155] op_sel_hi:[0,1]
	v_pk_fma_f32 v[152:153], v[122:123], v[174:175], v[152:153] op_sel_hi:[1,0,1]
	v_pk_fma_f32 v[122:123], v[120:121], v[174:175], v[154:155] op_sel_hi:[1,0,1]
	v_cvt_pk_bf16_f32 v120, v124, v125
	v_lshl_add_u64 v[124:125], s[26:27], 0, v[232:233]
	v_cvt_pk_bf16_f32 v121, v126, v127
	v_lshl_add_u64 v[232:233], v[124:125], 0, v[220:221]
	v_lshlrev_b32_e32 v125, 16, v144
	v_and_b32_e32 v127, 0xffff0000, v144
	v_lshlrev_b32_e32 v144, 16, v145
	v_and_b32_e32 v145, 0xffff0000, v145
	v_cvt_pk_bf16_f32 v122, v122, v123
	v_cvt_pk_bf16_f32 v123, v152, v153
	v_lshlrev_b32_e32 v153, 16, v146
	v_and_b32_e32 v155, 0xffff0000, v146
	v_lshlrev_b32_e32 v165, 16, v147
	v_and_b32_e32 v181, 0xffff0000, v147
	v_sub_f32_e32 v145, v145, v204
	v_sub_f32_e32 v144, v144, v204
	v_sub_f32_e32 v147, v127, v204
	v_sub_f32_e32 v146, v125, v204
	v_pk_mul_f32 v[146:147], v[202:203], v[146:147] op_sel_hi:[0,1]
	v_pk_mul_f32 v[144:145], v[202:203], v[144:145] op_sel_hi:[0,1]
	v_pk_fma_f32 v[144:145], v[138:139], v[144:145], v[142:143]
	v_pk_fma_f32 v[146:147], v[136:137], v[146:147], v[140:141]
	v_pk_mul_f32 v[144:145], v[176:177], v[144:145] op_sel_hi:[0,1]
	v_pk_mul_f32 v[146:147], v[176:177], v[146:147] op_sel_hi:[0,1]
	v_pk_fma_f32 v[118:119], v[118:119], v[174:175], v[144:145] op_sel_hi:[1,0,1]
	v_pk_fma_f32 v[116:117], v[116:117], v[174:175], v[146:147] op_sel_hi:[1,0,1]
	v_sub_f32_e32 v145, v181, v204
	v_sub_f32_e32 v144, v165, v204
	v_sub_f32_e32 v147, v155, v204
	v_sub_f32_e32 v146, v153, v204
	v_pk_mul_f32 v[146:147], v[202:203], v[146:147] op_sel_hi:[0,1]
	v_pk_mul_f32 v[144:145], v[202:203], v[144:145] op_sel_hi:[0,1]
	v_pk_fma_f32 v[144:145], v[130:131], v[144:145], v[134:135]
	v_pk_fma_f32 v[146:147], v[128:129], v[146:147], v[132:133]
	v_pk_mul_f32 v[144:145], v[176:177], v[144:145] op_sel_hi:[0,1]
	v_pk_mul_f32 v[146:147], v[176:177], v[146:147] op_sel_hi:[0,1]
	v_pk_fma_f32 v[144:145], v[114:115], v[174:175], v[144:145] op_sel_hi:[1,0,1]
	v_pk_fma_f32 v[114:115], v[112:113], v[174:175], v[146:147] op_sel_hi:[1,0,1]
	v_cvt_pk_bf16_f32 v113, v118, v119
	v_lshlrev_b32_e32 v125, 16, v242
	v_and_b32_e32 v127, 0xffff0000, v242
	v_lshlrev_b32_e32 v118, 16, v243
	v_and_b32_e32 v119, 0xffff0000, v243
	v_cvt_pk_bf16_f32 v114, v114, v115
	v_cvt_pk_bf16_f32 v115, v144, v145
	v_sub_f32_e32 v119, v119, v200
	v_sub_f32_e32 v118, v118, v200
	v_sub_f32_e32 v145, v127, v200
	v_sub_f32_e32 v144, v125, v200
	v_pk_mul_f32 v[144:145], v[198:199], v[144:145] op_sel_hi:[0,1]
	v_pk_mul_f32 v[118:119], v[198:199], v[118:119] op_sel_hi:[0,1]
	v_pk_fma_f32 v[118:119], v[138:139], v[118:119], v[142:143]
	v_pk_fma_f32 v[144:145], v[136:137], v[144:145], v[140:141]
	v_lshlrev_b32_e32 v146, 16, v244
	v_and_b32_e32 v147, 0xffff0000, v244
	v_lshlrev_b32_e32 v153, 16, v245
	v_and_b32_e32 v155, 0xffff0000, v245
	v_pk_mul_f32 v[144:145], v[176:177], v[144:145] op_sel_hi:[0,1]
	v_pk_mul_f32 v[118:119], v[176:177], v[118:119] op_sel_hi:[0,1]
	v_pk_fma_f32 v[110:111], v[110:111], v[174:175], v[118:119] op_sel_hi:[1,0,1]
	v_pk_fma_f32 v[108:109], v[108:109], v[174:175], v[144:145] op_sel_hi:[1,0,1]
	v_sub_f32_e32 v119, v155, v200
	v_sub_f32_e32 v118, v153, v200
	v_sub_f32_e32 v145, v147, v200
	v_sub_f32_e32 v144, v146, v200
	v_pk_mul_f32 v[144:145], v[198:199], v[144:145] op_sel_hi:[0,1]
	v_pk_mul_f32 v[118:119], v[198:199], v[118:119] op_sel_hi:[0,1]
	v_pk_fma_f32 v[118:119], v[130:131], v[118:119], v[134:135]
	v_pk_fma_f32 v[144:145], v[128:129], v[144:145], v[132:133]
	v_pk_mul_f32 v[118:119], v[176:177], v[118:119] op_sel_hi:[0,1]
	v_pk_mul_f32 v[144:145], v[176:177], v[144:145] op_sel_hi:[0,1]
	v_pk_fma_f32 v[118:119], v[106:107], v[174:175], v[118:119] op_sel_hi:[1,0,1]
	v_pk_fma_f32 v[106:107], v[104:105], v[174:175], v[144:145] op_sel_hi:[1,0,1]
	v_cvt_pk_bf16_f32 v105, v110, v111
	v_lshlrev_b32_e32 v110, 16, v149
	v_cvt_pk_bf16_f32 v106, v106, v107
	v_cvt_pk_bf16_f32 v107, v118, v119
	v_lshlrev_b32_e32 v118, 16, v148
	v_and_b32_e32 v119, 0xffff0000, v148
	v_and_b32_e32 v111, 0xffff0000, v149
	v_sub_f32_e32 v111, v111, v196
	v_sub_f32_e32 v110, v110, v196
	v_sub_f32_e32 v119, v119, v196
	v_sub_f32_e32 v118, v118, v196
; __device__ __forceinline__ unsigned cvt_pk_bf16(float lo, float hi) { unsigned r; asm("v_cvt_pk_bf16_f32 %0, %1, %2" : "=v"(r) : "v"(lo), "v"(hi)); return r; }
; __device__ __forceinline__ float bf_lo(unsigned w) { return __uint_as_float(w << 16); }
; __device__ __forceinline__ float bf_hi(unsigned w) { return __uint_as_float(w & 0xffff0000u); }
;     __device__ __forceinline__ void operator()(const f32x4 (&acc)[2][2][4][2], const Unit& u, int wr, int wc, int fr_in, int fq_in) const {
;     ...
;                 for (int m = 0; m < 4; ++m) { const size_t off = (size_t)(row0 + ai * HALF + m * 16) * 1024 + col0 + bj * HALF;
;                     if constexpr (BASE == 0) { pf[m][0] = *(const f32x4*)(basef + off); pf[m][1] = *(const f32x4*)(basef + off + 4); } else pb[m] = *(const u32x4*)(baseb + off); }
; #pragma unroll
;                 for (int m = 0; m < 4; ++m) { const size_t off = (size_t)(row0 + ai * HALF + m * 16) * 1024 + col0 + bj * HALF; f32x4 b[2];
;                     if constexpr (BASE == 0) { b[0] = pf[m][0]; b[1] = pf[m][1]; }
;                     else { const u32x4 pw = pb[m]; b[0] = (f32x4){bf_lo(pw.x), bf_hi(pw.x), bf_lo(pw.y), bf_hi(pw.y)}; b[1] = (f32x4){bf_lo(pw.z), bf_hi(pw.z), bf_lo(pw.w), bf_hi(pw.w)}; }
;                     f32x4 z[2];
; #pragma unroll
;                     for (int n = 0; n < 2; ++n) { if constexpr (BASE == 1) b[n] = (b[n] - rst.mu[ai][m]) * rst.rs[ai][m] * gv[n] + bv[n];
;                         z[n] = b[n] * al_ + acc[ai][bj][m][n] * s_; }
;                     u32x4 w; w.x = cvt_pk_bf16(z[0][0], z[0][1]); w.y = cvt_pk_bf16(z[0][2], z[0][3]); w.z = cvt_pk_bf16(z[1][0], z[1][1]); w.w = cvt_pk_bf16(z[1][2], z[1][3]);
;                     *(u32x4*)(zb + off) = w;
;                     const float r0 = bf_lo(w.x), r1 = bf_hi(w.x), r2 = bf_lo(w.y), r3 = bf_hi(w.y), r4 = bf_lo(w.z), r5 = bf_hi(w.z), r6 = bf_lo(w.w), r7 = bf_hi(w.w);
;                     s1[ai][m] += ((r0 + r1) + (r2 + r3)) + ((r4 + r5) + (r6 + r7)); s2[ai][m] += ((r0 * r0 + r1 * r1) + (r2 * r2 + r3 * r3)) + ((r4 * r4 + r5 * r5) + (r6 * r6 + r7 * r7)); }
	v_pk_mul_f32 v[118:119], v[194:195], v[118:119] op_sel_hi:[0,1]
	v_pk_mul_f32 v[110:111], v[194:195], v[110:111] op_sel_hi:[0,1]
	v_pk_fma_f32 v[110:111], v[138:139], v[110:111], v[142:143]
	v_pk_fma_f32 v[118:119], v[136:137], v[118:119], v[140:141]
	v_lshlrev_b32_e32 v125, 16, v150
	v_and_b32_e32 v127, 0xffff0000, v150
	v_lshlrev_b32_e32 v144, 16, v151
	v_and_b32_e32 v145, 0xffff0000, v151
	v_pk_mul_f32 v[118:119], v[176:177], v[118:119] op_sel_hi:[0,1]
	v_pk_mul_f32 v[110:111], v[176:177], v[110:111] op_sel_hi:[0,1]
	v_pk_fma_f32 v[102:103], v[102:103], v[174:175], v[110:111] op_sel_hi:[1,0,1]
	v_pk_fma_f32 v[100:101], v[100:101], v[174:175], v[118:119] op_sel_hi:[1,0,1]
	v_sub_f32_e32 v111, v145, v196
	v_sub_f32_e32 v110, v144, v196
	v_sub_f32_e32 v119, v127, v196
	v_sub_f32_e32 v118, v125, v196
	v_pk_mul_f32 v[118:119], v[194:195], v[118:119] op_sel_hi:[0,1]
	v_pk_mul_f32 v[110:111], v[194:195], v[110:111] op_sel_hi:[0,1]
	v_pk_fma_f32 v[110:111], v[130:131], v[110:111], v[134:135]
	v_pk_fma_f32 v[118:119], v[128:129], v[118:119], v[132:133]
	v_pk_mul_f32 v[110:111], v[176:177], v[110:111] op_sel_hi:[0,1]
	v_pk_mul_f32 v[118:119], v[176:177], v[118:119] op_sel_hi:[0,1]
	v_cvt_pk_bf16_f32 v112, v116, v117
	v_lshl_add_u64 v[116:117], s[26:27], 0, v[236:237]
	v_cvt_pk_bf16_f32 v104, v108, v109
	v_lshl_add_u64 v[108:109], s[26:27], 0, v[240:241]
	v_pk_fma_f32 v[110:111], v[98:99], v[174:175], v[110:111] op_sel_hi:[1,0,1]
	v_pk_fma_f32 v[98:99], v[96:97], v[174:175], v[118:119] op_sel_hi:[1,0,1]
	v_cvt_pk_bf16_f32 v96, v100, v101
	v_lshl_add_u64 v[100:101], s[26:27], 0, v[238:239]
	v_lshl_add_u64 v[116:117], v[116:117], 0, v[220:221]
	v_lshl_add_u64 v[108:109], v[108:109], 0, v[220:221]
	v_lshl_add_u64 v[100:101], v[100:101], 0, v[220:221]
	global_store_dwordx4 v[232:233], v[120:123], off
	global_store_dwordx4 v[116:117], v[112:115], off
	global_store_dwordx4 v[108:109], v[104:107], off
	v_cvt_pk_bf16_f32 v97, v102, v103
	v_cvt_pk_bf16_f32 v98, v98, v99
	v_cvt_pk_bf16_f32 v99, v110, v111
	global_store_dwordx4 v[100:101], v[96:99], off
	v_lshlrev_b64 v[144:145], 11, v[222:223]
	v_lshl_add_u64 v[102:103], v[234:235], 0, v[144:145]
	global_load_dwordx4 v[236:239], v[102:103], off
	v_lshlrev_b64 v[146:147], 11, v[226:227]
	v_lshl_add_u64 v[110:111], v[234:235], 0, v[146:147]
	global_load_dwordx4 v[240:243], v[110:111], off
	v_lshlrev_b64 v[150:151], 11, v[210:211]
	v_lshl_add_u64 v[148:149], v[234:235], 0, v[150:151]
	global_load_dwordx4 v[244:247], v[148:149], off
	v_lshlrev_b64 v[210:211], 11, v[212:213]
	v_lshl_add_u64 v[118:119], v[234:235], 0, v[210:211]
	global_load_dwordx4 v[248:251], v[118:119], off
	v_and_b32_e32 v154, 0xffff0000, v120
	v_lshlrev_b32_e32 v152, 16, v121
	v_and_b32_e32 v126, 0xffff0000, v122
	v_lshlrev_b32_e32 v124, 16, v123
	s_waitcnt vmcnt(0)
	v_lshlrev_b32_e32 v125, 16, v236
	v_and_b32_e32 v127, 0xffff0000, v236
	v_lshlrev_b32_e32 v153, 16, v237
	v_and_b32_e32 v155, 0xffff0000, v237
	v_sub_f32_e32 v213, v155, v192
	v_sub_f32_e32 v212, v153, v192
	v_sub_f32_e32 v223, v127, v192
	v_sub_f32_e32 v222, v125, v192
	v_pk_mul_f32 v[222:223], v[190:191], v[222:223] op_sel_hi:[0,1]
	v_pk_mul_f32 v[212:213], v[190:191], v[212:213] op_sel_hi:[0,1]
	v_pk_fma_f32 v[212:213], v[138:139], v[212:213], v[142:143]
	v_pk_fma_f32 v[222:223], v[136:137], v[222:223], v[140:141]
	v_lshlrev_b32_e32 v165, 16, v238
	v_and_b32_e32 v181, 0xffff0000, v238
	v_lshlrev_b32_e32 v185, 16, v239
	v_and_b32_e32 v189, 0xffff0000, v239
	v_pk_mul_f32 v[222:223], v[176:177], v[222:223] op_sel_hi:[0,1]
	v_pk_mul_f32 v[212:213], v[176:177], v[212:213] op_sel_hi:[0,1]
	v_pk_fma_f32 v[94:95], v[94:95], v[174:175], v[212:213] op_sel_hi:[1,0,1]
	v_pk_fma_f32 v[92:93], v[92:93], v[174:175], v[222:223] op_sel_hi:[1,0,1]
	v_sub_f32_e32 v213, v189, v192
	v_sub_f32_e32 v212, v185, v192
	v_sub_f32_e32 v223, v181, v192
	v_sub_f32_e32 v222, v165, v192
	v_pk_mul_f32 v[222:223], v[190:191], v[222:223] op_sel_hi:[0,1]
	v_pk_mul_f32 v[212:213], v[190:191], v[212:213] op_sel_hi:[0,1]
	v_pk_fma_f32 v[212:213], v[130:131], v[212:213], v[134:135]
	v_pk_fma_f32 v[222:223], v[128:129], v[222:223], v[132:133]
	v_pk_mul_f32 v[212:213], v[176:177], v[212:213] op_sel_hi:[0,1]
	v_pk_mul_f32 v[222:223], v[176:177], v[222:223] op_sel_hi:[0,1]
	v_pk_fma_f32 v[212:213], v[90:91], v[174:175], v[212:213] op_sel_hi:[1,0,1]
	v_pk_fma_f32 v[90:91], v[88:89], v[174:175], v[222:223] op_sel_hi:[1,0,1]
	v_cvt_pk_bf16_f32 v88, v92, v93
	v_lshl_add_u64 v[92:93], s[26:27], 0, v[144:145]
	v_cvt_pk_bf16_f32 v89, v94, v95
	v_lshl_add_u64 v[144:145], v[92:93], 0, v[220:221]
	v_lshlrev_b32_e32 v94, 16, v240
	v_and_b32_e32 v95, 0xffff0000, v240
	v_lshlrev_b32_e32 v92, 16, v241
	v_and_b32_e32 v93, 0xffff0000, v241
	v_sub_f32_e32 v93, v93, v188
	v_sub_f32_e32 v92, v92, v188
	v_sub_f32_e32 v95, v95, v188
	v_sub_f32_e32 v94, v94, v188
	v_pk_mul_f32 v[94:95], v[186:187], v[94:95] op_sel_hi:[0,1]
	v_pk_mul_f32 v[92:93], v[186:187], v[92:93] op_sel_hi:[0,1]
	v_pk_fma_f32 v[92:93], v[138:139], v[92:93], v[142:143]
	v_pk_fma_f32 v[94:95], v[136:137], v[94:95], v[140:141]
	v_lshlrev_b32_e32 v125, 16, v242
	v_and_b32_e32 v127, 0xffff0000, v242
	v_lshlrev_b32_e32 v153, 16, v243
	v_and_b32_e32 v155, 0xffff0000, v243
	v_pk_mul_f32 v[94:95], v[176:177], v[94:95] op_sel_hi:[0,1]
	v_pk_mul_f32 v[92:93], v[176:177], v[92:93] op_sel_hi:[0,1]
	v_pk_fma_f32 v[86:87], v[86:87], v[174:175], v[92:93] op_sel_hi:[1,0,1]
	v_pk_fma_f32 v[84:85], v[84:85], v[174:175], v[94:95] op_sel_hi:[1,0,1]
	v_sub_f32_e32 v93, v155, v188
	v_sub_f32_e32 v92, v153, v188
	v_sub_f32_e32 v95, v127, v188
	v_sub_f32_e32 v94, v125, v188
; __device__ __forceinline__ unsigned cvt_pk_bf16(float lo, float hi) { unsigned r; asm("v_cvt_pk_bf16_f32 %0, %1, %2" : "=v"(r) : "v"(lo), "v"(hi)); return r; }
; __device__ __forceinline__ float bf_lo(unsigned w) { return __uint_as_float(w << 16); }
; __device__ __forceinline__ float bf_hi(unsigned w) { return __uint_as_float(w & 0xffff0000u); }
;     __device__ __forceinline__ void operator()(const f32x4 (&acc)[2][2][4][2], const Unit& u, int wr, int wc, int fr_in, int fq_in) const {
;     ...
;                 for (int m = 0; m < 4; ++m) { const size_t off = (size_t)(row0 + ai * HALF + m * 16) * 1024 + col0 + bj * HALF;
;                     if constexpr (BASE == 0) { pf[m][0] = *(const f32x4*)(basef + off); pf[m][1] = *(const f32x4*)(basef + off + 4); } else pb[m] = *(const u32x4*)(baseb + off); }
; #pragma unroll
;                 for (int m = 0; m < 4; ++m) { const size_t off = (size_t)(row0 + ai * HALF + m * 16) * 1024 + col0 + bj * HALF; f32x4 b[2];
;                     if constexpr (BASE == 0) { b[0] = pf[m][0]; b[1] = pf[m][1]; }
;                     else { const u32x4 pw = pb[m]; b[0] = (f32x4){bf_lo(pw.x), bf_hi(pw.x), bf_lo(pw.y), bf_hi(pw.y)}; b[1] = (f32x4){bf_lo(pw.z), bf_hi(pw.z), bf_lo(pw.w), bf_hi(pw.w)}; }
;                     f32x4 z[2];
; #pragma unroll
;                     for (int n = 0; n < 2; ++n) { if constexpr (BASE == 1) b[n] = (b[n] - rst.mu[ai][m]) * rst.rs[ai][m] * gv[n] + bv[n];
;                         z[n] = b[n] * al_ + acc[ai][bj][m][n] * s_; }
;                     u32x4 w; w.x = cvt_pk_bf16(z[0][0], z[0][1]); w.y = cvt_pk_bf16(z[0][2], z[0][3]); w.z = cvt_pk_bf16(z[1][0], z[1][1]); w.w = cvt_pk_bf16(z[1][2], z[1][3]);
;                     *(u32x4*)(zb + off) = w;
;                     const float r0 = bf_lo(w.x), r1 = bf_hi(w.x), r2 = bf_lo(w.y), r3 = bf_hi(w.y), r4 = bf_lo(w.z), r5 = bf_hi(w.z), r6 = bf_lo(w.w), r7 = bf_hi(w.w);
;                     s1[ai][m] += ((r0 + r1) + (r2 + r3)) + ((r4 + r5) + (r6 + r7)); s2[ai][m] += ((r0 * r0 + r1 * r1) + (r2 * r2 + r3 * r3)) + ((r4 * r4 + r5 * r5) + (r6 * r6 + r7 * r7)); }
	v_pk_mul_f32 v[94:95], v[186:187], v[94:95] op_sel_hi:[0,1]
	v_pk_mul_f32 v[92:93], v[186:187], v[92:93] op_sel_hi:[0,1]
	v_pk_fma_f32 v[92:93], v[130:131], v[92:93], v[134:135]
	v_pk_fma_f32 v[94:95], v[128:129], v[94:95], v[132:133]
	v_pk_mul_f32 v[92:93], v[176:177], v[92:93] op_sel_hi:[0,1]
	v_pk_mul_f32 v[94:95], v[176:177], v[94:95] op_sel_hi:[0,1]
	v_pk_fma_f32 v[92:93], v[82:83], v[174:175], v[92:93] op_sel_hi:[1,0,1]
	v_pk_fma_f32 v[82:83], v[80:81], v[174:175], v[94:95] op_sel_hi:[1,0,1]
	v_cvt_pk_bf16_f32 v80, v84, v85
	v_lshl_add_u64 v[84:85], s[26:27], 0, v[146:147]
	v_cvt_pk_bf16_f32 v81, v86, v87
	v_lshl_add_u64 v[146:147], v[84:85], 0, v[220:221]
	v_lshlrev_b32_e32 v86, 16, v244
	v_and_b32_e32 v87, 0xffff0000, v244
	v_lshlrev_b32_e32 v84, 16, v245
	v_and_b32_e32 v85, 0xffff0000, v245
	v_sub_f32_e32 v85, v85, v184
	v_sub_f32_e32 v84, v84, v184
	v_sub_f32_e32 v87, v87, v184
	v_sub_f32_e32 v86, v86, v184
	v_pk_mul_f32 v[86:87], v[182:183], v[86:87] op_sel_hi:[0,1]
	v_pk_mul_f32 v[84:85], v[182:183], v[84:85] op_sel_hi:[0,1]
	v_pk_fma_f32 v[84:85], v[138:139], v[84:85], v[142:143]
	v_pk_fma_f32 v[86:87], v[136:137], v[86:87], v[140:141]
	v_cvt_pk_bf16_f32 v82, v82, v83
	v_cvt_pk_bf16_f32 v83, v92, v93
	v_lshlrev_b32_e32 v92, 16, v246
	v_and_b32_e32 v93, 0xffff0000, v246
	v_lshlrev_b32_e32 v94, 16, v247
	v_and_b32_e32 v95, 0xffff0000, v247
	v_pk_mul_f32 v[86:87], v[176:177], v[86:87] op_sel_hi:[0,1]
	v_pk_mul_f32 v[84:85], v[176:177], v[84:85] op_sel_hi:[0,1]
	v_pk_fma_f32 v[78:79], v[78:79], v[174:175], v[84:85] op_sel_hi:[1,0,1]
	v_pk_fma_f32 v[76:77], v[76:77], v[174:175], v[86:87] op_sel_hi:[1,0,1]
	v_sub_f32_e32 v85, v95, v184
	v_sub_f32_e32 v84, v94, v184
	v_sub_f32_e32 v87, v93, v184
	v_sub_f32_e32 v86, v92, v184
	v_pk_mul_f32 v[86:87], v[182:183], v[86:87] op_sel_hi:[0,1]
	v_pk_mul_f32 v[84:85], v[182:183], v[84:85] op_sel_hi:[0,1]
	v_pk_fma_f32 v[84:85], v[130:131], v[84:85], v[134:135]
	v_pk_fma_f32 v[86:87], v[128:129], v[86:87], v[132:133]
	v_pk_mul_f32 v[84:85], v[176:177], v[84:85] op_sel_hi:[0,1]
	v_pk_mul_f32 v[86:87], v[176:177], v[86:87] op_sel_hi:[0,1]
	v_pk_fma_f32 v[84:85], v[74:75], v[174:175], v[84:85] op_sel_hi:[1,0,1]
	v_pk_fma_f32 v[74:75], v[72:73], v[174:175], v[86:87] op_sel_hi:[1,0,1]
	v_cvt_pk_bf16_f32 v72, v76, v77
	v_lshl_add_u64 v[76:77], s[26:27], 0, v[150:151]
	v_cvt_pk_bf16_f32 v73, v78, v79
	v_lshl_add_u64 v[150:151], v[76:77], 0, v[220:221]
	v_lshlrev_b32_e32 v78, 16, v248
	v_and_b32_e32 v79, 0xffff0000, v248
	v_lshlrev_b32_e32 v76, 16, v249
	v_and_b32_e32 v77, 0xffff0000, v249
	v_sub_f32_e32 v77, v77, v180
	v_sub_f32_e32 v76, v76, v180
	v_sub_f32_e32 v79, v79, v180
	v_sub_f32_e32 v78, v78, v180
	v_pk_mul_f32 v[78:79], v[178:179], v[78:79] op_sel_hi:[0,1]
	v_pk_mul_f32 v[76:77], v[178:179], v[76:77] op_sel_hi:[0,1]
	v_pk_fma_f32 v[76:77], v[138:139], v[76:77], v[142:143]
	v_pk_fma_f32 v[78:79], v[136:137], v[78:79], v[140:141]
	v_cvt_pk_bf16_f32 v74, v74, v75
	v_cvt_pk_bf16_f32 v75, v84, v85
	v_lshlrev_b32_e32 v84, 16, v250
	v_and_b32_e32 v85, 0xffff0000, v250
	v_lshlrev_b32_e32 v86, 16, v251
	v_and_b32_e32 v87, 0xffff0000, v251
	v_pk_mul_f32 v[78:79], v[176:177], v[78:79] op_sel_hi:[0,1]
	v_pk_mul_f32 v[76:77], v[176:177], v[76:77] op_sel_hi:[0,1]
	v_pk_fma_f32 v[70:71], v[70:71], v[174:175], v[76:77] op_sel_hi:[1,0,1]
	v_pk_fma_f32 v[68:69], v[68:69], v[174:175], v[78:79] op_sel_hi:[1,0,1]
	v_sub_f32_e32 v77, v87, v180
	v_sub_f32_e32 v76, v86, v180
	v_sub_f32_e32 v79, v85, v180
	v_sub_f32_e32 v78, v84, v180
	v_pk_mul_f32 v[78:79], v[178:179], v[78:79] op_sel_hi:[0,1]
	v_pk_mul_f32 v[76:77], v[178:179], v[76:77] op_sel_hi:[0,1]
	v_pk_fma_f32 v[76:77], v[130:131], v[76:77], v[134:135]
	v_pk_fma_f32 v[78:79], v[128:129], v[78:79], v[132:133]
	v_pk_mul_f32 v[76:77], v[176:177], v[76:77] op_sel_hi:[0,1]
	v_pk_mul_f32 v[78:79], v[176:177], v[78:79] op_sel_hi:[0,1]
	v_pk_fma_f32 v[76:77], v[66:67], v[174:175], v[76:77] op_sel_hi:[1,0,1]
	v_pk_fma_f32 v[66:67], v[64:65], v[174:175], v[78:79] op_sel_hi:[1,0,1]
	v_cvt_pk_bf16_f32 v64, v68, v69
	v_lshl_add_u64 v[68:69], s[26:27], 0, v[210:211]
	v_lshl_add_u64 v[128:129], v[68:69], 0, v[220:221]
	v_cvt_pk_bf16_f32 v90, v90, v91
	v_cvt_pk_bf16_f32 v91, v212, v213
	global_store_dwordx4 v[144:145], v[88:91], off
	global_store_dwordx4 v[146:147], v[80:83], off
	global_store_dwordx4 v[150:151], v[72:75], off
	v_cvt_pk_bf16_f32 v65, v70, v71
	v_cvt_pk_bf16_f32 v66, v66, v67
	v_cvt_pk_bf16_f32 v67, v76, v77
	global_store_dwordx4 v[128:129], v[64:67], off
	global_load_dwordx4 v[68:71], v[216:217], off offset:528
	global_load_dwordx4 v[84:87], v[216:217], off offset:512
	global_load_dwordx4 v[76:79], v[214:215], off offset:528
	global_load_dwordx4 v[92:95], v[214:215], off offset:512
	global_load_dwordx4 v[130:133], v[218:219], off offset:256
	global_load_dwordx4 v[134:137], v[224:225], off offset:256
	global_load_dwordx4 v[138:141], v[228:229], off offset:256
	global_load_dwordx4 v[210:213], v[230:231], off offset:256
	s_waitcnt vmcnt(0)
; __device__ __forceinline__ unsigned cvt_pk_bf16(float lo, float hi) { unsigned r; asm("v_cvt_pk_bf16_f32 %0, %1, %2" : "=v"(r) : "v"(lo), "v"(hi)); return r; }
; __device__ __forceinline__ float bf_lo(unsigned w) { return __uint_as_float(w << 16); }
; __device__ __forceinline__ float bf_hi(unsigned w) { return __uint_as_float(w & 0xffff0000u); }
;     __device__ __forceinline__ void operator()(const f32x4 (&acc)[2][2][4][2], const Unit& u, int wr, int wc, int fr_in, int fq_in) const {
;     ...
;                 for (int m = 0; m < 4; ++m) { const size_t off = (size_t)(row0 + ai * HALF + m * 16) * 1024 + col0 + bj * HALF;
;                     if constexpr (BASE == 0) { pf[m][0] = *(const f32x4*)(basef + off); pf[m][1] = *(const f32x4*)(basef + off + 4); } else pb[m] = *(const u32x4*)(baseb + off); }
; #pragma unroll
;                 for (int m = 0; m < 4; ++m) { const size_t off = (size_t)(row0 + ai * HALF + m * 16) * 1024 + col0 + bj * HALF; f32x4 b[2];
;                     if constexpr (BASE == 0) { b[0] = pf[m][0]; b[1] = pf[m][1]; }
;                     else { const u32x4 pw = pb[m]; b[0] = (f32x4){bf_lo(pw.x), bf_hi(pw.x), bf_lo(pw.y), bf_hi(pw.y)}; b[1] = (f32x4){bf_lo(pw.z), bf_hi(pw.z), bf_lo(pw.w), bf_hi(pw.w)}; }
;                     f32x4 z[2];
; #pragma unroll
;                     for (int n = 0; n < 2; ++n) { if constexpr (BASE == 1) b[n] = (b[n] - rst.mu[ai][m]) * rst.rs[ai][m] * gv[n] + bv[n];
;                         z[n] = b[n] * al_ + acc[ai][bj][m][n] * s_; }
;                     u32x4 w; w.x = cvt_pk_bf16(z[0][0], z[0][1]); w.y = cvt_pk_bf16(z[0][2], z[0][3]); w.z = cvt_pk_bf16(z[1][0], z[1][1]); w.w = cvt_pk_bf16(z[1][2], z[1][3]);
;                     *(u32x4*)(zb + off) = w;
;                     const float r0 = bf_lo(w.x), r1 = bf_hi(w.x), r2 = bf_lo(w.y), r3 = bf_hi(w.y), r4 = bf_lo(w.z), r5 = bf_hi(w.z), r6 = bf_lo(w.w), r7 = bf_hi(w.w);
;                     s1[ai][m] += ((r0 + r1) + (r2 + r3)) + ((r4 + r5) + (r6 + r7)); s2[ai][m] += ((r0 * r0 + r1 * r1) + (r2 * r2 + r3 * r3)) + ((r4 * r4 + r5 * r5) + (r6 * r6 + r7 * r7)); }
	v_lshlrev_b32_e32 v125, 16, v130
	v_and_b32_e32 v127, 0xffff0000, v130
	v_lshlrev_b32_e32 v130, 16, v131
	v_and_b32_e32 v131, 0xffff0000, v131
	v_lshlrev_b32_e32 v142, 16, v132
	v_and_b32_e32 v143, 0xffff0000, v132
	v_lshlrev_b32_e32 v153, 16, v133
	v_and_b32_e32 v155, 0xffff0000, v133
	v_sub_f32_e32 v131, v131, v208
	v_sub_f32_e32 v130, v130, v208
	v_sub_f32_e32 v133, v127, v208
	v_sub_f32_e32 v132, v125, v208
	v_pk_mul_f32 v[132:133], v[206:207], v[132:133] op_sel_hi:[0,1]
	v_pk_mul_f32 v[130:131], v[206:207], v[130:131] op_sel_hi:[0,1]
	v_pk_fma_f32 v[130:131], v[86:87], v[130:131], v[94:95]
	v_pk_fma_f32 v[132:133], v[84:85], v[132:133], v[92:93]
	v_pk_mul_f32 v[130:131], v[176:177], v[130:131] op_sel_hi:[0,1]
	v_pk_mul_f32 v[132:133], v[176:177], v[132:133] op_sel_hi:[0,1]
	v_pk_fma_f32 v[62:63], v[62:63], v[174:175], v[130:131] op_sel_hi:[1,0,1]
	v_pk_fma_f32 v[60:61], v[60:61], v[174:175], v[132:133] op_sel_hi:[1,0,1]
	v_sub_f32_e32 v131, v155, v208
	v_sub_f32_e32 v130, v153, v208
	v_sub_f32_e32 v133, v143, v208
	v_sub_f32_e32 v132, v142, v208
	v_pk_mul_f32 v[132:133], v[206:207], v[132:133] op_sel_hi:[0,1]
	v_pk_mul_f32 v[130:131], v[206:207], v[130:131] op_sel_hi:[0,1]
	v_pk_fma_f32 v[130:131], v[70:71], v[130:131], v[78:79]
	v_pk_fma_f32 v[132:133], v[68:69], v[132:133], v[76:77]
	v_pk_mul_f32 v[130:131], v[176:177], v[130:131] op_sel_hi:[0,1]
	v_pk_mul_f32 v[132:133], v[176:177], v[132:133] op_sel_hi:[0,1]
	v_pk_fma_f32 v[130:131], v[58:59], v[174:175], v[130:131] op_sel_hi:[1,0,1]
	v_pk_fma_f32 v[58:59], v[56:57], v[174:175], v[132:133] op_sel_hi:[1,0,1]
	v_cvt_pk_bf16_f32 v57, v62, v63
	v_cvt_pk_bf16_f32 v56, v60, v61
	v_and_b32_e32 v125, 0xffff0000, v134
	v_cvt_pk_bf16_f32 v58, v58, v59
	v_cvt_pk_bf16_f32 v59, v130, v131
	global_store_dwordx4 v[232:233], v[56:59], off offset:256
	v_and_b32_e32 v63, 0xffff0000, v59
	v_and_b32_e32 v62, 0xffff0000, v58
	v_lshlrev_b32_e32 v61, 16, v59
	v_lshlrev_b32_e32 v60, 16, v58
	v_pk_mul_f32 v[58:59], v[62:63], v[62:63]
	v_lshlrev_b32_e32 v127, 16, v135
	v_pk_fma_f32 v[58:59], v[60:61], v[60:61], v[58:59]
	v_and_b32_e32 v130, 0xffff0000, v135
	v_pk_add_f32 v[58:59], v[58:59], v[58:59] op_sel_hi:[0,1]
	v_lshlrev_b32_e32 v58, 16, v134
	v_sub_f32_e32 v131, v130, v204
	v_sub_f32_e32 v130, v127, v204
	v_sub_f32_e32 v133, v125, v204
	v_sub_f32_e32 v132, v58, v204
	v_pk_mul_f32 v[132:133], v[202:203], v[132:133] op_sel_hi:[0,1]
	v_pk_mul_f32 v[130:131], v[202:203], v[130:131] op_sel_hi:[0,1]
	v_pk_fma_f32 v[130:131], v[86:87], v[130:131], v[94:95]
	v_pk_fma_f32 v[132:133], v[84:85], v[132:133], v[92:93]
	v_lshlrev_b32_e32 v134, 16, v136
	v_and_b32_e32 v135, 0xffff0000, v136
	v_lshlrev_b32_e32 v136, 16, v137
	v_and_b32_e32 v137, 0xffff0000, v137
	v_pk_mul_f32 v[132:133], v[176:177], v[132:133] op_sel_hi:[0,1]
	v_pk_mul_f32 v[130:131], v[176:177], v[130:131] op_sel_hi:[0,1]
	v_pk_fma_f32 v[54:55], v[54:55], v[174:175], v[130:131] op_sel_hi:[1,0,1]
	v_pk_fma_f32 v[52:53], v[52:53], v[174:175], v[132:133] op_sel_hi:[1,0,1]
	v_sub_f32_e32 v131, v137, v204
	v_sub_f32_e32 v130, v136, v204
	v_sub_f32_e32 v133, v135, v204
	v_sub_f32_e32 v132, v134, v204
	v_pk_mul_f32 v[132:133], v[202:203], v[132:133] op_sel_hi:[0,1]
	v_pk_mul_f32 v[130:131], v[202:203], v[130:131] op_sel_hi:[0,1]
	v_pk_fma_f32 v[130:131], v[70:71], v[130:131], v[78:79]
	v_pk_fma_f32 v[132:133], v[68:69], v[132:133], v[76:77]
	v_pk_mul_f32 v[130:131], v[176:177], v[130:131] op_sel_hi:[0,1]
	v_pk_mul_f32 v[132:133], v[176:177], v[132:133] op_sel_hi:[0,1]
	v_pk_fma_f32 v[130:131], v[50:51], v[174:175], v[130:131] op_sel_hi:[1,0,1]
	v_pk_fma_f32 v[50:51], v[48:49], v[174:175], v[132:133] op_sel_hi:[1,0,1]
	v_cvt_pk_bf16_f32 v48, v52, v53
	v_cvt_pk_bf16_f32 v49, v54, v55
	v_lshlrev_b32_e32 v54, 16, v138
	v_and_b32_e32 v55, 0xffff0000, v138
	v_lshlrev_b32_e32 v52, 16, v139
	v_and_b32_e32 v53, 0xffff0000, v139
	v_sub_f32_e32 v53, v53, v200
	v_sub_f32_e32 v52, v52, v200
	v_sub_f32_e32 v55, v55, v200
	v_sub_f32_e32 v54, v54, v200
	v_pk_mul_f32 v[54:55], v[198:199], v[54:55] op_sel_hi:[0,1]
	v_pk_mul_f32 v[52:53], v[198:199], v[52:53] op_sel_hi:[0,1]
	v_pk_fma_f32 v[52:53], v[86:87], v[52:53], v[94:95]
	v_pk_fma_f32 v[54:55], v[84:85], v[54:55], v[92:93]
	v_cvt_pk_bf16_f32 v50, v50, v51
	v_cvt_pk_bf16_f32 v51, v130, v131
	global_store_dwordx4 v[116:117], v[48:51], off offset:256
	v_lshlrev_b32_e32 v58, 16, v140
	v_and_b32_e32 v116, 0xffff0000, v140
	v_lshlrev_b32_e32 v117, 16, v141
	v_and_b32_e32 v125, 0xffff0000, v141
	v_pk_mul_f32 v[54:55], v[176:177], v[54:55] op_sel_hi:[0,1]
	v_pk_mul_f32 v[52:53], v[176:177], v[52:53] op_sel_hi:[0,1]
	v_pk_fma_f32 v[46:47], v[46:47], v[174:175], v[52:53] op_sel_hi:[1,0,1]
	v_pk_fma_f32 v[44:45], v[44:45], v[174:175], v[54:55] op_sel_hi:[1,0,1]
	v_sub_f32_e32 v53, v125, v200
	v_sub_f32_e32 v52, v117, v200
	v_sub_f32_e32 v55, v116, v200
	v_sub_f32_e32 v54, v58, v200
	v_pk_mul_f32 v[54:55], v[198:199], v[54:55] op_sel_hi:[0,1]
	v_pk_mul_f32 v[52:53], v[198:199], v[52:53] op_sel_hi:[0,1]
	v_pk_fma_f32 v[52:53], v[70:71], v[52:53], v[78:79]
	v_pk_fma_f32 v[54:55], v[68:69], v[54:55], v[76:77]
	v_pk_mul_f32 v[52:53], v[176:177], v[52:53] op_sel_hi:[0,1]
	v_pk_mul_f32 v[54:55], v[176:177], v[54:55] op_sel_hi:[0,1]
	v_pk_fma_f32 v[52:53], v[42:43], v[174:175], v[52:53] op_sel_hi:[1,0,1]
	v_pk_fma_f32 v[42:43], v[40:41], v[174:175], v[54:55] op_sel_hi:[1,0,1]
	v_cvt_pk_bf16_f32 v40, v44, v45
	v_cvt_pk_bf16_f32 v41, v46, v47
	v_lshlrev_b32_e32 v46, 16, v210
	v_and_b32_e32 v47, 0xffff0000, v210
	v_lshlrev_b32_e32 v44, 16, v211
	v_and_b32_e32 v45, 0xffff0000, v211
	v_sub_f32_e32 v45, v45, v196
	v_sub_f32_e32 v44, v44, v196
; __device__ __forceinline__ unsigned cvt_pk_bf16(float lo, float hi) { unsigned r; asm("v_cvt_pk_bf16_f32 %0, %1, %2" : "=v"(r) : "v"(lo), "v"(hi)); return r; }
; __device__ __forceinline__ float bf_lo(unsigned w) { return __uint_as_float(w << 16); }
; __device__ __forceinline__ float bf_hi(unsigned w) { return __uint_as_float(w & 0xffff0000u); }
;     __device__ __forceinline__ void operator()(const f32x4 (&acc)[2][2][4][2], const Unit& u, int wr, int wc, int fr_in, int fq_in) const {
;     ...
;                 for (int m = 0; m < 4; ++m) { const size_t off = (size_t)(row0 + ai * HALF + m * 16) * 1024 + col0 + bj * HALF;
;                     if constexpr (BASE == 0) { pf[m][0] = *(const f32x4*)(basef + off); pf[m][1] = *(const f32x4*)(basef + off + 4); } else pb[m] = *(const u32x4*)(baseb + off); }
; #pragma unroll
;                 for (int m = 0; m < 4; ++m) { const size_t off = (size_t)(row0 + ai * HALF + m * 16) * 1024 + col0 + bj * HALF; f32x4 b[2];
;                     if constexpr (BASE == 0) { b[0] = pf[m][0]; b[1] = pf[m][1]; }
;                     else { const u32x4 pw = pb[m]; b[0] = (f32x4){bf_lo(pw.x), bf_hi(pw.x), bf_lo(pw.y), bf_hi(pw.y)}; b[1] = (f32x4){bf_lo(pw.z), bf_hi(pw.z), bf_lo(pw.w), bf_hi(pw.w)}; }
;                     f32x4 z[2];
; #pragma unroll
;                     for (int n = 0; n < 2; ++n) { if constexpr (BASE == 1) b[n] = (b[n] - rst.mu[ai][m]) * rst.rs[ai][m] * gv[n] + bv[n];
;                         z[n] = b[n] * al_ + acc[ai][bj][m][n] * s_; }
;                     u32x4 w; w.x = cvt_pk_bf16(z[0][0], z[0][1]); w.y = cvt_pk_bf16(z[0][2], z[0][3]); w.z = cvt_pk_bf16(z[1][0], z[1][1]); w.w = cvt_pk_bf16(z[1][2], z[1][3]);
;                     *(u32x4*)(zb + off) = w;
;                     const float r0 = bf_lo(w.x), r1 = bf_hi(w.x), r2 = bf_lo(w.y), r3 = bf_hi(w.y), r4 = bf_lo(w.z), r5 = bf_hi(w.z), r6 = bf_lo(w.w), r7 = bf_hi(w.w);
;                     s1[ai][m] += ((r0 + r1) + (r2 + r3)) + ((r4 + r5) + (r6 + r7)); s2[ai][m] += ((r0 * r0 + r1 * r1) + (r2 * r2 + r3 * r3)) + ((r4 * r4 + r5 * r5) + (r6 * r6 + r7 * r7)); }
	v_sub_f32_e32 v47, v47, v196
	v_sub_f32_e32 v46, v46, v196
	v_pk_mul_f32 v[46:47], v[194:195], v[46:47] op_sel_hi:[0,1]
	v_pk_mul_f32 v[44:45], v[194:195], v[44:45] op_sel_hi:[0,1]
	v_pk_fma_f32 v[44:45], v[86:87], v[44:45], v[94:95]
	v_pk_fma_f32 v[46:47], v[84:85], v[46:47], v[92:93]
	v_cvt_pk_bf16_f32 v42, v42, v43
	v_cvt_pk_bf16_f32 v43, v52, v53
	v_lshlrev_b32_e32 v52, 16, v212
	v_and_b32_e32 v53, 0xffff0000, v212
	v_lshlrev_b32_e32 v54, 16, v213
	v_and_b32_e32 v55, 0xffff0000, v213
	v_pk_mul_f32 v[46:47], v[176:177], v[46:47] op_sel_hi:[0,1]
	v_pk_mul_f32 v[44:45], v[176:177], v[44:45] op_sel_hi:[0,1]
	v_pk_fma_f32 v[38:39], v[38:39], v[174:175], v[44:45] op_sel_hi:[1,0,1]
	v_pk_fma_f32 v[36:37], v[36:37], v[174:175], v[46:47] op_sel_hi:[1,0,1]
	v_sub_f32_e32 v45, v55, v196
	v_sub_f32_e32 v44, v54, v196
	v_sub_f32_e32 v47, v53, v196
	v_sub_f32_e32 v46, v52, v196
	v_pk_mul_f32 v[46:47], v[194:195], v[46:47] op_sel_hi:[0,1]
	v_pk_mul_f32 v[44:45], v[194:195], v[44:45] op_sel_hi:[0,1]
	v_pk_fma_f32 v[44:45], v[70:71], v[44:45], v[78:79]
	v_pk_fma_f32 v[46:47], v[68:69], v[46:47], v[76:77]
	v_pk_mul_f32 v[44:45], v[176:177], v[44:45] op_sel_hi:[0,1]
	v_pk_mul_f32 v[46:47], v[176:177], v[46:47] op_sel_hi:[0,1]
	v_pk_fma_f32 v[44:45], v[34:35], v[174:175], v[44:45] op_sel_hi:[1,0,1]
	v_pk_fma_f32 v[34:35], v[32:33], v[174:175], v[46:47] op_sel_hi:[1,0,1]
	global_store_dwordx4 v[108:109], v[40:43], off offset:256
	v_cvt_pk_bf16_f32 v32, v36, v37
	v_cvt_pk_bf16_f32 v33, v38, v39
	v_cvt_pk_bf16_f32 v34, v34, v35
	v_cvt_pk_bf16_f32 v35, v44, v45
	global_store_dwordx4 v[100:101], v[32:35], off offset:256
	global_load_dwordx4 v[36:39], v[102:103], off offset:256
	global_load_dwordx4 v[44:47], v[110:111], off offset:256
	global_load_dwordx4 v[52:55], v[148:149], off offset:256
	s_nop 0
	global_load_dwordx4 v[100:103], v[118:119], off offset:256
	v_mov_b32_e32 v165, v59
	s_waitcnt vmcnt(0)
	v_lshlrev_b32_e32 v58, 16, v36
	v_and_b32_e32 v108, 0xffff0000, v36
	v_lshlrev_b32_e32 v36, 16, v37
	v_and_b32_e32 v37, 0xffff0000, v37
	v_lshlrev_b32_e32 v109, 16, v38
	v_and_b32_e32 v110, 0xffff0000, v38
	v_lshlrev_b32_e32 v111, 16, v39
	v_and_b32_e32 v116, 0xffff0000, v39
	v_sub_f32_e32 v37, v37, v192
	v_sub_f32_e32 v36, v36, v192
	v_sub_f32_e32 v39, v108, v192
	v_sub_f32_e32 v38, v58, v192
	v_pk_mul_f32 v[38:39], v[190:191], v[38:39] op_sel_hi:[0,1]
	v_pk_mul_f32 v[36:37], v[190:191], v[36:37] op_sel_hi:[0,1]
	v_pk_fma_f32 v[36:37], v[86:87], v[36:37], v[94:95]
	v_pk_fma_f32 v[38:39], v[84:85], v[38:39], v[92:93]
	v_pk_mul_f32 v[36:37], v[176:177], v[36:37] op_sel_hi:[0,1]
	v_pk_mul_f32 v[38:39], v[176:177], v[38:39] op_sel_hi:[0,1]
	v_pk_fma_f32 v[30:31], v[30:31], v[174:175], v[36:37] op_sel_hi:[1,0,1]
	v_pk_fma_f32 v[28:29], v[28:29], v[174:175], v[38:39] op_sel_hi:[1,0,1]
	v_sub_f32_e32 v37, v116, v192
	v_sub_f32_e32 v36, v111, v192
	v_sub_f32_e32 v39, v110, v192
	v_sub_f32_e32 v38, v109, v192
	v_pk_mul_f32 v[38:39], v[190:191], v[38:39] op_sel_hi:[0,1]
	v_pk_mul_f32 v[36:37], v[190:191], v[36:37] op_sel_hi:[0,1]
	v_pk_fma_f32 v[36:37], v[70:71], v[36:37], v[78:79]
	v_pk_fma_f32 v[38:39], v[68:69], v[38:39], v[76:77]
	v_pk_mul_f32 v[36:37], v[176:177], v[36:37] op_sel_hi:[0,1]
	v_pk_mul_f32 v[38:39], v[176:177], v[38:39] op_sel_hi:[0,1]
	v_pk_fma_f32 v[36:37], v[26:27], v[174:175], v[36:37] op_sel_hi:[1,0,1]
	v_pk_fma_f32 v[26:27], v[24:25], v[174:175], v[38:39] op_sel_hi:[1,0,1]
	v_cvt_pk_bf16_f32 v24, v28, v29
	v_cvt_pk_bf16_f32 v25, v30, v31
	v_lshlrev_b32_e32 v30, 16, v44
	v_and_b32_e32 v31, 0xffff0000, v44
	v_lshlrev_b32_e32 v28, 16, v45
	v_and_b32_e32 v29, 0xffff0000, v45
	v_sub_f32_e32 v29, v29, v188
	v_sub_f32_e32 v28, v28, v188
	v_sub_f32_e32 v31, v31, v188
	v_sub_f32_e32 v30, v30, v188
	v_pk_mul_f32 v[30:31], v[186:187], v[30:31] op_sel_hi:[0,1]
	v_pk_mul_f32 v[28:29], v[186:187], v[28:29] op_sel_hi:[0,1]
	v_pk_fma_f32 v[28:29], v[86:87], v[28:29], v[94:95]
	v_pk_fma_f32 v[30:31], v[84:85], v[30:31], v[92:93]
	v_cvt_pk_bf16_f32 v26, v26, v27
	v_cvt_pk_bf16_f32 v27, v36, v37
	v_lshlrev_b32_e32 v36, 16, v46
	v_and_b32_e32 v37, 0xffff0000, v46
	v_lshlrev_b32_e32 v38, 16, v47
	v_and_b32_e32 v39, 0xffff0000, v47
	v_pk_mul_f32 v[30:31], v[176:177], v[30:31] op_sel_hi:[0,1]
	v_pk_mul_f32 v[28:29], v[176:177], v[28:29] op_sel_hi:[0,1]
	v_pk_fma_f32 v[22:23], v[22:23], v[174:175], v[28:29] op_sel_hi:[1,0,1]
	v_pk_fma_f32 v[20:21], v[20:21], v[174:175], v[30:31] op_sel_hi:[1,0,1]
	v_sub_f32_e32 v29, v39, v188
	v_sub_f32_e32 v28, v38, v188
	v_sub_f32_e32 v31, v37, v188
	v_sub_f32_e32 v30, v36, v188
	v_pk_mul_f32 v[30:31], v[186:187], v[30:31] op_sel_hi:[0,1]
	v_pk_mul_f32 v[28:29], v[186:187], v[28:29] op_sel_hi:[0,1]
	v_pk_fma_f32 v[28:29], v[70:71], v[28:29], v[78:79]
	v_pk_fma_f32 v[30:31], v[68:69], v[30:31], v[76:77]
	v_pk_mul_f32 v[28:29], v[176:177], v[28:29] op_sel_hi:[0,1]
	v_pk_mul_f32 v[30:31], v[176:177], v[30:31] op_sel_hi:[0,1]
	v_pk_fma_f32 v[28:29], v[18:19], v[174:175], v[28:29] op_sel_hi:[1,0,1]
	v_pk_fma_f32 v[18:19], v[16:17], v[174:175], v[30:31] op_sel_hi:[1,0,1]
	v_cvt_pk_bf16_f32 v16, v20, v21
	v_cvt_pk_bf16_f32 v17, v22, v23
	v_lshlrev_b32_e32 v22, 16, v52
	v_and_b32_e32 v23, 0xffff0000, v52
	v_lshlrev_b32_e32 v20, 16, v53
	v_and_b32_e32 v21, 0xffff0000, v53
	v_sub_f32_e32 v21, v21, v184
	v_sub_f32_e32 v20, v20, v184
	v_sub_f32_e32 v23, v23, v184
	v_sub_f32_e32 v22, v22, v184
	v_pk_mul_f32 v[22:23], v[182:183], v[22:23] op_sel_hi:[0,1]
	v_pk_mul_f32 v[20:21], v[182:183], v[20:21] op_sel_hi:[0,1]
	v_pk_fma_f32 v[20:21], v[86:87], v[20:21], v[94:95]
	v_pk_fma_f32 v[22:23], v[84:85], v[22:23], v[92:93]
	v_cvt_pk_bf16_f32 v18, v18, v19
; __device__ __forceinline__ unsigned cvt_pk_bf16(float lo, float hi) { unsigned r; asm("v_cvt_pk_bf16_f32 %0, %1, %2" : "=v"(r) : "v"(lo), "v"(hi)); return r; }
; __device__ __forceinline__ float bf_lo(unsigned w) { return __uint_as_float(w << 16); }
; __device__ __forceinline__ float bf_hi(unsigned w) { return __uint_as_float(w & 0xffff0000u); }
; __device__ __forceinline__ void emit_row_stats(float (&s1)[2][4], float (&s2)[2][4], float* sp_new, const Unit& u, int wr, int wc, int fr, int fq, PG8_LAS unsigned char* xl) {
;     ...
;         for (int m = 0; m < 4; ++m) { float a = s1[ai][m], b = s2[ai][m]; a += __shfl_xor(a, 16); b += __shfl_xor(b, 16); a += __shfl_xor(a, 32); b += __shfl_xor(b, 32);
;             if (fq == 0) P[(ai * HALF + wr * 64 + m * 16 + fr) * 4 + wc] = (f32x2v){a, b}; }
;     __device__ __forceinline__ void operator()(const f32x4 (&acc)[2][2][4][2], const Unit& u, int wr, int wc, int fr_in, int fq_in) const {
;     ...
;                 for (int m = 0; m < 4; ++m) { const size_t off = (size_t)(row0 + ai * HALF + m * 16) * 1024 + col0 + bj * HALF; f32x4 b[2];
;                     if constexpr (BASE == 0) { b[0] = pf[m][0]; b[1] = pf[m][1]; }
;                     else { const u32x4 pw = pb[m]; b[0] = (f32x4){bf_lo(pw.x), bf_hi(pw.x), bf_lo(pw.y), bf_hi(pw.y)}; b[1] = (f32x4){bf_lo(pw.z), bf_hi(pw.z), bf_lo(pw.w), bf_hi(pw.w)}; }
;                     f32x4 z[2];
; #pragma unroll
;                     for (int n = 0; n < 2; ++n) { if constexpr (BASE == 1) b[n] = (b[n] - rst.mu[ai][m]) * rst.rs[ai][m] * gv[n] + bv[n];
;                         z[n] = b[n] * al_ + acc[ai][bj][m][n] * s_; }
;                     u32x4 w; w.x = cvt_pk_bf16(z[0][0], z[0][1]); w.y = cvt_pk_bf16(z[0][2], z[0][3]); w.z = cvt_pk_bf16(z[1][0], z[1][1]); w.w = cvt_pk_bf16(z[1][2], z[1][3]);
;                     *(u32x4*)(zb + off) = w;
;                     const float r0 = bf_lo(w.x), r1 = bf_hi(w.x), r2 = bf_lo(w.y), r3 = bf_hi(w.y), r4 = bf_lo(w.z), r5 = bf_hi(w.z), r6 = bf_lo(w.w), r7 = bf_hi(w.w);
;                     s1[ai][m] += ((r0 + r1) + (r2 + r3)) + ((r4 + r5) + (r6 + r7)); s2[ai][m] += ((r0 * r0 + r1 * r1) + (r2 * r2 + r3 * r3)) + ((r4 * r4 + r5 * r5) + (r6 * r6 + r7 * r7)); }
	v_cvt_pk_bf16_f32 v19, v28, v29
	v_lshlrev_b32_e32 v28, 16, v54
	v_and_b32_e32 v29, 0xffff0000, v54
	v_lshlrev_b32_e32 v30, 16, v55
	v_and_b32_e32 v31, 0xffff0000, v55
	v_pk_mul_f32 v[22:23], v[176:177], v[22:23] op_sel_hi:[0,1]
	v_pk_mul_f32 v[20:21], v[176:177], v[20:21] op_sel_hi:[0,1]
	v_pk_fma_f32 v[14:15], v[14:15], v[174:175], v[20:21] op_sel_hi:[1,0,1]
	v_pk_fma_f32 v[12:13], v[12:13], v[174:175], v[22:23] op_sel_hi:[1,0,1]
	v_sub_f32_e32 v21, v31, v184
	v_sub_f32_e32 v20, v30, v184
	v_sub_f32_e32 v23, v29, v184
	v_sub_f32_e32 v22, v28, v184
	v_pk_mul_f32 v[22:23], v[182:183], v[22:23] op_sel_hi:[0,1]
	v_pk_mul_f32 v[20:21], v[182:183], v[20:21] op_sel_hi:[0,1]
	v_pk_fma_f32 v[20:21], v[70:71], v[20:21], v[78:79]
	v_pk_fma_f32 v[22:23], v[68:69], v[22:23], v[76:77]
	v_pk_mul_f32 v[20:21], v[176:177], v[20:21] op_sel_hi:[0,1]
	v_pk_mul_f32 v[22:23], v[176:177], v[22:23] op_sel_hi:[0,1]
	v_pk_fma_f32 v[20:21], v[10:11], v[174:175], v[20:21] op_sel_hi:[1,0,1]
	v_pk_fma_f32 v[10:11], v[8:9], v[174:175], v[22:23] op_sel_hi:[1,0,1]
	v_cvt_pk_bf16_f32 v8, v12, v13
	v_cvt_pk_bf16_f32 v9, v14, v15
	v_lshlrev_b32_e32 v14, 16, v100
	v_and_b32_e32 v15, 0xffff0000, v100
	v_lshlrev_b32_e32 v12, 16, v101
	v_and_b32_e32 v13, 0xffff0000, v101
	v_sub_f32_e32 v13, v13, v180
	v_sub_f32_e32 v12, v12, v180
	v_sub_f32_e32 v15, v15, v180
	v_sub_f32_e32 v14, v14, v180
	v_pk_mul_f32 v[14:15], v[178:179], v[14:15] op_sel_hi:[0,1]
	v_pk_mul_f32 v[12:13], v[178:179], v[12:13] op_sel_hi:[0,1]
	v_pk_fma_f32 v[12:13], v[86:87], v[12:13], v[94:95]
	v_pk_fma_f32 v[14:15], v[84:85], v[14:15], v[92:93]
	v_cvt_pk_bf16_f32 v10, v10, v11
	v_cvt_pk_bf16_f32 v11, v20, v21
	v_lshlrev_b32_e32 v20, 16, v102
	v_and_b32_e32 v21, 0xffff0000, v102
	v_lshlrev_b32_e32 v22, 16, v103
	v_and_b32_e32 v23, 0xffff0000, v103
	v_pk_mul_f32 v[14:15], v[176:177], v[14:15] op_sel_hi:[0,1]
	v_pk_mul_f32 v[12:13], v[176:177], v[12:13] op_sel_hi:[0,1]
	v_pk_fma_f32 v[6:7], v[6:7], v[174:175], v[12:13] op_sel_hi:[1,0,1]
	v_pk_fma_f32 v[4:5], v[4:5], v[174:175], v[14:15] op_sel_hi:[1,0,1]
	v_sub_f32_e32 v13, v23, v180
	v_sub_f32_e32 v12, v22, v180
	v_sub_f32_e32 v15, v21, v180
	v_sub_f32_e32 v14, v20, v180
	v_pk_mul_f32 v[14:15], v[178:179], v[14:15] op_sel_hi:[0,1]
	v_pk_mul_f32 v[12:13], v[178:179], v[12:13] op_sel_hi:[0,1]
	v_pk_fma_f32 v[12:13], v[70:71], v[12:13], v[78:79]
	v_pk_fma_f32 v[14:15], v[68:69], v[14:15], v[76:77]
	v_pk_mul_f32 v[12:13], v[176:177], v[12:13] op_sel_hi:[0,1]
	v_pk_mul_f32 v[14:15], v[176:177], v[14:15] op_sel_hi:[0,1]
	v_pk_fma_f32 v[12:13], v[2:3], v[174:175], v[12:13] op_sel_hi:[1,0,1]
	v_pk_fma_f32 v[2:3], v[0:1], v[174:175], v[14:15] op_sel_hi:[1,0,1]
	v_cvt_pk_bf16_f32 v0, v4, v5
	v_and_b32_e32 v5, 64, v195
	v_xor_b32_e32 v4, 16, v195
	v_add_u32_e32 v5, 64, v5
	v_cmp_lt_i32_e32 vcc, v4, v5
	v_cvt_pk_bf16_f32 v2, v2, v3
	v_cvt_pk_bf16_f32 v3, v12, v13
	v_cvt_pk_bf16_f32 v1, v6, v7
	v_and_b32_e32 v21, 0xffff0000, v56
	v_and_b32_e32 v20, 0xffff0000, v121
	v_cndmask_b32_e32 v4, v195, v4, vcc
	v_lshlrev_b32_e32 v13, 2, v4
	v_xor_b32_e32 v4, 32, v195
	v_cmp_lt_i32_e32 vcc, v4, v5
	v_lshlrev_b32_e32 v5, 16, v56
	v_mov_b32_e32 v155, v5
	v_cndmask_b32_e32 v4, v195, v4, vcc
	v_lshlrev_b32_e32 v12, 2, v4
	v_lshlrev_b32_e32 v4, 16, v120
	v_pk_mul_f32 v[6:7], v[4:5], v[4:5]
	v_pk_mul_f32 v[14:15], v[154:155], v[154:155]
	v_mov_b32_e32 v153, v21
	v_pk_mov_b32 v[54:55], v[4:5], v[6:7] op_sel:[1,0]
	v_pk_add_f32 v[4:5], v[4:5], v[154:155]
	v_pk_mul_f32 v[22:23], v[152:153], v[152:153]
	v_pk_mul_f32 v[28:29], v[20:21], v[20:21]
	v_lshlrev_b32_e32 v30, 16, v122
	v_lshlrev_b32_e32 v31, 16, v57
	v_and_b32_e32 v45, 0xffff0000, v57
	v_and_b32_e32 v44, 0xffff0000, v123
	v_pk_mov_b32 v[14:15], v[20:21], v[14:15] op_sel:[1,0]
	v_mov_b32_e32 v5, v7
	v_pk_add_f32 v[6:7], v[20:21], v[152:153]
	v_mov_b32_e32 v127, v31
	v_mov_b32_e32 v125, v45
	v_pk_add_f32 v[14:15], v[54:55], v[14:15]
	v_pk_mov_b32 v[22:23], v[30:31], v[22:23] op_sel:[1,0]
	v_pk_mov_b32 v[54:55], v[44:45], v[28:29] op_sel:[1,0]
	v_mov_b32_e32 v7, v29
	v_pk_mul_f32 v[36:37], v[30:31], v[30:31]
	v_pk_mul_f32 v[38:39], v[126:127], v[126:127]
	v_pk_mul_f32 v[46:47], v[124:125], v[124:125]
	v_pk_mul_f32 v[52:53], v[44:45], v[44:45]
	v_pk_add_f32 v[22:23], v[22:23], v[54:55]
	v_pk_add_f32 v[4:5], v[4:5], v[6:7]
	v_pk_add_f32 v[6:7], v[30:31], v[126:127]
	v_pk_add_f32 v[20:21], v[44:45], v[124:125]
	v_pk_add_f32 v[14:15], v[14:15], v[22:23]
	v_mov_b32_e32 v22, v60
	v_mov_b32_e32 v23, v36
	v_mov_b32_e32 v54, v62
	v_mov_b32_e32 v55, v38
	v_pk_mov_b32 v[38:39], v[60:61], v[46:47] op_sel:[1,0]
	v_pk_mov_b32 v[46:47], v[62:63], v[52:53] op_sel:[1,0]
	v_mov_b32_e32 v7, v37
	v_mov_b32_e32 v21, v53
	v_pk_add_f32 v[22:23], v[22:23], v[54:55]
	v_pk_add_f32 v[38:39], v[38:39], v[46:47]
	v_pk_add_f32 v[6:7], v[6:7], v[20:21]
	v_pk_add_f32 v[22:23], v[22:23], v[38:39]
	v_pk_add_f32 v[4:5], v[4:5], v[6:7]
	v_pk_add_f32 v[14:15], v[14:15], v[22:23]
	v_pk_add_f32 v[4:5], v[4:5], v[164:165]
	global_store_dwordx4 v[144:145], v[24:27], off offset:256
	v_pk_add_f32 v[4:5], v[14:15], v[4:5]
	ds_bpermute_b32 v6, v13, v4
	ds_bpermute_b32 v7, v13, v5
	global_store_dwordx4 v[146:147], v[16:19], off offset:256
	global_store_dwordx4 v[150:151], v[8:11], off offset:256
	global_store_dwordx4 v[128:129], v[0:3], off offset:256
	s_waitcnt lgkmcnt(0)
	v_pk_add_f32 v[4:5], v[4:5], v[6:7]
	ds_bpermute_b32 v6, v12, v4
	ds_bpermute_b32 v7, v12, v5
	v_cmp_eq_u32_e32 vcc, 0, v203
	v_lshl_add_u32 v14, v199, 5, s66
	s_and_saveexec_b64 s[8:9], vcc
	s_cbranch_execz .LBB0_1367
	s_waitcnt lgkmcnt(0)
	v_pk_add_f32 v[4:5], v[4:5], v[6:7]
	ds_write_b64 v14, v[4:5]

; __device__ __forceinline__ void load_row_stats(const float* sp, int row0, RowStats& r) {
; #pragma unroll
;     for (int ai = 0; ai < 2; ++ai) { asm volatile("" ::: "memory");
; #pragma unroll
;         for (int m = 0; m < 4; ++m) { const float* p = sp + (size_t)(row0 + ai * HALF + m * 16) * 8; const f32x4 a = *(const f32x4*)p, b = *(const f32x4*)(p + 4);
;             const float s1 = (a[0] + a[2]) + (b[0] + b[2]), s2 = (a[1] + a[3]) + (b[1] + b[3]); const float mu = s1 * (1.f / 1024.f); const float var = s2 * (1.f / 1024.f) - mu * mu;
;             r.mu[ai][m] = mu; r.rs[ai][m] = __builtin_amdgcn_rsqf(__builtin_fmaxf(var, 0.f) + 1e-5f); } }
;     __device__ __forceinline__ void operator()(const f32x4 (&acc)[2][2][4][2], const Unit& u, int wr, int wc, int fr_in, int fq_in) const {
;     ...
;         const int row0 = u.pm * BM + wr * 64 + fr, col0 = u.pn * BM + wc * 32 + 8 * fq;
;         RowStats rst; load_row_stats(sp, row0, rst);
; #pragma unroll
;         for (int bj = 0; bj < 2; ++bj) { f32x4 csv[2], cbv[2], gv[2], bv[2];
; #pragma unroll
;             for (int n = 0; n < 2; ++n) { csv[n] = *(const f32x4*)(cs + col0 + bj * HALF + 4 * n); cbv[n] = *(const f32x4*)(cb + col0 + bj * HALF + 4 * n); gv[n] = *(const f32x4*)(lg + col0 + bj * HALF + 4 * n); bv[n] = *(const f32x4*)(lb + col0 + bj * HALF + 4 * n); }
; #pragma unroll
;             for (int am = 0; am < (FINAL ? 8 : 4); ++am) { constexpr int GR = FINAL ? 1 : 2; const int ai = (am * GR) >> 2; u32x4 ppw[4], pzw[4];
; #pragma unroll
;                 for (int m = (am * GR) & 3; m < ((am * GR) & 3) + GR; ++m) { const size_t off = (size_t)(row0 + ai * HALF + m * 16) * 1024 + col0 + bj * HALF; ppw[m] = *(const u32x4*)(pexb + off); pzw[m] = *(const u32x4*)(zb + off); }
.LBB0_1458:
	s_lshl_b32 s10, s10, 8
	v_mov_b32_e32 v104, v187
	v_mov_b32_e32 v105, v191
	s_add_i32 s10, s10, s28
	s_andn2_b64 vcc, exec, s[38:39]
	v_add_u32_e32 v244, s10, v104
	s_lshl_b32 s10, s11, 8
	s_or_b32 s10, s10, s59
	v_ashrrev_i32_e32 v245, 31, v244
	v_lshl_add_u32 v216, v105, 3, s10
	s_cselect_b32 s99, 1, 0
	v_readfirstlane_b32 s98, v254
	v_and_b32_e32 v104, 0xffffff00, v244
	s_nop 0
	s_cmpk_lt_u32 s98, 0x100
	s_cbranch_scc0 .Lrs4_skip
	v_add_u32_e32 v104, v104, v254
	v_mov_b32_e32 v105, 0
	v_lshlrev_b64 v[104:105], 5, v[104:105]
	v_lshl_add_u64 v[108:109], s[46:47], 0, v[104:105]
	global_load_dwordx4 v[104:107], v[108:109], off offset:16
	s_nop 0
	global_load_dwordx4 v[108:111], v[108:109], off
	s_waitcnt vmcnt(0)
	v_pk_add_f32 v[104:105], v[104:105], v[106:107]
	v_pk_add_f32 v[108:109], v[108:109], v[110:111]
	s_nop 0
	v_pk_add_f32 v[104:105], v[108:109], v[104:105]
	s_nop 0
	v_pk_mul_f32 v[104:105], v[104:105], s[58:59] op_sel_hi:[1,0]
	v_lshlrev_b32_e32 v106, 3, v254
	v_add_u32_e32 v106, 0x22400, v106
	ds_write_b64 v106, v[104:105]
.Lrs4_skip:
	s_waitcnt vmcnt(0) lgkmcnt(0)
	s_barrier
	v_and_b32_e32 v106, 0xff, v244
	v_lshlrev_b32_e32 v106, 3, v106
	v_add_u32_e32 v106, 0x22400, v106
	ds_read_b64 v[212:213], v106
	ds_read_b64 v[208:209], v106 offset:128
	ds_read_b64 v[204:205], v106 offset:256
	ds_read_b64 v[200:201], v106 offset:384
	ds_read_b64 v[196:197], v106 offset:1024
	ds_read_b64 v[192:193], v106 offset:1152
	ds_read_b64 v[188:189], v106 offset:1280
	ds_read_b64 v[184:185], v106 offset:1408
	s_cmp_lg_u32 s99, 0
	s_waitcnt lgkmcnt(0)
	v_add_u32_e32 v242, 16, v244
	v_ashrrev_i32_e32 v243, 31, v242
	v_add_u32_e32 v240, 32, v244
	v_ashrrev_i32_e32 v241, 31, v240
	v_add_u32_e32 v238, 48, v244
	v_ashrrev_i32_e32 v239, 31, v238
	v_add_u32_e32 v236, 0x80, v244
	v_ashrrev_i32_e32 v237, 31, v236
	v_add_u32_e32 v234, 0x90, v244
	v_ashrrev_i32_e32 v235, 31, v234
	v_add_u32_e32 v220, 0xa0, v244
	v_ashrrev_i32_e32 v221, 31, v220
	v_add_u32_e32 v218, 0xb0, v244
	v_ashrrev_i32_e32 v219, 31, v218
	v_ashrrev_i32_e32 v217, 31, v216
	v_lshlrev_b64 v[230:231], 10, v[244:245]
	v_lshl_add_u64 v[160:161], v[230:231], 0, v[216:217]
	v_lshlrev_b64 v[160:161], 1, v[160:161]
	v_lshl_add_u64 v[162:163], s[44:45], 0, v[160:161]
	v_lshl_add_u64 v[160:161], s[40:41], 0, v[160:161]
	v_lshlrev_b64 v[232:233], 10, v[242:243]
	s_mov_b64 s[10:11], -1
	s_nop 0
	v_fma_f32 v104, -v212, v212, v213
	v_max_f32_e32 v104, 0, v104
	v_add_f32_e32 v104, 0x3727c5ac, v104
	v_rsq_f32_e32 v214, v104
	s_nop 0
	v_fma_f32 v104, -v208, v208, v209
	v_max_f32_e32 v104, 0, v104
	v_add_f32_e32 v104, 0x3727c5ac, v104
	v_rsq_f32_e32 v210, v104
	s_nop 0
	v_fma_f32 v104, -v204, v204, v205
	v_max_f32_e32 v104, 0, v104
	v_add_f32_e32 v104, 0x3727c5ac, v104
	v_rsq_f32_e32 v206, v104
	s_nop 0
	v_fma_f32 v104, -v200, v200, v201
	v_max_f32_e32 v104, 0, v104
	v_add_f32_e32 v104, 0x3727c5ac, v104
	v_rsq_f32_e32 v202, v104
	s_nop 0
	v_fma_f32 v104, -v196, v196, v197
	v_max_f32_e32 v104, 0, v104
	v_add_f32_e32 v104, 0x3727c5ac, v104
	v_rsq_f32_e32 v198, v104
	s_nop 0
	v_fma_f32 v104, -v192, v192, v193
	v_max_f32_e32 v104, 0, v104
	v_add_f32_e32 v104, 0x3727c5ac, v104
	v_rsq_f32_e32 v194, v104
	s_nop 0
	v_fma_f32 v104, -v188, v188, v189
	v_max_f32_e32 v104, 0, v104
	v_add_f32_e32 v104, 0x3727c5ac, v104
	v_rsq_f32_e32 v190, v104
	s_nop 0
	v_fma_f32 v104, -v184, v184, v185
	v_max_f32_e32 v104, 0, v104
	v_add_f32_e32 v104, 0x3727c5ac, v104
	v_rsq_f32_e32 v186, v104
	v_lshlrev_b64 v[104:105], 2, v[216:217]
	v_lshl_add_u64 v[228:229], s[48:49], 0, v[104:105]
	v_lshl_add_u64 v[226:227], s[50:51], 0, v[104:105]
	v_lshl_add_u64 v[224:225], s[4:5], 0, v[104:105]
	v_lshl_add_u64 v[222:223], s[6:7], 0, v[104:105]
	global_load_dwordx4 v[108:111], v[228:229], off offset:16
	global_load_dwordx4 v[116:119], v[228:229], off
	global_load_dwordx4 v[104:107], v[226:227], off offset:16
	global_load_dwordx4 v[112:115], v[226:227], off
	global_load_dwordx4 v[120:123], v[224:225], off offset:16
	global_load_dwordx4 v[136:139], v[224:225], off
	global_load_dwordx4 v[124:127], v[222:223], off offset:16
	global_load_dwordx4 v[140:143], v[222:223], off
	global_load_dwordx4 v[168:171], v[162:163], off
	global_load_dwordx4 v[248:251], v[160:161], off
	v_lshl_add_u64 v[160:161], v[232:233], 0, v[216:217]
	v_lshlrev_b64 v[164:165], 1, v[160:161]
	v_lshl_add_u64 v[160:161], s[44:45], 0, v[164:165]
	v_lshl_add_u64 v[164:165], s[40:41], 0, v[164:165]
	global_load_dwordx4 v[160:163], v[160:161], off
	s_waitcnt vmcnt(0)
; __device__ __forceinline__ unsigned cvt_pk_bf16(float lo, float hi) { unsigned r; asm("v_cvt_pk_bf16_f32 %0, %1, %2" : "=v"(r) : "v"(lo), "v"(hi)); return r; }
; __device__ __forceinline__ float fast_sigmoid(float v) { return __builtin_amdgcn_rcpf(1.0f + __builtin_amdgcn_exp2f(-1.4426950408889634f * v)); }
;     __device__ __forceinline__ void operator()(const f32x4 (&acc)[2][2][4][2], const Unit& u, int wr, int wc, int fr_in, int fq_in) const {
;     ...
;             for (int am = 0; am < (FINAL ? 8 : 4); ++am) { constexpr int GR = FINAL ? 1 : 2; const int ai = (am * GR) >> 2; u32x4 ppw[4], pzw[4];
; #pragma unroll
;                 for (int m = (am * GR) & 3; m < ((am * GR) & 3) + GR; ++m) { const size_t off = (size_t)(row0 + ai * HALF + m * 16) * 1024 + col0 + bj * HALF; ppw[m] = *(const u32x4*)(pexb + off); pzw[m] = *(const u32x4*)(zb + off); }
;                 asm volatile("" ::: "memory");
; #pragma unroll
;                 for (int m = (am * GR) & 3; m < ((am * GR) & 3) + GR; ++m) { const size_t off = (size_t)(row0 + ai * HALF + m * 16) * 1024 + col0 + bj * HALF; const float mu = rst.mu[ai][m], rs = rst.rs[ai][m];
;                     const u32x4 pw = ppw[m]; const u32x4 zw = pzw[m];
;                     const f32x4 x0 = ((f32x4){bf_lo(zw.x), bf_hi(zw.x), bf_lo(zw.y), bf_hi(zw.y)} - mu) * rs * gv[0] + bv[0], x1 = ((f32x4){bf_lo(zw.z), bf_hi(zw.z), bf_lo(zw.w), bf_hi(zw.w)} - mu) * rs * gv[1] + bv[1];
;                     const f32x4 a0 = ln_fix(acc[ai][bj][m][0], mu, rs, csv[0], cbv[0]), a1 = ln_fix(acc[ai][bj][m][1], mu, rs, csv[1], cbv[1]); f32x4 o0, o1;
;                     o0[0] = x0[0] + fast_sigmoid(a0[0]) * bf_lo(pw.x); o0[1] = x0[1] + fast_sigmoid(a0[1]) * bf_hi(pw.x);
;                     o0[2] = x0[2] + fast_sigmoid(a0[2]) * bf_lo(pw.y); o0[3] = x0[3] + fast_sigmoid(a0[3]) * bf_hi(pw.y);
;                     o1[0] = x1[0] + fast_sigmoid(a1[0]) * bf_lo(pw.z); o1[1] = x1[1] + fast_sigmoid(a1[1]) * bf_hi(pw.z);
;                     o1[2] = x1[2] + fast_sigmoid(a1[2]) * bf_lo(pw.w); o1[3] = x1[3] + fast_sigmoid(a1[3]) * bf_hi(pw.w);
;                     if constexpr (FINAL) { *(f32x4*)(outf + off) = o0; *(f32x4*)(outf + off + 4) = o1; }
;                     else { u32x4 w; w.x = cvt_pk_bf16(o0[0], o0[1]); w.y = cvt_pk_bf16(o0[2], o0[3]); w.z = cvt_pk_bf16(o1[0], o1[1]); w.w = cvt_pk_bf16(o1[2], o1[3]); *(u32x4*)(pexb + off) = w; } } } }
	v_pk_fma_f32 v[152:153], v[212:213], v[108:109], v[152:153] op_sel_hi:[0,1,1] neg_lo:[1,0,0] neg_hi:[1,0,0]
	global_load_dwordx4 v[164:167], v[164:165], off
	v_pk_fma_f32 v[156:157], v[212:213], v[116:117], v[156:157] op_sel_hi:[0,1,1] neg_lo:[1,0,0] neg_hi:[1,0,0]
	v_pk_fma_f32 v[158:159], v[212:213], v[118:119], v[158:159] op_sel_hi:[0,1,1] neg_lo:[1,0,0] neg_hi:[1,0,0]
	v_pk_fma_f32 v[154:155], v[212:213], v[110:111], v[154:155] op_sel_hi:[0,1,1] neg_lo:[1,0,0] neg_hi:[1,0,0]
	v_pk_fma_f32 v[148:149], v[208:209], v[116:117], v[148:149] op_sel_hi:[0,1,1] neg_lo:[1,0,0] neg_hi:[1,0,0]
	v_pk_fma_f32 v[150:151], v[208:209], v[118:119], v[150:151] op_sel_hi:[0,1,1] neg_lo:[1,0,0] neg_hi:[1,0,0]
	v_pk_fma_f32 v[132:133], v[204:205], v[116:117], v[132:133] op_sel_hi:[0,1,1] neg_lo:[1,0,0] neg_hi:[1,0,0]
	v_lshlrev_b32_e32 v211, 16, v248
	v_and_b32_e32 v215, 0xffff0000, v248
	v_lshlrev_b32_e32 v246, 16, v249
	v_and_b32_e32 v247, 0xffff0000, v249
	v_sub_f32_e32 v247, v247, v212
	v_sub_f32_e32 v246, v246, v212
	v_sub_f32_e32 v249, v215, v212
	v_sub_f32_e32 v248, v211, v212
	v_pk_mul_f32 v[248:249], v[214:215], v[248:249] op_sel_hi:[0,1]
	v_pk_mul_f32 v[246:247], v[214:215], v[246:247] op_sel_hi:[0,1]
	v_and_b32_e32 v215, 0xffff0000, v250
	v_pk_fma_f32 v[156:157], v[214:215], v[156:157], v[112:113] op_sel_hi:[0,1,1]
	v_mul_f32_e32 v157, 0xbfb8aa3b, v157
	v_exp_f32_e32 v157, v157
	v_lshlrev_b32_e32 v211, 16, v250
	v_pk_fma_f32 v[248:249], v[136:137], v[248:249], v[140:141]
	v_sub_f32_e32 v252, v211, v212
	v_add_f32_e32 v157, 1.0, v157
	v_rcp_f32_e32 v157, v157
	v_pk_fma_f32 v[158:159], v[214:215], v[158:159], v[114:115] op_sel_hi:[0,1,1]
	v_lshlrev_b32_e32 v211, 16, v168
	v_and_b32_e32 v168, 0xffff0000, v168
	v_fmac_f32_e32 v249, v157, v168
	v_mul_f32_e32 v157, 0xbfb8aa3b, v158
	v_exp_f32_e32 v157, v157
	v_pk_fma_f32 v[246:247], v[138:139], v[246:247], v[142:143]
	v_lshlrev_b32_e32 v158, 16, v169
	v_pk_fma_f32 v[152:153], v[214:215], v[152:153], v[104:105] op_sel_hi:[0,1,1]
	v_add_f32_e32 v157, 1.0, v157
	v_rcp_f32_e32 v157, v157
	v_mul_f32_e32 v152, 0xbfb8aa3b, v152
	v_exp_f32_e32 v152, v152
	v_sub_f32_e32 v253, v215, v212
	v_fma_f32 v157, v157, v158, v246
	v_mul_f32_e32 v158, 0xbfb8aa3b, v159
	v_exp_f32_e32 v158, v158
	v_add_f32_e32 v152, 1.0, v152
	v_rcp_f32_e32 v152, v152
	v_pk_mul_f32 v[252:253], v[214:215], v[252:253] op_sel_hi:[0,1]
	v_add_f32_e32 v158, 1.0, v158
	v_rcp_f32_e32 v158, v158
	v_and_b32_e32 v159, 0xffff0000, v169
	v_pk_fma_f32 v[252:253], v[120:121], v[252:253], v[124:125]
	v_pk_fma_f32 v[154:155], v[214:215], v[154:155], v[106:107] op_sel_hi:[0,1,1]
	v_fmac_f32_e32 v247, v158, v159
	v_lshlrev_b32_e32 v158, 16, v170
	v_fma_f32 v158, v152, v158, v252
	v_mul_f32_e32 v152, 0xbfb8aa3b, v153
	v_exp_f32_e32 v152, v152
	v_and_b32_e32 v153, 0xffff0000, v170
	v_lshlrev_b32_e32 v250, 16, v251
	v_and_b32_e32 v251, 0xffff0000, v251
	v_add_f32_e32 v152, 1.0, v152
	v_rcp_f32_e32 v152, v152
	v_sub_f32_e32 v251, v251, v212
	v_sub_f32_e32 v250, v250, v212
	v_pk_mul_f32 v[250:251], v[214:215], v[250:251] op_sel_hi:[0,1]
	v_fmac_f32_e32 v253, v152, v153
	v_mul_f32_e32 v152, 0xbfb8aa3b, v154
	v_exp_f32_e32 v152, v152
	v_pk_fma_f32 v[250:251], v[122:123], v[250:251], v[126:127]
	v_mul_f32_e32 v156, 0xbfb8aa3b, v156
	v_lshlrev_b32_e32 v153, 16, v171
	v_add_f32_e32 v152, 1.0, v152
	v_rcp_f32_e32 v152, v152
	v_exp_f32_e32 v156, v156
	v_pk_fma_f32 v[148:149], v[210:211], v[148:149], v[112:113] op_sel_hi:[0,1,1]
	v_mul_f32_e32 v148, 0xbfb8aa3b, v148
	v_fma_f32 v159, v152, v153, v250
	v_mul_f32_e32 v152, 0xbfb8aa3b, v155
	v_exp_f32_e32 v152, v152
	v_add_f32_e32 v156, 1.0, v156
	v_rcp_f32_e32 v156, v156
	v_exp_f32_e32 v148, v148
	v_add_f32_e32 v152, 1.0, v152
	v_rcp_f32_e32 v152, v152
	v_mul_f32_e32 v149, 0xbfb8aa3b, v149
	v_fma_f32 v156, v156, v211, v248
	v_and_b32_e32 v153, 0xffff0000, v171
	v_exp_f32_e32 v149, v149
	v_fmac_f32_e32 v251, v152, v153
	v_cvt_pk_bf16_f32 v152, v156, v249
	v_cvt_pk_bf16_f32 v153, v157, v247
	v_lshlrev_b64 v[156:157], 11, v[244:245]
	v_lshl_add_u64 v[156:157], s[44:45], 0, v[156:157]
	v_lshlrev_b64 v[168:169], 1, v[216:217]
	v_cvt_pk_bf16_f32 v154, v158, v253
	v_cvt_pk_bf16_f32 v155, v159, v251
	v_lshl_add_u64 v[156:157], v[156:157], 0, v[168:169]
	v_add_f32_e32 v148, 1.0, v148
	global_store_dwordx4 v[156:157], v[152:155], off
	v_rcp_f32_e32 v148, v148
	v_add_f32_e32 v149, 1.0, v149
	s_waitcnt vmcnt(0)
; __device__ __forceinline__ unsigned cvt_pk_bf16(float lo, float hi) { unsigned r; asm("v_cvt_pk_bf16_f32 %0, %1, %2" : "=v"(r) : "v"(lo), "v"(hi)); return r; }
; __device__ __forceinline__ float fast_sigmoid(float v) { return __builtin_amdgcn_rcpf(1.0f + __builtin_amdgcn_exp2f(-1.4426950408889634f * v)); }
;     __device__ __forceinline__ void operator()(const f32x4 (&acc)[2][2][4][2], const Unit& u, int wr, int wc, int fr_in, int fq_in) const {
;     ...
;             for (int am = 0; am < (FINAL ? 8 : 4); ++am) { constexpr int GR = FINAL ? 1 : 2; const int ai = (am * GR) >> 2; u32x4 ppw[4], pzw[4];
; #pragma unroll
;                 for (int m = (am * GR) & 3; m < ((am * GR) & 3) + GR; ++m) { const size_t off = (size_t)(row0 + ai * HALF + m * 16) * 1024 + col0 + bj * HALF; ppw[m] = *(const u32x4*)(pexb + off); pzw[m] = *(const u32x4*)(zb + off); }
;                 asm volatile("" ::: "memory");
; #pragma unroll
;                 for (int m = (am * GR) & 3; m < ((am * GR) & 3) + GR; ++m) { const size_t off = (size_t)(row0 + ai * HALF + m * 16) * 1024 + col0 + bj * HALF; const float mu = rst.mu[ai][m], rs = rst.rs[ai][m];
;                     const u32x4 pw = ppw[m]; const u32x4 zw = pzw[m];
;                     const f32x4 x0 = ((f32x4){bf_lo(zw.x), bf_hi(zw.x), bf_lo(zw.y), bf_hi(zw.y)} - mu) * rs * gv[0] + bv[0], x1 = ((f32x4){bf_lo(zw.z), bf_hi(zw.z), bf_lo(zw.w), bf_hi(zw.w)} - mu) * rs * gv[1] + bv[1];
;                     const f32x4 a0 = ln_fix(acc[ai][bj][m][0], mu, rs, csv[0], cbv[0]), a1 = ln_fix(acc[ai][bj][m][1], mu, rs, csv[1], cbv[1]); f32x4 o0, o1;
;                     o0[0] = x0[0] + fast_sigmoid(a0[0]) * bf_lo(pw.x); o0[1] = x0[1] + fast_sigmoid(a0[1]) * bf_hi(pw.x);
;                     o0[2] = x0[2] + fast_sigmoid(a0[2]) * bf_lo(pw.y); o0[3] = x0[3] + fast_sigmoid(a0[3]) * bf_hi(pw.y);
;                     o1[0] = x1[0] + fast_sigmoid(a1[0]) * bf_lo(pw.z); o1[1] = x1[1] + fast_sigmoid(a1[1]) * bf_hi(pw.z);
;                     o1[2] = x1[2] + fast_sigmoid(a1[2]) * bf_lo(pw.w); o1[3] = x1[3] + fast_sigmoid(a1[3]) * bf_hi(pw.w);
;                     if constexpr (FINAL) { *(f32x4*)(outf + off) = o0; *(f32x4*)(outf + off + 4) = o1; }
;                     else { u32x4 w; w.x = cvt_pk_bf16(o0[0], o0[1]); w.y = cvt_pk_bf16(o0[2], o0[3]); w.z = cvt_pk_bf16(o1[0], o1[1]); w.w = cvt_pk_bf16(o1[2], o1[3]); *(u32x4*)(pexb + off) = w; } } } }
	v_lshlrev_b32_e32 v154, 16, v164
	v_and_b32_e32 v155, 0xffff0000, v164
	v_sub_f32_e32 v155, v155, v208
	v_sub_f32_e32 v154, v154, v208
	v_rcp_f32_e32 v149, v149
	v_lshlrev_b32_e32 v152, 16, v165
	v_and_b32_e32 v153, 0xffff0000, v165
	v_pk_mul_f32 v[154:155], v[210:211], v[154:155] op_sel_hi:[0,1]
	v_lshlrev_b32_e32 v164, 16, v166
	v_and_b32_e32 v165, 0xffff0000, v166
	v_lshlrev_b32_e32 v158, 16, v167
	v_and_b32_e32 v159, 0xffff0000, v167
	v_pk_fma_f32 v[166:167], v[208:209], v[108:109], v[144:145] op_sel_hi:[0,1,1] neg_lo:[1,0,0] neg_hi:[1,0,0]
	v_pk_fma_f32 v[154:155], v[136:137], v[154:155], v[140:141]
	v_pk_fma_f32 v[144:145], v[208:209], v[110:111], v[146:147] op_sel_hi:[0,1,1] neg_lo:[1,0,0] neg_hi:[1,0,0]
	v_pk_fma_f32 v[146:147], v[210:211], v[166:167], v[104:105] op_sel_hi:[0,1,1]
	v_lshlrev_b32_e32 v166, 16, v160
	v_pk_fma_f32 v[150:151], v[210:211], v[150:151], v[114:115] op_sel_hi:[0,1,1]
	v_fma_f32 v148, v148, v166, v154
	v_and_b32_e32 v154, 0xffff0000, v160
	v_fmac_f32_e32 v155, v149, v154
	v_mul_f32_e32 v149, 0xbfb8aa3b, v150
	v_exp_f32_e32 v149, v149
	v_sub_f32_e32 v153, v153, v208
	v_sub_f32_e32 v152, v152, v208
	v_pk_mul_f32 v[152:153], v[210:211], v[152:153] op_sel_hi:[0,1]
	v_add_f32_e32 v149, 1.0, v149
	v_rcp_f32_e32 v149, v149
	v_pk_fma_f32 v[152:153], v[138:139], v[152:153], v[142:143]
	v_lshlrev_b32_e32 v150, 16, v161
	v_mul_f32_e32 v146, 0xbfb8aa3b, v146
	v_fma_f32 v149, v149, v150, v152
	v_mul_f32_e32 v150, 0xbfb8aa3b, v151
	v_exp_f32_e32 v150, v150
	v_pk_fma_f32 v[144:145], v[210:211], v[144:145], v[106:107] op_sel_hi:[0,1,1]
	v_exp_f32_e32 v146, v146
	v_mul_f32_e32 v147, 0xbfb8aa3b, v147
	v_exp_f32_e32 v147, v147
	v_mul_f32_e32 v144, 0xbfb8aa3b, v144
	v_exp_f32_e32 v144, v144
	v_add_f32_e32 v150, 1.0, v150
	v_rcp_f32_e32 v150, v150
	v_add_f32_e32 v146, 1.0, v146
	v_rcp_f32_e32 v146, v146
	v_add_f32_e32 v147, 1.0, v147
	v_sub_f32_e32 v165, v165, v208
	v_sub_f32_e32 v164, v164, v208
	v_rcp_f32_e32 v147, v147
	v_add_f32_e32 v144, 1.0, v144
	v_pk_mul_f32 v[164:165], v[210:211], v[164:165] op_sel_hi:[0,1]
	v_and_b32_e32 v151, 0xffff0000, v161
	v_rcp_f32_e32 v144, v144
	v_sub_f32_e32 v159, v159, v208
	v_sub_f32_e32 v158, v158, v208
	v_pk_fma_f32 v[164:165], v[120:121], v[164:165], v[124:125]
	v_fmac_f32_e32 v153, v150, v151
	v_lshlrev_b32_e32 v150, 16, v162
	v_pk_mul_f32 v[158:159], v[210:211], v[158:159] op_sel_hi:[0,1]
	v_fma_f32 v146, v146, v150, v164
	v_and_b32_e32 v150, 0xffff0000, v162
	v_pk_fma_f32 v[158:159], v[122:123], v[158:159], v[126:127]
	v_fmac_f32_e32 v165, v147, v150
	v_lshlrev_b32_e32 v147, 16, v163
	v_fma_f32 v147, v144, v147, v158
	v_mul_f32_e32 v144, 0xbfb8aa3b, v145
	v_exp_f32_e32 v144, v144
	v_and_b32_e32 v145, 0xffff0000, v163
	v_lshlrev_b64 v[160:161], 10, v[240:241]
	v_cvt_pk_bf16_f32 v146, v146, v165
	v_add_f32_e32 v144, 1.0, v144
	v_rcp_f32_e32 v144, v144
	v_lshlrev_b64 v[162:163], 10, v[238:239]
	v_pk_fma_f32 v[132:133], v[206:207], v[132:133], v[112:113] op_sel_hi:[0,1,1]
	v_mul_f32_e32 v133, 0xbfb8aa3b, v133
	v_fmac_f32_e32 v159, v144, v145
	v_cvt_pk_bf16_f32 v144, v148, v155
	v_cvt_pk_bf16_f32 v145, v149, v153
	v_lshlrev_b64 v[148:149], 11, v[242:243]
	v_lshl_add_u64 v[148:149], s[44:45], 0, v[148:149]
	v_cvt_pk_bf16_f32 v147, v147, v159
	v_lshl_add_u64 v[158:159], v[148:149], 0, v[168:169]
	global_store_dwordx4 v[158:159], v[144:147], off
	v_exp_f32_e32 v133, v133
	v_pk_fma_f32 v[134:135], v[204:205], v[118:119], v[134:135] op_sel_hi:[0,1,1] neg_lo:[1,0,0] neg_hi:[1,0,0]
	v_lshl_add_u64 v[144:145], v[160:161], 0, v[216:217]
	v_lshlrev_b64 v[144:145], 1, v[144:145]
	v_lshl_add_u64 v[146:147], s[44:45], 0, v[144:145]
	v_lshl_add_u64 v[144:145], s[40:41], 0, v[144:145]
	global_load_dwordx4 v[152:155], v[146:147], off
	global_load_dwordx4 v[242:245], v[144:145], off
	v_lshl_add_u64 v[144:145], v[162:163], 0, v[216:217]
	v_lshlrev_b64 v[148:149], 1, v[144:145]
	v_lshl_add_u64 v[144:145], s[44:45], 0, v[148:149]
	v_lshl_add_u64 v[148:149], s[40:41], 0, v[148:149]
	global_load_dwordx4 v[144:147], v[144:145], off
	v_add_f32_e32 v133, 1.0, v133
	global_load_dwordx4 v[148:151], v[148:149], off
	v_rcp_f32_e32 v133, v133
	v_pk_fma_f32 v[134:135], v[206:207], v[134:135], v[114:115] op_sel_hi:[0,1,1]
	v_pk_fma_f32 v[128:129], v[204:205], v[108:109], v[128:129] op_sel_hi:[0,1,1] neg_lo:[1,0,0] neg_hi:[1,0,0]
	v_pk_fma_f32 v[128:129], v[206:207], v[128:129], v[104:105] op_sel_hi:[0,1,1]
	v_mul_f32_e32 v128, 0xbfb8aa3b, v128
	v_exp_f32_e32 v128, v128
	v_pk_fma_f32 v[130:131], v[204:205], v[110:111], v[130:131] op_sel_hi:[0,1,1] neg_lo:[1,0,0] neg_hi:[1,0,0]
	v_pk_fma_f32 v[130:131], v[206:207], v[130:131], v[106:107] op_sel_hi:[0,1,1]
	v_mul_f32_e32 v132, 0xbfb8aa3b, v132
	v_add_f32_e32 v128, 1.0, v128
	v_rcp_f32_e32 v128, v128
	v_exp_f32_e32 v132, v132
	v_pk_fma_f32 v[100:101], v[200:201], v[116:117], v[100:101] op_sel_hi:[0,1,1] neg_lo:[1,0,0] neg_hi:[1,0,0]
	v_pk_fma_f32 v[100:101], v[202:203], v[100:101], v[112:113] op_sel_hi:[0,1,1]
	v_mul_f32_e32 v100, 0xbfb8aa3b, v100
	v_add_f32_e32 v132, 1.0, v132
	v_rcp_f32_e32 v132, v132
	v_exp_f32_e32 v100, v100
	v_mul_f32_e32 v101, 0xbfb8aa3b, v101
	v_exp_f32_e32 v101, v101
	v_add_f32_e32 v100, 1.0, v100
	v_rcp_f32_e32 v100, v100
	v_add_f32_e32 v101, 1.0, v101
	v_rcp_f32_e32 v101, v101
	v_pk_fma_f32 v[102:103], v[200:201], v[118:119], v[102:103] op_sel_hi:[0,1,1] neg_lo:[1,0,0] neg_hi:[1,0,0]
	v_pk_fma_f32 v[102:103], v[202:203], v[102:103], v[114:115] op_sel_hi:[0,1,1]
	v_pk_fma_f32 v[96:97], v[200:201], v[108:109], v[96:97] op_sel_hi:[0,1,1] neg_lo:[1,0,0] neg_hi:[1,0,0]
	v_pk_fma_f32 v[96:97], v[202:203], v[96:97], v[104:105] op_sel_hi:[0,1,1]
; __device__ __forceinline__ unsigned cvt_pk_bf16(float lo, float hi) { unsigned r; asm("v_cvt_pk_bf16_f32 %0, %1, %2" : "=v"(r) : "v"(lo), "v"(hi)); return r; }
; __device__ __forceinline__ float fast_sigmoid(float v) { return __builtin_amdgcn_rcpf(1.0f + __builtin_amdgcn_exp2f(-1.4426950408889634f * v)); }
;     __device__ __forceinline__ void operator()(const f32x4 (&acc)[2][2][4][2], const Unit& u, int wr, int wc, int fr_in, int fq_in) const {
;     ...
;             for (int am = 0; am < (FINAL ? 8 : 4); ++am) { constexpr int GR = FINAL ? 1 : 2; const int ai = (am * GR) >> 2; u32x4 ppw[4], pzw[4];
; #pragma unroll
;                 for (int m = (am * GR) & 3; m < ((am * GR) & 3) + GR; ++m) { const size_t off = (size_t)(row0 + ai * HALF + m * 16) * 1024 + col0 + bj * HALF; ppw[m] = *(const u32x4*)(pexb + off); pzw[m] = *(const u32x4*)(zb + off); }
;                 asm volatile("" ::: "memory");
; #pragma unroll
;                 for (int m = (am * GR) & 3; m < ((am * GR) & 3) + GR; ++m) { const size_t off = (size_t)(row0 + ai * HALF + m * 16) * 1024 + col0 + bj * HALF; const float mu = rst.mu[ai][m], rs = rst.rs[ai][m];
;                     const u32x4 pw = ppw[m]; const u32x4 zw = pzw[m];
;                     const f32x4 x0 = ((f32x4){bf_lo(zw.x), bf_hi(zw.x), bf_lo(zw.y), bf_hi(zw.y)} - mu) * rs * gv[0] + bv[0], x1 = ((f32x4){bf_lo(zw.z), bf_hi(zw.z), bf_lo(zw.w), bf_hi(zw.w)} - mu) * rs * gv[1] + bv[1];
;                     const f32x4 a0 = ln_fix(acc[ai][bj][m][0], mu, rs, csv[0], cbv[0]), a1 = ln_fix(acc[ai][bj][m][1], mu, rs, csv[1], cbv[1]); f32x4 o0, o1;
;                     o0[0] = x0[0] + fast_sigmoid(a0[0]) * bf_lo(pw.x); o0[1] = x0[1] + fast_sigmoid(a0[1]) * bf_hi(pw.x);
;                     o0[2] = x0[2] + fast_sigmoid(a0[2]) * bf_lo(pw.y); o0[3] = x0[3] + fast_sigmoid(a0[3]) * bf_hi(pw.y);
;                     o1[0] = x1[0] + fast_sigmoid(a1[0]) * bf_lo(pw.z); o1[1] = x1[1] + fast_sigmoid(a1[1]) * bf_hi(pw.z);
;                     o1[2] = x1[2] + fast_sigmoid(a1[2]) * bf_lo(pw.w); o1[3] = x1[3] + fast_sigmoid(a1[3]) * bf_hi(pw.w);
;                     if constexpr (FINAL) { *(f32x4*)(outf + off) = o0; *(f32x4*)(outf + off + 4) = o1; }
;                     else { u32x4 w; w.x = cvt_pk_bf16(o0[0], o0[1]); w.y = cvt_pk_bf16(o0[2], o0[3]); w.z = cvt_pk_bf16(o1[0], o1[1]); w.w = cvt_pk_bf16(o1[2], o1[3]); *(u32x4*)(pexb + off) = w; } } } }
	v_mul_f32_e32 v96, 0xbfb8aa3b, v96
	v_exp_f32_e32 v96, v96
	v_pk_fma_f32 v[98:99], v[200:201], v[110:111], v[98:99] op_sel_hi:[0,1,1] neg_lo:[1,0,0] neg_hi:[1,0,0]
	v_pk_fma_f32 v[98:99], v[202:203], v[98:99], v[106:107] op_sel_hi:[0,1,1]
	v_pk_fma_f32 v[92:93], v[196:197], v[116:117], v[92:93] op_sel_hi:[0,1,1] neg_lo:[1,0,0] neg_hi:[1,0,0]
	v_add_f32_e32 v96, 1.0, v96
	v_rcp_f32_e32 v96, v96
	v_pk_fma_f32 v[92:93], v[92:93], v[198:199], v[112:113] op_sel_hi:[1,0,1]
	v_pk_fma_f32 v[94:95], v[196:197], v[118:119], v[94:95] op_sel_hi:[0,1,1] neg_lo:[1,0,0] neg_hi:[1,0,0]
	v_mul_f32_e32 v93, 0xbfb8aa3b, v93
	v_exp_f32_e32 v93, v93
	v_pk_fma_f32 v[94:95], v[94:95], v[198:199], v[114:115] op_sel_hi:[1,0,1]
	v_pk_fma_f32 v[88:89], v[196:197], v[108:109], v[88:89] op_sel_hi:[0,1,1] neg_lo:[1,0,0] neg_hi:[1,0,0]
	v_pk_fma_f32 v[88:89], v[198:199], v[88:89], v[104:105] op_sel_hi:[0,1,1]
	v_add_f32_e32 v93, 1.0, v93
	v_rcp_f32_e32 v93, v93
	v_mul_f32_e32 v88, 0xbfb8aa3b, v88
	v_exp_f32_e32 v88, v88
	v_pk_fma_f32 v[90:91], v[196:197], v[110:111], v[90:91] op_sel_hi:[0,1,1] neg_lo:[1,0,0] neg_hi:[1,0,0]
	v_pk_fma_f32 v[90:91], v[198:199], v[90:91], v[106:107] op_sel_hi:[0,1,1]
	v_mul_f32_e32 v92, 0xbfb8aa3b, v92
	v_add_f32_e32 v88, 1.0, v88
	v_rcp_f32_e32 v88, v88
	v_exp_f32_e32 v92, v92
	v_pk_fma_f32 v[84:85], v[116:117], v[192:193], v[84:85] op_sel_hi:[1,0,1] neg_lo:[1,0,0] neg_hi:[1,0,0]
	v_pk_fma_f32 v[80:81], v[192:193], v[108:109], v[80:81] op_sel_hi:[0,1,1] neg_lo:[1,0,0] neg_hi:[1,0,0]
	v_pk_fma_f32 v[84:85], v[84:85], v[194:195], v[112:113] op_sel_hi:[1,0,1]
	v_add_f32_e32 v92, 1.0, v92
	v_rcp_f32_e32 v92, v92
	v_mul_f32_e32 v84, 0xbfb8aa3b, v84
	v_exp_f32_e32 v84, v84
	v_mul_f32_e32 v85, 0xbfb8aa3b, v85
	v_exp_f32_e32 v85, v85
	v_pk_fma_f32 v[80:81], v[194:195], v[80:81], v[104:105] op_sel_hi:[0,1,1]
	v_add_f32_e32 v84, 1.0, v84
	v_rcp_f32_e32 v84, v84
	v_add_f32_e32 v85, 1.0, v85
	v_rcp_f32_e32 v85, v85
	v_mul_f32_e32 v80, 0xbfb8aa3b, v80
	v_exp_f32_e32 v80, v80
	v_pk_fma_f32 v[82:83], v[192:193], v[110:111], v[82:83] op_sel_hi:[0,1,1] neg_lo:[1,0,0] neg_hi:[1,0,0]
	v_pk_fma_f32 v[82:83], v[194:195], v[82:83], v[106:107] op_sel_hi:[0,1,1]
	v_pk_fma_f32 v[76:77], v[116:117], v[188:189], v[76:77] op_sel_hi:[1,0,1] neg_lo:[1,0,0] neg_hi:[1,0,0]
	s_waitcnt vmcnt(0)
	v_lshlrev_b32_e32 v166, 16, v242
	v_and_b32_e32 v167, 0xffff0000, v242
	v_sub_f32_e32 v167, v167, v204
	v_sub_f32_e32 v166, v166, v204
	v_pk_mul_f32 v[166:167], v[206:207], v[166:167] op_sel_hi:[0,1]
	v_lshlrev_b32_e32 v211, 16, v244
	v_pk_fma_f32 v[166:167], v[136:137], v[166:167], v[140:141]
	v_sub_f32_e32 v242, v211, v204
	v_lshlrev_b32_e32 v211, 16, v152
	v_and_b32_e32 v152, 0xffff0000, v152
	v_fmac_f32_e32 v167, v133, v152
	v_mul_f32_e32 v133, 0xbfb8aa3b, v134
	v_exp_f32_e32 v133, v133
	v_lshlrev_b32_e32 v164, 16, v243
	v_and_b32_e32 v165, 0xffff0000, v243
	v_sub_f32_e32 v165, v165, v204
	v_add_f32_e32 v133, 1.0, v133
	v_rcp_f32_e32 v133, v133
	v_sub_f32_e32 v164, v164, v204
	v_pk_mul_f32 v[164:165], v[206:207], v[164:165] op_sel_hi:[0,1]
	v_pk_fma_f32 v[164:165], v[138:139], v[164:165], v[142:143]
	v_lshlrev_b32_e32 v134, 16, v153
	v_fma_f32 v133, v133, v134, v164
	v_mul_f32_e32 v134, 0xbfb8aa3b, v135
	v_exp_f32_e32 v134, v134
	v_and_b32_e32 v215, 0xffff0000, v244
	v_sub_f32_e32 v243, v215, v204
	v_pk_mul_f32 v[242:243], v[206:207], v[242:243] op_sel_hi:[0,1]
	v_add_f32_e32 v134, 1.0, v134
	v_rcp_f32_e32 v134, v134
	v_and_b32_e32 v135, 0xffff0000, v153
	v_pk_fma_f32 v[242:243], v[120:121], v[242:243], v[124:125]
	v_lshlrev_b32_e32 v170, 16, v245
	v_fmac_f32_e32 v165, v134, v135
	v_lshlrev_b32_e32 v134, 16, v154
	v_fma_f32 v134, v128, v134, v242
	v_mul_f32_e32 v128, 0xbfb8aa3b, v129
	v_exp_f32_e32 v128, v128
	v_and_b32_e32 v129, 0xffff0000, v154
	v_and_b32_e32 v171, 0xffff0000, v245
	v_sub_f32_e32 v171, v171, v204
	v_add_f32_e32 v128, 1.0, v128
	v_rcp_f32_e32 v128, v128
	v_sub_f32_e32 v170, v170, v204
	v_pk_mul_f32 v[170:171], v[206:207], v[170:171] op_sel_hi:[0,1]
	v_pk_fma_f32 v[170:171], v[122:123], v[170:171], v[126:127]
	v_fmac_f32_e32 v243, v128, v129
	v_mul_f32_e32 v128, 0xbfb8aa3b, v130
	v_exp_f32_e32 v128, v128
	v_lshlrev_b32_e32 v129, 16, v155
	v_fma_f32 v132, v132, v211, v166
	v_cvt_pk_bf16_f32 v130, v134, v243
	v_add_f32_e32 v128, 1.0, v128
	v_rcp_f32_e32 v128, v128
	v_lshlrev_b32_e32 v134, 16, v151
	v_sub_f32_e32 v134, v134, v200
	v_add_f32_e32 v80, 1.0, v80
	v_fma_f32 v135, v128, v129, v170
	v_mul_f32_e32 v128, 0xbfb8aa3b, v131
	v_exp_f32_e32 v128, v128
	v_and_b32_e32 v129, 0xffff0000, v155
	v_rcp_f32_e32 v80, v80
	v_pk_fma_f32 v[76:77], v[76:77], v[190:191], v[112:113] op_sel_hi:[1,0,1]
	v_add_f32_e32 v128, 1.0, v128
	v_rcp_f32_e32 v128, v128
	v_mul_f32_e32 v77, 0xbfb8aa3b, v77
	v_exp_f32_e32 v77, v77
	v_pk_fma_f32 v[72:73], v[188:189], v[108:109], v[72:73] op_sel_hi:[0,1,1] neg_lo:[1,0,0] neg_hi:[1,0,0]
	v_fmac_f32_e32 v171, v128, v129
	v_cvt_pk_bf16_f32 v128, v132, v167
	v_cvt_pk_bf16_f32 v129, v133, v165
	v_lshlrev_b64 v[132:133], 11, v[240:241]
	v_lshl_add_u64 v[132:133], s[44:45], 0, v[132:133]
	v_cvt_pk_bf16_f32 v131, v135, v171
	v_lshl_add_u64 v[132:133], v[132:133], 0, v[168:169]
	global_store_dwordx4 v[132:133], v[128:131], off
	v_and_b32_e32 v135, 0xffff0000, v151
	v_sub_f32_e32 v135, v135, v200
	v_lshlrev_b32_e32 v130, 16, v148
	v_and_b32_e32 v131, 0xffff0000, v148
	v_sub_f32_e32 v131, v131, v200
	v_sub_f32_e32 v130, v130, v200
	v_pk_mul_f32 v[130:131], v[202:203], v[130:131] op_sel_hi:[0,1]
	v_lshlrev_b32_e32 v128, 16, v149
	v_and_b32_e32 v129, 0xffff0000, v149
	v_pk_fma_f32 v[130:131], v[136:137], v[130:131], v[140:141]
	v_lshlrev_b32_e32 v148, 16, v150
; __device__ __forceinline__ unsigned cvt_pk_bf16(float lo, float hi) { unsigned r; asm("v_cvt_pk_bf16_f32 %0, %1, %2" : "=v"(r) : "v"(lo), "v"(hi)); return r; }
; __device__ __forceinline__ float fast_sigmoid(float v) { return __builtin_amdgcn_rcpf(1.0f + __builtin_amdgcn_exp2f(-1.4426950408889634f * v)); }
;     __device__ __forceinline__ void operator()(const f32x4 (&acc)[2][2][4][2], const Unit& u, int wr, int wc, int fr_in, int fq_in) const {
;     ...
;             for (int am = 0; am < (FINAL ? 8 : 4); ++am) { constexpr int GR = FINAL ? 1 : 2; const int ai = (am * GR) >> 2; u32x4 ppw[4], pzw[4];
; #pragma unroll
;                 for (int m = (am * GR) & 3; m < ((am * GR) & 3) + GR; ++m) { const size_t off = (size_t)(row0 + ai * HALF + m * 16) * 1024 + col0 + bj * HALF; ppw[m] = *(const u32x4*)(pexb + off); pzw[m] = *(const u32x4*)(zb + off); }
;                 asm volatile("" ::: "memory");
; #pragma unroll
;                 for (int m = (am * GR) & 3; m < ((am * GR) & 3) + GR; ++m) { const size_t off = (size_t)(row0 + ai * HALF + m * 16) * 1024 + col0 + bj * HALF; const float mu = rst.mu[ai][m], rs = rst.rs[ai][m];
;                     const u32x4 pw = ppw[m]; const u32x4 zw = pzw[m];
;                     const f32x4 x0 = ((f32x4){bf_lo(zw.x), bf_hi(zw.x), bf_lo(zw.y), bf_hi(zw.y)} - mu) * rs * gv[0] + bv[0], x1 = ((f32x4){bf_lo(zw.z), bf_hi(zw.z), bf_lo(zw.w), bf_hi(zw.w)} - mu) * rs * gv[1] + bv[1];
;                     const f32x4 a0 = ln_fix(acc[ai][bj][m][0], mu, rs, csv[0], cbv[0]), a1 = ln_fix(acc[ai][bj][m][1], mu, rs, csv[1], cbv[1]); f32x4 o0, o1;
;                     o0[0] = x0[0] + fast_sigmoid(a0[0]) * bf_lo(pw.x); o0[1] = x0[1] + fast_sigmoid(a0[1]) * bf_hi(pw.x);
;                     o0[2] = x0[2] + fast_sigmoid(a0[2]) * bf_lo(pw.y); o0[3] = x0[3] + fast_sigmoid(a0[3]) * bf_hi(pw.y);
;                     o1[0] = x1[0] + fast_sigmoid(a1[0]) * bf_lo(pw.z); o1[1] = x1[1] + fast_sigmoid(a1[1]) * bf_hi(pw.z);
;                     o1[2] = x1[2] + fast_sigmoid(a1[2]) * bf_lo(pw.w); o1[3] = x1[3] + fast_sigmoid(a1[3]) * bf_hi(pw.w);
;                     if constexpr (FINAL) { *(f32x4*)(outf + off) = o0; *(f32x4*)(outf + off + 4) = o1; }
;                     else { u32x4 w; w.x = cvt_pk_bf16(o0[0], o0[1]); w.y = cvt_pk_bf16(o0[2], o0[3]); w.z = cvt_pk_bf16(o1[0], o1[1]); w.w = cvt_pk_bf16(o1[2], o1[3]); *(u32x4*)(pexb + off) = w; } } } }
	v_and_b32_e32 v149, 0xffff0000, v150
	v_lshlrev_b32_e32 v150, 16, v144
	v_fma_f32 v100, v100, v150, v130
	v_and_b32_e32 v130, 0xffff0000, v144
	v_fmac_f32_e32 v131, v101, v130
	v_mul_f32_e32 v101, 0xbfb8aa3b, v102
	v_exp_f32_e32 v101, v101
	v_sub_f32_e32 v129, v129, v200
	v_sub_f32_e32 v128, v128, v200
	v_pk_mul_f32 v[128:129], v[202:203], v[128:129] op_sel_hi:[0,1]
	v_add_f32_e32 v101, 1.0, v101
	v_rcp_f32_e32 v101, v101
	v_pk_fma_f32 v[128:129], v[138:139], v[128:129], v[142:143]
	v_lshlrev_b32_e32 v102, 16, v145
	v_sub_f32_e32 v149, v149, v200
	v_fma_f32 v101, v101, v102, v128
	v_mul_f32_e32 v102, 0xbfb8aa3b, v103
	v_exp_f32_e32 v102, v102
	v_sub_f32_e32 v148, v148, v200
	v_pk_mul_f32 v[148:149], v[202:203], v[148:149] op_sel_hi:[0,1]
	v_and_b32_e32 v103, 0xffff0000, v145
	v_add_f32_e32 v102, 1.0, v102
	v_rcp_f32_e32 v102, v102
	v_pk_fma_f32 v[148:149], v[120:121], v[148:149], v[124:125]
	v_pk_mul_f32 v[134:135], v[202:203], v[134:135] op_sel_hi:[0,1]
	v_pk_fma_f32 v[134:135], v[122:123], v[134:135], v[126:127]
	v_fmac_f32_e32 v129, v102, v103
	v_lshlrev_b32_e32 v102, 16, v146
	v_fma_f32 v102, v96, v102, v148
	v_mul_f32_e32 v96, 0xbfb8aa3b, v97
	v_exp_f32_e32 v96, v96
	v_and_b32_e32 v97, 0xffff0000, v146
	v_lshlrev_b64 v[144:145], 10, v[236:237]
	v_add_f32_e32 v77, 1.0, v77
	v_add_f32_e32 v96, 1.0, v96
	v_rcp_f32_e32 v96, v96
	v_rcp_f32_e32 v77, v77
	v_pk_fma_f32 v[72:73], v[72:73], v[190:191], v[104:105] op_sel_hi:[1,0,1]
	v_pk_fma_f32 v[74:75], v[188:189], v[110:111], v[74:75] op_sel_hi:[0,1,1] neg_lo:[1,0,0] neg_hi:[1,0,0]
	v_fmac_f32_e32 v149, v96, v97
	v_mul_f32_e32 v96, 0xbfb8aa3b, v98
	v_exp_f32_e32 v96, v96
	v_lshlrev_b32_e32 v97, 16, v147
	v_cvt_pk_bf16_f32 v98, v102, v149
	v_mul_f32_e32 v72, 0xbfb8aa3b, v72
	v_add_f32_e32 v96, 1.0, v96
	v_rcp_f32_e32 v96, v96
	v_exp_f32_e32 v72, v72
	v_pk_fma_f32 v[74:75], v[74:75], v[190:191], v[106:107] op_sel_hi:[1,0,1]
	v_mul_f32_e32 v76, 0xbfb8aa3b, v76
	v_fma_f32 v103, v96, v97, v134
	v_mul_f32_e32 v96, 0xbfb8aa3b, v99
	v_exp_f32_e32 v96, v96
	v_and_b32_e32 v97, 0xffff0000, v147
	v_lshlrev_b64 v[146:147], 10, v[234:235]
	v_add_f32_e32 v72, 1.0, v72
	v_add_f32_e32 v96, 1.0, v96
	v_rcp_f32_e32 v96, v96
	v_rcp_f32_e32 v72, v72
	v_exp_f32_e32 v76, v76
	v_pk_fma_f32 v[68:69], v[116:117], v[184:185], v[68:69] op_sel_hi:[1,0,1] neg_lo:[1,0,0] neg_hi:[1,0,0]
	v_fmac_f32_e32 v135, v96, v97
	v_cvt_pk_bf16_f32 v96, v100, v131
	v_cvt_pk_bf16_f32 v97, v101, v129
	v_lshlrev_b64 v[100:101], 11, v[238:239]
	v_lshl_add_u64 v[100:101], s[44:45], 0, v[100:101]
	v_cvt_pk_bf16_f32 v99, v103, v135
	v_lshl_add_u64 v[134:135], v[100:101], 0, v[168:169]
	global_store_dwordx4 v[134:135], v[96:99], off
	v_add_f32_e32 v76, 1.0, v76
	v_rcp_f32_e32 v76, v76
	v_lshl_add_u64 v[96:97], v[144:145], 0, v[216:217]
	v_lshlrev_b64 v[96:97], 1, v[96:97]
	v_lshl_add_u64 v[98:99], s[44:45], 0, v[96:97]
	v_lshl_add_u64 v[96:97], s[40:41], 0, v[96:97]
	global_load_dwordx4 v[100:103], v[98:99], off
	global_load_dwordx4 v[148:151], v[96:97], off
	v_lshl_add_u64 v[96:97], v[146:147], 0, v[216:217]
	v_lshlrev_b64 v[128:129], 1, v[96:97]
	v_lshl_add_u64 v[96:97], s[44:45], 0, v[128:129]
	v_lshl_add_u64 v[128:129], s[40:41], 0, v[128:129]
	global_load_dwordx4 v[96:99], v[96:97], off
	v_pk_fma_f32 v[68:69], v[68:69], v[186:187], v[112:113] op_sel_hi:[1,0,1]
	global_load_dwordx4 v[128:131], v[128:129], off
	v_mul_f32_e32 v68, 0xbfb8aa3b, v68
	v_exp_f32_e32 v68, v68
	v_mul_f32_e32 v69, 0xbfb8aa3b, v69
	v_exp_f32_e32 v69, v69
	v_pk_fma_f32 v[64:65], v[108:109], v[184:185], v[64:65] op_sel_hi:[1,0,1] neg_lo:[1,0,0] neg_hi:[1,0,0]
	v_add_f32_e32 v68, 1.0, v68
	v_rcp_f32_e32 v68, v68
	v_add_f32_e32 v69, 1.0, v69
	v_rcp_f32_e32 v69, v69
	v_pk_fma_f32 v[64:65], v[64:65], v[186:187], v[104:105] op_sel_hi:[1,0,1]
	s_waitcnt vmcnt(0)
	v_lshlrev_b32_e32 v164, 16, v100
	v_lshlrev_b32_e32 v152, 16, v148
	v_and_b32_e32 v153, 0xffff0000, v148
	v_sub_f32_e32 v153, v153, v196
	v_sub_f32_e32 v152, v152, v196
	v_pk_mul_f32 v[152:153], v[198:199], v[152:153] op_sel_hi:[0,1]
	v_pk_fma_f32 v[152:153], v[136:137], v[152:153], v[140:141]
	v_and_b32_e32 v100, 0xffff0000, v100
	v_fmac_f32_e32 v153, v93, v100
	v_mul_f32_e32 v93, 0xbfb8aa3b, v94
	v_exp_f32_e32 v93, v93
	v_lshlrev_b32_e32 v148, 16, v149
	v_and_b32_e32 v149, 0xffff0000, v149
	v_sub_f32_e32 v149, v149, v196
	v_add_f32_e32 v93, 1.0, v93
	v_rcp_f32_e32 v93, v93
	v_sub_f32_e32 v148, v148, v196
	v_pk_mul_f32 v[148:149], v[198:199], v[148:149] op_sel_hi:[0,1]
	v_pk_fma_f32 v[148:149], v[138:139], v[148:149], v[142:143]
	v_lshlrev_b32_e32 v94, 16, v101
	v_fma_f32 v93, v93, v94, v148
	v_mul_f32_e32 v94, 0xbfb8aa3b, v95
	v_exp_f32_e32 v94, v94
	v_lshlrev_b32_e32 v154, 16, v150
	v_and_b32_e32 v155, 0xffff0000, v150
	v_sub_f32_e32 v155, v155, v196
	v_add_f32_e32 v94, 1.0, v94
	v_rcp_f32_e32 v94, v94
	v_sub_f32_e32 v154, v154, v196
	v_pk_mul_f32 v[154:155], v[198:199], v[154:155] op_sel_hi:[0,1]
	v_and_b32_e32 v95, 0xffff0000, v101
	v_pk_fma_f32 v[154:155], v[120:121], v[154:155], v[124:125]
	v_fmac_f32_e32 v149, v94, v95
	v_lshlrev_b32_e32 v94, 16, v102
	v_fma_f32 v94, v88, v94, v154
	v_mul_f32_e32 v88, 0xbfb8aa3b, v89
	v_exp_f32_e32 v88, v88
	v_and_b32_e32 v89, 0xffff0000, v102
	v_lshlrev_b32_e32 v150, 16, v151
	v_and_b32_e32 v151, 0xffff0000, v151
	v_add_f32_e32 v88, 1.0, v88
	v_rcp_f32_e32 v88, v88
	v_sub_f32_e32 v151, v151, v196
	v_sub_f32_e32 v150, v150, v196
	v_pk_mul_f32 v[150:151], v[198:199], v[150:151] op_sel_hi:[0,1]
	v_fmac_f32_e32 v155, v88, v89
	v_mul_f32_e32 v88, 0xbfb8aa3b, v90
	v_exp_f32_e32 v88, v88
	v_pk_fma_f32 v[150:151], v[122:123], v[150:151], v[126:127]
	v_lshlrev_b32_e32 v89, 16, v103
; __device__ __forceinline__ unsigned cvt_pk_bf16(float lo, float hi) { unsigned r; asm("v_cvt_pk_bf16_f32 %0, %1, %2" : "=v"(r) : "v"(lo), "v"(hi)); return r; }
; __device__ __forceinline__ float fast_sigmoid(float v) { return __builtin_amdgcn_rcpf(1.0f + __builtin_amdgcn_exp2f(-1.4426950408889634f * v)); }
;     __device__ __forceinline__ void operator()(const f32x4 (&acc)[2][2][4][2], const Unit& u, int wr, int wc, int fr_in, int fq_in) const {
;     ...
;             for (int am = 0; am < (FINAL ? 8 : 4); ++am) { constexpr int GR = FINAL ? 1 : 2; const int ai = (am * GR) >> 2; u32x4 ppw[4], pzw[4];
; #pragma unroll
;                 for (int m = (am * GR) & 3; m < ((am * GR) & 3) + GR; ++m) { const size_t off = (size_t)(row0 + ai * HALF + m * 16) * 1024 + col0 + bj * HALF; ppw[m] = *(const u32x4*)(pexb + off); pzw[m] = *(const u32x4*)(zb + off); }
;                 asm volatile("" ::: "memory");
; #pragma unroll
;                 for (int m = (am * GR) & 3; m < ((am * GR) & 3) + GR; ++m) { const size_t off = (size_t)(row0 + ai * HALF + m * 16) * 1024 + col0 + bj * HALF; const float mu = rst.mu[ai][m], rs = rst.rs[ai][m];
;                     const u32x4 pw = ppw[m]; const u32x4 zw = pzw[m];
;                     const f32x4 x0 = ((f32x4){bf_lo(zw.x), bf_hi(zw.x), bf_lo(zw.y), bf_hi(zw.y)} - mu) * rs * gv[0] + bv[0], x1 = ((f32x4){bf_lo(zw.z), bf_hi(zw.z), bf_lo(zw.w), bf_hi(zw.w)} - mu) * rs * gv[1] + bv[1];
;                     const f32x4 a0 = ln_fix(acc[ai][bj][m][0], mu, rs, csv[0], cbv[0]), a1 = ln_fix(acc[ai][bj][m][1], mu, rs, csv[1], cbv[1]); f32x4 o0, o1;
;                     o0[0] = x0[0] + fast_sigmoid(a0[0]) * bf_lo(pw.x); o0[1] = x0[1] + fast_sigmoid(a0[1]) * bf_hi(pw.x);
;                     o0[2] = x0[2] + fast_sigmoid(a0[2]) * bf_lo(pw.y); o0[3] = x0[3] + fast_sigmoid(a0[3]) * bf_hi(pw.y);
;                     o1[0] = x1[0] + fast_sigmoid(a1[0]) * bf_lo(pw.z); o1[1] = x1[1] + fast_sigmoid(a1[1]) * bf_hi(pw.z);
;                     o1[2] = x1[2] + fast_sigmoid(a1[2]) * bf_lo(pw.w); o1[3] = x1[3] + fast_sigmoid(a1[3]) * bf_hi(pw.w);
;                     if constexpr (FINAL) { *(f32x4*)(outf + off) = o0; *(f32x4*)(outf + off + 4) = o1; }
;                     else { u32x4 w; w.x = cvt_pk_bf16(o0[0], o0[1]); w.y = cvt_pk_bf16(o0[2], o0[3]); w.z = cvt_pk_bf16(o1[0], o1[1]); w.w = cvt_pk_bf16(o1[2], o1[3]); *(u32x4*)(pexb + off) = w; } } } }
	v_fma_f32 v92, v92, v164, v152
	v_add_f32_e32 v88, 1.0, v88
	v_rcp_f32_e32 v88, v88
	v_cvt_pk_bf16_f32 v90, v94, v155
	v_lshlrev_b32_e32 v102, 16, v96
	v_lshlrev_b32_e32 v94, 16, v130
	v_fma_f32 v95, v88, v89, v150
	v_mul_f32_e32 v88, 0xbfb8aa3b, v91
	v_exp_f32_e32 v88, v88
	v_and_b32_e32 v89, 0xffff0000, v103
	v_sub_f32_e32 v94, v94, v192
	v_mul_f32_e32 v64, 0xbfb8aa3b, v64
	v_add_f32_e32 v88, 1.0, v88
	v_rcp_f32_e32 v88, v88
	v_exp_f32_e32 v64, v64
	v_fmac_f32_e32 v151, v88, v89
	v_cvt_pk_bf16_f32 v88, v92, v153
	v_cvt_pk_bf16_f32 v89, v93, v149
	v_lshlrev_b64 v[92:93], 11, v[236:237]
	v_lshl_add_u64 v[92:93], s[44:45], 0, v[92:93]
	v_cvt_pk_bf16_f32 v91, v95, v151
	v_lshl_add_u64 v[148:149], v[92:93], 0, v[168:169]
	v_lshlrev_b32_e32 v92, 16, v131
	v_and_b32_e32 v93, 0xffff0000, v131
	global_store_dwordx4 v[148:149], v[88:91], off
	v_sub_f32_e32 v93, v93, v192
	v_sub_f32_e32 v92, v92, v192
	v_lshlrev_b32_e32 v90, 16, v128
	v_and_b32_e32 v91, 0xffff0000, v128
	v_sub_f32_e32 v91, v91, v192
	v_sub_f32_e32 v90, v90, v192
	v_pk_mul_f32 v[92:93], v[194:195], v[92:93] op_sel_hi:[0,1]
	v_pk_mul_f32 v[90:91], v[194:195], v[90:91] op_sel_hi:[0,1]
	v_pk_fma_f32 v[100:101], v[122:123], v[92:93], v[126:127]
	v_xor_b32_e32 v93, 0x80000000, v119
	v_xor_b32_e32 v92, 0x80000000, v118
	v_pk_fma_f32 v[90:91], v[136:137], v[90:91], v[140:141]
	v_pk_fma_f32 v[86:87], v[92:93], v[192:193], v[86:87] op_sel_hi:[1,0,1]
	v_fma_f32 v84, v84, v102, v90
	v_pk_fma_f32 v[86:87], v[86:87], v[194:195], v[114:115] op_sel_hi:[1,0,1]
	v_and_b32_e32 v90, 0xffff0000, v96
	v_fmac_f32_e32 v91, v85, v90
	v_mul_f32_e32 v85, 0xbfb8aa3b, v86
	v_exp_f32_e32 v85, v85
	v_lshlrev_b32_e32 v88, 16, v129
	v_and_b32_e32 v89, 0xffff0000, v129
	v_sub_f32_e32 v89, v89, v192
	v_add_f32_e32 v85, 1.0, v85
	v_rcp_f32_e32 v85, v85
	v_sub_f32_e32 v88, v88, v192
	v_pk_mul_f32 v[88:89], v[194:195], v[88:89] op_sel_hi:[0,1]
	v_pk_fma_f32 v[88:89], v[138:139], v[88:89], v[142:143]
	v_lshlrev_b32_e32 v86, 16, v97
	v_fma_f32 v85, v85, v86, v88
	v_mul_f32_e32 v86, 0xbfb8aa3b, v87
	v_exp_f32_e32 v86, v86
	v_and_b32_e32 v95, 0xffff0000, v130
	v_sub_f32_e32 v95, v95, v192
	v_pk_mul_f32 v[94:95], v[194:195], v[94:95] op_sel_hi:[0,1]
	v_add_f32_e32 v86, 1.0, v86
	v_rcp_f32_e32 v86, v86
	v_and_b32_e32 v87, 0xffff0000, v97
	v_pk_fma_f32 v[94:95], v[120:121], v[94:95], v[124:125]
	v_lshlrev_b64 v[128:129], 10, v[220:221]
	v_fmac_f32_e32 v89, v86, v87
	v_lshlrev_b32_e32 v86, 16, v98
	v_fma_f32 v86, v80, v86, v94
	v_mul_f32_e32 v80, 0xbfb8aa3b, v81
	v_exp_f32_e32 v80, v80
	v_and_b32_e32 v81, 0xffff0000, v98
	v_lshlrev_b64 v[130:131], 10, v[218:219]
	v_pk_fma_f32 v[78:79], v[92:93], v[188:189], v[78:79] op_sel_hi:[1,0,1]
	v_add_f32_e32 v80, 1.0, v80
	v_rcp_f32_e32 v80, v80
	v_pk_fma_f32 v[78:79], v[78:79], v[190:191], v[114:115] op_sel_hi:[1,0,1]
	v_pk_fma_f32 v[70:71], v[92:93], v[184:185], v[70:71] op_sel_hi:[1,0,1]
	v_add_f32_e32 v64, 1.0, v64
	v_fmac_f32_e32 v95, v80, v81
	v_mul_f32_e32 v80, 0xbfb8aa3b, v82
	v_exp_f32_e32 v80, v80
	v_lshlrev_b32_e32 v81, 16, v99
	v_cvt_pk_bf16_f32 v82, v86, v95
	v_pk_fma_f32 v[70:71], v[70:71], v[186:187], v[114:115] op_sel_hi:[1,0,1]
	v_add_f32_e32 v80, 1.0, v80
	v_rcp_f32_e32 v80, v80
	v_rcp_f32_e32 v64, v64
	v_fma_f32 v87, v80, v81, v100
	v_mul_f32_e32 v80, 0xbfb8aa3b, v83
	v_exp_f32_e32 v80, v80
	v_and_b32_e32 v81, 0xffff0000, v99
	v_add_f32_e32 v80, 1.0, v80
	v_rcp_f32_e32 v80, v80
	s_nop 0
	v_fmac_f32_e32 v101, v80, v81
	v_cvt_pk_bf16_f32 v80, v84, v91
	v_cvt_pk_bf16_f32 v81, v85, v89
	v_lshlrev_b64 v[84:85], 11, v[234:235]
	v_lshl_add_u64 v[84:85], s[44:45], 0, v[84:85]
	v_lshl_add_u64 v[118:119], v[84:85], 0, v[168:169]
	v_cvt_pk_bf16_f32 v83, v87, v101
	global_store_dwordx4 v[118:119], v[80:83], off
	s_nop 1
	v_lshl_add_u64 v[80:81], v[128:129], 0, v[216:217]
	v_lshlrev_b64 v[80:81], 1, v[80:81]
	v_lshl_add_u64 v[82:83], s[44:45], 0, v[80:81]
	v_lshl_add_u64 v[80:81], s[40:41], 0, v[80:81]
	global_load_dwordx4 v[84:87], v[82:83], off
	global_load_dwordx4 v[94:97], v[80:81], off
	v_lshl_add_u64 v[80:81], v[130:131], 0, v[216:217]
	v_lshlrev_b64 v[88:89], 1, v[80:81]
	v_lshl_add_u64 v[80:81], s[44:45], 0, v[88:89]
	v_lshl_add_u64 v[88:89], s[40:41], 0, v[88:89]
	global_load_dwordx4 v[80:83], v[80:81], off
	s_waitcnt vmcnt(0)
;     __device__ __forceinline__ void operator()(const f32x4 (&acc)[2][2][4][2], const Unit& u, int wr, int wc, int fr_in, int fq_in) const {
;     ...
;             for (int n = 0; n < 2; ++n) { csv[n] = *(const f32x4*)(cs + col0 + bj * HALF + 4 * n); cbv[n] = *(const f32x4*)(cb + col0 + bj * HALF + 4 * n); gv[n] = *(const f32x4*)(lg + col0 + bj * HALF + 4 * n); bv[n] = *(const f32x4*)(lb + col0 + bj * HALF + 4 * n); }
; #pragma unroll
;             for (int am = 0; am < (FINAL ? 8 : 4); ++am) { constexpr int GR = FINAL ? 1 : 2; const int ai = (am * GR) >> 2; u32x4 ppw[4], pzw[4];
; #pragma unroll
;                 for (int m = (am * GR) & 3; m < ((am * GR) & 3) + GR; ++m) { const size_t off = (size_t)(row0 + ai * HALF + m * 16) * 1024 + col0 + bj * HALF; ppw[m] = *(const u32x4*)(pexb + off); pzw[m] = *(const u32x4*)(zb + off); }
;                 asm volatile("" ::: "memory");
; #pragma unroll
;                 for (int m = (am * GR) & 3; m < ((am * GR) & 3) + GR; ++m) { const size_t off = (size_t)(row0 + ai * HALF + m * 16) * 1024 + col0 + bj * HALF; const float mu = rst.mu[ai][m], rs = rst.rs[ai][m];
;                     const u32x4 pw = ppw[m]; const u32x4 zw = pzw[m];
;                     const f32x4 x0 = ((f32x4){bf_lo(zw.x), bf_hi(zw.x), bf_lo(zw.y), bf_hi(zw.y)} - mu) * rs * gv[0] + bv[0], x1 = ((f32x4){bf_lo(zw.z), bf_hi(zw.z), bf_lo(zw.w), bf_hi(zw.w)} - mu) * rs * gv[1] + bv[1];
;                     const f32x4 a0 = ln_fix(acc[ai][bj][m][0], mu, rs, csv[0], cbv[0]), a1 = ln_fix(acc[ai][bj][m][1], mu, rs, csv[1], cbv[1]); f32x4 o0, o1;
;                     o0[0] = x0[0] + fast_sigmoid(a0[0]) * bf_lo(pw.x); o0[1] = x0[1] + fast_sigmoid(a0[1]) * bf_hi(pw.x);
;                     o0[2] = x0[2] + fast_sigmoid(a0[2]) * bf_lo(pw.y); o0[3] = x0[3] + fast_sigmoid(a0[3]) * bf_hi(pw.y);
;                     o1[0] = x1[0] + fast_sigmoid(a1[0]) * bf_lo(pw.z); o1[1] = x1[1] + fast_sigmoid(a1[1]) * bf_hi(pw.z);
;                     o1[2] = x1[2] + fast_sigmoid(a1[2]) * bf_lo(pw.w); o1[3] = x1[3] + fast_sigmoid(a1[3]) * bf_hi(pw.w);
;                     if constexpr (FINAL) { *(f32x4*)(outf + off) = o0; *(f32x4*)(outf + off + 4) = o1; }
;                     else { u32x4 w; w.x = cvt_pk_bf16(o0[0], o0[1]); w.y = cvt_pk_bf16(o0[2], o0[3]); w.z = cvt_pk_bf16(o1[0], o1[1]); w.w = cvt_pk_bf16(o1[2], o1[3]); *(u32x4*)(pexb + off) = w; } } } }
	v_lshlrev_b32_e32 v102, 16, v84
	global_load_dwordx4 v[88:91], v[88:89], off
	v_lshlrev_b32_e32 v98, 16, v94
	v_and_b32_e32 v99, 0xffff0000, v94
	v_sub_f32_e32 v99, v99, v188
	v_sub_f32_e32 v98, v98, v188
	v_pk_mul_f32 v[98:99], v[190:191], v[98:99] op_sel_hi:[0,1]
	v_pk_fma_f32 v[98:99], v[136:137], v[98:99], v[140:141]
	v_and_b32_e32 v84, 0xffff0000, v84
	v_fmac_f32_e32 v99, v77, v84
	v_mul_f32_e32 v77, 0xbfb8aa3b, v78
	v_exp_f32_e32 v77, v77
	v_lshlrev_b32_e32 v94, 16, v95
	v_and_b32_e32 v95, 0xffff0000, v95
	v_sub_f32_e32 v95, v95, v188
	v_add_f32_e32 v77, 1.0, v77
	v_rcp_f32_e32 v77, v77
	v_sub_f32_e32 v94, v94, v188
	v_pk_mul_f32 v[94:95], v[190:191], v[94:95] op_sel_hi:[0,1]
	v_pk_fma_f32 v[94:95], v[138:139], v[94:95], v[142:143]
	v_lshlrev_b32_e32 v78, 16, v85
	v_fma_f32 v77, v77, v78, v94
	v_mul_f32_e32 v78, 0xbfb8aa3b, v79
	v_exp_f32_e32 v78, v78
	v_lshlrev_b32_e32 v100, 16, v96
	v_and_b32_e32 v101, 0xffff0000, v96
	v_sub_f32_e32 v101, v101, v188
	v_add_f32_e32 v78, 1.0, v78
	v_rcp_f32_e32 v78, v78
	v_sub_f32_e32 v100, v100, v188
	v_pk_mul_f32 v[100:101], v[190:191], v[100:101] op_sel_hi:[0,1]
	v_and_b32_e32 v79, 0xffff0000, v85
	v_pk_fma_f32 v[100:101], v[120:121], v[100:101], v[124:125]
	v_fmac_f32_e32 v95, v78, v79
	v_lshlrev_b32_e32 v78, 16, v86
	v_fma_f32 v78, v72, v78, v100
	v_mul_f32_e32 v72, 0xbfb8aa3b, v73
	v_exp_f32_e32 v72, v72
	v_and_b32_e32 v73, 0xffff0000, v86
	v_lshlrev_b32_e32 v96, 16, v97
	v_and_b32_e32 v97, 0xffff0000, v97
	v_add_f32_e32 v72, 1.0, v72
	v_rcp_f32_e32 v72, v72
	v_sub_f32_e32 v97, v97, v188
	v_sub_f32_e32 v96, v96, v188
	v_pk_mul_f32 v[96:97], v[190:191], v[96:97] op_sel_hi:[0,1]
	v_fmac_f32_e32 v101, v72, v73
	v_mul_f32_e32 v72, 0xbfb8aa3b, v74
	v_exp_f32_e32 v72, v72
	v_pk_fma_f32 v[96:97], v[122:123], v[96:97], v[126:127]
	v_lshlrev_b32_e32 v73, 16, v87
	v_fma_f32 v76, v76, v102, v98
	v_add_f32_e32 v72, 1.0, v72
	v_rcp_f32_e32 v72, v72
	v_cvt_pk_bf16_f32 v74, v78, v101
	v_xor_b32_e32 v85, 0x80000000, v111
	v_fma_f32 v79, v72, v73, v96
	v_mul_f32_e32 v72, 0xbfb8aa3b, v75
	v_exp_f32_e32 v72, v72
	v_and_b32_e32 v73, 0xffff0000, v87
	v_xor_b32_e32 v84, 0x80000000, v110
	v_pk_fma_f32 v[66:67], v[84:85], v[184:185], v[66:67] op_sel_hi:[1,0,1]
	v_add_f32_e32 v72, 1.0, v72
	v_rcp_f32_e32 v72, v72
	v_lshlrev_b32_e32 v84, 16, v80
	v_pk_fma_f32 v[66:67], v[66:67], v[186:187], v[106:107] op_sel_hi:[1,0,1]
	v_lshl_add_u64 v[110:111], v[216:217], 0, s[52:53]
	v_fmac_f32_e32 v97, v72, v73
	v_cvt_pk_bf16_f32 v72, v76, v99
	v_cvt_pk_bf16_f32 v73, v77, v95
	v_lshlrev_b64 v[76:77], 11, v[220:221]
	v_lshl_add_u64 v[76:77], s[44:45], 0, v[76:77]
	v_cvt_pk_bf16_f32 v75, v79, v97
	v_lshl_add_u64 v[150:151], v[76:77], 0, v[168:169]
	global_store_dwordx4 v[150:151], v[72:75], off
	v_lshl_add_u64 v[96:97], v[110:111], 0, v[230:231]
	v_lshl_add_u64 v[96:97], v[96:97], 1, s[40:41]
	v_lshl_add_u64 v[104:105], v[110:111], 0, v[232:233]
	v_lshl_add_u64 v[104:105], v[104:105], 1, s[40:41]
	s_waitcnt vmcnt(0)
	v_lshlrev_b32_e32 v74, 16, v88
	v_and_b32_e32 v75, 0xffff0000, v88
	v_sub_f32_e32 v75, v75, v184
	v_sub_f32_e32 v74, v74, v184
	v_pk_mul_f32 v[74:75], v[186:187], v[74:75] op_sel_hi:[0,1]
	v_pk_fma_f32 v[74:75], v[136:137], v[74:75], v[140:141]
	v_lshlrev_b32_e32 v72, 16, v89
	v_fma_f32 v68, v68, v84, v74
	v_and_b32_e32 v74, 0xffff0000, v80
	v_fmac_f32_e32 v75, v69, v74
	v_mul_f32_e32 v69, 0xbfb8aa3b, v70
	v_exp_f32_e32 v69, v69
	v_and_b32_e32 v73, 0xffff0000, v89
	v_sub_f32_e32 v73, v73, v184
	v_sub_f32_e32 v72, v72, v184
	v_add_f32_e32 v69, 1.0, v69
	v_rcp_f32_e32 v69, v69
	v_pk_mul_f32 v[72:73], v[186:187], v[72:73] op_sel_hi:[0,1]
	v_pk_fma_f32 v[72:73], v[138:139], v[72:73], v[142:143]
	v_lshlrev_b32_e32 v70, 16, v81
	v_fma_f32 v69, v69, v70, v72
	v_mul_f32_e32 v70, 0xbfb8aa3b, v71
	v_exp_f32_e32 v70, v70
	v_lshlrev_b32_e32 v78, 16, v90
	v_and_b32_e32 v79, 0xffff0000, v90
	v_sub_f32_e32 v79, v79, v184
	v_add_f32_e32 v70, 1.0, v70
	v_rcp_f32_e32 v70, v70
	v_sub_f32_e32 v78, v78, v184
	v_pk_mul_f32 v[78:79], v[186:187], v[78:79] op_sel_hi:[0,1]
	v_and_b32_e32 v71, 0xffff0000, v81
	v_pk_fma_f32 v[78:79], v[120:121], v[78:79], v[124:125]
	v_fmac_f32_e32 v73, v70, v71
	v_lshlrev_b32_e32 v70, 16, v82
	v_fma_f32 v70, v64, v70, v78
	v_mul_f32_e32 v64, 0xbfb8aa3b, v65
	v_exp_f32_e32 v64, v64
	v_and_b32_e32 v65, 0xffff0000, v82
	v_lshlrev_b32_e32 v76, 16, v91
	v_and_b32_e32 v77, 0xffff0000, v91
	v_add_f32_e32 v64, 1.0, v64
	v_rcp_f32_e32 v64, v64
	v_sub_f32_e32 v77, v77, v184
	v_sub_f32_e32 v76, v76, v184
	v_pk_mul_f32 v[76:77], v[186:187], v[76:77] op_sel_hi:[0,1]
	v_fmac_f32_e32 v79, v64, v65
	v_mul_f32_e32 v64, 0xbfb8aa3b, v66
	v_exp_f32_e32 v64, v64
	v_pk_fma_f32 v[76:77], v[122:123], v[76:77], v[126:127]
	v_lshlrev_b32_e32 v65, 16, v83
	v_cvt_pk_bf16_f32 v66, v70, v79
	v_add_f32_e32 v64, 1.0, v64
	v_rcp_f32_e32 v64, v64
	s_nop 0
	v_fma_f32 v71, v64, v65, v76
	v_mul_f32_e32 v64, 0xbfb8aa3b, v67
	v_exp_f32_e32 v64, v64
	v_and_b32_e32 v65, 0xffff0000, v83
	v_add_f32_e32 v64, 1.0, v64
	v_rcp_f32_e32 v64, v64
	s_nop 0
	v_fmac_f32_e32 v77, v64, v65
	v_cvt_pk_bf16_f32 v64, v68, v75
	v_cvt_pk_bf16_f32 v65, v69, v73
	v_lshlrev_b64 v[68:69], 11, v[218:219]
	v_lshl_add_u64 v[68:69], s[44:45], 0, v[68:69]
	v_lshl_add_u64 v[108:109], v[68:69], 0, v[168:169]
	v_cvt_pk_bf16_f32 v67, v71, v77
	global_store_dwordx4 v[108:109], v[64:67], off
	global_load_dwordx4 v[64:67], v[228:229], off offset:528
	s_nop 0
	global_load_dwordx4 v[72:75], v[228:229], off offset:512
	global_load_dwordx4 v[68:71], v[226:227], off offset:528
	global_load_dwordx4 v[76:79], v[226:227], off offset:512
	global_load_dwordx4 v[80:83], v[224:225], off offset:528
	global_load_dwordx4 v[88:91], v[224:225], off offset:512
	global_load_dwordx4 v[84:87], v[222:223], off offset:528
	global_load_dwordx4 v[92:95], v[222:223], off offset:512
	global_load_dwordx4 v[112:115], v[96:97], off
	global_load_dwordx4 v[100:103], v[156:157], off offset:256
	s_waitcnt vmcnt(0)
; __device__ __forceinline__ unsigned cvt_pk_bf16(float lo, float hi) { unsigned r; asm("v_cvt_pk_bf16_f32 %0, %1, %2" : "=v"(r) : "v"(lo), "v"(hi)); return r; }
; __device__ __forceinline__ float fast_sigmoid(float v) { return __builtin_amdgcn_rcpf(1.0f + __builtin_amdgcn_exp2f(-1.4426950408889634f * v)); }
;     __device__ __forceinline__ void operator()(const f32x4 (&acc)[2][2][4][2], const Unit& u, int wr, int wc, int fr_in, int fq_in) const {
;     ...
;             for (int am = 0; am < (FINAL ? 8 : 4); ++am) { constexpr int GR = FINAL ? 1 : 2; const int ai = (am * GR) >> 2; u32x4 ppw[4], pzw[4];
; #pragma unroll
;                 for (int m = (am * GR) & 3; m < ((am * GR) & 3) + GR; ++m) { const size_t off = (size_t)(row0 + ai * HALF + m * 16) * 1024 + col0 + bj * HALF; ppw[m] = *(const u32x4*)(pexb + off); pzw[m] = *(const u32x4*)(zb + off); }
;                 asm volatile("" ::: "memory");
; #pragma unroll
;                 for (int m = (am * GR) & 3; m < ((am * GR) & 3) + GR; ++m) { const size_t off = (size_t)(row0 + ai * HALF + m * 16) * 1024 + col0 + bj * HALF; const float mu = rst.mu[ai][m], rs = rst.rs[ai][m];
;                     const u32x4 pw = ppw[m]; const u32x4 zw = pzw[m];
;                     const f32x4 x0 = ((f32x4){bf_lo(zw.x), bf_hi(zw.x), bf_lo(zw.y), bf_hi(zw.y)} - mu) * rs * gv[0] + bv[0], x1 = ((f32x4){bf_lo(zw.z), bf_hi(zw.z), bf_lo(zw.w), bf_hi(zw.w)} - mu) * rs * gv[1] + bv[1];
;                     const f32x4 a0 = ln_fix(acc[ai][bj][m][0], mu, rs, csv[0], cbv[0]), a1 = ln_fix(acc[ai][bj][m][1], mu, rs, csv[1], cbv[1]); f32x4 o0, o1;
;                     o0[0] = x0[0] + fast_sigmoid(a0[0]) * bf_lo(pw.x); o0[1] = x0[1] + fast_sigmoid(a0[1]) * bf_hi(pw.x);
;                     o0[2] = x0[2] + fast_sigmoid(a0[2]) * bf_lo(pw.y); o0[3] = x0[3] + fast_sigmoid(a0[3]) * bf_hi(pw.y);
;                     o1[0] = x1[0] + fast_sigmoid(a1[0]) * bf_lo(pw.z); o1[1] = x1[1] + fast_sigmoid(a1[1]) * bf_hi(pw.z);
;                     o1[2] = x1[2] + fast_sigmoid(a1[2]) * bf_lo(pw.w); o1[3] = x1[3] + fast_sigmoid(a1[3]) * bf_hi(pw.w);
;                     if constexpr (FINAL) { *(f32x4*)(outf + off) = o0; *(f32x4*)(outf + off + 4) = o1; }
;                     else { u32x4 w; w.x = cvt_pk_bf16(o0[0], o0[1]); w.y = cvt_pk_bf16(o0[2], o0[3]); w.z = cvt_pk_bf16(o1[0], o1[1]); w.w = cvt_pk_bf16(o1[2], o1[3]); *(u32x4*)(pexb + off) = w; } } } }
	v_pk_fma_f32 v[56:57], v[212:213], v[64:65], v[56:57] op_sel_hi:[0,1,1] neg_lo:[1,0,0] neg_hi:[1,0,0]
	global_load_dwordx4 v[104:107], v[104:105], off
	v_pk_fma_f32 v[60:61], v[212:213], v[72:73], v[60:61] op_sel_hi:[0,1,1] neg_lo:[1,0,0] neg_hi:[1,0,0]
	global_load_dwordx4 v[96:99], v[158:159], off offset:256
	v_pk_fma_f32 v[60:61], v[214:215], v[60:61], v[76:77] op_sel_hi:[0,1,1]
	v_mul_f32_e32 v61, 0xbfb8aa3b, v61
	v_exp_f32_e32 v61, v61
	v_pk_fma_f32 v[62:63], v[212:213], v[74:75], v[62:63] op_sel_hi:[0,1,1] neg_lo:[1,0,0] neg_hi:[1,0,0]
	v_lshlrev_b32_e32 v116, 16, v112
	v_and_b32_e32 v117, 0xffff0000, v112
	v_add_f32_e32 v61, 1.0, v61
	v_rcp_f32_e32 v61, v61
	v_sub_f32_e32 v117, v117, v212
	v_sub_f32_e32 v116, v116, v212
	v_pk_mul_f32 v[116:117], v[214:215], v[116:117] op_sel_hi:[0,1]
	v_pk_fma_f32 v[116:117], v[88:89], v[116:117], v[92:93]
	v_pk_fma_f32 v[62:63], v[214:215], v[62:63], v[78:79] op_sel_hi:[0,1,1]
	v_lshlrev_b32_e32 v122, 16, v100
	v_and_b32_e32 v100, 0xffff0000, v100
	v_fmac_f32_e32 v117, v61, v100
	v_mul_f32_e32 v61, 0xbfb8aa3b, v62
	v_exp_f32_e32 v61, v61
	v_lshlrev_b32_e32 v112, 16, v113
	v_and_b32_e32 v113, 0xffff0000, v113
	v_sub_f32_e32 v113, v113, v212
	v_add_f32_e32 v61, 1.0, v61
	v_rcp_f32_e32 v61, v61
	v_sub_f32_e32 v112, v112, v212
	v_pk_mul_f32 v[112:113], v[214:215], v[112:113] op_sel_hi:[0,1]
	v_pk_fma_f32 v[112:113], v[90:91], v[112:113], v[94:95]
	v_lshlrev_b32_e32 v62, 16, v101
	v_pk_fma_f32 v[56:57], v[214:215], v[56:57], v[68:69] op_sel_hi:[0,1,1]
	v_fma_f32 v61, v61, v62, v112
	v_mul_f32_e32 v62, 0xbfb8aa3b, v63
	v_exp_f32_e32 v62, v62
	v_mul_f32_e32 v56, 0xbfb8aa3b, v56
	v_exp_f32_e32 v56, v56
	v_lshlrev_b32_e32 v120, 16, v114
	v_add_f32_e32 v62, 1.0, v62
	v_rcp_f32_e32 v62, v62
	v_add_f32_e32 v56, 1.0, v56
	v_and_b32_e32 v121, 0xffff0000, v114
	v_rcp_f32_e32 v56, v56
	v_sub_f32_e32 v121, v121, v212
	v_sub_f32_e32 v120, v120, v212
	v_pk_mul_f32 v[120:121], v[214:215], v[120:121] op_sel_hi:[0,1]
	v_and_b32_e32 v63, 0xffff0000, v101
	v_pk_fma_f32 v[120:121], v[80:81], v[120:121], v[84:85]
	v_fmac_f32_e32 v113, v62, v63
	v_lshlrev_b32_e32 v62, 16, v102
	v_fma_f32 v62, v56, v62, v120
	v_mul_f32_e32 v56, 0xbfb8aa3b, v57
	v_exp_f32_e32 v56, v56
	v_pk_fma_f32 v[58:59], v[212:213], v[66:67], v[58:59] op_sel_hi:[0,1,1] neg_lo:[1,0,0] neg_hi:[1,0,0]
	v_pk_fma_f32 v[58:59], v[214:215], v[58:59], v[70:71] op_sel_hi:[0,1,1]
	v_and_b32_e32 v57, 0xffff0000, v102
	v_add_f32_e32 v56, 1.0, v56
	v_rcp_f32_e32 v56, v56
	v_lshlrev_b32_e32 v114, 16, v115
	v_and_b32_e32 v115, 0xffff0000, v115
	v_sub_f32_e32 v115, v115, v212
	v_fmac_f32_e32 v121, v56, v57
	v_mul_f32_e32 v56, 0xbfb8aa3b, v58
	v_exp_f32_e32 v56, v56
	v_sub_f32_e32 v114, v114, v212
	v_pk_mul_f32 v[114:115], v[214:215], v[114:115] op_sel_hi:[0,1]
	v_pk_fma_f32 v[114:115], v[82:83], v[114:115], v[86:87]
	v_add_f32_e32 v56, 1.0, v56
	v_rcp_f32_e32 v56, v56
	v_lshlrev_b32_e32 v57, 16, v103
	v_mul_f32_e32 v60, 0xbfb8aa3b, v60
	v_exp_f32_e32 v60, v60
	v_fma_f32 v63, v56, v57, v114
	v_mul_f32_e32 v56, 0xbfb8aa3b, v59
	v_exp_f32_e32 v56, v56
	v_pk_fma_f32 v[52:53], v[208:209], v[72:73], v[52:53] op_sel_hi:[0,1,1] neg_lo:[1,0,0] neg_hi:[1,0,0]
	v_pk_fma_f32 v[52:53], v[210:211], v[52:53], v[76:77] op_sel_hi:[0,1,1]
	v_mul_f32_e32 v52, 0xbfb8aa3b, v52
	v_add_f32_e32 v56, 1.0, v56
	v_add_f32_e32 v60, 1.0, v60
	v_rcp_f32_e32 v56, v56
	v_exp_f32_e32 v52, v52
	v_mul_f32_e32 v53, 0xbfb8aa3b, v53
	v_rcp_f32_e32 v60, v60
	v_exp_f32_e32 v53, v53
	v_and_b32_e32 v57, 0xffff0000, v103
	v_fmac_f32_e32 v115, v56, v57
	v_cvt_pk_bf16_f32 v58, v62, v121
	v_cvt_pk_bf16_f32 v59, v63, v115
	v_add_f32_e32 v52, 1.0, v52
	v_fma_f32 v60, v60, v122, v116
	v_cvt_pk_bf16_f32 v56, v60, v117
	v_cvt_pk_bf16_f32 v57, v61, v113
	global_store_dwordx4 v[156:157], v[56:59], off offset:256
	v_rcp_f32_e32 v52, v52
	v_add_f32_e32 v53, 1.0, v53
	s_waitcnt vmcnt(0)
	v_lshlrev_b32_e32 v58, 16, v104
	v_and_b32_e32 v59, 0xffff0000, v104
	v_sub_f32_e32 v59, v59, v208
	v_sub_f32_e32 v58, v58, v208
	v_rcp_f32_e32 v53, v53
	v_pk_mul_f32 v[58:59], v[210:211], v[58:59] op_sel_hi:[0,1]
	v_pk_fma_f32 v[58:59], v[88:89], v[58:59], v[92:93]
	v_pk_fma_f32 v[54:55], v[208:209], v[74:75], v[54:55] op_sel_hi:[0,1,1] neg_lo:[1,0,0] neg_hi:[1,0,0]
	v_lshlrev_b32_e32 v100, 16, v96
	v_pk_fma_f32 v[54:55], v[210:211], v[54:55], v[78:79] op_sel_hi:[0,1,1]
	v_fma_f32 v52, v52, v100, v58
	v_and_b32_e32 v58, 0xffff0000, v96
	v_fmac_f32_e32 v59, v53, v58
	v_mul_f32_e32 v53, 0xbfb8aa3b, v54
	v_exp_f32_e32 v53, v53
	v_lshlrev_b32_e32 v56, 16, v105
	v_and_b32_e32 v57, 0xffff0000, v105
	v_sub_f32_e32 v57, v57, v208
	v_add_f32_e32 v53, 1.0, v53
	v_rcp_f32_e32 v53, v53
	v_sub_f32_e32 v56, v56, v208
	v_pk_mul_f32 v[56:57], v[210:211], v[56:57] op_sel_hi:[0,1]
	v_pk_fma_f32 v[56:57], v[90:91], v[56:57], v[94:95]
	v_pk_fma_f32 v[48:49], v[208:209], v[64:65], v[48:49] op_sel_hi:[0,1,1] neg_lo:[1,0,0] neg_hi:[1,0,0]
	v_lshlrev_b32_e32 v54, 16, v97
	v_pk_fma_f32 v[48:49], v[210:211], v[48:49], v[68:69] op_sel_hi:[0,1,1]
	v_fma_f32 v53, v53, v54, v56
	v_mul_f32_e32 v54, 0xbfb8aa3b, v55
	v_exp_f32_e32 v54, v54
	v_mul_f32_e32 v48, 0xbfb8aa3b, v48
	v_exp_f32_e32 v48, v48
	v_lshlrev_b32_e32 v62, 16, v106
	v_add_f32_e32 v54, 1.0, v54
	v_rcp_f32_e32 v54, v54
	v_add_f32_e32 v48, 1.0, v48
	v_and_b32_e32 v63, 0xffff0000, v106
	v_rcp_f32_e32 v48, v48
	v_sub_f32_e32 v63, v63, v208
	v_sub_f32_e32 v62, v62, v208
	v_pk_mul_f32 v[62:63], v[210:211], v[62:63] op_sel_hi:[0,1]
	v_and_b32_e32 v55, 0xffff0000, v97
	v_pk_fma_f32 v[62:63], v[80:81], v[62:63], v[84:85]
	v_fmac_f32_e32 v57, v54, v55
	v_lshlrev_b32_e32 v54, 16, v98
	v_fma_f32 v54, v48, v54, v62
; __device__ __forceinline__ unsigned cvt_pk_bf16(float lo, float hi) { unsigned r; asm("v_cvt_pk_bf16_f32 %0, %1, %2" : "=v"(r) : "v"(lo), "v"(hi)); return r; }
; __device__ __forceinline__ float fast_sigmoid(float v) { return __builtin_amdgcn_rcpf(1.0f + __builtin_amdgcn_exp2f(-1.4426950408889634f * v)); }
;     __device__ __forceinline__ void operator()(const f32x4 (&acc)[2][2][4][2], const Unit& u, int wr, int wc, int fr_in, int fq_in) const {
;     ...
;             for (int am = 0; am < (FINAL ? 8 : 4); ++am) { constexpr int GR = FINAL ? 1 : 2; const int ai = (am * GR) >> 2; u32x4 ppw[4], pzw[4];
; #pragma unroll
;                 for (int m = (am * GR) & 3; m < ((am * GR) & 3) + GR; ++m) { const size_t off = (size_t)(row0 + ai * HALF + m * 16) * 1024 + col0 + bj * HALF; ppw[m] = *(const u32x4*)(pexb + off); pzw[m] = *(const u32x4*)(zb + off); }
;                 asm volatile("" ::: "memory");
; #pragma unroll
;                 for (int m = (am * GR) & 3; m < ((am * GR) & 3) + GR; ++m) { const size_t off = (size_t)(row0 + ai * HALF + m * 16) * 1024 + col0 + bj * HALF; const float mu = rst.mu[ai][m], rs = rst.rs[ai][m];
;                     const u32x4 pw = ppw[m]; const u32x4 zw = pzw[m];
;                     const f32x4 x0 = ((f32x4){bf_lo(zw.x), bf_hi(zw.x), bf_lo(zw.y), bf_hi(zw.y)} - mu) * rs * gv[0] + bv[0], x1 = ((f32x4){bf_lo(zw.z), bf_hi(zw.z), bf_lo(zw.w), bf_hi(zw.w)} - mu) * rs * gv[1] + bv[1];
;                     const f32x4 a0 = ln_fix(acc[ai][bj][m][0], mu, rs, csv[0], cbv[0]), a1 = ln_fix(acc[ai][bj][m][1], mu, rs, csv[1], cbv[1]); f32x4 o0, o1;
;                     o0[0] = x0[0] + fast_sigmoid(a0[0]) * bf_lo(pw.x); o0[1] = x0[1] + fast_sigmoid(a0[1]) * bf_hi(pw.x);
;                     o0[2] = x0[2] + fast_sigmoid(a0[2]) * bf_lo(pw.y); o0[3] = x0[3] + fast_sigmoid(a0[3]) * bf_hi(pw.y);
;                     o1[0] = x1[0] + fast_sigmoid(a1[0]) * bf_lo(pw.z); o1[1] = x1[1] + fast_sigmoid(a1[1]) * bf_hi(pw.z);
;                     o1[2] = x1[2] + fast_sigmoid(a1[2]) * bf_lo(pw.w); o1[3] = x1[3] + fast_sigmoid(a1[3]) * bf_hi(pw.w);
;                     if constexpr (FINAL) { *(f32x4*)(outf + off) = o0; *(f32x4*)(outf + off + 4) = o1; }
;                     else { u32x4 w; w.x = cvt_pk_bf16(o0[0], o0[1]); w.y = cvt_pk_bf16(o0[2], o0[3]); w.z = cvt_pk_bf16(o1[0], o1[1]); w.w = cvt_pk_bf16(o1[2], o1[3]); *(u32x4*)(pexb + off) = w; } } } }
	v_mul_f32_e32 v48, 0xbfb8aa3b, v49
	v_exp_f32_e32 v48, v48
	v_pk_fma_f32 v[50:51], v[208:209], v[66:67], v[50:51] op_sel_hi:[0,1,1] neg_lo:[1,0,0] neg_hi:[1,0,0]
	v_pk_fma_f32 v[50:51], v[210:211], v[50:51], v[70:71] op_sel_hi:[0,1,1]
	v_and_b32_e32 v49, 0xffff0000, v98
	v_add_f32_e32 v48, 1.0, v48
	v_rcp_f32_e32 v48, v48
	v_lshlrev_b32_e32 v60, 16, v107
	v_and_b32_e32 v61, 0xffff0000, v107
	v_sub_f32_e32 v61, v61, v208
	v_fmac_f32_e32 v63, v48, v49
	v_mul_f32_e32 v48, 0xbfb8aa3b, v50
	v_exp_f32_e32 v48, v48
	v_sub_f32_e32 v60, v60, v208
	v_pk_mul_f32 v[60:61], v[210:211], v[60:61] op_sel_hi:[0,1]
	v_pk_fma_f32 v[60:61], v[82:83], v[60:61], v[86:87]
	v_add_f32_e32 v48, 1.0, v48
	v_rcp_f32_e32 v48, v48
	v_lshlrev_b32_e32 v49, 16, v99
	v_cvt_pk_bf16_f32 v50, v54, v63
	v_pk_fma_f32 v[44:45], v[204:205], v[72:73], v[44:45] op_sel_hi:[0,1,1] neg_lo:[1,0,0] neg_hi:[1,0,0]
	v_fma_f32 v55, v48, v49, v60
	v_mul_f32_e32 v48, 0xbfb8aa3b, v51
	v_exp_f32_e32 v48, v48
	v_and_b32_e32 v49, 0xffff0000, v99
	v_pk_fma_f32 v[44:45], v[206:207], v[44:45], v[76:77] op_sel_hi:[0,1,1]
	v_mul_f32_e32 v45, 0xbfb8aa3b, v45
	v_add_f32_e32 v48, 1.0, v48
	v_rcp_f32_e32 v48, v48
	v_exp_f32_e32 v45, v45
	v_pk_fma_f32 v[46:47], v[204:205], v[74:75], v[46:47] op_sel_hi:[0,1,1] neg_lo:[1,0,0] neg_hi:[1,0,0]
	v_pk_fma_f32 v[46:47], v[206:207], v[46:47], v[78:79] op_sel_hi:[0,1,1]
	v_fmac_f32_e32 v61, v48, v49
	v_cvt_pk_bf16_f32 v48, v52, v59
	v_cvt_pk_bf16_f32 v49, v53, v57
	v_cvt_pk_bf16_f32 v51, v55, v61
	global_store_dwordx4 v[158:159], v[48:51], off offset:256
	global_load_dwordx4 v[56:59], v[132:133], off offset:256
	v_lshl_add_u64 v[52:53], v[110:111], 0, v[162:163]
	v_lshl_add_u64 v[48:49], v[110:111], 0, v[160:161]
	v_lshl_add_u64 v[48:49], v[48:49], 1, s[40:41]
	global_load_dwordx4 v[60:63], v[48:49], off
	v_lshl_add_u64 v[52:53], v[52:53], 1, s[40:41]
	global_load_dwordx4 v[52:55], v[52:53], off
	v_add_f32_e32 v45, 1.0, v45
	global_load_dwordx4 v[48:51], v[134:135], off offset:256
	v_rcp_f32_e32 v45, v45
	v_pk_fma_f32 v[40:41], v[204:205], v[64:65], v[40:41] op_sel_hi:[0,1,1] neg_lo:[1,0,0] neg_hi:[1,0,0]
	v_pk_fma_f32 v[40:41], v[206:207], v[40:41], v[68:69] op_sel_hi:[0,1,1]
	v_mul_f32_e32 v40, 0xbfb8aa3b, v40
	v_exp_f32_e32 v40, v40
	v_pk_fma_f32 v[42:43], v[204:205], v[66:67], v[42:43] op_sel_hi:[0,1,1] neg_lo:[1,0,0] neg_hi:[1,0,0]
	v_pk_fma_f32 v[42:43], v[206:207], v[42:43], v[70:71] op_sel_hi:[0,1,1]
	v_mul_f32_e32 v44, 0xbfb8aa3b, v44
	v_add_f32_e32 v40, 1.0, v40
	v_rcp_f32_e32 v40, v40
	v_exp_f32_e32 v44, v44
	v_pk_fma_f32 v[36:37], v[200:201], v[72:73], v[36:37] op_sel_hi:[0,1,1] neg_lo:[1,0,0] neg_hi:[1,0,0]
	v_pk_fma_f32 v[36:37], v[202:203], v[36:37], v[76:77] op_sel_hi:[0,1,1]
	v_mul_f32_e32 v36, 0xbfb8aa3b, v36
	v_add_f32_e32 v44, 1.0, v44
	v_exp_f32_e32 v36, v36
	v_mul_f32_e32 v37, 0xbfb8aa3b, v37
	v_rcp_f32_e32 v44, v44
	v_exp_f32_e32 v37, v37
	v_add_f32_e32 v36, 1.0, v36
	v_rcp_f32_e32 v36, v36
	v_add_f32_e32 v37, 1.0, v37
	v_rcp_f32_e32 v37, v37
	v_pk_fma_f32 v[38:39], v[200:201], v[74:75], v[38:39] op_sel_hi:[0,1,1] neg_lo:[1,0,0] neg_hi:[1,0,0]
	v_pk_fma_f32 v[38:39], v[202:203], v[38:39], v[78:79] op_sel_hi:[0,1,1]
	v_pk_fma_f32 v[32:33], v[200:201], v[64:65], v[32:33] op_sel_hi:[0,1,1] neg_lo:[1,0,0] neg_hi:[1,0,0]
	v_pk_fma_f32 v[32:33], v[202:203], v[32:33], v[68:69] op_sel_hi:[0,1,1]
	v_mul_f32_e32 v32, 0xbfb8aa3b, v32
	v_exp_f32_e32 v32, v32
	v_pk_fma_f32 v[34:35], v[200:201], v[66:67], v[34:35] op_sel_hi:[0,1,1] neg_lo:[1,0,0] neg_hi:[1,0,0]
	v_pk_fma_f32 v[34:35], v[202:203], v[34:35], v[70:71] op_sel_hi:[0,1,1]
	v_pk_fma_f32 v[28:29], v[196:197], v[72:73], v[28:29] op_sel_hi:[0,1,1] neg_lo:[1,0,0] neg_hi:[1,0,0]
	v_add_f32_e32 v32, 1.0, v32
	v_rcp_f32_e32 v32, v32
	v_pk_fma_f32 v[28:29], v[198:199], v[28:29], v[76:77] op_sel_hi:[0,1,1]
	v_mul_f32_e32 v29, 0xbfb8aa3b, v29
	v_exp_f32_e32 v29, v29
	v_pk_fma_f32 v[30:31], v[196:197], v[74:75], v[30:31] op_sel_hi:[0,1,1] neg_lo:[1,0,0] neg_hi:[1,0,0]
	v_pk_fma_f32 v[30:31], v[198:199], v[30:31], v[78:79] op_sel_hi:[0,1,1]
	v_pk_fma_f32 v[24:25], v[196:197], v[64:65], v[24:25] op_sel_hi:[0,1,1] neg_lo:[1,0,0] neg_hi:[1,0,0]
	v_add_f32_e32 v29, 1.0, v29
	v_rcp_f32_e32 v29, v29
	v_pk_fma_f32 v[24:25], v[198:199], v[24:25], v[68:69] op_sel_hi:[0,1,1]
	v_mul_f32_e32 v24, 0xbfb8aa3b, v24
	v_exp_f32_e32 v24, v24
	v_pk_fma_f32 v[26:27], v[196:197], v[66:67], v[26:27] op_sel_hi:[0,1,1] neg_lo:[1,0,0] neg_hi:[1,0,0]
	v_pk_fma_f32 v[26:27], v[198:199], v[26:27], v[70:71] op_sel_hi:[0,1,1]
	v_mul_f32_e32 v28, 0xbfb8aa3b, v28
	v_add_f32_e32 v24, 1.0, v24
	v_rcp_f32_e32 v24, v24
	v_exp_f32_e32 v28, v28
	v_pk_fma_f32 v[20:21], v[192:193], v[72:73], v[20:21] op_sel_hi:[0,1,1] neg_lo:[1,0,0] neg_hi:[1,0,0]
	v_pk_fma_f32 v[20:21], v[194:195], v[20:21], v[76:77] op_sel_hi:[0,1,1]
	v_mul_f32_e32 v20, 0xbfb8aa3b, v20
	v_add_f32_e32 v28, 1.0, v28
	v_exp_f32_e32 v20, v20
	v_mul_f32_e32 v21, 0xbfb8aa3b, v21
	v_rcp_f32_e32 v28, v28
	v_exp_f32_e32 v21, v21
	v_add_f32_e32 v20, 1.0, v20
	v_rcp_f32_e32 v20, v20
	v_pk_fma_f32 v[22:23], v[192:193], v[74:75], v[22:23] op_sel_hi:[0,1,1] neg_lo:[1,0,0] neg_hi:[1,0,0]
	v_add_f32_e32 v21, 1.0, v21
	v_rcp_f32_e32 v21, v21
	v_pk_fma_f32 v[22:23], v[194:195], v[22:23], v[78:79] op_sel_hi:[0,1,1]
	v_pk_fma_f32 v[16:17], v[192:193], v[64:65], v[16:17] op_sel_hi:[0,1,1] neg_lo:[1,0,0] neg_hi:[1,0,0]
	v_pk_fma_f32 v[16:17], v[194:195], v[16:17], v[68:69] op_sel_hi:[0,1,1]
	v_mul_f32_e32 v16, 0xbfb8aa3b, v16
	v_exp_f32_e32 v16, v16
	v_pk_fma_f32 v[18:19], v[192:193], v[66:67], v[18:19] op_sel_hi:[0,1,1] neg_lo:[1,0,0] neg_hi:[1,0,0]
	s_waitcnt vmcnt(0)
; __device__ __forceinline__ unsigned cvt_pk_bf16(float lo, float hi) { unsigned r; asm("v_cvt_pk_bf16_f32 %0, %1, %2" : "=v"(r) : "v"(lo), "v"(hi)); return r; }
; __device__ __forceinline__ float fast_sigmoid(float v) { return __builtin_amdgcn_rcpf(1.0f + __builtin_amdgcn_exp2f(-1.4426950408889634f * v)); }
;     __device__ __forceinline__ void operator()(const f32x4 (&acc)[2][2][4][2], const Unit& u, int wr, int wc, int fr_in, int fq_in) const {
;     ...
;             for (int am = 0; am < (FINAL ? 8 : 4); ++am) { constexpr int GR = FINAL ? 1 : 2; const int ai = (am * GR) >> 2; u32x4 ppw[4], pzw[4];
; #pragma unroll
;                 for (int m = (am * GR) & 3; m < ((am * GR) & 3) + GR; ++m) { const size_t off = (size_t)(row0 + ai * HALF + m * 16) * 1024 + col0 + bj * HALF; ppw[m] = *(const u32x4*)(pexb + off); pzw[m] = *(const u32x4*)(zb + off); }
;                 asm volatile("" ::: "memory");
; #pragma unroll
;                 for (int m = (am * GR) & 3; m < ((am * GR) & 3) + GR; ++m) { const size_t off = (size_t)(row0 + ai * HALF + m * 16) * 1024 + col0 + bj * HALF; const float mu = rst.mu[ai][m], rs = rst.rs[ai][m];
;                     const u32x4 pw = ppw[m]; const u32x4 zw = pzw[m];
;                     const f32x4 x0 = ((f32x4){bf_lo(zw.x), bf_hi(zw.x), bf_lo(zw.y), bf_hi(zw.y)} - mu) * rs * gv[0] + bv[0], x1 = ((f32x4){bf_lo(zw.z), bf_hi(zw.z), bf_lo(zw.w), bf_hi(zw.w)} - mu) * rs * gv[1] + bv[1];
;                     const f32x4 a0 = ln_fix(acc[ai][bj][m][0], mu, rs, csv[0], cbv[0]), a1 = ln_fix(acc[ai][bj][m][1], mu, rs, csv[1], cbv[1]); f32x4 o0, o1;
;                     o0[0] = x0[0] + fast_sigmoid(a0[0]) * bf_lo(pw.x); o0[1] = x0[1] + fast_sigmoid(a0[1]) * bf_hi(pw.x);
;                     o0[2] = x0[2] + fast_sigmoid(a0[2]) * bf_lo(pw.y); o0[3] = x0[3] + fast_sigmoid(a0[3]) * bf_hi(pw.y);
;                     o1[0] = x1[0] + fast_sigmoid(a1[0]) * bf_lo(pw.z); o1[1] = x1[1] + fast_sigmoid(a1[1]) * bf_hi(pw.z);
;                     o1[2] = x1[2] + fast_sigmoid(a1[2]) * bf_lo(pw.w); o1[3] = x1[3] + fast_sigmoid(a1[3]) * bf_hi(pw.w);
;                     if constexpr (FINAL) { *(f32x4*)(outf + off) = o0; *(f32x4*)(outf + off + 4) = o1; }
;                     else { u32x4 w; w.x = cvt_pk_bf16(o0[0], o0[1]); w.y = cvt_pk_bf16(o0[2], o0[3]); w.z = cvt_pk_bf16(o1[0], o1[1]); w.w = cvt_pk_bf16(o1[2], o1[3]); *(u32x4*)(pexb + off) = w; } } } }
	v_lshlrev_b32_e32 v100, 16, v56
	v_and_b32_e32 v56, 0xffff0000, v56
	v_add_f32_e32 v16, 1.0, v16
	v_rcp_f32_e32 v16, v16
	v_lshlrev_b32_e32 v96, 16, v60
	v_and_b32_e32 v97, 0xffff0000, v60
	v_sub_f32_e32 v97, v97, v204
	v_sub_f32_e32 v96, v96, v204
	v_pk_mul_f32 v[96:97], v[206:207], v[96:97] op_sel_hi:[0,1]
	v_pk_fma_f32 v[96:97], v[88:89], v[96:97], v[92:93]
	v_lshlrev_b32_e32 v60, 16, v61
	v_fmac_f32_e32 v97, v45, v56
	v_mul_f32_e32 v45, 0xbfb8aa3b, v46
	v_exp_f32_e32 v45, v45
	v_and_b32_e32 v61, 0xffff0000, v61
	v_sub_f32_e32 v61, v61, v204
	v_sub_f32_e32 v60, v60, v204
	v_add_f32_e32 v45, 1.0, v45
	v_rcp_f32_e32 v45, v45
	v_pk_mul_f32 v[60:61], v[206:207], v[60:61] op_sel_hi:[0,1]
	v_pk_fma_f32 v[60:61], v[90:91], v[60:61], v[94:95]
	v_lshlrev_b32_e32 v46, 16, v57
	v_fma_f32 v45, v45, v46, v60
	v_mul_f32_e32 v46, 0xbfb8aa3b, v47
	v_exp_f32_e32 v46, v46
	v_lshlrev_b32_e32 v98, 16, v62
	v_and_b32_e32 v99, 0xffff0000, v62
	v_sub_f32_e32 v99, v99, v204
	v_add_f32_e32 v46, 1.0, v46
	v_rcp_f32_e32 v46, v46
	v_sub_f32_e32 v98, v98, v204
	v_pk_mul_f32 v[98:99], v[206:207], v[98:99] op_sel_hi:[0,1]
	v_and_b32_e32 v47, 0xffff0000, v57
	v_pk_fma_f32 v[98:99], v[80:81], v[98:99], v[84:85]
	v_fmac_f32_e32 v61, v46, v47
	v_lshlrev_b32_e32 v46, 16, v58
	v_fma_f32 v46, v40, v46, v98
	v_mul_f32_e32 v40, 0xbfb8aa3b, v41
	v_exp_f32_e32 v40, v40
	v_and_b32_e32 v41, 0xffff0000, v58
	v_lshlrev_b32_e32 v62, 16, v63
	v_and_b32_e32 v63, 0xffff0000, v63
	v_add_f32_e32 v40, 1.0, v40
	v_rcp_f32_e32 v40, v40
	v_sub_f32_e32 v63, v63, v204
	v_sub_f32_e32 v62, v62, v204
	v_pk_mul_f32 v[62:63], v[206:207], v[62:63] op_sel_hi:[0,1]
	v_fmac_f32_e32 v99, v40, v41
	v_mul_f32_e32 v40, 0xbfb8aa3b, v42
	v_exp_f32_e32 v40, v40
	v_pk_fma_f32 v[62:63], v[82:83], v[62:63], v[86:87]
	v_lshlrev_b32_e32 v41, 16, v59
	v_cvt_pk_bf16_f32 v42, v46, v99
	v_add_f32_e32 v40, 1.0, v40
	v_rcp_f32_e32 v40, v40
	v_fma_f32 v44, v44, v100, v96
	v_lshlrev_b32_e32 v46, 16, v54
	v_sub_f32_e32 v46, v46, v200
	v_fma_f32 v47, v40, v41, v62
	v_mul_f32_e32 v40, 0xbfb8aa3b, v43
	v_exp_f32_e32 v40, v40
	v_and_b32_e32 v41, 0xffff0000, v59
	v_pk_fma_f32 v[18:19], v[194:195], v[18:19], v[70:71] op_sel_hi:[0,1,1]
	v_pk_fma_f32 v[12:13], v[188:189], v[72:73], v[12:13] op_sel_hi:[0,1,1] neg_lo:[1,0,0] neg_hi:[1,0,0]
	v_add_f32_e32 v40, 1.0, v40
	v_rcp_f32_e32 v40, v40
	v_pk_fma_f32 v[12:13], v[190:191], v[12:13], v[76:77] op_sel_hi:[0,1,1]
	v_mul_f32_e32 v13, 0xbfb8aa3b, v13
	v_exp_f32_e32 v13, v13
	v_fmac_f32_e32 v63, v40, v41
	v_cvt_pk_bf16_f32 v43, v47, v63
	v_cvt_pk_bf16_f32 v40, v44, v97
	v_cvt_pk_bf16_f32 v41, v45, v61
	global_store_dwordx4 v[132:133], v[40:43], off offset:256
	v_and_b32_e32 v47, 0xffff0000, v54
	v_sub_f32_e32 v47, v47, v200
	v_lshlrev_b32_e32 v42, 16, v52
	v_and_b32_e32 v43, 0xffff0000, v52
	v_sub_f32_e32 v43, v43, v200
	v_sub_f32_e32 v42, v42, v200
	v_pk_mul_f32 v[42:43], v[202:203], v[42:43] op_sel_hi:[0,1]
	v_pk_fma_f32 v[42:43], v[88:89], v[42:43], v[92:93]
	v_lshlrev_b32_e32 v52, 16, v48
	v_fma_f32 v36, v36, v52, v42
	v_and_b32_e32 v42, 0xffff0000, v48
	v_fmac_f32_e32 v43, v37, v42
	v_mul_f32_e32 v37, 0xbfb8aa3b, v38
	v_exp_f32_e32 v37, v37
	v_lshlrev_b32_e32 v40, 16, v53
	v_and_b32_e32 v41, 0xffff0000, v53
	v_sub_f32_e32 v41, v41, v200
	v_add_f32_e32 v37, 1.0, v37
	v_rcp_f32_e32 v37, v37
	v_sub_f32_e32 v40, v40, v200
	v_pk_mul_f32 v[40:41], v[202:203], v[40:41] op_sel_hi:[0,1]
	v_pk_fma_f32 v[40:41], v[90:91], v[40:41], v[94:95]
	v_lshlrev_b32_e32 v38, 16, v49
	v_fma_f32 v37, v37, v38, v40
	v_mul_f32_e32 v38, 0xbfb8aa3b, v39
	v_exp_f32_e32 v38, v38
	v_pk_mul_f32 v[46:47], v[202:203], v[46:47] op_sel_hi:[0,1]
	v_and_b32_e32 v39, 0xffff0000, v49
	v_pk_fma_f32 v[46:47], v[80:81], v[46:47], v[84:85]
	v_add_f32_e32 v38, 1.0, v38
	v_rcp_f32_e32 v38, v38
	v_lshlrev_b32_e32 v44, 16, v55
	v_and_b32_e32 v45, 0xffff0000, v55
	v_sub_f32_e32 v45, v45, v200
	v_fmac_f32_e32 v41, v38, v39
	v_lshlrev_b32_e32 v38, 16, v50
	v_fma_f32 v38, v32, v38, v46
	v_mul_f32_e32 v32, 0xbfb8aa3b, v33
	v_exp_f32_e32 v32, v32
	v_and_b32_e32 v33, 0xffff0000, v50
	v_sub_f32_e32 v44, v44, v200
	v_pk_mul_f32 v[44:45], v[202:203], v[44:45] op_sel_hi:[0,1]
	v_add_f32_e32 v32, 1.0, v32
	v_rcp_f32_e32 v32, v32
	v_pk_fma_f32 v[44:45], v[82:83], v[44:45], v[86:87]
	v_add_f32_e32 v13, 1.0, v13
	v_rcp_f32_e32 v13, v13
	v_fmac_f32_e32 v47, v32, v33
	v_mul_f32_e32 v32, 0xbfb8aa3b, v34
	v_exp_f32_e32 v32, v32
	v_lshlrev_b32_e32 v33, 16, v51
	v_cvt_pk_bf16_f32 v34, v38, v47
	v_pk_fma_f32 v[14:15], v[188:189], v[74:75], v[14:15] op_sel_hi:[0,1,1] neg_lo:[1,0,0] neg_hi:[1,0,0]
	v_add_f32_e32 v32, 1.0, v32
	v_rcp_f32_e32 v32, v32
	v_pk_fma_f32 v[14:15], v[190:191], v[14:15], v[78:79] op_sel_hi:[0,1,1]
	v_pk_fma_f32 v[8:9], v[188:189], v[64:65], v[8:9] op_sel_hi:[0,1,1] neg_lo:[1,0,0] neg_hi:[1,0,0]
	v_pk_fma_f32 v[8:9], v[190:191], v[8:9], v[68:69] op_sel_hi:[0,1,1]
	v_fma_f32 v39, v32, v33, v44
	v_mul_f32_e32 v32, 0xbfb8aa3b, v35
	v_exp_f32_e32 v32, v32
	v_and_b32_e32 v33, 0xffff0000, v51
	v_mul_f32_e32 v8, 0xbfb8aa3b, v8
	v_exp_f32_e32 v8, v8
	v_add_f32_e32 v32, 1.0, v32
	v_rcp_f32_e32 v32, v32
	v_pk_fma_f32 v[10:11], v[188:189], v[66:67], v[10:11] op_sel_hi:[0,1,1] neg_lo:[1,0,0] neg_hi:[1,0,0]
	v_add_f32_e32 v8, 1.0, v8
	v_rcp_f32_e32 v8, v8
	v_fmac_f32_e32 v45, v32, v33
	v_cvt_pk_bf16_f32 v32, v36, v43
	v_cvt_pk_bf16_f32 v33, v37, v41
	v_cvt_pk_bf16_f32 v35, v39, v45
	global_store_dwordx4 v[134:135], v[32:35], off offset:256
	global_load_dwordx4 v[40:43], v[148:149], off offset:256
	v_lshl_add_u64 v[36:37], v[110:111], 0, v[146:147]
	v_lshl_add_u64 v[32:33], v[110:111], 0, v[144:145]
	v_lshl_add_u64 v[32:33], v[32:33], 1, s[40:41]
	global_load_dwordx4 v[44:47], v[32:33], off
	v_lshl_add_u64 v[36:37], v[36:37], 1, s[40:41]
	global_load_dwordx4 v[36:39], v[36:37], off
	v_pk_fma_f32 v[10:11], v[190:191], v[10:11], v[70:71] op_sel_hi:[0,1,1]
	global_load_dwordx4 v[32:35], v[118:119], off offset:256
	v_mul_f32_e32 v12, 0xbfb8aa3b, v12
	v_exp_f32_e32 v12, v12
	v_pk_fma_f32 v[4:5], v[184:185], v[72:73], v[4:5] op_sel_hi:[0,1,1] neg_lo:[1,0,0] neg_hi:[1,0,0]
	v_pk_fma_f32 v[4:5], v[186:187], v[4:5], v[76:77] op_sel_hi:[0,1,1]
	v_mul_f32_e32 v4, 0xbfb8aa3b, v4
	v_add_f32_e32 v12, 1.0, v12
	v_exp_f32_e32 v4, v4
	v_mul_f32_e32 v5, 0xbfb8aa3b, v5
	v_rcp_f32_e32 v12, v12
	v_exp_f32_e32 v5, v5
	v_add_f32_e32 v4, 1.0, v4
	v_rcp_f32_e32 v4, v4
	v_pk_fma_f32 v[6:7], v[184:185], v[74:75], v[6:7] op_sel_hi:[0,1,1] neg_lo:[1,0,0] neg_hi:[1,0,0]
	v_add_f32_e32 v5, 1.0, v5
	v_rcp_f32_e32 v5, v5
	v_pk_fma_f32 v[6:7], v[186:187], v[6:7], v[78:79] op_sel_hi:[0,1,1]
	v_pk_fma_f32 v[0:1], v[184:185], v[64:65], v[0:1] op_sel_hi:[0,1,1] neg_lo:[1,0,0] neg_hi:[1,0,0]
	v_pk_fma_f32 v[0:1], v[186:187], v[0:1], v[68:69] op_sel_hi:[0,1,1]
	v_mul_f32_e32 v0, 0xbfb8aa3b, v0
	v_exp_f32_e32 v0, v0
	v_pk_fma_f32 v[2:3], v[184:185], v[66:67], v[2:3] op_sel_hi:[0,1,1] neg_lo:[1,0,0] neg_hi:[1,0,0]
	v_pk_fma_f32 v[2:3], v[186:187], v[2:3], v[70:71] op_sel_hi:[0,1,1]
	v_add_f32_e32 v0, 1.0, v0
	v_rcp_f32_e32 v0, v0
	s_waitcnt vmcnt(0)
; __device__ __forceinline__ unsigned cvt_pk_bf16(float lo, float hi) { unsigned r; asm("v_cvt_pk_bf16_f32 %0, %1, %2" : "=v"(r) : "v"(lo), "v"(hi)); return r; }
; __device__ __forceinline__ float fast_sigmoid(float v) { return __builtin_amdgcn_rcpf(1.0f + __builtin_amdgcn_exp2f(-1.4426950408889634f * v)); }
;     __device__ __forceinline__ void operator()(const f32x4 (&acc)[2][2][4][2], const Unit& u, int wr, int wc, int fr_in, int fq_in) const {
;     ...
;             for (int am = 0; am < (FINAL ? 8 : 4); ++am) { constexpr int GR = FINAL ? 1 : 2; const int ai = (am * GR) >> 2; u32x4 ppw[4], pzw[4];
; #pragma unroll
;                 for (int m = (am * GR) & 3; m < ((am * GR) & 3) + GR; ++m) { const size_t off = (size_t)(row0 + ai * HALF + m * 16) * 1024 + col0 + bj * HALF; ppw[m] = *(const u32x4*)(pexb + off); pzw[m] = *(const u32x4*)(zb + off); }
;                 asm volatile("" ::: "memory");
; #pragma unroll
;                 for (int m = (am * GR) & 3; m < ((am * GR) & 3) + GR; ++m) { const size_t off = (size_t)(row0 + ai * HALF + m * 16) * 1024 + col0 + bj * HALF; const float mu = rst.mu[ai][m], rs = rst.rs[ai][m];
;                     const u32x4 pw = ppw[m]; const u32x4 zw = pzw[m];
;                     const f32x4 x0 = ((f32x4){bf_lo(zw.x), bf_hi(zw.x), bf_lo(zw.y), bf_hi(zw.y)} - mu) * rs * gv[0] + bv[0], x1 = ((f32x4){bf_lo(zw.z), bf_hi(zw.z), bf_lo(zw.w), bf_hi(zw.w)} - mu) * rs * gv[1] + bv[1];
;                     const f32x4 a0 = ln_fix(acc[ai][bj][m][0], mu, rs, csv[0], cbv[0]), a1 = ln_fix(acc[ai][bj][m][1], mu, rs, csv[1], cbv[1]); f32x4 o0, o1;
;                     o0[0] = x0[0] + fast_sigmoid(a0[0]) * bf_lo(pw.x); o0[1] = x0[1] + fast_sigmoid(a0[1]) * bf_hi(pw.x);
;                     o0[2] = x0[2] + fast_sigmoid(a0[2]) * bf_lo(pw.y); o0[3] = x0[3] + fast_sigmoid(a0[3]) * bf_hi(pw.y);
;                     o1[0] = x1[0] + fast_sigmoid(a1[0]) * bf_lo(pw.z); o1[1] = x1[1] + fast_sigmoid(a1[1]) * bf_hi(pw.z);
;                     o1[2] = x1[2] + fast_sigmoid(a1[2]) * bf_lo(pw.w); o1[3] = x1[3] + fast_sigmoid(a1[3]) * bf_hi(pw.w);
;                     if constexpr (FINAL) { *(f32x4*)(outf + off) = o0; *(f32x4*)(outf + off + 4) = o1; }
;                     else { u32x4 w; w.x = cvt_pk_bf16(o0[0], o0[1]); w.y = cvt_pk_bf16(o0[2], o0[3]); w.z = cvt_pk_bf16(o1[0], o1[1]); w.w = cvt_pk_bf16(o1[2], o1[3]); *(u32x4*)(pexb + off) = w; } } } }
	v_lshlrev_b32_e32 v52, 16, v40
	v_and_b32_e32 v40, 0xffff0000, v40
	v_lshlrev_b32_e32 v48, 16, v44
	v_and_b32_e32 v49, 0xffff0000, v44
	v_sub_f32_e32 v49, v49, v196
	v_sub_f32_e32 v48, v48, v196
	v_pk_mul_f32 v[48:49], v[198:199], v[48:49] op_sel_hi:[0,1]
	v_pk_fma_f32 v[48:49], v[88:89], v[48:49], v[92:93]
	v_lshlrev_b32_e32 v44, 16, v45
	v_fmac_f32_e32 v49, v29, v40
	v_mul_f32_e32 v29, 0xbfb8aa3b, v30
	v_exp_f32_e32 v29, v29
	v_and_b32_e32 v45, 0xffff0000, v45
	v_sub_f32_e32 v45, v45, v196
	v_sub_f32_e32 v44, v44, v196
	v_add_f32_e32 v29, 1.0, v29
	v_rcp_f32_e32 v29, v29
	v_pk_mul_f32 v[44:45], v[198:199], v[44:45] op_sel_hi:[0,1]
	v_pk_fma_f32 v[44:45], v[90:91], v[44:45], v[94:95]
	v_lshlrev_b32_e32 v30, 16, v41
	v_fma_f32 v29, v29, v30, v44
	v_mul_f32_e32 v30, 0xbfb8aa3b, v31
	v_exp_f32_e32 v30, v30
	v_lshlrev_b32_e32 v50, 16, v46
	v_and_b32_e32 v51, 0xffff0000, v46
	v_sub_f32_e32 v51, v51, v196
	v_add_f32_e32 v30, 1.0, v30
	v_rcp_f32_e32 v30, v30
	v_sub_f32_e32 v50, v50, v196
	v_pk_mul_f32 v[50:51], v[198:199], v[50:51] op_sel_hi:[0,1]
	v_and_b32_e32 v31, 0xffff0000, v41
	v_pk_fma_f32 v[50:51], v[80:81], v[50:51], v[84:85]
	v_fmac_f32_e32 v45, v30, v31
	v_lshlrev_b32_e32 v30, 16, v42
	v_fma_f32 v30, v24, v30, v50
	v_mul_f32_e32 v24, 0xbfb8aa3b, v25
	v_exp_f32_e32 v24, v24
	v_and_b32_e32 v25, 0xffff0000, v42
	v_lshlrev_b32_e32 v46, 16, v47
	v_and_b32_e32 v47, 0xffff0000, v47
	v_add_f32_e32 v24, 1.0, v24
	v_rcp_f32_e32 v24, v24
	v_sub_f32_e32 v47, v47, v196
	v_sub_f32_e32 v46, v46, v196
	v_pk_mul_f32 v[46:47], v[198:199], v[46:47] op_sel_hi:[0,1]
	v_fmac_f32_e32 v51, v24, v25
	v_mul_f32_e32 v24, 0xbfb8aa3b, v26
	v_exp_f32_e32 v24, v24
	v_pk_fma_f32 v[46:47], v[82:83], v[46:47], v[86:87]
	v_lshlrev_b32_e32 v25, 16, v43
	v_cvt_pk_bf16_f32 v26, v30, v51
	v_add_f32_e32 v24, 1.0, v24
	v_rcp_f32_e32 v24, v24
	v_fma_f32 v28, v28, v52, v48
	v_lshlrev_b32_e32 v30, 16, v38
	v_sub_f32_e32 v30, v30, v192
	v_fma_f32 v31, v24, v25, v46
	v_mul_f32_e32 v24, 0xbfb8aa3b, v27
	v_exp_f32_e32 v24, v24
	v_and_b32_e32 v25, 0xffff0000, v43
	v_add_f32_e32 v24, 1.0, v24
	v_rcp_f32_e32 v24, v24
	s_nop 0
	v_fmac_f32_e32 v47, v24, v25
	v_cvt_pk_bf16_f32 v27, v31, v47
	v_cvt_pk_bf16_f32 v24, v28, v49
	v_cvt_pk_bf16_f32 v25, v29, v45
	global_store_dwordx4 v[148:149], v[24:27], off offset:256
	v_and_b32_e32 v31, 0xffff0000, v38
	v_sub_f32_e32 v31, v31, v192
	v_lshlrev_b32_e32 v26, 16, v36
	v_and_b32_e32 v27, 0xffff0000, v36
	v_sub_f32_e32 v27, v27, v192
	v_sub_f32_e32 v26, v26, v192
	v_pk_mul_f32 v[26:27], v[194:195], v[26:27] op_sel_hi:[0,1]
	v_pk_fma_f32 v[26:27], v[88:89], v[26:27], v[92:93]
	v_lshlrev_b32_e32 v36, 16, v32
	v_fma_f32 v20, v20, v36, v26
	v_and_b32_e32 v26, 0xffff0000, v32
	v_fmac_f32_e32 v27, v21, v26
	v_mul_f32_e32 v21, 0xbfb8aa3b, v22
	v_exp_f32_e32 v21, v21
	v_lshlrev_b32_e32 v24, 16, v37
	v_and_b32_e32 v25, 0xffff0000, v37
	v_sub_f32_e32 v25, v25, v192
	v_add_f32_e32 v21, 1.0, v21
	v_rcp_f32_e32 v21, v21
	v_sub_f32_e32 v24, v24, v192
	v_pk_mul_f32 v[24:25], v[194:195], v[24:25] op_sel_hi:[0,1]
	v_pk_fma_f32 v[24:25], v[90:91], v[24:25], v[94:95]
	v_lshlrev_b32_e32 v22, 16, v33
	v_fma_f32 v21, v21, v22, v24
	v_mul_f32_e32 v22, 0xbfb8aa3b, v23
	v_exp_f32_e32 v22, v22
	v_pk_mul_f32 v[30:31], v[194:195], v[30:31] op_sel_hi:[0,1]
	v_and_b32_e32 v23, 0xffff0000, v33
	v_pk_fma_f32 v[30:31], v[80:81], v[30:31], v[84:85]
	v_add_f32_e32 v22, 1.0, v22
	v_rcp_f32_e32 v22, v22
	v_lshlrev_b32_e32 v28, 16, v39
	v_and_b32_e32 v29, 0xffff0000, v39
	v_sub_f32_e32 v29, v29, v192
	v_fmac_f32_e32 v25, v22, v23
	v_lshlrev_b32_e32 v22, 16, v34
	v_fma_f32 v22, v16, v22, v30
	v_mul_f32_e32 v16, 0xbfb8aa3b, v17
	v_exp_f32_e32 v16, v16
	v_and_b32_e32 v17, 0xffff0000, v34
	v_sub_f32_e32 v28, v28, v192
	v_pk_mul_f32 v[28:29], v[194:195], v[28:29] op_sel_hi:[0,1]
	v_add_f32_e32 v16, 1.0, v16
	v_rcp_f32_e32 v16, v16
	v_pk_fma_f32 v[28:29], v[82:83], v[28:29], v[86:87]
	v_fmac_f32_e32 v31, v16, v17
	v_mul_f32_e32 v16, 0xbfb8aa3b, v18
	v_exp_f32_e32 v16, v16
	v_lshlrev_b32_e32 v17, 16, v35
	v_cvt_pk_bf16_f32 v18, v22, v31
	v_add_f32_e32 v16, 1.0, v16
	v_rcp_f32_e32 v16, v16
	s_nop 0
	v_fma_f32 v23, v16, v17, v28
	v_mul_f32_e32 v16, 0xbfb8aa3b, v19
	v_exp_f32_e32 v16, v16
	v_and_b32_e32 v17, 0xffff0000, v35
	v_add_f32_e32 v16, 1.0, v16
	v_rcp_f32_e32 v16, v16
	s_nop 0
	v_fmac_f32_e32 v29, v16, v17
	v_cvt_pk_bf16_f32 v16, v20, v27
	v_cvt_pk_bf16_f32 v17, v21, v25
	v_cvt_pk_bf16_f32 v19, v23, v29
	global_store_dwordx4 v[118:119], v[16:19], off offset:256
	global_load_dwordx4 v[24:27], v[150:151], off offset:256
	v_lshl_add_u64 v[20:21], v[110:111], 0, v[130:131]
	v_lshl_add_u64 v[16:17], v[110:111], 0, v[128:129]
	v_lshl_add_u64 v[16:17], v[16:17], 1, s[40:41]
	global_load_dwordx4 v[28:31], v[16:17], off
	v_lshl_add_u64 v[20:21], v[20:21], 1, s[40:41]
	global_load_dwordx4 v[20:23], v[20:21], off
	s_waitcnt vmcnt(0)
;     __device__ __forceinline__ void operator()(const f32x4 (&acc)[2][2][4][2], const Unit& u, int wr, int wc, int fr_in, int fq_in) const {
;     ...
;             for (int am = 0; am < (FINAL ? 8 : 4); ++am) { constexpr int GR = FINAL ? 1 : 2; const int ai = (am * GR) >> 2; u32x4 ppw[4], pzw[4];
; #pragma unroll
;                 for (int m = (am * GR) & 3; m < ((am * GR) & 3) + GR; ++m) { const size_t off = (size_t)(row0 + ai * HALF + m * 16) * 1024 + col0 + bj * HALF; ppw[m] = *(const u32x4*)(pexb + off); pzw[m] = *(const u32x4*)(zb + off); }
;                 asm volatile("" ::: "memory");
; #pragma unroll
;                 for (int m = (am * GR) & 3; m < ((am * GR) & 3) + GR; ++m) { const size_t off = (size_t)(row0 + ai * HALF + m * 16) * 1024 + col0 + bj * HALF; const float mu = rst.mu[ai][m], rs = rst.rs[ai][m];
;                     const u32x4 pw = ppw[m]; const u32x4 zw = pzw[m];
;                     const f32x4 x0 = ((f32x4){bf_lo(zw.x), bf_hi(zw.x), bf_lo(zw.y), bf_hi(zw.y)} - mu) * rs * gv[0] + bv[0], x1 = ((f32x4){bf_lo(zw.z), bf_hi(zw.z), bf_lo(zw.w), bf_hi(zw.w)} - mu) * rs * gv[1] + bv[1];
;                     const f32x4 a0 = ln_fix(acc[ai][bj][m][0], mu, rs, csv[0], cbv[0]), a1 = ln_fix(acc[ai][bj][m][1], mu, rs, csv[1], cbv[1]); f32x4 o0, o1;
;                     o0[0] = x0[0] + fast_sigmoid(a0[0]) * bf_lo(pw.x); o0[1] = x0[1] + fast_sigmoid(a0[1]) * bf_hi(pw.x);
;                     o0[2] = x0[2] + fast_sigmoid(a0[2]) * bf_lo(pw.y); o0[3] = x0[3] + fast_sigmoid(a0[3]) * bf_hi(pw.y);
;                     o1[0] = x1[0] + fast_sigmoid(a1[0]) * bf_lo(pw.z); o1[1] = x1[1] + fast_sigmoid(a1[1]) * bf_hi(pw.z);
;                     o1[2] = x1[2] + fast_sigmoid(a1[2]) * bf_lo(pw.w); o1[3] = x1[3] + fast_sigmoid(a1[3]) * bf_hi(pw.w);
;                     if constexpr (FINAL) { *(f32x4*)(outf + off) = o0; *(f32x4*)(outf + off + 4) = o1; }
;                     else { u32x4 w; w.x = cvt_pk_bf16(o0[0], o0[1]); w.y = cvt_pk_bf16(o0[2], o0[3]); w.z = cvt_pk_bf16(o1[0], o1[1]); w.w = cvt_pk_bf16(o1[2], o1[3]); *(u32x4*)(pexb + off) = w; } } } }
; template <class Epi, class Sched, bool ALIGN_EPI = false, bool SP2 = false>
; __device__ __forceinline__ void gemm_phase(PG8_LAS unsigned char* lds, const Gemm g, const Sched& S, const Epi& E) {
;     ...
;         cur = nxt; cA = nA; cB = nB; ++ui;
;         if constexpr (ALIGN_EPI) { if (wr == 1) PG8_BAR; }
	v_lshlrev_b32_e32 v32, 16, v28
	global_load_dwordx4 v[16:19], v[108:109], off offset:256
	v_and_b32_e32 v33, 0xffff0000, v28
	v_sub_f32_e32 v33, v33, v188
	v_sub_f32_e32 v32, v32, v188
	v_pk_mul_f32 v[32:33], v[190:191], v[32:33] op_sel_hi:[0,1]
	v_pk_fma_f32 v[32:33], v[88:89], v[32:33], v[92:93]
	v_lshlrev_b32_e32 v36, 16, v24
	v_and_b32_e32 v24, 0xffff0000, v24
	v_fmac_f32_e32 v33, v13, v24
	v_mul_f32_e32 v13, 0xbfb8aa3b, v14
	v_exp_f32_e32 v13, v13
	v_lshlrev_b32_e32 v28, 16, v29
	v_and_b32_e32 v29, 0xffff0000, v29
	v_sub_f32_e32 v29, v29, v188
	v_add_f32_e32 v13, 1.0, v13
	v_rcp_f32_e32 v13, v13
	v_sub_f32_e32 v28, v28, v188
	v_pk_mul_f32 v[28:29], v[190:191], v[28:29] op_sel_hi:[0,1]
	v_pk_fma_f32 v[28:29], v[90:91], v[28:29], v[94:95]
	v_lshlrev_b32_e32 v14, 16, v25
	v_fma_f32 v13, v13, v14, v28
	v_mul_f32_e32 v14, 0xbfb8aa3b, v15
	v_exp_f32_e32 v14, v14
	v_lshlrev_b32_e32 v34, 16, v30
	v_and_b32_e32 v35, 0xffff0000, v30
	v_sub_f32_e32 v35, v35, v188
	v_add_f32_e32 v14, 1.0, v14
	v_rcp_f32_e32 v14, v14
	v_sub_f32_e32 v34, v34, v188
	v_pk_mul_f32 v[34:35], v[190:191], v[34:35] op_sel_hi:[0,1]
	v_and_b32_e32 v15, 0xffff0000, v25
	v_pk_fma_f32 v[34:35], v[80:81], v[34:35], v[84:85]
	v_fmac_f32_e32 v29, v14, v15
	v_lshlrev_b32_e32 v14, 16, v26
	v_fma_f32 v14, v8, v14, v34
	v_mul_f32_e32 v8, 0xbfb8aa3b, v9
	v_exp_f32_e32 v8, v8
	v_and_b32_e32 v9, 0xffff0000, v26
	v_lshlrev_b32_e32 v30, 16, v31
	v_and_b32_e32 v31, 0xffff0000, v31
	v_add_f32_e32 v8, 1.0, v8
	v_rcp_f32_e32 v8, v8
	v_sub_f32_e32 v31, v31, v188
	v_sub_f32_e32 v30, v30, v188
	v_pk_mul_f32 v[30:31], v[190:191], v[30:31] op_sel_hi:[0,1]
	v_fmac_f32_e32 v35, v8, v9
	v_mul_f32_e32 v8, 0xbfb8aa3b, v10
	v_exp_f32_e32 v8, v8
	v_pk_fma_f32 v[30:31], v[82:83], v[30:31], v[86:87]
	v_lshlrev_b32_e32 v9, 16, v27
	v_cvt_pk_bf16_f32 v10, v14, v35
	v_add_f32_e32 v8, 1.0, v8
	v_rcp_f32_e32 v8, v8
	v_fma_f32 v12, v12, v36, v32
	v_lshlrev_b32_e32 v14, 16, v22
	v_fma_f32 v15, v8, v9, v30
	v_mul_f32_e32 v8, 0xbfb8aa3b, v11
	v_exp_f32_e32 v8, v8
	v_and_b32_e32 v9, 0xffff0000, v27
	v_sub_f32_e32 v14, v14, v184
	v_add_f32_e32 v8, 1.0, v8
	v_rcp_f32_e32 v8, v8
	s_nop 0
	v_fmac_f32_e32 v31, v8, v9
	v_cvt_pk_bf16_f32 v11, v15, v31
	v_cvt_pk_bf16_f32 v8, v12, v33
	v_cvt_pk_bf16_f32 v9, v13, v29
	global_store_dwordx4 v[150:151], v[8:11], off offset:256
	v_and_b32_e32 v15, 0xffff0000, v22
	v_sub_f32_e32 v15, v15, v184
	v_lshlrev_b32_e32 v10, 16, v20
	v_and_b32_e32 v11, 0xffff0000, v20
	v_sub_f32_e32 v11, v11, v184
	v_sub_f32_e32 v10, v10, v184
	v_pk_mul_f32 v[10:11], v[186:187], v[10:11] op_sel_hi:[0,1]
	v_pk_fma_f32 v[10:11], v[88:89], v[10:11], v[92:93]
	s_waitcnt vmcnt(0)
	v_lshlrev_b32_e32 v20, 16, v16
	v_fma_f32 v4, v4, v20, v10
	v_and_b32_e32 v10, 0xffff0000, v16
	v_fmac_f32_e32 v11, v5, v10
	v_mul_f32_e32 v5, 0xbfb8aa3b, v6
	v_exp_f32_e32 v5, v5
	v_lshlrev_b32_e32 v8, 16, v21
	v_and_b32_e32 v9, 0xffff0000, v21
	v_sub_f32_e32 v9, v9, v184
	v_add_f32_e32 v5, 1.0, v5
	v_rcp_f32_e32 v5, v5
	v_sub_f32_e32 v8, v8, v184
	v_pk_mul_f32 v[8:9], v[186:187], v[8:9] op_sel_hi:[0,1]
	v_pk_fma_f32 v[8:9], v[90:91], v[8:9], v[94:95]
	v_lshlrev_b32_e32 v6, 16, v17
	v_fma_f32 v5, v5, v6, v8
	v_mul_f32_e32 v6, 0xbfb8aa3b, v7
	v_exp_f32_e32 v6, v6
	v_pk_mul_f32 v[14:15], v[186:187], v[14:15] op_sel_hi:[0,1]
	v_and_b32_e32 v7, 0xffff0000, v17
	v_pk_fma_f32 v[14:15], v[80:81], v[14:15], v[84:85]
	v_add_f32_e32 v6, 1.0, v6
	v_rcp_f32_e32 v6, v6
	v_lshlrev_b32_e32 v12, 16, v23
	v_and_b32_e32 v13, 0xffff0000, v23
	v_sub_f32_e32 v13, v13, v184
	v_fmac_f32_e32 v9, v6, v7
	v_lshlrev_b32_e32 v6, 16, v18
	v_fma_f32 v6, v0, v6, v14
	v_mul_f32_e32 v0, 0xbfb8aa3b, v1
	v_exp_f32_e32 v0, v0
	v_and_b32_e32 v1, 0xffff0000, v18
	v_sub_f32_e32 v12, v12, v184
	v_pk_mul_f32 v[12:13], v[186:187], v[12:13] op_sel_hi:[0,1]
	v_add_f32_e32 v0, 1.0, v0
	v_rcp_f32_e32 v0, v0
	v_pk_fma_f32 v[12:13], v[82:83], v[12:13], v[86:87]
	v_fmac_f32_e32 v15, v0, v1
	v_mul_f32_e32 v0, 0xbfb8aa3b, v2
	v_exp_f32_e32 v0, v0
	v_lshlrev_b32_e32 v1, 16, v19
	v_cvt_pk_bf16_f32 v2, v6, v15
	v_add_f32_e32 v0, 1.0, v0
	v_rcp_f32_e32 v0, v0
	s_nop 0
	v_fma_f32 v7, v0, v1, v12
	v_mul_f32_e32 v0, 0xbfb8aa3b, v3
	v_exp_f32_e32 v0, v0
	v_and_b32_e32 v1, 0xffff0000, v19
	v_add_f32_e32 v0, 1.0, v0
	v_rcp_f32_e32 v0, v0
	s_nop 0
	v_fmac_f32_e32 v13, v0, v1
	v_cvt_pk_bf16_f32 v0, v4, v11
	v_cvt_pk_bf16_f32 v1, v5, v9
	v_cvt_pk_bf16_f32 v3, v7, v13
	global_store_dwordx4 v[108:109], v[0:3], off offset:256
	s_cbranch_vccnz .LBB0_1446
	s_andn2_b64 vcc, exec, s[42:43]
	s_cbranch_vccnz .LBB0_1445
	s_barrier
	s_branch .LBB0_1445

; __device__ __forceinline__ void load_row_stats(const float* sp, int row0, RowStats& r) {
; #pragma unroll
;     for (int ai = 0; ai < 2; ++ai) { asm volatile("" ::: "memory");
; #pragma unroll
;         for (int m = 0; m < 4; ++m) { const float* p = sp + (size_t)(row0 + ai * HALF + m * 16) * 8; const f32x4 a = *(const f32x4*)p, b = *(const f32x4*)(p + 4);
;             const float s1 = (a[0] + a[2]) + (b[0] + b[2]), s2 = (a[1] + a[3]) + (b[1] + b[3]); const float mu = s1 * (1.f / 1024.f); const float var = s2 * (1.f / 1024.f) - mu * mu;
;             r.mu[ai][m] = mu; r.rs[ai][m] = __builtin_amdgcn_rsqf(__builtin_fmaxf(var, 0.f) + 1e-5f); } }
;     __device__ __forceinline__ void operator()(const f32x4 (&acc)[2][2][4][2], const Unit& u, int wr, int wc, int fr_in, int fq_in) const {
;     ...
;         const int row0 = u.pm * BM + wr * 64 + fr; const int t = u.pn >> 2; bf16_t* base = t ? V : U;
;         const int col0 = (u.pn & 3) * BM + wc * 32 + 8 * fq, n0 = u.pn * BM + wc * 32 + 8 * fq;
;         RowStats rst; load_row_stats(sp, row0, rst);
; #pragma unroll
;         for (int bj = 0; bj < 2; ++bj) { f32x4 csv[2], cbv[2];
; #pragma unroll
;             for (int n = 0; n < 2; ++n) { csv[n] = *(const f32x4*)(cs + n0 + bj * HALF + 4 * n); cbv[n] = *(const f32x4*)(cb + n0 + bj * HALF + 4 * n) + *(const f32x4*)(bias + n0 + bj * HALF + 4 * n); }
.LBB0_1698:
	s_lshl_b32 s10, s10, 8
	v_mov_b32_e32 v120, v171
	v_mov_b32_e32 v121, v175
	s_add_i32 s10, s10, s15
	s_cmp_lt_u32 s18, 4
	v_add_u32_e32 v222, s10, v120
	v_ashrrev_i32_e32 v223, 31, v222
	s_cselect_b32 s99, 1, 0
	v_readfirstlane_b32 s98, v254
	v_and_b32_e32 v124, 0xffffff00, v222
	s_nop 0
	s_cmpk_lt_u32 s98, 0x100
	s_cbranch_scc0 .Lrs5_skip
	v_add_u32_e32 v124, v124, v254
	v_mov_b32_e32 v125, 0
	v_lshlrev_b64 v[124:125], 5, v[124:125]
	v_lshl_add_u64 v[136:137], s[24:25], 0, v[124:125]
	global_load_dwordx4 v[124:127], v[136:137], off offset:16
	s_nop 0
	global_load_dwordx4 v[136:139], v[136:137], off
	s_waitcnt vmcnt(0)
	v_pk_add_f32 v[124:125], v[124:125], v[126:127]
	v_pk_add_f32 v[136:137], v[136:137], v[138:139]
	s_nop 0
	v_pk_add_f32 v[124:125], v[136:137], v[124:125]
	s_nop 0
	v_pk_mul_f32 v[124:125], v[124:125], s[42:43] op_sel_hi:[1,0]
	v_lshlrev_b32_e32 v126, 3, v254
	v_add_u32_e32 v126, 0x22400, v126
	ds_write_b64 v126, v[124:125]
.Lrs5_skip:
	s_waitcnt vmcnt(0) lgkmcnt(0)
	s_barrier
	v_and_b32_e32 v126, 0xff, v222
	v_lshlrev_b32_e32 v126, 3, v126
	v_add_u32_e32 v126, 0x22400, v126
	ds_read_b64 v[196:197], v126
	ds_read_b64 v[192:193], v126 offset:128
	ds_read_b64 v[188:189], v126 offset:256
	ds_read_b64 v[184:185], v126 offset:384
	ds_read_b64 v[180:181], v126 offset:1024
	ds_read_b64 v[176:177], v126 offset:1152
	ds_read_b64 v[172:173], v126 offset:1280
	ds_read_b64 v[168:169], v126 offset:1408
	s_cmp_lg_u32 s99, 0
	s_waitcnt lgkmcnt(0)
	v_add_u32_e32 v220, 16, v222
	v_ashrrev_i32_e32 v221, 31, v220
	v_add_u32_e32 v218, 32, v222
	v_ashrrev_i32_e32 v219, 31, v218
	v_add_u32_e32 v216, 48, v222
	v_ashrrev_i32_e32 v217, 31, v216
	v_add_u32_e32 v214, 0x80, v222
	v_ashrrev_i32_e32 v215, 31, v214
	v_add_u32_e32 v212, 0x90, v222
	v_ashrrev_i32_e32 v213, 31, v212
	v_add_u32_e32 v210, 0xa0, v222
	v_ashrrev_i32_e32 v211, 31, v210
	v_add_u32_e32 v208, 0xb0, v222
	v_ashrrev_i32_e32 v209, 31, v208
	v_lshlrev_b32_e32 v120, 3, v121
	s_mov_b32 s10, 0xbc00000
	s_cselect_b32 s10, s10, 0xfc00000
	s_add_u32 s10, s4, s10
	s_addc_u32 s11, s5, 0
	s_lshl_b32 s12, s18, 8
	s_and_b32 s13, s12, 0x300
	s_or_b32 s13, s13, s16
	s_or_b32 s12, s12, s16
	v_add_u32_e32 v122, s13, v120
	v_add_u32_e32 v120, s12, v120
	v_ashrrev_i32_e32 v123, 31, v122
	v_lshl_add_u64 v[202:203], v[122:123], 1, s[10:11]
	s_mov_b64 s[10:11], -1
	s_andn2_b64 vcc, exec, s[38:39]
	v_fma_f32 v121, -v196, v196, v197
	v_max_f32_e32 v121, 0, v121
	v_add_f32_e32 v121, 0x3727c5ac, v121
	v_rsq_f32_e32 v198, v121
	v_fma_f32 v121, -v192, v192, v193
	v_max_f32_e32 v121, 0, v121
	v_add_f32_e32 v121, 0x3727c5ac, v121
	v_rsq_f32_e32 v194, v121
	v_fma_f32 v121, -v188, v188, v189
	v_max_f32_e32 v121, 0, v121
	v_add_f32_e32 v121, 0x3727c5ac, v121
	v_rsq_f32_e32 v190, v121
	v_fma_f32 v121, -v184, v184, v185
	v_max_f32_e32 v121, 0, v121
	v_add_f32_e32 v121, 0x3727c5ac, v121
	v_rsq_f32_e32 v186, v121
	v_fma_f32 v121, -v180, v180, v181
	v_max_f32_e32 v121, 0, v121
	v_add_f32_e32 v121, 0x3727c5ac, v121
	v_rsq_f32_e32 v182, v121
	v_fma_f32 v121, -v176, v176, v177
	v_max_f32_e32 v121, 0, v121
	v_add_f32_e32 v121, 0x3727c5ac, v121
	v_rsq_f32_e32 v178, v121
	v_fma_f32 v121, -v172, v172, v173
	v_max_f32_e32 v121, 0, v121
	v_add_f32_e32 v121, 0x3727c5ac, v121
	v_rsq_f32_e32 v174, v121
	s_nop 0
	v_fma_f32 v121, -v168, v168, v169
	v_max_f32_e32 v121, 0, v121
	v_add_f32_e32 v121, 0x3727c5ac, v121
	v_rsq_f32_e32 v170, v121
	v_ashrrev_i32_e32 v121, 31, v120
	v_lshlrev_b64 v[120:121], 2, v[120:121]
	v_lshl_add_u64 v[204:205], s[26:27], 0, v[120:121]
	v_lshl_add_u64 v[206:207], s[28:29], 0, v[120:121]
	s_waitcnt lgkmcnt(0)
	v_lshl_add_u64 v[200:201], s[6:7], 0, v[120:121]
	global_load_dwordx4 v[120:123], v[204:205], off offset:16
	global_load_dwordx4 v[124:127], v[204:205], off
	global_load_dwordx4 v[136:139], v[206:207], off offset:16
	global_load_dwordx4 v[144:147], v[206:207], off
	global_load_dwordx4 v[140:143], v[200:201], off offset:16
	global_load_dwordx4 v[148:151], v[200:201], off
	s_waitcnt vmcnt(5)
	v_pk_fma_f32 v[128:129], v[196:197], v[120:121], v[128:129] op_sel_hi:[0,1,1] neg_lo:[1,0,0] neg_hi:[1,0,0]
	s_waitcnt vmcnt(4)
	v_pk_fma_f32 v[132:133], v[196:197], v[124:125], v[132:133] op_sel_hi:[0,1,1] neg_lo:[1,0,0] neg_hi:[1,0,0]
	v_pk_fma_f32 v[134:135], v[196:197], v[126:127], v[134:135] op_sel_hi:[0,1,1] neg_lo:[1,0,0] neg_hi:[1,0,0]
	v_pk_fma_f32 v[130:131], v[196:197], v[122:123], v[130:131] op_sel_hi:[0,1,1] neg_lo:[1,0,0] neg_hi:[1,0,0]
	s_waitcnt vmcnt(1)
	v_pk_add_f32 v[138:139], v[138:139], v[142:143]
	s_waitcnt vmcnt(0)
; __device__ __forceinline__ unsigned cvt_pk_bf16(float lo, float hi) { unsigned r; asm("v_cvt_pk_bf16_f32 %0, %1, %2" : "=v"(r) : "v"(lo), "v"(hi)); return r; }
; __device__ __forceinline__ float gelu_tanh(float v) { const float u = 0.7978845608028654f * (v + 0.044715f * v * v * v); return v * fast_sigmoid(2.0f * u); }
; __device__ __forceinline__ f32x4 ln_fix(const f32x4& a, float mu, float rs, const f32x4& cs, const f32x4& cb) { return (a - cs * mu) * rs + cb; }
; __device__ __forceinline__ float fast_sigmoid(float v) { return __builtin_amdgcn_rcpf(1.0f + __builtin_amdgcn_exp2f(-1.4426950408889634f * v)); }
;     __device__ __forceinline__ void operator()(const f32x4 (&acc)[2][2][4][2], const Unit& u, int wr, int wc, int fr_in, int fq_in) const {
;     ...
;                 for (int m = 0; m < 4; ++m) { bf16_t* rowp = base + (size_t)(row0 + ai * HALF + m * 16) * 1024 + col0 + bj * HALF;
;                     f32x4 v0 = ln_fix(acc[ai][bj][m][0], rst.mu[ai][m], rst.rs[ai][m], csv[0], cbv[0]), v1 = ln_fix(acc[ai][bj][m][1], rst.mu[ai][m], rst.rs[ai][m], csv[1], cbv[1]);
; #pragma unroll
;                     for (int j = 0; j < 4; ++j) { v0[j] = gelu_tanh(v0[j]); v1[j] = gelu_tanh(v1[j]); }
;                     u32x4 w; w.x = cvt_pk_bf16(v0[0], v0[1]); w.y = cvt_pk_bf16(v0[2], v0[3]); w.z = cvt_pk_bf16(v1[0], v1[1]); w.w = cvt_pk_bf16(v1[2], v1[3]);
;                     *(u32x4*)rowp = w; } }
	v_pk_add_f32 v[144:145], v[144:145], v[148:149]
	v_pk_add_f32 v[136:137], v[136:137], v[140:141]
	v_pk_fma_f32 v[132:133], v[198:199], v[132:133], v[144:145] op_sel_hi:[0,1,1]
	v_mul_f32_e32 v142, 0x3d372713, v132
	v_mul_f32_e32 v142, v132, v142
	v_fma_f32 v142, v132, v142, v132
	v_mul_f32_e32 v142, 0x3f4c422a, v142
	v_add_f32_e32 v142, v142, v142
	v_mul_f32_e32 v142, 0xbfb8aa3b, v142
	v_exp_f32_e32 v142, v142
	v_pk_fma_f32 v[128:129], v[198:199], v[128:129], v[136:137] op_sel_hi:[0,1,1]
	v_pk_add_f32 v[146:147], v[146:147], v[150:151]
	v_pk_fma_f32 v[130:131], v[198:199], v[130:131], v[138:139] op_sel_hi:[0,1,1]
	v_add_f32_e32 v142, 1.0, v142
	v_rcp_f32_e32 v142, v142
	v_pk_fma_f32 v[134:135], v[198:199], v[134:135], v[146:147] op_sel_hi:[0,1,1]
	v_lshlrev_b64 v[140:141], 11, v[222:223]
	v_pk_fma_f32 v[116:117], v[192:193], v[124:125], v[116:117] op_sel_hi:[0,1,1] neg_lo:[1,0,0] neg_hi:[1,0,0]
	v_mul_f32_e32 v132, v132, v142
	v_mul_f32_e32 v142, 0x3d372713, v128
	v_mul_f32_e32 v142, v128, v142
	v_fma_f32 v142, v128, v142, v128
	v_mul_f32_e32 v142, 0x3f4c422a, v142
	v_add_f32_e32 v142, v142, v142
	v_mul_f32_e32 v142, 0xbfb8aa3b, v142
	v_exp_f32_e32 v142, v142
	v_pk_fma_f32 v[116:117], v[194:195], v[116:117], v[144:145] op_sel_hi:[0,1,1]
	v_pk_fma_f32 v[112:113], v[192:193], v[120:121], v[112:113] op_sel_hi:[0,1,1] neg_lo:[1,0,0] neg_hi:[1,0,0]
	v_pk_fma_f32 v[112:113], v[194:195], v[112:113], v[136:137] op_sel_hi:[0,1,1]
	v_add_f32_e32 v142, 1.0, v142
	v_rcp_f32_e32 v142, v142
	v_pk_fma_f32 v[118:119], v[192:193], v[126:127], v[118:119] op_sel_hi:[0,1,1] neg_lo:[1,0,0] neg_hi:[1,0,0]
	v_pk_fma_f32 v[118:119], v[194:195], v[118:119], v[146:147] op_sel_hi:[0,1,1]
	v_pk_fma_f32 v[114:115], v[192:193], v[122:123], v[114:115] op_sel_hi:[0,1,1] neg_lo:[1,0,0] neg_hi:[1,0,0]
	v_mul_f32_e32 v142, v128, v142
	v_mul_f32_e32 v128, 0x3d372713, v133
	v_mul_f32_e32 v128, v133, v128
	v_fma_f32 v128, v133, v128, v133
	v_mul_f32_e32 v128, 0x3f4c422a, v128
	v_add_f32_e32 v128, v128, v128
	v_mul_f32_e32 v128, 0xbfb8aa3b, v128
	v_exp_f32_e32 v128, v128
	v_pk_fma_f32 v[114:115], v[194:195], v[114:115], v[138:139] op_sel_hi:[0,1,1]
	v_pk_fma_f32 v[108:109], v[188:189], v[124:125], v[108:109] op_sel_hi:[0,1,1] neg_lo:[1,0,0] neg_hi:[1,0,0]
	v_pk_fma_f32 v[108:109], v[190:191], v[108:109], v[144:145] op_sel_hi:[0,1,1]
	v_add_f32_e32 v128, 1.0, v128
	v_rcp_f32_e32 v128, v128
	v_pk_fma_f32 v[104:105], v[188:189], v[120:121], v[104:105] op_sel_hi:[0,1,1] neg_lo:[1,0,0] neg_hi:[1,0,0]
	v_pk_fma_f32 v[104:105], v[190:191], v[104:105], v[136:137] op_sel_hi:[0,1,1]
	v_pk_fma_f32 v[110:111], v[188:189], v[126:127], v[110:111] op_sel_hi:[0,1,1] neg_lo:[1,0,0] neg_hi:[1,0,0]
	v_mul_f32_e32 v133, v133, v128
	v_mul_f32_e32 v128, 0x3d372713, v129
	v_mul_f32_e32 v128, v129, v128
	v_fma_f32 v128, v129, v128, v129
	v_mul_f32_e32 v128, 0x3f4c422a, v128
	v_add_f32_e32 v128, v128, v128
	v_mul_f32_e32 v128, 0xbfb8aa3b, v128
	v_exp_f32_e32 v128, v128
	v_pk_fma_f32 v[110:111], v[190:191], v[110:111], v[146:147] op_sel_hi:[0,1,1]
	v_pk_fma_f32 v[106:107], v[188:189], v[122:123], v[106:107] op_sel_hi:[0,1,1] neg_lo:[1,0,0] neg_hi:[1,0,0]
	v_pk_fma_f32 v[106:107], v[190:191], v[106:107], v[138:139] op_sel_hi:[0,1,1]
	v_add_f32_e32 v128, 1.0, v128
	v_rcp_f32_e32 v128, v128
	v_pk_fma_f32 v[100:101], v[184:185], v[124:125], v[100:101] op_sel_hi:[0,1,1] neg_lo:[1,0,0] neg_hi:[1,0,0]
	v_pk_fma_f32 v[100:101], v[186:187], v[100:101], v[144:145] op_sel_hi:[0,1,1]
	v_pk_fma_f32 v[96:97], v[184:185], v[120:121], v[96:97] op_sel_hi:[0,1,1] neg_lo:[1,0,0] neg_hi:[1,0,0]
	v_mul_f32_e32 v143, v129, v128
	v_mul_f32_e32 v128, 0x3d372713, v134
	v_mul_f32_e32 v128, v134, v128
	v_fma_f32 v128, v134, v128, v134
	v_mul_f32_e32 v128, 0x3f4c422a, v128
	v_add_f32_e32 v128, v128, v128
	v_mul_f32_e32 v128, 0xbfb8aa3b, v128
	v_exp_f32_e32 v128, v128
	v_pk_fma_f32 v[96:97], v[186:187], v[96:97], v[136:137] op_sel_hi:[0,1,1]
	v_pk_fma_f32 v[102:103], v[184:185], v[126:127], v[102:103] op_sel_hi:[0,1,1] neg_lo:[1,0,0] neg_hi:[1,0,0]
	v_pk_fma_f32 v[102:103], v[186:187], v[102:103], v[146:147] op_sel_hi:[0,1,1]
	v_add_f32_e32 v128, 1.0, v128
	v_rcp_f32_e32 v128, v128
	v_pk_fma_f32 v[98:99], v[184:185], v[122:123], v[98:99] op_sel_hi:[0,1,1] neg_lo:[1,0,0] neg_hi:[1,0,0]
	v_pk_fma_f32 v[98:99], v[186:187], v[98:99], v[138:139] op_sel_hi:[0,1,1]
	v_pk_fma_f32 v[92:93], v[180:181], v[124:125], v[92:93] op_sel_hi:[0,1,1] neg_lo:[1,0,0] neg_hi:[1,0,0]
	v_mul_f32_e32 v134, v134, v128
	v_mul_f32_e32 v128, 0x3d372713, v130
	v_mul_f32_e32 v128, v130, v128
	v_fma_f32 v128, v130, v128, v130
	v_mul_f32_e32 v128, 0x3f4c422a, v128
	v_add_f32_e32 v128, v128, v128
	v_mul_f32_e32 v128, 0xbfb8aa3b, v128
	v_exp_f32_e32 v128, v128
	v_pk_fma_f32 v[92:93], v[92:93], v[182:183], v[144:145] op_sel_hi:[1,0,1]
	v_pk_fma_f32 v[88:89], v[180:181], v[120:121], v[88:89] op_sel_hi:[0,1,1] neg_lo:[1,0,0] neg_hi:[1,0,0]
	v_pk_fma_f32 v[88:89], v[182:183], v[88:89], v[136:137] op_sel_hi:[0,1,1]
	v_add_f32_e32 v128, 1.0, v128
	v_rcp_f32_e32 v128, v128
	v_pk_fma_f32 v[94:95], v[180:181], v[126:127], v[94:95] op_sel_hi:[0,1,1] neg_lo:[1,0,0] neg_hi:[1,0,0]
	v_pk_fma_f32 v[94:95], v[94:95], v[182:183], v[146:147] op_sel_hi:[1,0,1]
	v_pk_fma_f32 v[90:91], v[180:181], v[122:123], v[90:91] op_sel_hi:[0,1,1] neg_lo:[1,0,0] neg_hi:[1,0,0]
	v_mul_f32_e32 v148, v130, v128
	v_mul_f32_e32 v128, 0x3d372713, v135
	v_mul_f32_e32 v128, v135, v128
	v_fma_f32 v128, v135, v128, v135
	v_mul_f32_e32 v128, 0x3f4c422a, v128
	v_add_f32_e32 v128, v128, v128
	v_mul_f32_e32 v128, 0xbfb8aa3b, v128
	v_exp_f32_e32 v128, v128
	v_cvt_pk_bf16_f32 v130, v132, v133
; __device__ __forceinline__ unsigned cvt_pk_bf16(float lo, float hi) { unsigned r; asm("v_cvt_pk_bf16_f32 %0, %1, %2" : "=v"(r) : "v"(lo), "v"(hi)); return r; }
; __device__ __forceinline__ float gelu_tanh(float v) { const float u = 0.7978845608028654f * (v + 0.044715f * v * v * v); return v * fast_sigmoid(2.0f * u); }
; __device__ __forceinline__ f32x4 ln_fix(const f32x4& a, float mu, float rs, const f32x4& cs, const f32x4& cb) { return (a - cs * mu) * rs + cb; }
; __device__ __forceinline__ float fast_sigmoid(float v) { return __builtin_amdgcn_rcpf(1.0f + __builtin_amdgcn_exp2f(-1.4426950408889634f * v)); }
;     __device__ __forceinline__ void operator()(const f32x4 (&acc)[2][2][4][2], const Unit& u, int wr, int wc, int fr_in, int fq_in) const {
;     ...
;                 for (int m = 0; m < 4; ++m) { bf16_t* rowp = base + (size_t)(row0 + ai * HALF + m * 16) * 1024 + col0 + bj * HALF;
;                     f32x4 v0 = ln_fix(acc[ai][bj][m][0], rst.mu[ai][m], rst.rs[ai][m], csv[0], cbv[0]), v1 = ln_fix(acc[ai][bj][m][1], rst.mu[ai][m], rst.rs[ai][m], csv[1], cbv[1]);
; #pragma unroll
;                     for (int j = 0; j < 4; ++j) { v0[j] = gelu_tanh(v0[j]); v1[j] = gelu_tanh(v1[j]); }
;                     u32x4 w; w.x = cvt_pk_bf16(v0[0], v0[1]); w.y = cvt_pk_bf16(v0[2], v0[3]); w.z = cvt_pk_bf16(v1[0], v1[1]); w.w = cvt_pk_bf16(v1[2], v1[3]);
;                     *(u32x4*)rowp = w; } }
	v_cvt_pk_bf16_f32 v132, v142, v143
	v_pk_fma_f32 v[90:91], v[182:183], v[90:91], v[138:139] op_sel_hi:[0,1,1]
	v_add_f32_e32 v128, 1.0, v128
	v_rcp_f32_e32 v128, v128
	v_pk_fma_f32 v[80:81], v[176:177], v[120:121], v[80:81] op_sel_hi:[0,1,1] neg_lo:[1,0,0] neg_hi:[1,0,0]
	v_pk_fma_f32 v[80:81], v[80:81], v[178:179], v[136:137] op_sel_hi:[1,0,1]
	v_pk_fma_f32 v[82:83], v[176:177], v[122:123], v[82:83] op_sel_hi:[0,1,1] neg_lo:[1,0,0] neg_hi:[1,0,0]
	v_mul_f32_e32 v135, v135, v128
	v_mul_f32_e32 v128, 0x3d372713, v131
	v_mul_f32_e32 v128, v131, v128
	v_fma_f32 v128, v131, v128, v131
	v_mul_f32_e32 v128, 0x3f4c422a, v128
	v_add_f32_e32 v128, v128, v128
	v_mul_f32_e32 v128, 0xbfb8aa3b, v128
	v_exp_f32_e32 v128, v128
	v_pk_fma_f32 v[82:83], v[82:83], v[178:179], v[138:139] op_sel_hi:[1,0,1]
	v_pk_fma_f32 v[76:77], v[124:125], v[172:173], v[76:77] op_sel_hi:[1,0,1] neg_lo:[1,0,0] neg_hi:[1,0,0]
	v_pk_fma_f32 v[72:73], v[172:173], v[120:121], v[72:73] op_sel_hi:[0,1,1] neg_lo:[1,0,0] neg_hi:[1,0,0]
	v_add_f32_e32 v128, 1.0, v128
	v_rcp_f32_e32 v128, v128
	v_pk_fma_f32 v[76:77], v[76:77], v[174:175], v[144:145] op_sel_hi:[1,0,1]
	v_pk_fma_f32 v[72:73], v[72:73], v[174:175], v[136:137] op_sel_hi:[1,0,1]
	v_pk_fma_f32 v[74:75], v[172:173], v[122:123], v[74:75] op_sel_hi:[0,1,1] neg_lo:[1,0,0] neg_hi:[1,0,0]
	v_mul_f32_e32 v149, v131, v128
	v_lshl_add_u64 v[128:129], v[202:203], 0, v[140:141]
	v_cvt_pk_bf16_f32 v131, v134, v135
	v_cvt_pk_bf16_f32 v133, v148, v149
	global_store_dwordx4 v[128:129], v[130:133], off
	v_pk_fma_f32 v[74:75], v[74:75], v[174:175], v[138:139] op_sel_hi:[1,0,1]
	v_pk_fma_f32 v[68:69], v[124:125], v[168:169], v[68:69] op_sel_hi:[1,0,1] neg_lo:[1,0,0] neg_hi:[1,0,0]
	v_mul_f32_e32 v132, 0x3d372713, v116
	v_mul_f32_e32 v132, v116, v132
	v_fma_f32 v132, v116, v132, v116
	v_mul_f32_e32 v132, 0x3f4c422a, v132
	v_add_f32_e32 v132, v132, v132
	v_mul_f32_e32 v132, 0xbfb8aa3b, v132
	v_exp_f32_e32 v132, v132
	v_lshlrev_b64 v[130:131], 11, v[220:221]
	v_pk_fma_f32 v[68:69], v[68:69], v[170:171], v[144:145] op_sel_hi:[1,0,1]
	v_pk_fma_f32 v[64:65], v[120:121], v[168:169], v[64:65] op_sel_hi:[1,0,1] neg_lo:[1,0,0] neg_hi:[1,0,0]
	v_add_f32_e32 v132, 1.0, v132
	v_rcp_f32_e32 v132, v132
	v_pk_fma_f32 v[64:65], v[64:65], v[170:171], v[136:137] op_sel_hi:[1,0,1]
	v_mul_f32_e32 v116, v116, v132
	v_mul_f32_e32 v132, 0x3d372713, v112
	v_mul_f32_e32 v132, v112, v132
	v_fma_f32 v132, v112, v132, v112
	v_mul_f32_e32 v132, 0x3f4c422a, v132
	v_add_f32_e32 v132, v132, v132
	v_mul_f32_e32 v132, 0xbfb8aa3b, v132
	v_exp_f32_e32 v132, v132
	s_nop 0
	v_add_f32_e32 v132, 1.0, v132
	v_rcp_f32_e32 v132, v132
	s_nop 0
	v_mul_f32_e32 v132, v112, v132
	v_mul_f32_e32 v112, 0x3d372713, v117
	v_mul_f32_e32 v112, v117, v112
	v_fma_f32 v112, v117, v112, v117
	v_mul_f32_e32 v112, 0x3f4c422a, v112
	v_add_f32_e32 v112, v112, v112
	v_mul_f32_e32 v112, 0xbfb8aa3b, v112
	v_exp_f32_e32 v112, v112
	s_nop 0
	v_add_f32_e32 v112, 1.0, v112
	v_rcp_f32_e32 v112, v112
	s_nop 0
	v_mul_f32_e32 v117, v117, v112
	v_mul_f32_e32 v112, 0x3d372713, v113
	v_mul_f32_e32 v112, v113, v112
	v_fma_f32 v112, v113, v112, v113
	v_mul_f32_e32 v112, 0x3f4c422a, v112
	v_add_f32_e32 v112, v112, v112
	v_mul_f32_e32 v112, 0xbfb8aa3b, v112
	v_exp_f32_e32 v112, v112
	s_nop 0
	v_add_f32_e32 v112, 1.0, v112
	v_rcp_f32_e32 v112, v112
	s_nop 0
	v_mul_f32_e32 v133, v113, v112
	v_mul_f32_e32 v112, 0x3d372713, v118
	v_mul_f32_e32 v112, v118, v112
	v_fma_f32 v112, v118, v112, v118
	v_mul_f32_e32 v112, 0x3f4c422a, v112
	v_add_f32_e32 v112, v112, v112
	v_mul_f32_e32 v112, 0xbfb8aa3b, v112
	v_exp_f32_e32 v112, v112
	s_nop 0
	v_add_f32_e32 v112, 1.0, v112
	v_rcp_f32_e32 v112, v112
	s_nop 0
	v_mul_f32_e32 v118, v118, v112
	v_mul_f32_e32 v112, 0x3d372713, v114
	v_mul_f32_e32 v112, v114, v112
	v_fma_f32 v112, v114, v112, v114
	v_mul_f32_e32 v112, 0x3f4c422a, v112
	v_add_f32_e32 v112, v112, v112
	v_mul_f32_e32 v112, 0xbfb8aa3b, v112
	v_exp_f32_e32 v112, v112
	s_nop 0
	v_add_f32_e32 v112, 1.0, v112
	v_rcp_f32_e32 v112, v112
	s_nop 0
	v_mul_f32_e32 v134, v114, v112
	v_mul_f32_e32 v112, 0x3d372713, v119
	v_mul_f32_e32 v112, v119, v112
	v_fma_f32 v112, v119, v112, v119
	v_mul_f32_e32 v112, 0x3f4c422a, v112
	v_add_f32_e32 v112, v112, v112
	v_mul_f32_e32 v112, 0xbfb8aa3b, v112
	v_exp_f32_e32 v112, v112
	v_cvt_pk_bf16_f32 v114, v116, v117
	v_cvt_pk_bf16_f32 v116, v132, v133
	s_nop 0
	v_add_f32_e32 v112, 1.0, v112
	v_rcp_f32_e32 v112, v112
	s_nop 0
	v_mul_f32_e32 v119, v119, v112
	v_mul_f32_e32 v112, 0x3d372713, v115
	v_mul_f32_e32 v112, v115, v112
	v_fma_f32 v112, v115, v112, v115
	v_mul_f32_e32 v112, 0x3f4c422a, v112
	v_add_f32_e32 v112, v112, v112
	v_mul_f32_e32 v112, 0xbfb8aa3b, v112
	v_exp_f32_e32 v112, v112
	s_nop 0
	v_add_f32_e32 v112, 1.0, v112
	v_rcp_f32_e32 v112, v112
	s_nop 0
	v_mul_f32_e32 v135, v115, v112
	v_lshl_add_u64 v[112:113], v[202:203], 0, v[130:131]
	v_cvt_pk_bf16_f32 v115, v118, v119
	v_cvt_pk_bf16_f32 v117, v134, v135
	global_store_dwordx4 v[112:113], v[114:117], off
	s_nop 1
	v_mul_f32_e32 v116, 0x3d372713, v108
	v_mul_f32_e32 v116, v108, v116
	v_fma_f32 v116, v108, v116, v108
	v_mul_f32_e32 v116, 0x3f4c422a, v116
	v_add_f32_e32 v116, v116, v116
	v_mul_f32_e32 v116, 0xbfb8aa3b, v116
	v_exp_f32_e32 v116, v116
	v_lshlrev_b64 v[114:115], 11, v[218:219]
	v_add_f32_e32 v116, 1.0, v116
	v_rcp_f32_e32 v116, v116
	s_nop 0
	v_mul_f32_e32 v108, v108, v116
	v_mul_f32_e32 v116, 0x3d372713, v104
	v_mul_f32_e32 v116, v104, v116
	v_fma_f32 v116, v104, v116, v104
	v_mul_f32_e32 v116, 0x3f4c422a, v116
	v_add_f32_e32 v116, v116, v116
	v_mul_f32_e32 v116, 0xbfb8aa3b, v116
	v_exp_f32_e32 v116, v116
	s_nop 0
; __device__ __forceinline__ unsigned cvt_pk_bf16(float lo, float hi) { unsigned r; asm("v_cvt_pk_bf16_f32 %0, %1, %2" : "=v"(r) : "v"(lo), "v"(hi)); return r; }
; __device__ __forceinline__ float gelu_tanh(float v) { const float u = 0.7978845608028654f * (v + 0.044715f * v * v * v); return v * fast_sigmoid(2.0f * u); }
; __device__ __forceinline__ f32x4 ln_fix(const f32x4& a, float mu, float rs, const f32x4& cs, const f32x4& cb) { return (a - cs * mu) * rs + cb; }
; __device__ __forceinline__ float fast_sigmoid(float v) { return __builtin_amdgcn_rcpf(1.0f + __builtin_amdgcn_exp2f(-1.4426950408889634f * v)); }
;     __device__ __forceinline__ void operator()(const f32x4 (&acc)[2][2][4][2], const Unit& u, int wr, int wc, int fr_in, int fq_in) const {
;     ...
;                 for (int m = 0; m < 4; ++m) { bf16_t* rowp = base + (size_t)(row0 + ai * HALF + m * 16) * 1024 + col0 + bj * HALF;
;                     f32x4 v0 = ln_fix(acc[ai][bj][m][0], rst.mu[ai][m], rst.rs[ai][m], csv[0], cbv[0]), v1 = ln_fix(acc[ai][bj][m][1], rst.mu[ai][m], rst.rs[ai][m], csv[1], cbv[1]);
; #pragma unroll
;                     for (int j = 0; j < 4; ++j) { v0[j] = gelu_tanh(v0[j]); v1[j] = gelu_tanh(v1[j]); }
;                     u32x4 w; w.x = cvt_pk_bf16(v0[0], v0[1]); w.y = cvt_pk_bf16(v0[2], v0[3]); w.z = cvt_pk_bf16(v1[0], v1[1]); w.w = cvt_pk_bf16(v1[2], v1[3]);
;                     *(u32x4*)rowp = w; } }
	v_add_f32_e32 v116, 1.0, v116
	v_rcp_f32_e32 v116, v116
	s_nop 0
	v_mul_f32_e32 v116, v104, v116
	v_mul_f32_e32 v104, 0x3d372713, v109
	v_mul_f32_e32 v104, v109, v104
	v_fma_f32 v104, v109, v104, v109
	v_mul_f32_e32 v104, 0x3f4c422a, v104
	v_add_f32_e32 v104, v104, v104
	v_mul_f32_e32 v104, 0xbfb8aa3b, v104
	v_exp_f32_e32 v104, v104
	s_nop 0
	v_add_f32_e32 v104, 1.0, v104
	v_rcp_f32_e32 v104, v104
	s_nop 0
	v_mul_f32_e32 v109, v109, v104
	v_mul_f32_e32 v104, 0x3d372713, v105
	v_mul_f32_e32 v104, v105, v104
	v_fma_f32 v104, v105, v104, v105
	v_mul_f32_e32 v104, 0x3f4c422a, v104
	v_add_f32_e32 v104, v104, v104
	v_mul_f32_e32 v104, 0xbfb8aa3b, v104
	v_exp_f32_e32 v104, v104
	s_nop 0
	v_add_f32_e32 v104, 1.0, v104
	v_rcp_f32_e32 v104, v104
	s_nop 0
	v_mul_f32_e32 v117, v105, v104
	v_mul_f32_e32 v104, 0x3d372713, v110
	v_mul_f32_e32 v104, v110, v104
	v_fma_f32 v104, v110, v104, v110
	v_mul_f32_e32 v104, 0x3f4c422a, v104
	v_add_f32_e32 v104, v104, v104
	v_mul_f32_e32 v104, 0xbfb8aa3b, v104
	v_exp_f32_e32 v104, v104
	s_nop 0
	v_add_f32_e32 v104, 1.0, v104
	v_rcp_f32_e32 v104, v104
	s_nop 0
	v_mul_f32_e32 v110, v110, v104
	v_mul_f32_e32 v104, 0x3d372713, v106
	v_mul_f32_e32 v104, v106, v104
	v_fma_f32 v104, v106, v104, v106
	v_mul_f32_e32 v104, 0x3f4c422a, v104
	v_add_f32_e32 v104, v104, v104
	v_mul_f32_e32 v104, 0xbfb8aa3b, v104
	v_exp_f32_e32 v104, v104
	s_nop 0
	v_add_f32_e32 v104, 1.0, v104
	v_rcp_f32_e32 v104, v104
	s_nop 0
	v_mul_f32_e32 v118, v106, v104
	v_mul_f32_e32 v104, 0x3d372713, v111
	v_mul_f32_e32 v104, v111, v104
	v_fma_f32 v104, v111, v104, v111
	v_mul_f32_e32 v104, 0x3f4c422a, v104
	v_add_f32_e32 v104, v104, v104
	v_mul_f32_e32 v104, 0xbfb8aa3b, v104
	v_exp_f32_e32 v104, v104
	v_cvt_pk_bf16_f32 v106, v108, v109
	v_cvt_pk_bf16_f32 v108, v116, v117
	s_nop 0
	v_add_f32_e32 v104, 1.0, v104
	v_rcp_f32_e32 v104, v104
	s_nop 0
	v_mul_f32_e32 v111, v111, v104
	v_mul_f32_e32 v104, 0x3d372713, v107
	v_mul_f32_e32 v104, v107, v104
	v_fma_f32 v104, v107, v104, v107
	v_mul_f32_e32 v104, 0x3f4c422a, v104
	v_add_f32_e32 v104, v104, v104
	v_mul_f32_e32 v104, 0xbfb8aa3b, v104
	v_exp_f32_e32 v104, v104
	s_nop 0
	v_add_f32_e32 v104, 1.0, v104
	v_rcp_f32_e32 v104, v104
	s_nop 0
	v_mul_f32_e32 v119, v107, v104
	v_lshl_add_u64 v[104:105], v[202:203], 0, v[114:115]
	v_cvt_pk_bf16_f32 v107, v110, v111
	v_cvt_pk_bf16_f32 v109, v118, v119
	global_store_dwordx4 v[104:105], v[106:109], off
	s_nop 1
	v_mul_f32_e32 v108, 0x3d372713, v100
	v_mul_f32_e32 v108, v100, v108
	v_fma_f32 v108, v100, v108, v100
	v_mul_f32_e32 v108, 0x3f4c422a, v108
	v_add_f32_e32 v108, v108, v108
	v_mul_f32_e32 v108, 0xbfb8aa3b, v108
	v_exp_f32_e32 v108, v108
	v_lshlrev_b64 v[106:107], 11, v[216:217]
	v_add_f32_e32 v108, 1.0, v108
	v_rcp_f32_e32 v108, v108
	s_nop 0
	v_mul_f32_e32 v100, v100, v108
	v_mul_f32_e32 v108, 0x3d372713, v96
	v_mul_f32_e32 v108, v96, v108
	v_fma_f32 v108, v96, v108, v96
	v_mul_f32_e32 v108, 0x3f4c422a, v108
	v_add_f32_e32 v108, v108, v108
	v_mul_f32_e32 v108, 0xbfb8aa3b, v108
	v_exp_f32_e32 v108, v108
	s_nop 0
	v_add_f32_e32 v108, 1.0, v108
	v_rcp_f32_e32 v108, v108
	s_nop 0
	v_mul_f32_e32 v108, v96, v108
	v_mul_f32_e32 v96, 0x3d372713, v101
	v_mul_f32_e32 v96, v101, v96
	v_fma_f32 v96, v101, v96, v101
	v_mul_f32_e32 v96, 0x3f4c422a, v96
	v_add_f32_e32 v96, v96, v96
	v_mul_f32_e32 v96, 0xbfb8aa3b, v96
	v_exp_f32_e32 v96, v96
	s_nop 0
	v_add_f32_e32 v96, 1.0, v96
	v_rcp_f32_e32 v96, v96
	s_nop 0
	v_mul_f32_e32 v101, v101, v96
	v_mul_f32_e32 v96, 0x3d372713, v97
	v_mul_f32_e32 v96, v97, v96
	v_fma_f32 v96, v97, v96, v97
	v_mul_f32_e32 v96, 0x3f4c422a, v96
	v_add_f32_e32 v96, v96, v96
	v_mul_f32_e32 v96, 0xbfb8aa3b, v96
	v_exp_f32_e32 v96, v96
	s_nop 0
	v_add_f32_e32 v96, 1.0, v96
	v_rcp_f32_e32 v96, v96
	s_nop 0
	v_mul_f32_e32 v109, v97, v96
	v_mul_f32_e32 v96, 0x3d372713, v102
	v_mul_f32_e32 v96, v102, v96
	v_fma_f32 v96, v102, v96, v102
	v_mul_f32_e32 v96, 0x3f4c422a, v96
	v_add_f32_e32 v96, v96, v96
	v_mul_f32_e32 v96, 0xbfb8aa3b, v96
	v_exp_f32_e32 v96, v96
	s_nop 0
	v_add_f32_e32 v96, 1.0, v96
	v_rcp_f32_e32 v96, v96
	s_nop 0
	v_mul_f32_e32 v102, v102, v96
	v_mul_f32_e32 v96, 0x3d372713, v98
	v_mul_f32_e32 v96, v98, v96
	v_fma_f32 v96, v98, v96, v98
	v_mul_f32_e32 v96, 0x3f4c422a, v96
	v_add_f32_e32 v96, v96, v96
	v_mul_f32_e32 v96, 0xbfb8aa3b, v96
	v_exp_f32_e32 v96, v96
	s_nop 0
	v_add_f32_e32 v96, 1.0, v96
	v_rcp_f32_e32 v96, v96
	s_nop 0
	v_mul_f32_e32 v110, v98, v96
	v_mul_f32_e32 v96, 0x3d372713, v103
	v_mul_f32_e32 v96, v103, v96
	v_fma_f32 v96, v103, v96, v103
	v_mul_f32_e32 v96, 0x3f4c422a, v96
	v_add_f32_e32 v96, v96, v96
	v_mul_f32_e32 v96, 0xbfb8aa3b, v96
	v_exp_f32_e32 v96, v96
	v_cvt_pk_bf16_f32 v98, v100, v101
	v_cvt_pk_bf16_f32 v100, v108, v109
	s_nop 0
	v_add_f32_e32 v96, 1.0, v96
	v_rcp_f32_e32 v96, v96
	s_nop 0
	v_mul_f32_e32 v103, v103, v96
	v_mul_f32_e32 v96, 0x3d372713, v99
	v_mul_f32_e32 v96, v99, v96
	v_fma_f32 v96, v99, v96, v99
	v_mul_f32_e32 v96, 0x3f4c422a, v96
	v_add_f32_e32 v96, v96, v96
	v_mul_f32_e32 v96, 0xbfb8aa3b, v96
	v_exp_f32_e32 v96, v96
	s_nop 0
	v_add_f32_e32 v96, 1.0, v96
	v_rcp_f32_e32 v96, v96
	s_nop 0
	v_mul_f32_e32 v111, v99, v96
	v_lshl_add_u64 v[96:97], v[202:203], 0, v[106:107]
	v_cvt_pk_bf16_f32 v99, v102, v103
	v_cvt_pk_bf16_f32 v101, v110, v111
	global_store_dwordx4 v[96:97], v[98:101], off
	s_nop 1
	v_mul_f32_e32 v100, 0x3d372713, v92
	v_mul_f32_e32 v100, v92, v100
	v_fma_f32 v100, v92, v100, v92
	v_mul_f32_e32 v100, 0x3f4c422a, v100
	v_add_f32_e32 v100, v100, v100
	v_mul_f32_e32 v100, 0xbfb8aa3b, v100
	v_exp_f32_e32 v100, v100
	v_lshlrev_b64 v[98:99], 11, v[214:215]
	v_add_f32_e32 v100, 1.0, v100
; __device__ __forceinline__ unsigned cvt_pk_bf16(float lo, float hi) { unsigned r; asm("v_cvt_pk_bf16_f32 %0, %1, %2" : "=v"(r) : "v"(lo), "v"(hi)); return r; }
; __device__ __forceinline__ float gelu_tanh(float v) { const float u = 0.7978845608028654f * (v + 0.044715f * v * v * v); return v * fast_sigmoid(2.0f * u); }
; __device__ __forceinline__ f32x4 ln_fix(const f32x4& a, float mu, float rs, const f32x4& cs, const f32x4& cb) { return (a - cs * mu) * rs + cb; }
; __device__ __forceinline__ float fast_sigmoid(float v) { return __builtin_amdgcn_rcpf(1.0f + __builtin_amdgcn_exp2f(-1.4426950408889634f * v)); }
;     __device__ __forceinline__ void operator()(const f32x4 (&acc)[2][2][4][2], const Unit& u, int wr, int wc, int fr_in, int fq_in) const {
;     ...
;                 for (int m = 0; m < 4; ++m) { bf16_t* rowp = base + (size_t)(row0 + ai * HALF + m * 16) * 1024 + col0 + bj * HALF;
;                     f32x4 v0 = ln_fix(acc[ai][bj][m][0], rst.mu[ai][m], rst.rs[ai][m], csv[0], cbv[0]), v1 = ln_fix(acc[ai][bj][m][1], rst.mu[ai][m], rst.rs[ai][m], csv[1], cbv[1]);
; #pragma unroll
;                     for (int j = 0; j < 4; ++j) { v0[j] = gelu_tanh(v0[j]); v1[j] = gelu_tanh(v1[j]); }
;                     u32x4 w; w.x = cvt_pk_bf16(v0[0], v0[1]); w.y = cvt_pk_bf16(v0[2], v0[3]); w.z = cvt_pk_bf16(v1[0], v1[1]); w.w = cvt_pk_bf16(v1[2], v1[3]);
;                     *(u32x4*)rowp = w; } }
	v_rcp_f32_e32 v100, v100
	s_nop 0
	v_mul_f32_e32 v92, v92, v100
	v_mul_f32_e32 v100, 0x3d372713, v88
	v_mul_f32_e32 v100, v88, v100
	v_fma_f32 v100, v88, v100, v88
	v_mul_f32_e32 v100, 0x3f4c422a, v100
	v_add_f32_e32 v100, v100, v100
	v_mul_f32_e32 v100, 0xbfb8aa3b, v100
	v_exp_f32_e32 v100, v100
	s_nop 0
	v_add_f32_e32 v100, 1.0, v100
	v_rcp_f32_e32 v100, v100
	s_nop 0
	v_mul_f32_e32 v100, v88, v100
	v_mul_f32_e32 v88, 0x3d372713, v93
	v_mul_f32_e32 v88, v93, v88
	v_fma_f32 v88, v93, v88, v93
	v_mul_f32_e32 v88, 0x3f4c422a, v88
	v_add_f32_e32 v88, v88, v88
	v_mul_f32_e32 v88, 0xbfb8aa3b, v88
	v_exp_f32_e32 v88, v88
	s_nop 0
	v_add_f32_e32 v88, 1.0, v88
	v_rcp_f32_e32 v88, v88
	s_nop 0
	v_mul_f32_e32 v93, v93, v88
	v_mul_f32_e32 v88, 0x3d372713, v89
	v_mul_f32_e32 v88, v89, v88
	v_fma_f32 v88, v89, v88, v89
	v_mul_f32_e32 v88, 0x3f4c422a, v88
	v_add_f32_e32 v88, v88, v88
	v_mul_f32_e32 v88, 0xbfb8aa3b, v88
	v_exp_f32_e32 v88, v88
	s_nop 0
	v_add_f32_e32 v88, 1.0, v88
	v_rcp_f32_e32 v88, v88
	s_nop 0
	v_mul_f32_e32 v101, v89, v88
	v_mul_f32_e32 v88, 0x3d372713, v94
	v_mul_f32_e32 v88, v94, v88
	v_fma_f32 v88, v94, v88, v94
	v_mul_f32_e32 v88, 0x3f4c422a, v88
	v_add_f32_e32 v88, v88, v88
	v_mul_f32_e32 v88, 0xbfb8aa3b, v88
	v_exp_f32_e32 v88, v88
	s_nop 0
	v_add_f32_e32 v88, 1.0, v88
	v_rcp_f32_e32 v88, v88
	s_nop 0
	v_mul_f32_e32 v94, v94, v88
	v_mul_f32_e32 v88, 0x3d372713, v90
	v_mul_f32_e32 v88, v90, v88
	v_fma_f32 v88, v90, v88, v90
	v_mul_f32_e32 v88, 0x3f4c422a, v88
	v_add_f32_e32 v88, v88, v88
	v_mul_f32_e32 v88, 0xbfb8aa3b, v88
	v_exp_f32_e32 v88, v88
	s_nop 0
	v_add_f32_e32 v88, 1.0, v88
	v_rcp_f32_e32 v88, v88
	s_nop 0
	v_mul_f32_e32 v102, v90, v88
	v_mul_f32_e32 v88, 0x3d372713, v95
	v_mul_f32_e32 v88, v95, v88
	v_fma_f32 v88, v95, v88, v95
	v_mul_f32_e32 v88, 0x3f4c422a, v88
	v_add_f32_e32 v88, v88, v88
	v_mul_f32_e32 v88, 0xbfb8aa3b, v88
	v_exp_f32_e32 v88, v88
	v_cvt_pk_bf16_f32 v90, v92, v93
	v_cvt_pk_bf16_f32 v92, v100, v101
	s_nop 0
	v_add_f32_e32 v88, 1.0, v88
	v_rcp_f32_e32 v88, v88
	s_nop 0
	v_mul_f32_e32 v95, v95, v88
	v_mul_f32_e32 v88, 0x3d372713, v91
	v_mul_f32_e32 v88, v91, v88
	v_fma_f32 v88, v91, v88, v91
	v_mul_f32_e32 v88, 0x3f4c422a, v88
	v_add_f32_e32 v88, v88, v88
	v_mul_f32_e32 v88, 0xbfb8aa3b, v88
	v_exp_f32_e32 v88, v88
	s_nop 0
	v_add_f32_e32 v88, 1.0, v88
	v_rcp_f32_e32 v88, v88
	s_nop 0
	v_mul_f32_e32 v103, v91, v88
	v_lshl_add_u64 v[88:89], v[202:203], 0, v[98:99]
	v_cvt_pk_bf16_f32 v93, v102, v103
	v_cvt_pk_bf16_f32 v91, v94, v95
	global_store_dwordx4 v[88:89], v[90:93], off
	s_nop 1
	v_pk_fma_f32 v[92:93], v[124:125], v[176:177], v[84:85] op_sel_hi:[1,0,1] neg_lo:[1,0,0] neg_hi:[1,0,0]
	v_xor_b32_e32 v85, 0x80000000, v127
	v_pk_fma_f32 v[92:93], v[92:93], v[178:179], v[144:145] op_sel_hi:[1,0,1]
	v_xor_b32_e32 v84, 0x80000000, v126
	v_mul_f32_e32 v94, 0x3d372713, v92
	v_mul_f32_e32 v94, v92, v94
	v_fma_f32 v94, v92, v94, v92
	v_mul_f32_e32 v94, 0x3f4c422a, v94
	v_add_f32_e32 v94, v94, v94
	v_mul_f32_e32 v94, 0xbfb8aa3b, v94
	v_exp_f32_e32 v94, v94
	v_pk_fma_f32 v[86:87], v[84:85], v[176:177], v[86:87] op_sel_hi:[1,0,1]
	v_lshlrev_b64 v[90:91], 11, v[212:213]
	v_pk_fma_f32 v[86:87], v[86:87], v[178:179], v[146:147] op_sel_hi:[1,0,1]
	v_add_f32_e32 v94, 1.0, v94
	v_rcp_f32_e32 v94, v94
	v_pk_fma_f32 v[78:79], v[84:85], v[172:173], v[78:79] op_sel_hi:[1,0,1]
	v_pk_fma_f32 v[70:71], v[84:85], v[168:169], v[70:71] op_sel_hi:[1,0,1]
	v_pk_fma_f32 v[78:79], v[78:79], v[174:175], v[146:147] op_sel_hi:[1,0,1]
	v_mul_f32_e32 v92, v92, v94
	v_mul_f32_e32 v94, 0x3d372713, v80
	v_mul_f32_e32 v94, v80, v94
	v_fma_f32 v94, v80, v94, v80
	v_mul_f32_e32 v94, 0x3f4c422a, v94
	v_add_f32_e32 v94, v94, v94
	v_mul_f32_e32 v94, 0xbfb8aa3b, v94
	v_exp_f32_e32 v94, v94
	v_pk_fma_f32 v[70:71], v[70:71], v[170:171], v[146:147] op_sel_hi:[1,0,1]
	v_add_f32_e32 v94, 1.0, v94
	v_rcp_f32_e32 v94, v94
	s_nop 0
	v_mul_f32_e32 v94, v80, v94
	v_mul_f32_e32 v80, 0x3d372713, v93
	v_mul_f32_e32 v80, v93, v80
	v_fma_f32 v80, v93, v80, v93
	v_mul_f32_e32 v80, 0x3f4c422a, v80
	v_add_f32_e32 v80, v80, v80
	v_mul_f32_e32 v80, 0xbfb8aa3b, v80
	v_exp_f32_e32 v80, v80
	s_nop 0
	v_add_f32_e32 v80, 1.0, v80
	v_rcp_f32_e32 v80, v80
	s_nop 0
	v_mul_f32_e32 v93, v93, v80
	v_mul_f32_e32 v80, 0x3d372713, v81
	v_mul_f32_e32 v80, v81, v80
	v_fma_f32 v80, v81, v80, v81
	v_mul_f32_e32 v80, 0x3f4c422a, v80
	v_add_f32_e32 v80, v80, v80
	v_mul_f32_e32 v80, 0xbfb8aa3b, v80
	v_exp_f32_e32 v80, v80
	s_nop 0
	v_add_f32_e32 v80, 1.0, v80
	v_rcp_f32_e32 v80, v80
	s_nop 0
	v_mul_f32_e32 v95, v81, v80
	v_mul_f32_e32 v80, 0x3d372713, v86
	v_mul_f32_e32 v80, v86, v80
	v_fma_f32 v80, v86, v80, v86
	v_mul_f32_e32 v80, 0x3f4c422a, v80
	v_add_f32_e32 v80, v80, v80
	v_mul_f32_e32 v80, 0xbfb8aa3b, v80
	v_exp_f32_e32 v80, v80
	s_nop 0
	v_add_f32_e32 v80, 1.0, v80
	v_rcp_f32_e32 v80, v80
	s_nop 0
	v_mul_f32_e32 v86, v86, v80
	v_mul_f32_e32 v80, 0x3d372713, v82
	v_mul_f32_e32 v80, v82, v80
	v_fma_f32 v80, v82, v80, v82
	v_mul_f32_e32 v80, 0x3f4c422a, v80
	v_add_f32_e32 v80, v80, v80
	v_mul_f32_e32 v80, 0xbfb8aa3b, v80
	v_exp_f32_e32 v80, v80
	s_nop 0
	v_add_f32_e32 v80, 1.0, v80
	v_rcp_f32_e32 v80, v80
	s_nop 0
	v_mul_f32_e32 v82, v82, v80
	v_mul_f32_e32 v80, 0x3d372713, v87
	v_mul_f32_e32 v80, v87, v80
	v_fma_f32 v80, v87, v80, v87
	v_mul_f32_e32 v80, 0x3f4c422a, v80
	v_add_f32_e32 v80, v80, v80
	v_mul_f32_e32 v80, 0xbfb8aa3b, v80
	v_exp_f32_e32 v80, v80
	s_nop 0
	v_add_f32_e32 v80, 1.0, v80
	v_rcp_f32_e32 v80, v80
	s_nop 0
	v_mul_f32_e32 v87, v87, v80
	v_mul_f32_e32 v80, 0x3d372713, v83
	v_mul_f32_e32 v80, v83, v80
	v_fma_f32 v80, v83, v80, v83
	v_mul_f32_e32 v80, 0x3f4c422a, v80
; __device__ __forceinline__ unsigned cvt_pk_bf16(float lo, float hi) { unsigned r; asm("v_cvt_pk_bf16_f32 %0, %1, %2" : "=v"(r) : "v"(lo), "v"(hi)); return r; }
; __device__ __forceinline__ float gelu_tanh(float v) { const float u = 0.7978845608028654f * (v + 0.044715f * v * v * v); return v * fast_sigmoid(2.0f * u); }
; __device__ __forceinline__ f32x4 ln_fix(const f32x4& a, float mu, float rs, const f32x4& cs, const f32x4& cb) { return (a - cs * mu) * rs + cb; }
; __device__ __forceinline__ float fast_sigmoid(float v) { return __builtin_amdgcn_rcpf(1.0f + __builtin_amdgcn_exp2f(-1.4426950408889634f * v)); }
;     __device__ __forceinline__ void operator()(const f32x4 (&acc)[2][2][4][2], const Unit& u, int wr, int wc, int fr_in, int fq_in) const {
;     ...
;         for (int bj = 0; bj < 2; ++bj) { f32x4 csv[2], cbv[2];
; #pragma unroll
;             for (int n = 0; n < 2; ++n) { csv[n] = *(const f32x4*)(cs + n0 + bj * HALF + 4 * n); cbv[n] = *(const f32x4*)(cb + n0 + bj * HALF + 4 * n) + *(const f32x4*)(bias + n0 + bj * HALF + 4 * n); }
; #pragma unroll
;             for (int ai = 0; ai < 2; ++ai)
; #pragma unroll
;                 for (int m = 0; m < 4; ++m) { bf16_t* rowp = base + (size_t)(row0 + ai * HALF + m * 16) * 1024 + col0 + bj * HALF;
;                     f32x4 v0 = ln_fix(acc[ai][bj][m][0], rst.mu[ai][m], rst.rs[ai][m], csv[0], cbv[0]), v1 = ln_fix(acc[ai][bj][m][1], rst.mu[ai][m], rst.rs[ai][m], csv[1], cbv[1]);
; #pragma unroll
;                     for (int j = 0; j < 4; ++j) { v0[j] = gelu_tanh(v0[j]); v1[j] = gelu_tanh(v1[j]); }
;                     u32x4 w; w.x = cvt_pk_bf16(v0[0], v0[1]); w.y = cvt_pk_bf16(v0[2], v0[3]); w.z = cvt_pk_bf16(v1[0], v1[1]); w.w = cvt_pk_bf16(v1[2], v1[3]);
;                     *(u32x4*)rowp = w; } }
	v_add_f32_e32 v80, v80, v80
	v_mul_f32_e32 v80, 0xbfb8aa3b, v80
	v_exp_f32_e32 v80, v80
	s_nop 0
	v_add_f32_e32 v80, 1.0, v80
	v_rcp_f32_e32 v80, v80
	s_nop 0
	v_mul_f32_e32 v83, v83, v80
	v_lshl_add_u64 v[80:81], v[202:203], 0, v[90:91]
	v_cvt_pk_bf16_f32 v91, v86, v87
	v_mul_f32_e32 v86, 0x3d372713, v76
	v_mul_f32_e32 v86, v76, v86
	v_fma_f32 v86, v76, v86, v76
	v_mul_f32_e32 v86, 0x3f4c422a, v86
	v_add_f32_e32 v86, v86, v86
	v_mul_f32_e32 v86, 0xbfb8aa3b, v86
	v_exp_f32_e32 v86, v86
	v_cvt_pk_bf16_f32 v90, v92, v93
	v_cvt_pk_bf16_f32 v92, v94, v95
	v_cvt_pk_bf16_f32 v93, v82, v83
	global_store_dwordx4 v[80:81], v[90:93], off
	v_add_f32_e32 v86, 1.0, v86
	v_rcp_f32_e32 v86, v86
	v_lshlrev_b64 v[82:83], 11, v[210:211]
	v_mul_f32_e32 v76, v76, v86
	v_mul_f32_e32 v86, 0x3d372713, v72
	v_mul_f32_e32 v86, v72, v86
	v_fma_f32 v86, v72, v86, v72
	v_mul_f32_e32 v86, 0x3f4c422a, v86
	v_add_f32_e32 v86, v86, v86
	v_mul_f32_e32 v86, 0xbfb8aa3b, v86
	v_exp_f32_e32 v86, v86
	s_nop 0
	v_add_f32_e32 v86, 1.0, v86
	v_rcp_f32_e32 v86, v86
	s_nop 0
	v_mul_f32_e32 v86, v72, v86
	v_mul_f32_e32 v72, 0x3d372713, v77
	v_mul_f32_e32 v72, v77, v72
	v_fma_f32 v72, v77, v72, v77
	v_mul_f32_e32 v72, 0x3f4c422a, v72
	v_add_f32_e32 v72, v72, v72
	v_mul_f32_e32 v72, 0xbfb8aa3b, v72
	v_exp_f32_e32 v72, v72
	s_nop 0
	v_add_f32_e32 v72, 1.0, v72
	v_rcp_f32_e32 v72, v72
	s_nop 0
	v_mul_f32_e32 v77, v77, v72
	v_mul_f32_e32 v72, 0x3d372713, v73
	v_mul_f32_e32 v72, v73, v72
	v_fma_f32 v72, v73, v72, v73
	v_mul_f32_e32 v72, 0x3f4c422a, v72
	v_add_f32_e32 v72, v72, v72
	v_mul_f32_e32 v72, 0xbfb8aa3b, v72
	v_exp_f32_e32 v72, v72
	s_nop 0
	v_add_f32_e32 v72, 1.0, v72
	v_rcp_f32_e32 v72, v72
	s_nop 0
	v_mul_f32_e32 v87, v73, v72
	v_mul_f32_e32 v72, 0x3d372713, v78
	v_mul_f32_e32 v72, v78, v72
	v_fma_f32 v72, v78, v72, v78
	v_mul_f32_e32 v72, 0x3f4c422a, v72
	v_add_f32_e32 v72, v72, v72
	v_mul_f32_e32 v72, 0xbfb8aa3b, v72
	v_exp_f32_e32 v72, v72
	s_nop 0
	v_add_f32_e32 v72, 1.0, v72
	v_rcp_f32_e32 v72, v72
	s_nop 0
	v_mul_f32_e32 v78, v78, v72
	v_mul_f32_e32 v72, 0x3d372713, v74
	v_mul_f32_e32 v72, v74, v72
	v_fma_f32 v72, v74, v72, v74
	v_mul_f32_e32 v72, 0x3f4c422a, v72
	v_add_f32_e32 v72, v72, v72
	v_mul_f32_e32 v72, 0xbfb8aa3b, v72
	v_exp_f32_e32 v72, v72
	s_nop 0
	v_add_f32_e32 v72, 1.0, v72
	v_rcp_f32_e32 v72, v72
	s_nop 0
	v_mul_f32_e32 v90, v74, v72
	v_mul_f32_e32 v72, 0x3d372713, v79
	v_mul_f32_e32 v72, v79, v72
	v_fma_f32 v72, v79, v72, v79
	v_mul_f32_e32 v72, 0x3f4c422a, v72
	v_add_f32_e32 v72, v72, v72
	v_mul_f32_e32 v72, 0xbfb8aa3b, v72
	v_exp_f32_e32 v72, v72
	v_cvt_pk_bf16_f32 v74, v76, v77
	v_cvt_pk_bf16_f32 v76, v86, v87
	s_nop 0
	v_add_f32_e32 v72, 1.0, v72
	v_rcp_f32_e32 v72, v72
	s_nop 0
	v_mul_f32_e32 v79, v79, v72
	v_mul_f32_e32 v72, 0x3d372713, v75
	v_mul_f32_e32 v72, v75, v72
	v_fma_f32 v72, v75, v72, v75
	v_mul_f32_e32 v72, 0x3f4c422a, v72
	v_add_f32_e32 v72, v72, v72
	v_mul_f32_e32 v72, 0xbfb8aa3b, v72
	v_exp_f32_e32 v72, v72
	s_nop 0
	v_add_f32_e32 v72, 1.0, v72
	v_rcp_f32_e32 v72, v72
	s_nop 0
	v_mul_f32_e32 v91, v75, v72
	v_lshl_add_u64 v[72:73], v[202:203], 0, v[82:83]
	v_cvt_pk_bf16_f32 v77, v90, v91
	v_cvt_pk_bf16_f32 v75, v78, v79
	global_store_dwordx4 v[72:73], v[74:77], off
	s_nop 1
	v_xor_b32_e32 v77, 0x80000000, v123
	v_xor_b32_e32 v76, 0x80000000, v122
	v_pk_fma_f32 v[66:67], v[76:77], v[168:169], v[66:67] op_sel_hi:[1,0,1]
	v_mul_f32_e32 v76, 0x3d372713, v68
	v_mul_f32_e32 v76, v68, v76
	v_fma_f32 v76, v68, v76, v68
	v_mul_f32_e32 v76, 0x3f4c422a, v76
	v_add_f32_e32 v76, v76, v76
	v_mul_f32_e32 v76, 0xbfb8aa3b, v76
	v_exp_f32_e32 v76, v76
	v_pk_fma_f32 v[66:67], v[66:67], v[170:171], v[138:139] op_sel_hi:[1,0,1]
	v_lshlrev_b64 v[74:75], 11, v[208:209]
	v_lshl_add_u64 v[74:75], v[202:203], 0, v[74:75]
	v_add_f32_e32 v76, 1.0, v76
	v_rcp_f32_e32 v76, v76
	s_nop 0
	v_mul_f32_e32 v68, v68, v76
	v_mul_f32_e32 v76, 0x3d372713, v64
	v_mul_f32_e32 v76, v64, v76
	v_fma_f32 v76, v64, v76, v64
	v_mul_f32_e32 v76, 0x3f4c422a, v76
	v_add_f32_e32 v76, v76, v76
	v_mul_f32_e32 v76, 0xbfb8aa3b, v76
	v_exp_f32_e32 v76, v76
	s_nop 0
	v_add_f32_e32 v76, 1.0, v76
	v_rcp_f32_e32 v76, v76
	s_nop 0
	v_mul_f32_e32 v76, v64, v76
	v_mul_f32_e32 v64, 0x3d372713, v69
	v_mul_f32_e32 v64, v69, v64
	v_fma_f32 v64, v69, v64, v69
	v_mul_f32_e32 v64, 0x3f4c422a, v64
	v_add_f32_e32 v64, v64, v64
	v_mul_f32_e32 v64, 0xbfb8aa3b, v64
	v_exp_f32_e32 v64, v64
	s_nop 0
	v_add_f32_e32 v64, 1.0, v64
	v_rcp_f32_e32 v64, v64
	s_nop 0
	v_mul_f32_e32 v64, v69, v64
	v_mul_f32_e32 v69, 0x3d372713, v65
	v_mul_f32_e32 v69, v65, v69
	v_fma_f32 v69, v65, v69, v65
	v_mul_f32_e32 v69, 0x3f4c422a, v69
	v_add_f32_e32 v69, v69, v69
	v_mul_f32_e32 v69, 0xbfb8aa3b, v69
	v_exp_f32_e32 v69, v69
	v_cvt_pk_bf16_f32 v64, v68, v64
	s_nop 0
	v_add_f32_e32 v69, 1.0, v69
	v_rcp_f32_e32 v69, v69
	s_nop 0
	v_mul_f32_e32 v69, v65, v69
	v_mul_f32_e32 v65, 0x3d372713, v70
	v_mul_f32_e32 v65, v70, v65
	v_fma_f32 v65, v70, v65, v70
	v_mul_f32_e32 v65, 0x3f4c422a, v65
	v_add_f32_e32 v65, v65, v65
	v_mul_f32_e32 v65, 0xbfb8aa3b, v65
	v_exp_f32_e32 v65, v65
	s_nop 0
	v_add_f32_e32 v65, 1.0, v65
	v_rcp_f32_e32 v65, v65
	s_nop 0
	v_mul_f32_e32 v65, v70, v65
	v_mul_f32_e32 v70, 0x3d372713, v66
	v_mul_f32_e32 v70, v66, v70
	v_fma_f32 v70, v66, v70, v66
	v_mul_f32_e32 v70, 0x3f4c422a, v70
	v_add_f32_e32 v70, v70, v70
	v_mul_f32_e32 v70, 0xbfb8aa3b, v70
	v_exp_f32_e32 v70, v70
	s_nop 0
	v_add_f32_e32 v70, 1.0, v70
	v_rcp_f32_e32 v70, v70
	s_nop 0
	v_mul_f32_e32 v70, v66, v70
	v_mul_f32_e32 v66, 0x3d372713, v71
	v_mul_f32_e32 v66, v71, v66
	v_fma_f32 v66, v71, v66, v71
	v_mul_f32_e32 v66, 0x3f4c422a, v66
	v_add_f32_e32 v66, v66, v66
	v_mul_f32_e32 v66, 0xbfb8aa3b, v66
	v_exp_f32_e32 v66, v66
	s_nop 0
	v_add_f32_e32 v66, 1.0, v66
	v_rcp_f32_e32 v66, v66
	s_nop 0
	v_mul_f32_e32 v66, v71, v66
	v_mul_f32_e32 v71, 0x3d372713, v67
	v_mul_f32_e32 v71, v67, v71
	v_fma_f32 v71, v67, v71, v67
	v_mul_f32_e32 v71, 0x3f4c422a, v71
	v_add_f32_e32 v71, v71, v71
	v_mul_f32_e32 v71, 0xbfb8aa3b, v71
	v_exp_f32_e32 v71, v71
	v_cvt_pk_bf16_f32 v65, v65, v66
	v_cvt_pk_bf16_f32 v66, v76, v69
	s_nop 0
	v_add_f32_e32 v71, 1.0, v71
	v_rcp_f32_e32 v71, v71
	s_nop 0
	v_mul_f32_e32 v67, v67, v71
	v_cvt_pk_bf16_f32 v67, v70, v67
	global_store_dwordx4 v[74:75], v[64:67], off
	global_load_dwordx4 v[64:67], v[204:205], off offset:528
	s_nop 0
	global_load_dwordx4 v[68:71], v[204:205], off offset:512
	global_load_dwordx4 v[84:87], v[206:207], off offset:528
	global_load_dwordx4 v[90:93], v[206:207], off offset:512
	global_load_dwordx4 v[98:101], v[200:201], off offset:528
	global_load_dwordx4 v[106:109], v[200:201], off offset:512
	s_waitcnt vmcnt(5)
; __device__ __forceinline__ unsigned cvt_pk_bf16(float lo, float hi) { unsigned r; asm("v_cvt_pk_bf16_f32 %0, %1, %2" : "=v"(r) : "v"(lo), "v"(hi)); return r; }
; __device__ __forceinline__ float gelu_tanh(float v) { const float u = 0.7978845608028654f * (v + 0.044715f * v * v * v); return v * fast_sigmoid(2.0f * u); }
; __device__ __forceinline__ f32x4 ln_fix(const f32x4& a, float mu, float rs, const f32x4& cs, const f32x4& cb) { return (a - cs * mu) * rs + cb; }
; __device__ __forceinline__ float fast_sigmoid(float v) { return __builtin_amdgcn_rcpf(1.0f + __builtin_amdgcn_exp2f(-1.4426950408889634f * v)); }
;     __device__ __forceinline__ void operator()(const f32x4 (&acc)[2][2][4][2], const Unit& u, int wr, int wc, int fr_in, int fq_in) const {
;     ...
;             for (int n = 0; n < 2; ++n) { csv[n] = *(const f32x4*)(cs + n0 + bj * HALF + 4 * n); cbv[n] = *(const f32x4*)(cb + n0 + bj * HALF + 4 * n) + *(const f32x4*)(bias + n0 + bj * HALF + 4 * n); }
; #pragma unroll
;             for (int ai = 0; ai < 2; ++ai)
; #pragma unroll
;                 for (int m = 0; m < 4; ++m) { bf16_t* rowp = base + (size_t)(row0 + ai * HALF + m * 16) * 1024 + col0 + bj * HALF;
;                     f32x4 v0 = ln_fix(acc[ai][bj][m][0], rst.mu[ai][m], rst.rs[ai][m], csv[0], cbv[0]), v1 = ln_fix(acc[ai][bj][m][1], rst.mu[ai][m], rst.rs[ai][m], csv[1], cbv[1]);
; #pragma unroll
;                     for (int j = 0; j < 4; ++j) { v0[j] = gelu_tanh(v0[j]); v1[j] = gelu_tanh(v1[j]); }
;                     u32x4 w; w.x = cvt_pk_bf16(v0[0], v0[1]); w.y = cvt_pk_bf16(v0[2], v0[3]); w.z = cvt_pk_bf16(v1[0], v1[1]); w.w = cvt_pk_bf16(v1[2], v1[3]);
;                     *(u32x4*)rowp = w; } }
	v_pk_fma_f32 v[56:57], v[196:197], v[64:65], v[56:57] op_sel_hi:[0,1,1] neg_lo:[1,0,0] neg_hi:[1,0,0]
	s_waitcnt vmcnt(4)
	v_pk_fma_f32 v[60:61], v[196:197], v[68:69], v[60:61] op_sel_hi:[0,1,1] neg_lo:[1,0,0] neg_hi:[1,0,0]
	v_pk_fma_f32 v[62:63], v[196:197], v[70:71], v[62:63] op_sel_hi:[0,1,1] neg_lo:[1,0,0] neg_hi:[1,0,0]
	v_pk_fma_f32 v[58:59], v[196:197], v[66:67], v[58:59] op_sel_hi:[0,1,1] neg_lo:[1,0,0] neg_hi:[1,0,0]
	s_waitcnt vmcnt(1)
	v_pk_add_f32 v[82:83], v[86:87], v[100:101]
	s_waitcnt vmcnt(0)
	v_pk_add_f32 v[78:79], v[90:91], v[106:107]
	v_pk_add_f32 v[84:85], v[84:85], v[98:99]
	v_pk_fma_f32 v[60:61], v[198:199], v[60:61], v[78:79] op_sel_hi:[0,1,1]
	v_mul_f32_e32 v86, 0x3d372713, v60
	v_mul_f32_e32 v86, v60, v86
	v_fma_f32 v86, v60, v86, v60
	v_mul_f32_e32 v86, 0x3f4c422a, v86
	v_add_f32_e32 v86, v86, v86
	v_mul_f32_e32 v86, 0xbfb8aa3b, v86
	v_exp_f32_e32 v86, v86
	v_pk_fma_f32 v[56:57], v[198:199], v[56:57], v[84:85] op_sel_hi:[0,1,1]
	v_pk_add_f32 v[76:77], v[92:93], v[108:109]
	v_pk_fma_f32 v[58:59], v[198:199], v[58:59], v[82:83] op_sel_hi:[0,1,1]
	v_add_f32_e32 v86, 1.0, v86
	v_rcp_f32_e32 v86, v86
	v_pk_fma_f32 v[62:63], v[198:199], v[62:63], v[76:77] op_sel_hi:[0,1,1]
	v_pk_fma_f32 v[52:53], v[192:193], v[68:69], v[52:53] op_sel_hi:[0,1,1] neg_lo:[1,0,0] neg_hi:[1,0,0]
	v_pk_fma_f32 v[52:53], v[194:195], v[52:53], v[78:79] op_sel_hi:[0,1,1]
	v_mul_f32_e32 v60, v60, v86
	v_mul_f32_e32 v86, 0x3d372713, v56
	v_mul_f32_e32 v86, v56, v86
	v_fma_f32 v86, v56, v86, v56
	v_mul_f32_e32 v86, 0x3f4c422a, v86
	v_add_f32_e32 v86, v86, v86
	v_mul_f32_e32 v86, 0xbfb8aa3b, v86
	v_exp_f32_e32 v86, v86
	v_pk_fma_f32 v[48:49], v[192:193], v[64:65], v[48:49] op_sel_hi:[0,1,1] neg_lo:[1,0,0] neg_hi:[1,0,0]
	v_pk_fma_f32 v[48:49], v[194:195], v[48:49], v[84:85] op_sel_hi:[0,1,1]
	v_pk_fma_f32 v[54:55], v[192:193], v[70:71], v[54:55] op_sel_hi:[0,1,1] neg_lo:[1,0,0] neg_hi:[1,0,0]
	v_add_f32_e32 v86, 1.0, v86
	v_rcp_f32_e32 v86, v86
	v_pk_fma_f32 v[54:55], v[194:195], v[54:55], v[76:77] op_sel_hi:[0,1,1]
	v_pk_fma_f32 v[50:51], v[192:193], v[66:67], v[50:51] op_sel_hi:[0,1,1] neg_lo:[1,0,0] neg_hi:[1,0,0]
	v_pk_fma_f32 v[50:51], v[194:195], v[50:51], v[82:83] op_sel_hi:[0,1,1]
	v_mul_f32_e32 v86, v56, v86
	v_mul_f32_e32 v56, 0x3d372713, v61
	v_mul_f32_e32 v56, v61, v56
	v_fma_f32 v56, v61, v56, v61
	v_mul_f32_e32 v56, 0x3f4c422a, v56
	v_add_f32_e32 v56, v56, v56
	v_mul_f32_e32 v56, 0xbfb8aa3b, v56
	v_exp_f32_e32 v56, v56
	v_pk_fma_f32 v[44:45], v[188:189], v[68:69], v[44:45] op_sel_hi:[0,1,1] neg_lo:[1,0,0] neg_hi:[1,0,0]
	v_pk_fma_f32 v[44:45], v[190:191], v[44:45], v[78:79] op_sel_hi:[0,1,1]
	v_pk_fma_f32 v[40:41], v[188:189], v[64:65], v[40:41] op_sel_hi:[0,1,1] neg_lo:[1,0,0] neg_hi:[1,0,0]
	v_add_f32_e32 v56, 1.0, v56
	v_rcp_f32_e32 v56, v56
	v_pk_fma_f32 v[40:41], v[190:191], v[40:41], v[84:85] op_sel_hi:[0,1,1]
	v_pk_fma_f32 v[46:47], v[188:189], v[70:71], v[46:47] op_sel_hi:[0,1,1] neg_lo:[1,0,0] neg_hi:[1,0,0]
	v_pk_fma_f32 v[46:47], v[190:191], v[46:47], v[76:77] op_sel_hi:[0,1,1]
	v_mul_f32_e32 v56, v61, v56
	v_mul_f32_e32 v61, 0x3d372713, v57
	v_mul_f32_e32 v61, v57, v61
	v_fma_f32 v61, v57, v61, v57
	v_mul_f32_e32 v61, 0x3f4c422a, v61
	v_add_f32_e32 v61, v61, v61
	v_mul_f32_e32 v61, 0xbfb8aa3b, v61
	v_exp_f32_e32 v61, v61
	v_cvt_pk_bf16_f32 v56, v60, v56
	v_pk_fma_f32 v[42:43], v[188:189], v[66:67], v[42:43] op_sel_hi:[0,1,1] neg_lo:[1,0,0] neg_hi:[1,0,0]
	v_pk_fma_f32 v[42:43], v[190:191], v[42:43], v[82:83] op_sel_hi:[0,1,1]
	v_add_f32_e32 v61, 1.0, v61
	v_rcp_f32_e32 v61, v61
	v_pk_fma_f32 v[36:37], v[184:185], v[68:69], v[36:37] op_sel_hi:[0,1,1] neg_lo:[1,0,0] neg_hi:[1,0,0]
	v_pk_fma_f32 v[36:37], v[186:187], v[36:37], v[78:79] op_sel_hi:[0,1,1]
	v_pk_fma_f32 v[32:33], v[184:185], v[64:65], v[32:33] op_sel_hi:[0,1,1] neg_lo:[1,0,0] neg_hi:[1,0,0]
	v_mul_f32_e32 v61, v57, v61
	v_mul_f32_e32 v57, 0x3d372713, v62
	v_mul_f32_e32 v57, v62, v57
	v_fma_f32 v57, v62, v57, v62
	v_mul_f32_e32 v57, 0x3f4c422a, v57
	v_add_f32_e32 v57, v57, v57
	v_mul_f32_e32 v57, 0xbfb8aa3b, v57
	v_exp_f32_e32 v57, v57
	v_pk_fma_f32 v[32:33], v[186:187], v[32:33], v[84:85] op_sel_hi:[0,1,1]
	v_pk_fma_f32 v[38:39], v[184:185], v[70:71], v[38:39] op_sel_hi:[0,1,1] neg_lo:[1,0,0] neg_hi:[1,0,0]
	v_pk_fma_f32 v[38:39], v[186:187], v[38:39], v[76:77] op_sel_hi:[0,1,1]
	v_add_f32_e32 v57, 1.0, v57
	v_rcp_f32_e32 v57, v57
	v_pk_fma_f32 v[34:35], v[184:185], v[66:67], v[34:35] op_sel_hi:[0,1,1] neg_lo:[1,0,0] neg_hi:[1,0,0]
	v_pk_fma_f32 v[34:35], v[186:187], v[34:35], v[82:83] op_sel_hi:[0,1,1]
	v_pk_fma_f32 v[28:29], v[180:181], v[68:69], v[28:29] op_sel_hi:[0,1,1] neg_lo:[1,0,0] neg_hi:[1,0,0]
	v_mul_f32_e32 v57, v62, v57
	v_mul_f32_e32 v62, 0x3d372713, v58
	v_mul_f32_e32 v62, v58, v62
	v_fma_f32 v62, v58, v62, v58
	v_mul_f32_e32 v62, 0x3f4c422a, v62
	v_add_f32_e32 v62, v62, v62
	v_mul_f32_e32 v62, 0xbfb8aa3b, v62
	v_exp_f32_e32 v62, v62
	v_pk_fma_f32 v[28:29], v[182:183], v[28:29], v[78:79] op_sel_hi:[0,1,1]
	v_pk_fma_f32 v[24:25], v[180:181], v[64:65], v[24:25] op_sel_hi:[0,1,1] neg_lo:[1,0,0] neg_hi:[1,0,0]
	v_pk_fma_f32 v[24:25], v[182:183], v[24:25], v[84:85] op_sel_hi:[0,1,1]
	v_add_f32_e32 v62, 1.0, v62
	v_rcp_f32_e32 v62, v62
	v_pk_fma_f32 v[30:31], v[180:181], v[70:71], v[30:31] op_sel_hi:[0,1,1] neg_lo:[1,0,0] neg_hi:[1,0,0]
	v_pk_fma_f32 v[30:31], v[182:183], v[30:31], v[76:77] op_sel_hi:[0,1,1]
	v_pk_fma_f32 v[26:27], v[180:181], v[66:67], v[26:27] op_sel_hi:[0,1,1] neg_lo:[1,0,0] neg_hi:[1,0,0]
	v_mul_f32_e32 v62, v58, v62
	v_mul_f32_e32 v58, 0x3d372713, v63
	v_mul_f32_e32 v58, v63, v58
	v_fma_f32 v58, v63, v58, v63
; __device__ __forceinline__ unsigned cvt_pk_bf16(float lo, float hi) { unsigned r; asm("v_cvt_pk_bf16_f32 %0, %1, %2" : "=v"(r) : "v"(lo), "v"(hi)); return r; }
; __device__ __forceinline__ float gelu_tanh(float v) { const float u = 0.7978845608028654f * (v + 0.044715f * v * v * v); return v * fast_sigmoid(2.0f * u); }
; __device__ __forceinline__ f32x4 ln_fix(const f32x4& a, float mu, float rs, const f32x4& cs, const f32x4& cb) { return (a - cs * mu) * rs + cb; }
; __device__ __forceinline__ float fast_sigmoid(float v) { return __builtin_amdgcn_rcpf(1.0f + __builtin_amdgcn_exp2f(-1.4426950408889634f * v)); }
;     __device__ __forceinline__ void operator()(const f32x4 (&acc)[2][2][4][2], const Unit& u, int wr, int wc, int fr_in, int fq_in) const {
;     ...
;                 for (int m = 0; m < 4; ++m) { bf16_t* rowp = base + (size_t)(row0 + ai * HALF + m * 16) * 1024 + col0 + bj * HALF;
;                     f32x4 v0 = ln_fix(acc[ai][bj][m][0], rst.mu[ai][m], rst.rs[ai][m], csv[0], cbv[0]), v1 = ln_fix(acc[ai][bj][m][1], rst.mu[ai][m], rst.rs[ai][m], csv[1], cbv[1]);
; #pragma unroll
;                     for (int j = 0; j < 4; ++j) { v0[j] = gelu_tanh(v0[j]); v1[j] = gelu_tanh(v1[j]); }
;                     u32x4 w; w.x = cvt_pk_bf16(v0[0], v0[1]); w.y = cvt_pk_bf16(v0[2], v0[3]); w.z = cvt_pk_bf16(v1[0], v1[1]); w.w = cvt_pk_bf16(v1[2], v1[3]);
;                     *(u32x4*)rowp = w; } }
	v_mul_f32_e32 v58, 0x3f4c422a, v58
	v_add_f32_e32 v58, v58, v58
	v_mul_f32_e32 v58, 0xbfb8aa3b, v58
	v_exp_f32_e32 v58, v58
	v_pk_fma_f32 v[26:27], v[182:183], v[26:27], v[82:83] op_sel_hi:[0,1,1]
	v_pk_fma_f32 v[20:21], v[176:177], v[68:69], v[20:21] op_sel_hi:[0,1,1] neg_lo:[1,0,0] neg_hi:[1,0,0]
	v_pk_fma_f32 v[20:21], v[178:179], v[20:21], v[78:79] op_sel_hi:[0,1,1]
	v_add_f32_e32 v58, 1.0, v58
	v_rcp_f32_e32 v58, v58
	v_pk_fma_f32 v[16:17], v[176:177], v[64:65], v[16:17] op_sel_hi:[0,1,1] neg_lo:[1,0,0] neg_hi:[1,0,0]
	v_pk_fma_f32 v[16:17], v[178:179], v[16:17], v[84:85] op_sel_hi:[0,1,1]
	v_pk_fma_f32 v[22:23], v[176:177], v[70:71], v[22:23] op_sel_hi:[0,1,1] neg_lo:[1,0,0] neg_hi:[1,0,0]
	v_mul_f32_e32 v58, v63, v58
	v_mul_f32_e32 v63, 0x3d372713, v59
	v_mul_f32_e32 v63, v59, v63
	v_fma_f32 v63, v59, v63, v59
	v_mul_f32_e32 v63, 0x3f4c422a, v63
	v_add_f32_e32 v63, v63, v63
	v_mul_f32_e32 v63, 0xbfb8aa3b, v63
	v_exp_f32_e32 v63, v63
	v_cvt_pk_bf16_f32 v57, v57, v58
	v_cvt_pk_bf16_f32 v58, v86, v61
	v_pk_fma_f32 v[22:23], v[178:179], v[22:23], v[76:77] op_sel_hi:[0,1,1]
	v_add_f32_e32 v63, 1.0, v63
	v_rcp_f32_e32 v63, v63
	v_pk_fma_f32 v[18:19], v[176:177], v[66:67], v[18:19] op_sel_hi:[0,1,1] neg_lo:[1,0,0] neg_hi:[1,0,0]
	v_pk_fma_f32 v[18:19], v[178:179], v[18:19], v[82:83] op_sel_hi:[0,1,1]
	v_pk_fma_f32 v[12:13], v[172:173], v[68:69], v[12:13] op_sel_hi:[0,1,1] neg_lo:[1,0,0] neg_hi:[1,0,0]
	v_mul_f32_e32 v59, v59, v63
	v_cvt_pk_bf16_f32 v59, v62, v59
	global_store_dwordx4 v[128:129], v[56:59], off offset:256
	v_pk_fma_f32 v[12:13], v[174:175], v[12:13], v[78:79] op_sel_hi:[0,1,1]
	v_pk_fma_f32 v[8:9], v[172:173], v[64:65], v[8:9] op_sel_hi:[0,1,1] neg_lo:[1,0,0] neg_hi:[1,0,0]
	v_mul_f32_e32 v56, 0x3d372713, v52
	v_mul_f32_e32 v56, v52, v56
	v_fma_f32 v56, v52, v56, v52
	v_mul_f32_e32 v56, 0x3f4c422a, v56
	v_add_f32_e32 v56, v56, v56
	v_mul_f32_e32 v56, 0xbfb8aa3b, v56
	v_exp_f32_e32 v56, v56
	v_pk_fma_f32 v[8:9], v[174:175], v[8:9], v[84:85] op_sel_hi:[0,1,1]
	v_pk_fma_f32 v[14:15], v[172:173], v[70:71], v[14:15] op_sel_hi:[0,1,1] neg_lo:[1,0,0] neg_hi:[1,0,0]
	v_pk_fma_f32 v[14:15], v[174:175], v[14:15], v[76:77] op_sel_hi:[0,1,1]
	v_add_f32_e32 v56, 1.0, v56
	v_rcp_f32_e32 v56, v56
	v_pk_fma_f32 v[10:11], v[172:173], v[66:67], v[10:11] op_sel_hi:[0,1,1] neg_lo:[1,0,0] neg_hi:[1,0,0]
	v_pk_fma_f32 v[10:11], v[174:175], v[10:11], v[82:83] op_sel_hi:[0,1,1]
	v_pk_fma_f32 v[4:5], v[168:169], v[68:69], v[4:5] op_sel_hi:[0,1,1] neg_lo:[1,0,0] neg_hi:[1,0,0]
	v_mul_f32_e32 v52, v52, v56
	v_mul_f32_e32 v56, 0x3d372713, v48
	v_mul_f32_e32 v56, v48, v56
	v_fma_f32 v56, v48, v56, v48
	v_mul_f32_e32 v56, 0x3f4c422a, v56
	v_add_f32_e32 v56, v56, v56
	v_mul_f32_e32 v56, 0xbfb8aa3b, v56
	v_exp_f32_e32 v56, v56
	v_pk_fma_f32 v[4:5], v[170:171], v[4:5], v[78:79] op_sel_hi:[0,1,1]
	v_pk_fma_f32 v[0:1], v[168:169], v[64:65], v[0:1] op_sel_hi:[0,1,1] neg_lo:[1,0,0] neg_hi:[1,0,0]
	v_pk_fma_f32 v[0:1], v[170:171], v[0:1], v[84:85] op_sel_hi:[0,1,1]
	v_add_f32_e32 v56, 1.0, v56
	v_rcp_f32_e32 v56, v56
	v_pk_fma_f32 v[6:7], v[168:169], v[70:71], v[6:7] op_sel_hi:[0,1,1] neg_lo:[1,0,0] neg_hi:[1,0,0]
	v_pk_fma_f32 v[6:7], v[170:171], v[6:7], v[76:77] op_sel_hi:[0,1,1]
	v_pk_fma_f32 v[2:3], v[168:169], v[66:67], v[2:3] op_sel_hi:[0,1,1] neg_lo:[1,0,0] neg_hi:[1,0,0]
	v_mul_f32_e32 v56, v48, v56
	v_mul_f32_e32 v48, 0x3d372713, v53
	v_mul_f32_e32 v48, v53, v48
	v_fma_f32 v48, v53, v48, v53
	v_mul_f32_e32 v48, 0x3f4c422a, v48
	v_add_f32_e32 v48, v48, v48
	v_mul_f32_e32 v48, 0xbfb8aa3b, v48
	v_exp_f32_e32 v48, v48
	v_pk_fma_f32 v[2:3], v[170:171], v[2:3], v[82:83] op_sel_hi:[0,1,1]
	v_add_f32_e32 v48, 1.0, v48
	v_rcp_f32_e32 v48, v48
	s_nop 0
	v_mul_f32_e32 v48, v53, v48
	v_mul_f32_e32 v53, 0x3d372713, v49
	v_mul_f32_e32 v53, v49, v53
	v_fma_f32 v53, v49, v53, v49
	v_mul_f32_e32 v53, 0x3f4c422a, v53
	v_add_f32_e32 v53, v53, v53
	v_mul_f32_e32 v53, 0xbfb8aa3b, v53
	v_exp_f32_e32 v53, v53
	v_cvt_pk_bf16_f32 v48, v52, v48
	s_nop 0
	v_add_f32_e32 v53, 1.0, v53
	v_rcp_f32_e32 v53, v53
	s_nop 0
	v_mul_f32_e32 v53, v49, v53
	v_mul_f32_e32 v49, 0x3d372713, v54
	v_mul_f32_e32 v49, v54, v49
	v_fma_f32 v49, v54, v49, v54
	v_mul_f32_e32 v49, 0x3f4c422a, v49
	v_add_f32_e32 v49, v49, v49
	v_mul_f32_e32 v49, 0xbfb8aa3b, v49
	v_exp_f32_e32 v49, v49
	s_nop 0
	v_add_f32_e32 v49, 1.0, v49
	v_rcp_f32_e32 v49, v49
	s_nop 0
	v_mul_f32_e32 v49, v54, v49
	v_mul_f32_e32 v54, 0x3d372713, v50
	v_mul_f32_e32 v54, v50, v54
	v_fma_f32 v54, v50, v54, v50
	v_mul_f32_e32 v54, 0x3f4c422a, v54
	v_add_f32_e32 v54, v54, v54
	v_mul_f32_e32 v54, 0xbfb8aa3b, v54
	v_exp_f32_e32 v54, v54
	s_nop 0
	v_add_f32_e32 v54, 1.0, v54
	v_rcp_f32_e32 v54, v54
	s_nop 0
	v_mul_f32_e32 v54, v50, v54
	v_mul_f32_e32 v50, 0x3d372713, v55
	v_mul_f32_e32 v50, v55, v50
	v_fma_f32 v50, v55, v50, v55
	v_mul_f32_e32 v50, 0x3f4c422a, v50
	v_add_f32_e32 v50, v50, v50
	v_mul_f32_e32 v50, 0xbfb8aa3b, v50
	v_exp_f32_e32 v50, v50
	s_nop 0
	v_add_f32_e32 v50, 1.0, v50
	v_rcp_f32_e32 v50, v50
	s_nop 0
	v_mul_f32_e32 v50, v55, v50
	v_mul_f32_e32 v55, 0x3d372713, v51
	v_mul_f32_e32 v55, v51, v55
	v_fma_f32 v55, v51, v55, v51
	v_mul_f32_e32 v55, 0x3f4c422a, v55
	v_add_f32_e32 v55, v55, v55
	v_mul_f32_e32 v55, 0xbfb8aa3b, v55
	v_exp_f32_e32 v55, v55
	v_cvt_pk_bf16_f32 v49, v49, v50
	v_cvt_pk_bf16_f32 v50, v56, v53
	s_nop 0
	v_add_f32_e32 v55, 1.0, v55
	v_rcp_f32_e32 v55, v55
	s_nop 0
	v_mul_f32_e32 v51, v51, v55
	v_cvt_pk_bf16_f32 v51, v54, v51
	global_store_dwordx4 v[112:113], v[48:51], off offset:256
	s_nop 1
	v_mul_f32_e32 v48, 0x3d372713, v44
	v_mul_f32_e32 v48, v44, v48
	v_fma_f32 v48, v44, v48, v44
; __device__ __forceinline__ unsigned cvt_pk_bf16(float lo, float hi) { unsigned r; asm("v_cvt_pk_bf16_f32 %0, %1, %2" : "=v"(r) : "v"(lo), "v"(hi)); return r; }
; __device__ __forceinline__ float gelu_tanh(float v) { const float u = 0.7978845608028654f * (v + 0.044715f * v * v * v); return v * fast_sigmoid(2.0f * u); }
; __device__ __forceinline__ f32x4 ln_fix(const f32x4& a, float mu, float rs, const f32x4& cs, const f32x4& cb) { return (a - cs * mu) * rs + cb; }
; __device__ __forceinline__ float fast_sigmoid(float v) { return __builtin_amdgcn_rcpf(1.0f + __builtin_amdgcn_exp2f(-1.4426950408889634f * v)); }
;     __device__ __forceinline__ void operator()(const f32x4 (&acc)[2][2][4][2], const Unit& u, int wr, int wc, int fr_in, int fq_in) const {
;     ...
;                 for (int m = 0; m < 4; ++m) { bf16_t* rowp = base + (size_t)(row0 + ai * HALF + m * 16) * 1024 + col0 + bj * HALF;
;                     f32x4 v0 = ln_fix(acc[ai][bj][m][0], rst.mu[ai][m], rst.rs[ai][m], csv[0], cbv[0]), v1 = ln_fix(acc[ai][bj][m][1], rst.mu[ai][m], rst.rs[ai][m], csv[1], cbv[1]);
; #pragma unroll
;                     for (int j = 0; j < 4; ++j) { v0[j] = gelu_tanh(v0[j]); v1[j] = gelu_tanh(v1[j]); }
;                     u32x4 w; w.x = cvt_pk_bf16(v0[0], v0[1]); w.y = cvt_pk_bf16(v0[2], v0[3]); w.z = cvt_pk_bf16(v1[0], v1[1]); w.w = cvt_pk_bf16(v1[2], v1[3]);
;                     *(u32x4*)rowp = w; } }
	v_mul_f32_e32 v48, 0x3f4c422a, v48
	v_add_f32_e32 v48, v48, v48
	v_mul_f32_e32 v48, 0xbfb8aa3b, v48
	v_exp_f32_e32 v48, v48
	s_nop 0
	v_add_f32_e32 v48, 1.0, v48
	v_rcp_f32_e32 v48, v48
	s_nop 0
	v_mul_f32_e32 v44, v44, v48
	v_mul_f32_e32 v48, 0x3d372713, v40
	v_mul_f32_e32 v48, v40, v48
	v_fma_f32 v48, v40, v48, v40
	v_mul_f32_e32 v48, 0x3f4c422a, v48
	v_add_f32_e32 v48, v48, v48
	v_mul_f32_e32 v48, 0xbfb8aa3b, v48
	v_exp_f32_e32 v48, v48
	s_nop 0
	v_add_f32_e32 v48, 1.0, v48
	v_rcp_f32_e32 v48, v48
	s_nop 0
	v_mul_f32_e32 v48, v40, v48
	v_mul_f32_e32 v40, 0x3d372713, v45
	v_mul_f32_e32 v40, v45, v40
	v_fma_f32 v40, v45, v40, v45
	v_mul_f32_e32 v40, 0x3f4c422a, v40
	v_add_f32_e32 v40, v40, v40
	v_mul_f32_e32 v40, 0xbfb8aa3b, v40
	v_exp_f32_e32 v40, v40
	s_nop 0
	v_add_f32_e32 v40, 1.0, v40
	v_rcp_f32_e32 v40, v40
	s_nop 0
	v_mul_f32_e32 v40, v45, v40
	v_mul_f32_e32 v45, 0x3d372713, v41
	v_mul_f32_e32 v45, v41, v45
	v_fma_f32 v45, v41, v45, v41
	v_mul_f32_e32 v45, 0x3f4c422a, v45
	v_add_f32_e32 v45, v45, v45
	v_mul_f32_e32 v45, 0xbfb8aa3b, v45
	v_exp_f32_e32 v45, v45
	v_cvt_pk_bf16_f32 v40, v44, v40
	s_nop 0
	v_add_f32_e32 v45, 1.0, v45
	v_rcp_f32_e32 v45, v45
	s_nop 0
	v_mul_f32_e32 v45, v41, v45
	v_mul_f32_e32 v41, 0x3d372713, v46
	v_mul_f32_e32 v41, v46, v41
	v_fma_f32 v41, v46, v41, v46
	v_mul_f32_e32 v41, 0x3f4c422a, v41
	v_add_f32_e32 v41, v41, v41
	v_mul_f32_e32 v41, 0xbfb8aa3b, v41
	v_exp_f32_e32 v41, v41
	s_nop 0
	v_add_f32_e32 v41, 1.0, v41
	v_rcp_f32_e32 v41, v41
	s_nop 0
	v_mul_f32_e32 v41, v46, v41
	v_mul_f32_e32 v46, 0x3d372713, v42
	v_mul_f32_e32 v46, v42, v46
	v_fma_f32 v46, v42, v46, v42
	v_mul_f32_e32 v46, 0x3f4c422a, v46
	v_add_f32_e32 v46, v46, v46
	v_mul_f32_e32 v46, 0xbfb8aa3b, v46
	v_exp_f32_e32 v46, v46
	s_nop 0
	v_add_f32_e32 v46, 1.0, v46
	v_rcp_f32_e32 v46, v46
	s_nop 0
	v_mul_f32_e32 v46, v42, v46
	v_mul_f32_e32 v42, 0x3d372713, v47
	v_mul_f32_e32 v42, v47, v42
	v_fma_f32 v42, v47, v42, v47
	v_mul_f32_e32 v42, 0x3f4c422a, v42
	v_add_f32_e32 v42, v42, v42
	v_mul_f32_e32 v42, 0xbfb8aa3b, v42
	v_exp_f32_e32 v42, v42
	s_nop 0
	v_add_f32_e32 v42, 1.0, v42
	v_rcp_f32_e32 v42, v42
	s_nop 0
	v_mul_f32_e32 v42, v47, v42
	v_mul_f32_e32 v47, 0x3d372713, v43
	v_mul_f32_e32 v47, v43, v47
	v_fma_f32 v47, v43, v47, v43
	v_mul_f32_e32 v47, 0x3f4c422a, v47
	v_add_f32_e32 v47, v47, v47
	v_mul_f32_e32 v47, 0xbfb8aa3b, v47
	v_exp_f32_e32 v47, v47
	v_cvt_pk_bf16_f32 v41, v41, v42
	v_cvt_pk_bf16_f32 v42, v48, v45
	s_nop 0
	v_add_f32_e32 v47, 1.0, v47
	v_rcp_f32_e32 v47, v47
	s_nop 0
	v_mul_f32_e32 v43, v43, v47
	v_cvt_pk_bf16_f32 v43, v46, v43
	global_store_dwordx4 v[104:105], v[40:43], off offset:256
	s_nop 1
	v_mul_f32_e32 v40, 0x3d372713, v36
	v_mul_f32_e32 v40, v36, v40
	v_fma_f32 v40, v36, v40, v36
	v_mul_f32_e32 v40, 0x3f4c422a, v40
	v_add_f32_e32 v40, v40, v40
	v_mul_f32_e32 v40, 0xbfb8aa3b, v40
	v_exp_f32_e32 v40, v40
	s_nop 0
	v_add_f32_e32 v40, 1.0, v40
	v_rcp_f32_e32 v40, v40
	s_nop 0
	v_mul_f32_e32 v36, v36, v40
	v_mul_f32_e32 v40, 0x3d372713, v32
	v_mul_f32_e32 v40, v32, v40
	v_fma_f32 v40, v32, v40, v32
	v_mul_f32_e32 v40, 0x3f4c422a, v40
	v_add_f32_e32 v40, v40, v40
	v_mul_f32_e32 v40, 0xbfb8aa3b, v40
	v_exp_f32_e32 v40, v40
	s_nop 0
	v_add_f32_e32 v40, 1.0, v40
	v_rcp_f32_e32 v40, v40
	s_nop 0
	v_mul_f32_e32 v40, v32, v40
	v_mul_f32_e32 v32, 0x3d372713, v37
	v_mul_f32_e32 v32, v37, v32
	v_fma_f32 v32, v37, v32, v37
	v_mul_f32_e32 v32, 0x3f4c422a, v32
	v_add_f32_e32 v32, v32, v32
	v_mul_f32_e32 v32, 0xbfb8aa3b, v32
	v_exp_f32_e32 v32, v32
	s_nop 0
	v_add_f32_e32 v32, 1.0, v32
	v_rcp_f32_e32 v32, v32
	s_nop 0
	v_mul_f32_e32 v32, v37, v32
	v_mul_f32_e32 v37, 0x3d372713, v33
	v_mul_f32_e32 v37, v33, v37
	v_fma_f32 v37, v33, v37, v33
	v_mul_f32_e32 v37, 0x3f4c422a, v37
	v_add_f32_e32 v37, v37, v37
	v_mul_f32_e32 v37, 0xbfb8aa3b, v37
	v_exp_f32_e32 v37, v37
	v_cvt_pk_bf16_f32 v32, v36, v32
	s_nop 0
	v_add_f32_e32 v37, 1.0, v37
	v_rcp_f32_e32 v37, v37
	s_nop 0
	v_mul_f32_e32 v37, v33, v37
	v_mul_f32_e32 v33, 0x3d372713, v38
	v_mul_f32_e32 v33, v38, v33
	v_fma_f32 v33, v38, v33, v38
	v_mul_f32_e32 v33, 0x3f4c422a, v33
	v_add_f32_e32 v33, v33, v33
	v_mul_f32_e32 v33, 0xbfb8aa3b, v33
	v_exp_f32_e32 v33, v33
	s_nop 0
	v_add_f32_e32 v33, 1.0, v33
	v_rcp_f32_e32 v33, v33
	s_nop 0
	v_mul_f32_e32 v33, v38, v33
	v_mul_f32_e32 v38, 0x3d372713, v34
	v_mul_f32_e32 v38, v34, v38
	v_fma_f32 v38, v34, v38, v34
	v_mul_f32_e32 v38, 0x3f4c422a, v38
	v_add_f32_e32 v38, v38, v38
	v_mul_f32_e32 v38, 0xbfb8aa3b, v38
	v_exp_f32_e32 v38, v38
	s_nop 0
	v_add_f32_e32 v38, 1.0, v38
	v_rcp_f32_e32 v38, v38
	s_nop 0
	v_mul_f32_e32 v38, v34, v38
	v_mul_f32_e32 v34, 0x3d372713, v39
	v_mul_f32_e32 v34, v39, v34
	v_fma_f32 v34, v39, v34, v39
	v_mul_f32_e32 v34, 0x3f4c422a, v34
	v_add_f32_e32 v34, v34, v34
	v_mul_f32_e32 v34, 0xbfb8aa3b, v34
	v_exp_f32_e32 v34, v34
	s_nop 0
	v_add_f32_e32 v34, 1.0, v34
	v_rcp_f32_e32 v34, v34
	s_nop 0
	v_mul_f32_e32 v34, v39, v34
	v_mul_f32_e32 v39, 0x3d372713, v35
	v_mul_f32_e32 v39, v35, v39
	v_fma_f32 v39, v35, v39, v35
	v_mul_f32_e32 v39, 0x3f4c422a, v39
	v_add_f32_e32 v39, v39, v39
	v_mul_f32_e32 v39, 0xbfb8aa3b, v39
	v_exp_f32_e32 v39, v39
	v_cvt_pk_bf16_f32 v33, v33, v34
	v_cvt_pk_bf16_f32 v34, v40, v37
	s_nop 0
	v_add_f32_e32 v39, 1.0, v39
	v_rcp_f32_e32 v39, v39
	s_nop 0
	v_mul_f32_e32 v35, v35, v39
	v_cvt_pk_bf16_f32 v35, v38, v35
	global_store_dwordx4 v[96:97], v[32:35], off offset:256
	s_nop 1
	v_mul_f32_e32 v32, 0x3d372713, v28
	v_mul_f32_e32 v32, v28, v32
	v_fma_f32 v32, v28, v32, v28
	v_mul_f32_e32 v32, 0x3f4c422a, v32
	v_add_f32_e32 v32, v32, v32
	v_mul_f32_e32 v32, 0xbfb8aa3b, v32
	v_exp_f32_e32 v32, v32
; __device__ __forceinline__ unsigned cvt_pk_bf16(float lo, float hi) { unsigned r; asm("v_cvt_pk_bf16_f32 %0, %1, %2" : "=v"(r) : "v"(lo), "v"(hi)); return r; }
; __device__ __forceinline__ float gelu_tanh(float v) { const float u = 0.7978845608028654f * (v + 0.044715f * v * v * v); return v * fast_sigmoid(2.0f * u); }
; __device__ __forceinline__ f32x4 ln_fix(const f32x4& a, float mu, float rs, const f32x4& cs, const f32x4& cb) { return (a - cs * mu) * rs + cb; }
; __device__ __forceinline__ float fast_sigmoid(float v) { return __builtin_amdgcn_rcpf(1.0f + __builtin_amdgcn_exp2f(-1.4426950408889634f * v)); }
;     __device__ __forceinline__ void operator()(const f32x4 (&acc)[2][2][4][2], const Unit& u, int wr, int wc, int fr_in, int fq_in) const {
;     ...
;                 for (int m = 0; m < 4; ++m) { bf16_t* rowp = base + (size_t)(row0 + ai * HALF + m * 16) * 1024 + col0 + bj * HALF;
;                     f32x4 v0 = ln_fix(acc[ai][bj][m][0], rst.mu[ai][m], rst.rs[ai][m], csv[0], cbv[0]), v1 = ln_fix(acc[ai][bj][m][1], rst.mu[ai][m], rst.rs[ai][m], csv[1], cbv[1]);
; #pragma unroll
;                     for (int j = 0; j < 4; ++j) { v0[j] = gelu_tanh(v0[j]); v1[j] = gelu_tanh(v1[j]); }
;                     u32x4 w; w.x = cvt_pk_bf16(v0[0], v0[1]); w.y = cvt_pk_bf16(v0[2], v0[3]); w.z = cvt_pk_bf16(v1[0], v1[1]); w.w = cvt_pk_bf16(v1[2], v1[3]);
;                     *(u32x4*)rowp = w; } }
	s_nop 0
	v_add_f32_e32 v32, 1.0, v32
	v_rcp_f32_e32 v32, v32
	s_nop 0
	v_mul_f32_e32 v28, v28, v32
	v_mul_f32_e32 v32, 0x3d372713, v24
	v_mul_f32_e32 v32, v24, v32
	v_fma_f32 v32, v24, v32, v24
	v_mul_f32_e32 v32, 0x3f4c422a, v32
	v_add_f32_e32 v32, v32, v32
	v_mul_f32_e32 v32, 0xbfb8aa3b, v32
	v_exp_f32_e32 v32, v32
	s_nop 0
	v_add_f32_e32 v32, 1.0, v32
	v_rcp_f32_e32 v32, v32
	s_nop 0
	v_mul_f32_e32 v32, v24, v32
	v_mul_f32_e32 v24, 0x3d372713, v29
	v_mul_f32_e32 v24, v29, v24
	v_fma_f32 v24, v29, v24, v29
	v_mul_f32_e32 v24, 0x3f4c422a, v24
	v_add_f32_e32 v24, v24, v24
	v_mul_f32_e32 v24, 0xbfb8aa3b, v24
	v_exp_f32_e32 v24, v24
	s_nop 0
	v_add_f32_e32 v24, 1.0, v24
	v_rcp_f32_e32 v24, v24
	s_nop 0
	v_mul_f32_e32 v24, v29, v24
	v_mul_f32_e32 v29, 0x3d372713, v25
	v_mul_f32_e32 v29, v25, v29
	v_fma_f32 v29, v25, v29, v25
	v_mul_f32_e32 v29, 0x3f4c422a, v29
	v_add_f32_e32 v29, v29, v29
	v_mul_f32_e32 v29, 0xbfb8aa3b, v29
	v_exp_f32_e32 v29, v29
	v_cvt_pk_bf16_f32 v24, v28, v24
	s_nop 0
	v_add_f32_e32 v29, 1.0, v29
	v_rcp_f32_e32 v29, v29
	s_nop 0
	v_mul_f32_e32 v29, v25, v29
	v_mul_f32_e32 v25, 0x3d372713, v30
	v_mul_f32_e32 v25, v30, v25
	v_fma_f32 v25, v30, v25, v30
	v_mul_f32_e32 v25, 0x3f4c422a, v25
	v_add_f32_e32 v25, v25, v25
	v_mul_f32_e32 v25, 0xbfb8aa3b, v25
	v_exp_f32_e32 v25, v25
	s_nop 0
	v_add_f32_e32 v25, 1.0, v25
	v_rcp_f32_e32 v25, v25
	s_nop 0
	v_mul_f32_e32 v25, v30, v25
	v_mul_f32_e32 v30, 0x3d372713, v26
	v_mul_f32_e32 v30, v26, v30
	v_fma_f32 v30, v26, v30, v26
	v_mul_f32_e32 v30, 0x3f4c422a, v30
	v_add_f32_e32 v30, v30, v30
	v_mul_f32_e32 v30, 0xbfb8aa3b, v30
	v_exp_f32_e32 v30, v30
	s_nop 0
	v_add_f32_e32 v30, 1.0, v30
	v_rcp_f32_e32 v30, v30
	s_nop 0
	v_mul_f32_e32 v30, v26, v30
	v_mul_f32_e32 v26, 0x3d372713, v31
	v_mul_f32_e32 v26, v31, v26
	v_fma_f32 v26, v31, v26, v31
	v_mul_f32_e32 v26, 0x3f4c422a, v26
	v_add_f32_e32 v26, v26, v26
	v_mul_f32_e32 v26, 0xbfb8aa3b, v26
	v_exp_f32_e32 v26, v26
	s_nop 0
	v_add_f32_e32 v26, 1.0, v26
	v_rcp_f32_e32 v26, v26
	s_nop 0
	v_mul_f32_e32 v26, v31, v26
	v_mul_f32_e32 v31, 0x3d372713, v27
	v_mul_f32_e32 v31, v27, v31
	v_fma_f32 v31, v27, v31, v27
	v_mul_f32_e32 v31, 0x3f4c422a, v31
	v_add_f32_e32 v31, v31, v31
	v_mul_f32_e32 v31, 0xbfb8aa3b, v31
	v_exp_f32_e32 v31, v31
	v_cvt_pk_bf16_f32 v25, v25, v26
	v_cvt_pk_bf16_f32 v26, v32, v29
	s_nop 0
	v_add_f32_e32 v31, 1.0, v31
	v_rcp_f32_e32 v31, v31
	s_nop 0
	v_mul_f32_e32 v27, v27, v31
	v_cvt_pk_bf16_f32 v27, v30, v27
	global_store_dwordx4 v[88:89], v[24:27], off offset:256
	s_nop 1
	v_mul_f32_e32 v24, 0x3d372713, v20
	v_mul_f32_e32 v24, v20, v24
	v_fma_f32 v24, v20, v24, v20
	v_mul_f32_e32 v24, 0x3f4c422a, v24
	v_add_f32_e32 v24, v24, v24
	v_mul_f32_e32 v24, 0xbfb8aa3b, v24
	v_exp_f32_e32 v24, v24
	s_nop 0
	v_add_f32_e32 v24, 1.0, v24
	v_rcp_f32_e32 v24, v24
	s_nop 0
	v_mul_f32_e32 v20, v20, v24
	v_mul_f32_e32 v24, 0x3d372713, v16
	v_mul_f32_e32 v24, v16, v24
	v_fma_f32 v24, v16, v24, v16
	v_mul_f32_e32 v24, 0x3f4c422a, v24
	v_add_f32_e32 v24, v24, v24
	v_mul_f32_e32 v24, 0xbfb8aa3b, v24
	v_exp_f32_e32 v24, v24
	s_nop 0
	v_add_f32_e32 v24, 1.0, v24
	v_rcp_f32_e32 v24, v24
	s_nop 0
	v_mul_f32_e32 v24, v16, v24
	v_mul_f32_e32 v16, 0x3d372713, v21
	v_mul_f32_e32 v16, v21, v16
	v_fma_f32 v16, v21, v16, v21
	v_mul_f32_e32 v16, 0x3f4c422a, v16
	v_add_f32_e32 v16, v16, v16
	v_mul_f32_e32 v16, 0xbfb8aa3b, v16
	v_exp_f32_e32 v16, v16
	s_nop 0
	v_add_f32_e32 v16, 1.0, v16
	v_rcp_f32_e32 v16, v16
	s_nop 0
	v_mul_f32_e32 v16, v21, v16
	v_mul_f32_e32 v21, 0x3d372713, v17
	v_mul_f32_e32 v21, v17, v21
	v_fma_f32 v21, v17, v21, v17
	v_mul_f32_e32 v21, 0x3f4c422a, v21
	v_add_f32_e32 v21, v21, v21
	v_mul_f32_e32 v21, 0xbfb8aa3b, v21
	v_exp_f32_e32 v21, v21
	v_cvt_pk_bf16_f32 v16, v20, v16
	s_nop 0
	v_add_f32_e32 v21, 1.0, v21
	v_rcp_f32_e32 v21, v21
	s_nop 0
	v_mul_f32_e32 v21, v17, v21
	v_mul_f32_e32 v17, 0x3d372713, v22
	v_mul_f32_e32 v17, v22, v17
	v_fma_f32 v17, v22, v17, v22
	v_mul_f32_e32 v17, 0x3f4c422a, v17
	v_add_f32_e32 v17, v17, v17
	v_mul_f32_e32 v17, 0xbfb8aa3b, v17
	v_exp_f32_e32 v17, v17
	s_nop 0
	v_add_f32_e32 v17, 1.0, v17
	v_rcp_f32_e32 v17, v17
	s_nop 0
	v_mul_f32_e32 v17, v22, v17
	v_mul_f32_e32 v22, 0x3d372713, v18
	v_mul_f32_e32 v22, v18, v22
	v_fma_f32 v22, v18, v22, v18
	v_mul_f32_e32 v22, 0x3f4c422a, v22
	v_add_f32_e32 v22, v22, v22
	v_mul_f32_e32 v22, 0xbfb8aa3b, v22
	v_exp_f32_e32 v22, v22
	s_nop 0
	v_add_f32_e32 v22, 1.0, v22
	v_rcp_f32_e32 v22, v22
	s_nop 0
	v_mul_f32_e32 v22, v18, v22
	v_mul_f32_e32 v18, 0x3d372713, v23
	v_mul_f32_e32 v18, v23, v18
	v_fma_f32 v18, v23, v18, v23
	v_mul_f32_e32 v18, 0x3f4c422a, v18
	v_add_f32_e32 v18, v18, v18
	v_mul_f32_e32 v18, 0xbfb8aa3b, v18
	v_exp_f32_e32 v18, v18
	s_nop 0
	v_add_f32_e32 v18, 1.0, v18
	v_rcp_f32_e32 v18, v18
	s_nop 0
	v_mul_f32_e32 v18, v23, v18
	v_mul_f32_e32 v23, 0x3d372713, v19
	v_mul_f32_e32 v23, v19, v23
	v_fma_f32 v23, v19, v23, v19
	v_mul_f32_e32 v23, 0x3f4c422a, v23
	v_add_f32_e32 v23, v23, v23
	v_mul_f32_e32 v23, 0xbfb8aa3b, v23
	v_exp_f32_e32 v23, v23
	v_cvt_pk_bf16_f32 v17, v17, v18
	v_cvt_pk_bf16_f32 v18, v24, v21
	s_nop 0
	v_add_f32_e32 v23, 1.0, v23
	v_rcp_f32_e32 v23, v23
	s_nop 0
	v_mul_f32_e32 v19, v19, v23
	v_cvt_pk_bf16_f32 v19, v22, v19
	global_store_dwordx4 v[80:81], v[16:19], off offset:256
	s_nop 1
	v_mul_f32_e32 v16, 0x3d372713, v12
; __device__ __forceinline__ unsigned cvt_pk_bf16(float lo, float hi) { unsigned r; asm("v_cvt_pk_bf16_f32 %0, %1, %2" : "=v"(r) : "v"(lo), "v"(hi)); return r; }
; __device__ __forceinline__ float gelu_tanh(float v) { const float u = 0.7978845608028654f * (v + 0.044715f * v * v * v); return v * fast_sigmoid(2.0f * u); }
; __device__ __forceinline__ f32x4 ln_fix(const f32x4& a, float mu, float rs, const f32x4& cs, const f32x4& cb) { return (a - cs * mu) * rs + cb; }
; #define PG8_BAR __builtin_amdgcn_s_barrier()
;     __device__ __forceinline__ void operator()(const f32x4 (&acc)[2][2][4][2], const Unit& u, int wr, int wc, int fr_in, int fq_in) const {
;     ...
;                 for (int m = 0; m < 4; ++m) { bf16_t* rowp = base + (size_t)(row0 + ai * HALF + m * 16) * 1024 + col0 + bj * HALF;
;                     f32x4 v0 = ln_fix(acc[ai][bj][m][0], rst.mu[ai][m], rst.rs[ai][m], csv[0], cbv[0]), v1 = ln_fix(acc[ai][bj][m][1], rst.mu[ai][m], rst.rs[ai][m], csv[1], cbv[1]);
; #pragma unroll
;                     for (int j = 0; j < 4; ++j) { v0[j] = gelu_tanh(v0[j]); v1[j] = gelu_tanh(v1[j]); }
;                     u32x4 w; w.x = cvt_pk_bf16(v0[0], v0[1]); w.y = cvt_pk_bf16(v0[2], v0[3]); w.z = cvt_pk_bf16(v1[0], v1[1]); w.w = cvt_pk_bf16(v1[2], v1[3]);
;                     *(u32x4*)rowp = w; } }
; template <class Epi, class Sched, bool ALIGN_EPI = false, bool SP2 = false>
; __device__ __forceinline__ void gemm_phase(PG8_LAS unsigned char* lds, const Gemm g, const Sched& S, const Epi& E) {
;     ...
;         cur = nxt; cA = nA; cB = nB; ++ui;
;         if constexpr (ALIGN_EPI) { if (wr == 1) PG8_BAR; }
	v_mul_f32_e32 v16, v12, v16
	v_fma_f32 v16, v12, v16, v12
	v_mul_f32_e32 v16, 0x3f4c422a, v16
	v_add_f32_e32 v16, v16, v16
	v_mul_f32_e32 v16, 0xbfb8aa3b, v16
	v_exp_f32_e32 v16, v16
	s_nop 0
	v_add_f32_e32 v16, 1.0, v16
	v_rcp_f32_e32 v16, v16
	s_nop 0
	v_mul_f32_e32 v12, v12, v16
	v_mul_f32_e32 v16, 0x3d372713, v8
	v_mul_f32_e32 v16, v8, v16
	v_fma_f32 v16, v8, v16, v8
	v_mul_f32_e32 v16, 0x3f4c422a, v16
	v_add_f32_e32 v16, v16, v16
	v_mul_f32_e32 v16, 0xbfb8aa3b, v16
	v_exp_f32_e32 v16, v16
	s_nop 0
	v_add_f32_e32 v16, 1.0, v16
	v_rcp_f32_e32 v16, v16
	s_nop 0
	v_mul_f32_e32 v16, v8, v16
	v_mul_f32_e32 v8, 0x3d372713, v13
	v_mul_f32_e32 v8, v13, v8
	v_fma_f32 v8, v13, v8, v13
	v_mul_f32_e32 v8, 0x3f4c422a, v8
	v_add_f32_e32 v8, v8, v8
	v_mul_f32_e32 v8, 0xbfb8aa3b, v8
	v_exp_f32_e32 v8, v8
	s_nop 0
	v_add_f32_e32 v8, 1.0, v8
	v_rcp_f32_e32 v8, v8
	s_nop 0
	v_mul_f32_e32 v8, v13, v8
	v_mul_f32_e32 v13, 0x3d372713, v9
	v_mul_f32_e32 v13, v9, v13
	v_fma_f32 v13, v9, v13, v9
	v_mul_f32_e32 v13, 0x3f4c422a, v13
	v_add_f32_e32 v13, v13, v13
	v_mul_f32_e32 v13, 0xbfb8aa3b, v13
	v_exp_f32_e32 v13, v13
	v_cvt_pk_bf16_f32 v8, v12, v8
	s_nop 0
	v_add_f32_e32 v13, 1.0, v13
	v_rcp_f32_e32 v13, v13
	s_nop 0
	v_mul_f32_e32 v13, v9, v13
	v_mul_f32_e32 v9, 0x3d372713, v14
	v_mul_f32_e32 v9, v14, v9
	v_fma_f32 v9, v14, v9, v14
	v_mul_f32_e32 v9, 0x3f4c422a, v9
	v_add_f32_e32 v9, v9, v9
	v_mul_f32_e32 v9, 0xbfb8aa3b, v9
	v_exp_f32_e32 v9, v9
	s_nop 0
	v_add_f32_e32 v9, 1.0, v9
	v_rcp_f32_e32 v9, v9
	s_nop 0
	v_mul_f32_e32 v9, v14, v9
	v_mul_f32_e32 v14, 0x3d372713, v10
	v_mul_f32_e32 v14, v10, v14
	v_fma_f32 v14, v10, v14, v10
	v_mul_f32_e32 v14, 0x3f4c422a, v14
	v_add_f32_e32 v14, v14, v14
	v_mul_f32_e32 v14, 0xbfb8aa3b, v14
	v_exp_f32_e32 v14, v14
	s_nop 0
	v_add_f32_e32 v14, 1.0, v14
	v_rcp_f32_e32 v14, v14
	s_nop 0
	v_mul_f32_e32 v14, v10, v14
	v_mul_f32_e32 v10, 0x3d372713, v15
	v_mul_f32_e32 v10, v15, v10
	v_fma_f32 v10, v15, v10, v15
	v_mul_f32_e32 v10, 0x3f4c422a, v10
	v_add_f32_e32 v10, v10, v10
	v_mul_f32_e32 v10, 0xbfb8aa3b, v10
	v_exp_f32_e32 v10, v10
	s_nop 0
	v_add_f32_e32 v10, 1.0, v10
	v_rcp_f32_e32 v10, v10
	s_nop 0
	v_mul_f32_e32 v10, v15, v10
	v_mul_f32_e32 v15, 0x3d372713, v11
	v_mul_f32_e32 v15, v11, v15
	v_fma_f32 v15, v11, v15, v11
	v_mul_f32_e32 v15, 0x3f4c422a, v15
	v_add_f32_e32 v15, v15, v15
	v_mul_f32_e32 v15, 0xbfb8aa3b, v15
	v_exp_f32_e32 v15, v15
	v_cvt_pk_bf16_f32 v9, v9, v10
	v_cvt_pk_bf16_f32 v10, v16, v13
	s_nop 0
	v_add_f32_e32 v15, 1.0, v15
	v_rcp_f32_e32 v15, v15
	s_nop 0
	v_mul_f32_e32 v11, v11, v15
	v_cvt_pk_bf16_f32 v11, v14, v11
	global_store_dwordx4 v[72:73], v[8:11], off offset:256
	s_nop 1
	v_mul_f32_e32 v8, 0x3d372713, v4
	v_mul_f32_e32 v8, v4, v8
	v_fma_f32 v8, v4, v8, v4
	v_mul_f32_e32 v8, 0x3f4c422a, v8
	v_add_f32_e32 v8, v8, v8
	v_mul_f32_e32 v8, 0xbfb8aa3b, v8
	v_exp_f32_e32 v8, v8
	s_nop 0
	v_add_f32_e32 v8, 1.0, v8
	v_rcp_f32_e32 v8, v8
	s_nop 0
	v_mul_f32_e32 v4, v4, v8
	v_mul_f32_e32 v8, 0x3d372713, v0
	v_mul_f32_e32 v8, v0, v8
	v_fma_f32 v8, v0, v8, v0
	v_mul_f32_e32 v8, 0x3f4c422a, v8
	v_add_f32_e32 v8, v8, v8
	v_mul_f32_e32 v8, 0xbfb8aa3b, v8
	v_exp_f32_e32 v8, v8
	s_nop 0
	v_add_f32_e32 v8, 1.0, v8
	v_rcp_f32_e32 v8, v8
	s_nop 0
	v_mul_f32_e32 v8, v0, v8
	v_mul_f32_e32 v0, 0x3d372713, v5
	v_mul_f32_e32 v0, v5, v0
	v_fma_f32 v0, v5, v0, v5
	v_mul_f32_e32 v0, 0x3f4c422a, v0
	v_add_f32_e32 v0, v0, v0
	v_mul_f32_e32 v0, 0xbfb8aa3b, v0
	v_exp_f32_e32 v0, v0
	s_nop 0
	v_add_f32_e32 v0, 1.0, v0
	v_rcp_f32_e32 v0, v0
	s_nop 0
	v_mul_f32_e32 v0, v5, v0
	v_mul_f32_e32 v5, 0x3d372713, v1
	v_mul_f32_e32 v5, v1, v5
	v_fma_f32 v5, v1, v5, v1
	v_mul_f32_e32 v5, 0x3f4c422a, v5
	v_add_f32_e32 v5, v5, v5
	v_mul_f32_e32 v5, 0xbfb8aa3b, v5
	v_exp_f32_e32 v5, v5
	v_cvt_pk_bf16_f32 v0, v4, v0
	s_nop 0
	v_add_f32_e32 v5, 1.0, v5
	v_rcp_f32_e32 v5, v5
	s_nop 0
	v_mul_f32_e32 v5, v1, v5
	v_mul_f32_e32 v1, 0x3d372713, v6
	v_mul_f32_e32 v1, v6, v1
	v_fma_f32 v1, v6, v1, v6
	v_mul_f32_e32 v1, 0x3f4c422a, v1
	v_add_f32_e32 v1, v1, v1
	v_mul_f32_e32 v1, 0xbfb8aa3b, v1
	v_exp_f32_e32 v1, v1
	s_nop 0
	v_add_f32_e32 v1, 1.0, v1
	v_rcp_f32_e32 v1, v1
	s_nop 0
	v_mul_f32_e32 v1, v6, v1
	v_mul_f32_e32 v6, 0x3d372713, v2
	v_mul_f32_e32 v6, v2, v6
	v_fma_f32 v6, v2, v6, v2
	v_mul_f32_e32 v6, 0x3f4c422a, v6
	v_add_f32_e32 v6, v6, v6
	v_mul_f32_e32 v6, 0xbfb8aa3b, v6
	v_exp_f32_e32 v6, v6
	s_nop 0
	v_add_f32_e32 v6, 1.0, v6
	v_rcp_f32_e32 v6, v6
	s_nop 0
	v_mul_f32_e32 v6, v2, v6
	v_mul_f32_e32 v2, 0x3d372713, v7
	v_mul_f32_e32 v2, v7, v2
	v_fma_f32 v2, v7, v2, v7
	v_mul_f32_e32 v2, 0x3f4c422a, v2
	v_add_f32_e32 v2, v2, v2
	v_mul_f32_e32 v2, 0xbfb8aa3b, v2
	v_exp_f32_e32 v2, v2
	s_nop 0
	v_add_f32_e32 v2, 1.0, v2
	v_rcp_f32_e32 v2, v2
	s_nop 0
	v_mul_f32_e32 v2, v7, v2
	v_mul_f32_e32 v7, 0x3d372713, v3
	v_mul_f32_e32 v7, v3, v7
	v_fma_f32 v7, v3, v7, v3
	v_mul_f32_e32 v7, 0x3f4c422a, v7
	v_add_f32_e32 v7, v7, v7
	v_mul_f32_e32 v7, 0xbfb8aa3b, v7
	v_exp_f32_e32 v7, v7
	v_cvt_pk_bf16_f32 v1, v1, v2
	v_cvt_pk_bf16_f32 v2, v8, v5
	s_nop 0
	v_add_f32_e32 v7, 1.0, v7
	v_rcp_f32_e32 v7, v7
	s_nop 0
	v_mul_f32_e32 v3, v3, v7
	v_cvt_pk_bf16_f32 v3, v6, v3
	global_store_dwordx4 v[74:75], v[0:3], off offset:256
	s_cbranch_vccnz .LBB0_1686
	s_andn2_b64 vcc, exec, s[22:23]
	s_cbranch_vccnz .LBB0_1685
	s_barrier
	s_branch .LBB0_1685

; __device__ __forceinline__ void load_row_stats(const float* sp, int row0, RowStats& r) {
; #pragma unroll
;     for (int ai = 0; ai < 2; ++ai) { asm volatile("" ::: "memory");
; #pragma unroll
;         for (int m = 0; m < 4; ++m) { const float* p = sp + (size_t)(row0 + ai * HALF + m * 16) * 8; const f32x4 a = *(const f32x4*)p, b = *(const f32x4*)(p + 4);
;             const float s1 = (a[0] + a[2]) + (b[0] + b[2]), s2 = (a[1] + a[3]) + (b[1] + b[3]); const float mu = s1 * (1.f / 1024.f); const float var = s2 * (1.f / 1024.f) - mu * mu;
;             r.mu[ai][m] = mu; r.rs[ai][m] = __builtin_amdgcn_rsqf(__builtin_fmaxf(var, 0.f) + 1e-5f); } }
;     __device__ __forceinline__ void operator()(const f32x4 (&acc)[2][2][4][2], const Unit& u, int wr, int wc, int fr_in, int fq_in) const {
;     ...
;         const int row0 = u.pm * BM + wr * 64 + fr, col0 = u.pn * BM + wc * 32 + 8 * fq;
;         float al_ = alpha, s_ = s; asm volatile("" : "+v"(al_), "+v"(s_));
;         RowStats rst;
;         if constexpr (BASE == 1) load_row_stats(sp_old, row0, rst);
.LBB0_1910:
	s_lshl_b32 s11, s48, 8
	v_mov_b32_e32 v199, v175
	v_mov_b32_e32 v203, v177
	s_add_i32 s8, s11, s60
	v_mov_b32_e32 v176, 0x3fb504f3
	v_add_u32_e32 v146, s8, v199
	v_ashrrev_i32_e32 v147, 31, v146
	v_mov_b32_e32 v174, 1.0
	s_cselect_b32 s99, 1, 0
	v_readfirstlane_b32 s98, v254
	v_and_b32_e32 v128, 0xffffff00, v146
	s_nop 0
	s_cmpk_lt_u32 s98, 0x100
	s_cbranch_scc0 .Lrs8_skip
	v_add_u32_e32 v128, v128, v254
	v_mov_b32_e32 v129, 0
	v_lshlrev_b64 v[128:129], 5, v[128:129]
	v_lshl_add_u64 v[132:133], s[24:25], 0, v[128:129]
	global_load_dwordx4 v[128:131], v[132:133], off offset:16
	s_nop 0
	global_load_dwordx4 v[132:135], v[132:133], off
	s_waitcnt vmcnt(0)
	v_pk_add_f32 v[128:129], v[128:129], v[130:131]
	v_pk_add_f32 v[132:133], v[132:133], v[134:135]
	s_nop 0
	v_pk_add_f32 v[128:129], v[132:133], v[128:129]
	s_nop 0
	v_pk_mul_f32 v[128:129], v[128:129], s[40:41] op_sel_hi:[1,0]
	v_lshlrev_b32_e32 v130, 3, v254
	v_add_u32_e32 v130, 0x22400, v130
	ds_write_b64 v130, v[128:129]

; __device__ __forceinline__ unsigned cvt_pk_bf16(float lo, float hi) { unsigned r; asm("v_cvt_pk_bf16_f32 %0, %1, %2" : "=v"(r) : "v"(lo), "v"(hi)); return r; }
; __device__ __forceinline__ void load_row_stats(const float* sp, int row0, RowStats& r) {
; #pragma unroll
;     for (int ai = 0; ai < 2; ++ai) { asm volatile("" ::: "memory");
; #pragma unroll
;         for (int m = 0; m < 4; ++m) { const float* p = sp + (size_t)(row0 + ai * HALF + m * 16) * 8; const f32x4 a = *(const f32x4*)p, b = *(const f32x4*)(p + 4);
;             const float s1 = (a[0] + a[2]) + (b[0] + b[2]), s2 = (a[1] + a[3]) + (b[1] + b[3]); const float mu = s1 * (1.f / 1024.f); const float var = s2 * (1.f / 1024.f) - mu * mu;
;             r.mu[ai][m] = mu; r.rs[ai][m] = __builtin_amdgcn_rsqf(__builtin_fmaxf(var, 0.f) + 1e-5f); } }
;     __device__ __forceinline__ void operator()(const f32x4 (&acc)[2][2][4][2], const Unit& u, int wr, int wc, int fr_in, int fq_in) const {
;     ...
;         const int row0 = u.pm * BM + wr * 64 + fr, n0 = u.pn * BM + wc * 32 + 8 * fq; const int kt = u.pn * 2 + (wc >> 1), cin = (wc & 1) * 32 + 8 * fq;
;         RowStats rst; f32x4 csv[2][2], cbv[2][2];
;         if constexpr (LN) { load_row_stats(sp, row0, rst);
; #pragma unroll
;             for (int bj = 0; bj < 2; ++bj)
; #pragma unroll
;                 for (int n = 0; n < 2; ++n) { csv[bj][n] = *(const f32x4*)(cs + n0 + bj * HALF + 4 * n); cbv[bj][n] = *(const f32x4*)(cb + n0 + bj * HALF + 4 * n); } }
; #pragma unroll
;         for (int ai = 0; ai < 2; ++ai)
; #pragma unroll
;             for (int m = 0; m < 4; ++m) { bf16_t* rowp = H + ((size_t)kt * mrows + (row0 + ai * HALF + m * 16)) * 64 + cin;
;                 float h[8];
; #pragma unroll
;                 for (int n = 0; n < 2; ++n) { f32x4 g = acc[ai][0][m][n], uu = acc[ai][1][m][n];
;                     if constexpr (LN) { g = ln_fix(g, rst.mu[ai][m], rst.rs[ai][m], csv[0][n], cbv[0][n]); uu = ln_fix(uu, rst.mu[ai][m], rst.rs[ai][m], csv[1][n], cbv[1][n]); }
; #pragma unroll
;                     for (int j = 0; j < 4; ++j) h[4 * n + j] = g[j] * fast_sigmoid(g[j]) * uu[j]; }
;                 u32x4 w; w.x = cvt_pk_bf16(h[0], h[1]); w.y = cvt_pk_bf16(h[2], h[3]); w.z = cvt_pk_bf16(h[4], h[5]); w.w = cvt_pk_bf16(h[6], h[7]);
;                 *(u32x4*)rowp = w; }
.LBB0_1995:
	s_lshl_b32 s35, s44, 8
	v_mov_b32_e32 v112, v179
	v_mov_b32_e32 v113, v185
	s_add_i32 s35, s35, s54
	s_andn2_b64 vcc, exec, s[38:39]
	v_add_u32_e32 v192, s35, v112
	v_ashrrev_i32_e32 v193, 31, v192
	s_cselect_b32 s99, 1, 0
	v_readfirstlane_b32 s98, v254
	v_and_b32_e32 v114, 0xffffff00, v192
	s_nop 0
	s_cmpk_lt_u32 s98, 0x100
	s_cbranch_scc0 .Lrs9_skip
	v_add_u32_e32 v114, v114, v254
	v_mov_b32_e32 v115, 0
	v_lshlrev_b64 v[114:115], 5, v[114:115]
	v_lshl_add_u64 v[118:119], s[10:11], 0, v[114:115]
	global_load_dwordx4 v[114:117], v[118:119], off offset:16
	s_nop 0
	global_load_dwordx4 v[128:131], v[118:119], off
	s_waitcnt vmcnt(0)
	v_pk_add_f32 v[114:115], v[114:115], v[116:117]
	v_pk_add_f32 v[118:119], v[128:129], v[130:131]
	s_nop 0
	v_pk_add_f32 v[114:115], v[118:119], v[114:115]
	s_nop 0
	v_pk_mul_f32 v[114:115], v[114:115], s[30:31] op_sel_hi:[1,0]
	v_lshlrev_b32_e32 v116, 3, v254
	v_add_u32_e32 v116, 0x22400, v116
	ds_write_b64 v116, v[114:115]
.Lrs9_skip:
	s_waitcnt vmcnt(0) lgkmcnt(0)
	s_barrier
	v_and_b32_e32 v116, 0xff, v192
	v_lshlrev_b32_e32 v116, 3, v116
	v_add_u32_e32 v116, 0x22400, v116
	ds_read_b64 v[226:227], v116
	ds_read_b64 v[220:221], v116 offset:128
	ds_read_b64 v[214:215], v116 offset:256
	ds_read_b64 v[200:201], v116 offset:384
	ds_read_b64 v[194:195], v116 offset:1024
	ds_read_b64 v[186:187], v116 offset:1152
	ds_read_b64 v[180:181], v116 offset:1280
	ds_read_b64 v[176:177], v116 offset:1408
	s_cmp_lg_u32 s99, 0
	s_waitcnt lgkmcnt(0)
	v_add_u32_e32 v224, 16, v192
	v_ashrrev_i32_e32 v225, 31, v224
	v_add_u32_e32 v218, 32, v192
	v_ashrrev_i32_e32 v219, 31, v218
	v_add_u32_e32 v212, 48, v192
	v_ashrrev_i32_e32 v213, 31, v212
	v_add_u32_e32 v204, 0x80, v192
	v_ashrrev_i32_e32 v205, 31, v204
	v_add_u32_e32 v196, 0x90, v192
	v_ashrrev_i32_e32 v197, 31, v196
	v_add_u32_e32 v188, 0xa0, v192
	v_ashrrev_i32_e32 v189, 31, v188
	v_add_u32_e32 v182, 0xb0, v192
	v_ashrrev_i32_e32 v183, 31, v182
	v_lshlrev_b32_e32 v206, 3, v113
	s_lshl_b32 s35, s45, 8
	s_or_b32 s35, s35, s55
	v_add_u32_e32 v112, s35, v206
	s_lshl_b32 s35, s45, 1
	s_or_b32 s44, s35, s59
	s_ashr_i32 s45, s44, 31
	s_lshl_b64 s[44:45], s[44:45], 15
	v_lshl_add_u64 v[192:193], s[44:45], 0, v[192:193]
	v_lshlrev_b64 v[192:193], 7, v[192:193]
	v_add_u32_e32 v230, s60, v206
	v_lshl_add_u64 v[232:233], s[6:7], 0, v[192:193]
	v_mov_b32_e32 v192, v144
	v_mov_b32_e32 v193, v140
	v_mov_b32_e32 v140, v145
	v_ashrrev_i32_e32 v231, 31, v230
	v_fma_f32 v113, -v226, v226, v227
	v_max_f32_e32 v113, 0, v113
	v_add_f32_e32 v113, 0x3727c5ac, v113
	v_rsq_f32_e32 v228, v113
	v_fma_f32 v113, -v220, v220, v221
	v_max_f32_e32 v113, 0, v113
	v_add_f32_e32 v113, 0x3727c5ac, v113
	v_rsq_f32_e32 v222, v113
	v_fma_f32 v113, -v214, v214, v215
	v_max_f32_e32 v113, 0, v113
	v_add_f32_e32 v113, 0x3727c5ac, v113
	v_rsq_f32_e32 v216, v113
	v_fma_f32 v113, -v200, v200, v201
	v_max_f32_e32 v113, 0, v113
	v_add_f32_e32 v113, 0x3727c5ac, v113
	v_rsq_f32_e32 v202, v113
	v_fma_f32 v113, -v194, v194, v195
	v_max_f32_e32 v113, 0, v113
	v_add_f32_e32 v113, 0x3727c5ac, v113
	v_rsq_f32_e32 v198, v113
	v_fma_f32 v113, -v186, v186, v187
	v_max_f32_e32 v113, 0, v113
	v_add_f32_e32 v113, 0x3727c5ac, v113
	v_rsq_f32_e32 v190, v113
	v_fma_f32 v113, -v180, v180, v181
	v_max_f32_e32 v113, 0, v113
	v_add_f32_e32 v113, 0x3727c5ac, v113
	v_rsq_f32_e32 v184, v113
	s_nop 0
	v_fma_f32 v113, -v176, v176, v177
	v_max_f32_e32 v113, 0, v113
	v_add_f32_e32 v113, 0x3727c5ac, v113
	v_rsq_f32_e32 v178, v113
	v_ashrrev_i32_e32 v113, 31, v112
	v_lshlrev_b64 v[112:113], 2, v[112:113]
	v_lshl_add_u64 v[136:137], s[12:13], 0, v[112:113]
	v_lshl_add_u64 v[156:157], s[22:23], 0, v[112:113]
	global_load_dwordx4 v[112:115], v[136:137], off offset:16
	global_load_dwordx4 v[128:131], v[136:137], off
	global_load_dwordx4 v[116:119], v[156:157], off offset:16
	global_load_dwordx4 v[132:135], v[156:157], off
	global_load_dwordx4 v[148:151], v[136:137], off offset:528
	s_nop 0
	global_load_dwordx4 v[136:139], v[136:137], off offset:512
	s_nop 0
	global_load_dwordx4 v[152:155], v[156:157], off offset:528
	s_nop 0
	global_load_dwordx4 v[156:159], v[156:157], off offset:512
	s_waitcnt vmcnt(0)
	v_mov_b32_e32 v207, v128
	v_mov_b32_e32 v211, v131
	v_mov_b32_e32 v206, v136
	v_pk_fma_f32 v[208:209], v[226:227], v[206:207], v[192:193] op_sel_hi:[0,1,1] neg_lo:[1,0,0] neg_hi:[1,0,0]
	v_mov_b32_e32 v192, v156
	v_mov_b32_e32 v193, v132
	v_pk_fma_f32 v[208:209], v[228:229], v[208:209], v[192:193] op_sel_hi:[0,1,1]
	v_mul_f32_e32 v132, 0xbfb8aa3b, v209
	v_exp_f32_e32 v132, v132
	v_mov_b32_e32 v156, v138
	v_mov_b32_e32 v210, v139
	v_add_f32_e32 v132, 1.0, v132
	v_rcp_f32_e32 v132, v132
	s_nop 0
	v_mul_f32_e32 v132, v209, v132
	v_mul_f32_e32 v223, v208, v132
	v_mov_b32_e32 v208, v137
	v_mov_b32_e32 v209, v129
	v_pk_fma_f32 v[140:141], v[226:227], v[208:209], v[140:141] op_sel_hi:[0,1,1] neg_lo:[1,0,0] neg_hi:[1,0,0]
	v_mov_b32_e32 v132, v157
	v_pk_fma_f32 v[140:141], v[228:229], v[140:141], v[132:133] op_sel_hi:[0,1,1]
	v_mul_f32_e32 v144, 0xbfb8aa3b, v141
	v_exp_f32_e32 v144, v144
	v_mov_b32_e32 v157, v130
	v_add_f32_e32 v144, 1.0, v144
	v_rcp_f32_e32 v144, v144
	s_nop 0
	v_mul_f32_e32 v141, v141, v144
	v_mul_f32_e32 v229, v140, v141
	v_mov_b32_e32 v140, v146
	v_mov_b32_e32 v141, v142
	v_pk_fma_f32 v[144:145], v[226:227], v[156:157], v[140:141] op_sel_hi:[0,1,1] neg_lo:[1,0,0] neg_hi:[1,0,0]
	v_mov_b32_e32 v140, v158
	v_mov_b32_e32 v141, v134
	v_pk_fma_f32 v[144:145], v[228:229], v[144:145], v[140:141] op_sel_hi:[0,1,1]
	v_mul_f32_e32 v134, 0xbfb8aa3b, v145
	v_exp_f32_e32 v134, v134
	v_mov_b32_e32 v142, v147
; __device__ __forceinline__ unsigned cvt_pk_bf16(float lo, float hi) { unsigned r; asm("v_cvt_pk_bf16_f32 %0, %1, %2" : "=v"(r) : "v"(lo), "v"(hi)); return r; }
; __device__ __forceinline__ f32x4 ln_fix(const f32x4& a, float mu, float rs, const f32x4& cs, const f32x4& cb) { return (a - cs * mu) * rs + cb; }
; __device__ __forceinline__ float fast_sigmoid(float v) { return __builtin_amdgcn_rcpf(1.0f + __builtin_amdgcn_exp2f(-1.4426950408889634f * v)); }
;     __device__ __forceinline__ void operator()(const f32x4 (&acc)[2][2][4][2], const Unit& u, int wr, int wc, int fr_in, int fq_in) const {
;     ...
;             for (int m = 0; m < 4; ++m) { bf16_t* rowp = H + ((size_t)kt * mrows + (row0 + ai * HALF + m * 16)) * 64 + cin;
;                 float h[8];
; #pragma unroll
;                 for (int n = 0; n < 2; ++n) { f32x4 g = acc[ai][0][m][n], uu = acc[ai][1][m][n];
;                     if constexpr (LN) { g = ln_fix(g, rst.mu[ai][m], rst.rs[ai][m], csv[0][n], cbv[0][n]); uu = ln_fix(uu, rst.mu[ai][m], rst.rs[ai][m], csv[1][n], cbv[1][n]); }
; #pragma unroll
;                     for (int j = 0; j < 4; ++j) h[4 * n + j] = g[j] * fast_sigmoid(g[j]) * uu[j]; }
;                 u32x4 w; w.x = cvt_pk_bf16(h[0], h[1]); w.y = cvt_pk_bf16(h[2], h[3]); w.z = cvt_pk_bf16(h[4], h[5]); w.w = cvt_pk_bf16(h[6], h[7]);
;                 *(u32x4*)rowp = w; }
	v_pk_fma_f32 v[142:143], v[226:227], v[210:211], v[142:143] op_sel_hi:[0,1,1] neg_lo:[1,0,0] neg_hi:[1,0,0]
	v_add_f32_e32 v134, 1.0, v134
	v_rcp_f32_e32 v134, v134
	s_nop 0
	v_mul_f32_e32 v134, v145, v134
	v_mul_f32_e32 v158, v144, v134
	v_mov_b32_e32 v134, v159
	v_pk_fma_f32 v[142:143], v[228:229], v[142:143], v[134:135] op_sel_hi:[0,1,1]
	v_mul_f32_e32 v144, 0xbfb8aa3b, v143
	v_exp_f32_e32 v144, v144
	v_mov_b32_e32 v145, v120
	v_mov_b32_e32 v120, v125
	v_mov_b32_e32 v125, v122
	v_add_f32_e32 v144, 1.0, v144
	v_rcp_f32_e32 v144, v144
	v_mov_b32_e32 v122, v127
	v_mul_f32_e32 v143, v143, v144
	v_mul_f32_e32 v159, v142, v143
	v_mov_b32_e32 v142, v148
	v_mov_b32_e32 v143, v112
	v_mov_b32_e32 v144, v124
	v_pk_fma_f32 v[146:147], v[226:227], v[142:143], v[144:145] op_sel_hi:[0,1,1] neg_lo:[1,0,0] neg_hi:[1,0,0]
	v_mov_b32_e32 v144, v152
	v_mov_b32_e32 v145, v116
	v_pk_fma_f32 v[146:147], v[228:229], v[146:147], v[144:145] op_sel_hi:[0,1,1]
	v_mul_f32_e32 v112, 0xbfb8aa3b, v147
	v_exp_f32_e32 v112, v112
	v_mov_b32_e32 v116, v153
	v_add_f32_e32 v112, 1.0, v112
	v_rcp_f32_e32 v112, v112
	s_nop 0
	v_mul_f32_e32 v112, v147, v112
	v_mul_f32_e32 v148, v146, v112
	v_mov_b32_e32 v112, v149
	v_pk_fma_f32 v[120:121], v[226:227], v[112:113], v[120:121] op_sel_hi:[0,1,1] neg_lo:[1,0,0] neg_hi:[1,0,0]
	v_pk_fma_f32 v[120:121], v[228:229], v[120:121], v[116:117] op_sel_hi:[0,1,1]
	v_mul_f32_e32 v124, 0xbfb8aa3b, v121
	v_exp_f32_e32 v124, v124
	s_nop 0
	v_add_f32_e32 v124, 1.0, v124
	v_rcp_f32_e32 v124, v124
	s_nop 0
	v_mul_f32_e32 v121, v121, v124
	v_mul_f32_e32 v149, v120, v121
	v_mov_b32_e32 v120, v150
	v_mov_b32_e32 v121, v114
	v_mov_b32_e32 v124, v126
	v_pk_fma_f32 v[146:147], v[226:227], v[120:121], v[124:125] op_sel_hi:[0,1,1] neg_lo:[1,0,0] neg_hi:[1,0,0]
	v_mov_b32_e32 v124, v154
	v_mov_b32_e32 v125, v118
	v_pk_fma_f32 v[146:147], v[228:229], v[146:147], v[124:125] op_sel_hi:[0,1,1]
	v_mul_f32_e32 v114, 0xbfb8aa3b, v147
	v_exp_f32_e32 v114, v114
	v_mov_b32_e32 v118, v155
	v_cvt_pk_bf16_f32 v148, v148, v149
	v_add_f32_e32 v114, 1.0, v114
	v_rcp_f32_e32 v114, v114
	s_nop 0
	v_mul_f32_e32 v114, v147, v114
	v_mul_f32_e32 v150, v146, v114
	v_mov_b32_e32 v114, v151
	v_pk_fma_f32 v[122:123], v[226:227], v[114:115], v[122:123] op_sel_hi:[0,1,1] neg_lo:[1,0,0] neg_hi:[1,0,0]
	v_pk_fma_f32 v[122:123], v[228:229], v[122:123], v[118:119] op_sel_hi:[0,1,1]
	v_mul_f32_e32 v126, 0xbfb8aa3b, v123
	v_exp_f32_e32 v126, v126
	v_cvt_pk_bf16_f32 v146, v223, v229
	v_cvt_pk_bf16_f32 v147, v158, v159
	s_nop 0
	v_add_f32_e32 v126, 1.0, v126
	v_rcp_f32_e32 v126, v126
	s_nop 0
	v_mul_f32_e32 v123, v123, v126
	v_mul_f32_e32 v151, v122, v123
	v_lshlrev_b64 v[122:123], 1, v[230:231]
	v_lshl_add_u64 v[126:127], v[232:233], 0, v[122:123]
	v_cvt_pk_bf16_f32 v149, v150, v151
	global_store_dwordx4 v[126:127], v[146:149], off
	v_lshl_add_u64 v[126:127], s[44:45], 0, v[224:225]
	v_lshlrev_b64 v[126:127], 7, v[126:127]
	v_mov_b32_e32 v146, v108
	v_mov_b32_e32 v147, v104
	v_pk_fma_f32 v[146:147], v[220:221], v[206:207], v[146:147] op_sel_hi:[0,1,1] neg_lo:[1,0,0] neg_hi:[1,0,0]
	v_pk_fma_f32 v[146:147], v[222:223], v[146:147], v[192:193] op_sel_hi:[0,1,1]
	v_mul_f32_e32 v104, 0xbfb8aa3b, v147
	v_exp_f32_e32 v104, v104
	v_lshl_add_u64 v[126:127], s[6:7], 0, v[126:127]
	v_add_f32_e32 v104, 1.0, v104
	v_rcp_f32_e32 v104, v104
	s_nop 0
	v_mul_f32_e32 v104, v147, v104
	v_mul_f32_e32 v108, v146, v104
	v_mov_b32_e32 v104, v109
	v_pk_fma_f32 v[104:105], v[220:221], v[208:209], v[104:105] op_sel_hi:[0,1,1] neg_lo:[1,0,0] neg_hi:[1,0,0]
	v_pk_fma_f32 v[104:105], v[222:223], v[104:105], v[132:133] op_sel_hi:[0,1,1]
	v_mul_f32_e32 v109, 0xbfb8aa3b, v105
	v_exp_f32_e32 v109, v109
	s_nop 0
	v_add_f32_e32 v109, 1.0, v109
	v_rcp_f32_e32 v109, v109
	s_nop 0
	v_mul_f32_e32 v105, v105, v109
	v_mul_f32_e32 v109, v104, v105
	v_mov_b32_e32 v104, v110
	v_mov_b32_e32 v105, v106
	v_pk_fma_f32 v[104:105], v[220:221], v[156:157], v[104:105] op_sel_hi:[0,1,1] neg_lo:[1,0,0] neg_hi:[1,0,0]
	v_pk_fma_f32 v[104:105], v[222:223], v[104:105], v[140:141] op_sel_hi:[0,1,1]
	v_mul_f32_e32 v106, 0xbfb8aa3b, v105
	v_exp_f32_e32 v106, v106
	s_nop 0
	v_add_f32_e32 v106, 1.0, v106
	v_rcp_f32_e32 v106, v106
	s_nop 0
	v_mul_f32_e32 v105, v105, v106
	v_mov_b32_e32 v106, v111
	v_mul_f32_e32 v110, v104, v105
	v_pk_fma_f32 v[104:105], v[220:221], v[210:211], v[106:107] op_sel_hi:[0,1,1] neg_lo:[1,0,0] neg_hi:[1,0,0]
	v_pk_fma_f32 v[104:105], v[222:223], v[104:105], v[134:135] op_sel_hi:[0,1,1]
	v_mul_f32_e32 v106, 0xbfb8aa3b, v105
	v_exp_f32_e32 v106, v106
	s_nop 0
	v_add_f32_e32 v106, 1.0, v106
	v_rcp_f32_e32 v106, v106
	s_nop 0
	v_mul_f32_e32 v105, v105, v106
	v_mul_f32_e32 v106, v104, v105
	v_mov_b32_e32 v104, v100
	v_mov_b32_e32 v105, v96
	v_pk_fma_f32 v[104:105], v[220:221], v[142:143], v[104:105] op_sel_hi:[0,1,1] neg_lo:[1,0,0] neg_hi:[1,0,0]
	v_pk_fma_f32 v[104:105], v[222:223], v[104:105], v[144:145] op_sel_hi:[0,1,1]
	v_mul_f32_e32 v96, 0xbfb8aa3b, v105
	v_exp_f32_e32 v96, v96
	s_nop 0
	v_add_f32_e32 v96, 1.0, v96
	v_rcp_f32_e32 v96, v96
	s_nop 0
	v_mul_f32_e32 v96, v105, v96
	v_mul_f32_e32 v104, v104, v96
	v_mov_b32_e32 v96, v101
	v_pk_fma_f32 v[96:97], v[220:221], v[112:113], v[96:97] op_sel_hi:[0,1,1] neg_lo:[1,0,0] neg_hi:[1,0,0]
	v_pk_fma_f32 v[96:97], v[222:223], v[96:97], v[116:117] op_sel_hi:[0,1,1]
	v_mul_f32_e32 v100, 0xbfb8aa3b, v97
	v_exp_f32_e32 v100, v100
	s_nop 0
	v_add_f32_e32 v100, 1.0, v100
	v_rcp_f32_e32 v100, v100
	s_nop 0
	v_mul_f32_e32 v97, v97, v100
	v_mul_f32_e32 v105, v96, v97
	v_mov_b32_e32 v96, v102
	v_mov_b32_e32 v97, v98
	v_pk_fma_f32 v[96:97], v[220:221], v[120:121], v[96:97] op_sel_hi:[0,1,1] neg_lo:[1,0,0] neg_hi:[1,0,0]
; __device__ __forceinline__ unsigned cvt_pk_bf16(float lo, float hi) { unsigned r; asm("v_cvt_pk_bf16_f32 %0, %1, %2" : "=v"(r) : "v"(lo), "v"(hi)); return r; }
; __device__ __forceinline__ f32x4 ln_fix(const f32x4& a, float mu, float rs, const f32x4& cs, const f32x4& cb) { return (a - cs * mu) * rs + cb; }
; __device__ __forceinline__ float fast_sigmoid(float v) { return __builtin_amdgcn_rcpf(1.0f + __builtin_amdgcn_exp2f(-1.4426950408889634f * v)); }
;     __device__ __forceinline__ void operator()(const f32x4 (&acc)[2][2][4][2], const Unit& u, int wr, int wc, int fr_in, int fq_in) const {
;     ...
;             for (int m = 0; m < 4; ++m) { bf16_t* rowp = H + ((size_t)kt * mrows + (row0 + ai * HALF + m * 16)) * 64 + cin;
;                 float h[8];
; #pragma unroll
;                 for (int n = 0; n < 2; ++n) { f32x4 g = acc[ai][0][m][n], uu = acc[ai][1][m][n];
;                     if constexpr (LN) { g = ln_fix(g, rst.mu[ai][m], rst.rs[ai][m], csv[0][n], cbv[0][n]); uu = ln_fix(uu, rst.mu[ai][m], rst.rs[ai][m], csv[1][n], cbv[1][n]); }
; #pragma unroll
;                     for (int j = 0; j < 4; ++j) h[4 * n + j] = g[j] * fast_sigmoid(g[j]) * uu[j]; }
;                 u32x4 w; w.x = cvt_pk_bf16(h[0], h[1]); w.y = cvt_pk_bf16(h[2], h[3]); w.z = cvt_pk_bf16(h[4], h[5]); w.w = cvt_pk_bf16(h[6], h[7]);
;                 *(u32x4*)rowp = w; }
	v_pk_fma_f32 v[96:97], v[222:223], v[96:97], v[124:125] op_sel_hi:[0,1,1]
	v_mul_f32_e32 v98, 0xbfb8aa3b, v97
	v_exp_f32_e32 v98, v98
	v_lshl_add_u64 v[100:101], v[126:127], 0, v[122:123]
	v_add_f32_e32 v98, 1.0, v98
	v_rcp_f32_e32 v98, v98
	s_nop 0
	v_mul_f32_e32 v97, v97, v98
	v_mov_b32_e32 v98, v103
	v_mul_f32_e32 v102, v96, v97
	v_pk_fma_f32 v[96:97], v[220:221], v[114:115], v[98:99] op_sel_hi:[0,1,1] neg_lo:[1,0,0] neg_hi:[1,0,0]
	v_pk_fma_f32 v[96:97], v[222:223], v[96:97], v[118:119] op_sel_hi:[0,1,1]
	v_mul_f32_e32 v98, 0xbfb8aa3b, v97
	v_exp_f32_e32 v98, v98
	s_nop 0
	v_add_f32_e32 v98, 1.0, v98
	v_rcp_f32_e32 v98, v98
	s_nop 0
	v_mul_f32_e32 v97, v97, v98
	v_mul_f32_e32 v99, v96, v97
	v_cvt_pk_bf16_f32 v98, v104, v105
	v_cvt_pk_bf16_f32 v99, v102, v99
	v_cvt_pk_bf16_f32 v96, v108, v109
	v_cvt_pk_bf16_f32 v97, v110, v106
	global_store_dwordx4 v[100:101], v[96:99], off
	s_nop 1
	v_mov_b32_e32 v98, v92
	v_mov_b32_e32 v99, v88
	v_pk_fma_f32 v[98:99], v[214:215], v[206:207], v[98:99] op_sel_hi:[0,1,1] neg_lo:[1,0,0] neg_hi:[1,0,0]
	v_pk_fma_f32 v[98:99], v[216:217], v[98:99], v[192:193] op_sel_hi:[0,1,1]
	v_mul_f32_e32 v88, 0xbfb8aa3b, v99
	v_exp_f32_e32 v88, v88
	v_lshl_add_u64 v[96:97], s[44:45], 0, v[218:219]
	v_lshlrev_b64 v[96:97], 7, v[96:97]
	v_lshl_add_u64 v[96:97], s[6:7], 0, v[96:97]
	v_add_f32_e32 v88, 1.0, v88
	v_rcp_f32_e32 v88, v88
	s_nop 0
	v_mul_f32_e32 v88, v99, v88
	v_mul_f32_e32 v92, v98, v88
	v_mov_b32_e32 v88, v93
	v_pk_fma_f32 v[88:89], v[214:215], v[208:209], v[88:89] op_sel_hi:[0,1,1] neg_lo:[1,0,0] neg_hi:[1,0,0]
	v_pk_fma_f32 v[88:89], v[216:217], v[88:89], v[132:133] op_sel_hi:[0,1,1]
	v_mul_f32_e32 v93, 0xbfb8aa3b, v89
	v_exp_f32_e32 v93, v93
	s_nop 0
	v_add_f32_e32 v93, 1.0, v93
	v_rcp_f32_e32 v93, v93
	s_nop 0
	v_mul_f32_e32 v89, v89, v93
	v_mul_f32_e32 v93, v88, v89
	v_mov_b32_e32 v88, v94
	v_mov_b32_e32 v89, v90
	v_pk_fma_f32 v[88:89], v[214:215], v[156:157], v[88:89] op_sel_hi:[0,1,1] neg_lo:[1,0,0] neg_hi:[1,0,0]
	v_pk_fma_f32 v[88:89], v[216:217], v[88:89], v[140:141] op_sel_hi:[0,1,1]
	v_mul_f32_e32 v90, 0xbfb8aa3b, v89
	v_exp_f32_e32 v90, v90
	s_nop 0
	v_add_f32_e32 v90, 1.0, v90
	v_rcp_f32_e32 v90, v90
	s_nop 0
	v_mul_f32_e32 v89, v89, v90
	v_mov_b32_e32 v90, v95
	v_mul_f32_e32 v94, v88, v89
	v_pk_fma_f32 v[88:89], v[214:215], v[210:211], v[90:91] op_sel_hi:[0,1,1] neg_lo:[1,0,0] neg_hi:[1,0,0]
	v_pk_fma_f32 v[88:89], v[216:217], v[88:89], v[134:135] op_sel_hi:[0,1,1]
	v_mul_f32_e32 v90, 0xbfb8aa3b, v89
	v_exp_f32_e32 v90, v90
	s_nop 0
	v_add_f32_e32 v90, 1.0, v90
	v_rcp_f32_e32 v90, v90
	s_nop 0
	v_mul_f32_e32 v89, v89, v90
	v_mul_f32_e32 v90, v88, v89
	v_mov_b32_e32 v88, v84
	v_mov_b32_e32 v89, v80
	v_pk_fma_f32 v[88:89], v[214:215], v[142:143], v[88:89] op_sel_hi:[0,1,1] neg_lo:[1,0,0] neg_hi:[1,0,0]
	v_pk_fma_f32 v[88:89], v[216:217], v[88:89], v[144:145] op_sel_hi:[0,1,1]
	v_mul_f32_e32 v80, 0xbfb8aa3b, v89
	v_exp_f32_e32 v80, v80
	s_nop 0
	v_add_f32_e32 v80, 1.0, v80
	v_rcp_f32_e32 v80, v80
	s_nop 0
	v_mul_f32_e32 v80, v89, v80
	v_mul_f32_e32 v88, v88, v80
	v_mov_b32_e32 v80, v85
	v_pk_fma_f32 v[80:81], v[214:215], v[112:113], v[80:81] op_sel_hi:[0,1,1] neg_lo:[1,0,0] neg_hi:[1,0,0]
	v_pk_fma_f32 v[80:81], v[216:217], v[80:81], v[116:117] op_sel_hi:[0,1,1]
	v_mul_f32_e32 v84, 0xbfb8aa3b, v81
	v_exp_f32_e32 v84, v84
	s_nop 0
	v_add_f32_e32 v84, 1.0, v84
	v_rcp_f32_e32 v84, v84
	s_nop 0
	v_mul_f32_e32 v81, v81, v84
	v_mul_f32_e32 v89, v80, v81
	v_mov_b32_e32 v80, v86
	v_mov_b32_e32 v81, v82
	v_pk_fma_f32 v[80:81], v[214:215], v[120:121], v[80:81] op_sel_hi:[0,1,1] neg_lo:[1,0,0] neg_hi:[1,0,0]
	v_pk_fma_f32 v[80:81], v[216:217], v[80:81], v[124:125] op_sel_hi:[0,1,1]
	v_mul_f32_e32 v82, 0xbfb8aa3b, v81
	v_exp_f32_e32 v82, v82
	v_lshl_add_u64 v[84:85], v[96:97], 0, v[122:123]
	v_add_f32_e32 v82, 1.0, v82
	v_rcp_f32_e32 v82, v82
	s_nop 0
	v_mul_f32_e32 v81, v81, v82
	v_mov_b32_e32 v82, v87
	v_mul_f32_e32 v86, v80, v81
	v_pk_fma_f32 v[80:81], v[214:215], v[114:115], v[82:83] op_sel_hi:[0,1,1] neg_lo:[1,0,0] neg_hi:[1,0,0]
	v_pk_fma_f32 v[80:81], v[216:217], v[80:81], v[118:119] op_sel_hi:[0,1,1]
	v_mul_f32_e32 v82, 0xbfb8aa3b, v81
	v_exp_f32_e32 v82, v82
	s_nop 0
	v_add_f32_e32 v82, 1.0, v82
	v_rcp_f32_e32 v82, v82
	s_nop 0
	v_mul_f32_e32 v81, v81, v82
	v_mul_f32_e32 v83, v80, v81
	v_cvt_pk_bf16_f32 v82, v88, v89
	v_cvt_pk_bf16_f32 v83, v86, v83
	v_cvt_pk_bf16_f32 v80, v92, v93
	v_cvt_pk_bf16_f32 v81, v94, v90
	global_store_dwordx4 v[84:85], v[80:83], off
	s_nop 1
	v_mov_b32_e32 v82, v76
	v_mov_b32_e32 v83, v72
	v_pk_fma_f32 v[82:83], v[200:201], v[206:207], v[82:83] op_sel_hi:[0,1,1] neg_lo:[1,0,0] neg_hi:[1,0,0]
	v_pk_fma_f32 v[82:83], v[202:203], v[82:83], v[192:193] op_sel_hi:[0,1,1]
	v_mul_f32_e32 v72, 0xbfb8aa3b, v83
	v_exp_f32_e32 v72, v72
	v_lshl_add_u64 v[80:81], s[44:45], 0, v[212:213]
	v_lshlrev_b64 v[80:81], 7, v[80:81]
	v_lshl_add_u64 v[80:81], s[6:7], 0, v[80:81]
	v_add_f32_e32 v72, 1.0, v72
	v_rcp_f32_e32 v72, v72
	s_nop 0
	v_mul_f32_e32 v72, v83, v72
	v_mul_f32_e32 v76, v82, v72
	v_mov_b32_e32 v72, v77
	v_pk_fma_f32 v[72:73], v[200:201], v[208:209], v[72:73] op_sel_hi:[0,1,1] neg_lo:[1,0,0] neg_hi:[1,0,0]
	v_pk_fma_f32 v[72:73], v[202:203], v[72:73], v[132:133] op_sel_hi:[0,1,1]
	v_mul_f32_e32 v77, 0xbfb8aa3b, v73
	v_exp_f32_e32 v77, v77
	s_nop 0
	v_add_f32_e32 v77, 1.0, v77
	v_rcp_f32_e32 v77, v77
	s_nop 0
	v_mul_f32_e32 v73, v73, v77
	v_mul_f32_e32 v77, v72, v73
	v_mov_b32_e32 v72, v78
	v_mov_b32_e32 v73, v74
	v_pk_fma_f32 v[72:73], v[200:201], v[156:157], v[72:73] op_sel_hi:[0,1,1] neg_lo:[1,0,0] neg_hi:[1,0,0]
	v_pk_fma_f32 v[72:73], v[202:203], v[72:73], v[140:141] op_sel_hi:[0,1,1]
; __device__ __forceinline__ unsigned cvt_pk_bf16(float lo, float hi) { unsigned r; asm("v_cvt_pk_bf16_f32 %0, %1, %2" : "=v"(r) : "v"(lo), "v"(hi)); return r; }
; __device__ __forceinline__ float fast_sigmoid(float v) { return __builtin_amdgcn_rcpf(1.0f + __builtin_amdgcn_exp2f(-1.4426950408889634f * v)); }
; __device__ __forceinline__ f32x4 ln_fix(const f32x4& a, float mu, float rs, const f32x4& cs, const f32x4& cb) { return (a - cs * mu) * rs + cb; }
;     __device__ __forceinline__ void operator()(const f32x4 (&acc)[2][2][4][2], const Unit& u, int wr, int wc, int fr_in, int fq_in) const {
;     ...
;         for (int ai = 0; ai < 2; ++ai)
; #pragma unroll
;             for (int m = 0; m < 4; ++m) { bf16_t* rowp = H + ((size_t)kt * mrows + (row0 + ai * HALF + m * 16)) * 64 + cin;
;                 float h[8];
; #pragma unroll
;                 for (int n = 0; n < 2; ++n) { f32x4 g = acc[ai][0][m][n], uu = acc[ai][1][m][n];
;                     if constexpr (LN) { g = ln_fix(g, rst.mu[ai][m], rst.rs[ai][m], csv[0][n], cbv[0][n]); uu = ln_fix(uu, rst.mu[ai][m], rst.rs[ai][m], csv[1][n], cbv[1][n]); }
; #pragma unroll
;                     for (int j = 0; j < 4; ++j) h[4 * n + j] = g[j] * fast_sigmoid(g[j]) * uu[j]; }
;                 u32x4 w; w.x = cvt_pk_bf16(h[0], h[1]); w.y = cvt_pk_bf16(h[2], h[3]); w.z = cvt_pk_bf16(h[4], h[5]); w.w = cvt_pk_bf16(h[6], h[7]);
;                 *(u32x4*)rowp = w; }
	v_mul_f32_e32 v74, 0xbfb8aa3b, v73
	v_exp_f32_e32 v74, v74
	s_nop 0
	v_add_f32_e32 v74, 1.0, v74
	v_rcp_f32_e32 v74, v74
	s_nop 0
	v_mul_f32_e32 v73, v73, v74
	v_mov_b32_e32 v74, v79
	v_mul_f32_e32 v78, v72, v73
	v_pk_fma_f32 v[72:73], v[200:201], v[210:211], v[74:75] op_sel_hi:[0,1,1] neg_lo:[1,0,0] neg_hi:[1,0,0]
	v_pk_fma_f32 v[72:73], v[202:203], v[72:73], v[134:135] op_sel_hi:[0,1,1]
	v_mul_f32_e32 v74, 0xbfb8aa3b, v73
	v_exp_f32_e32 v74, v74
	s_nop 0
	v_add_f32_e32 v74, 1.0, v74
	v_rcp_f32_e32 v74, v74
	s_nop 0
	v_mul_f32_e32 v73, v73, v74
	v_mul_f32_e32 v74, v72, v73
	v_mov_b32_e32 v72, v68
	v_mov_b32_e32 v73, v64
	v_pk_fma_f32 v[72:73], v[200:201], v[142:143], v[72:73] op_sel_hi:[0,1,1] neg_lo:[1,0,0] neg_hi:[1,0,0]
	v_pk_fma_f32 v[72:73], v[202:203], v[72:73], v[144:145] op_sel_hi:[0,1,1]
	v_mul_f32_e32 v64, 0xbfb8aa3b, v73
	v_exp_f32_e32 v64, v64
	s_nop 0
	v_add_f32_e32 v64, 1.0, v64
	v_rcp_f32_e32 v64, v64
	s_nop 0
	v_mul_f32_e32 v64, v73, v64
	v_mul_f32_e32 v72, v72, v64
	v_mov_b32_e32 v64, v69
	v_pk_fma_f32 v[64:65], v[200:201], v[112:113], v[64:65] op_sel_hi:[0,1,1] neg_lo:[1,0,0] neg_hi:[1,0,0]
	v_pk_fma_f32 v[64:65], v[202:203], v[64:65], v[116:117] op_sel_hi:[0,1,1]
	v_mul_f32_e32 v68, 0xbfb8aa3b, v65
	v_exp_f32_e32 v68, v68
	s_nop 0
	v_add_f32_e32 v68, 1.0, v68
	v_rcp_f32_e32 v68, v68
	s_nop 0
	v_mul_f32_e32 v65, v65, v68
	v_mul_f32_e32 v73, v64, v65
	v_mov_b32_e32 v64, v70
	v_mov_b32_e32 v65, v66
	v_pk_fma_f32 v[64:65], v[200:201], v[120:121], v[64:65] op_sel_hi:[0,1,1] neg_lo:[1,0,0] neg_hi:[1,0,0]
	v_pk_fma_f32 v[64:65], v[202:203], v[64:65], v[124:125] op_sel_hi:[0,1,1]
	v_mul_f32_e32 v66, 0xbfb8aa3b, v65
	v_exp_f32_e32 v66, v66
	v_lshl_add_u64 v[68:69], v[80:81], 0, v[122:123]
	v_add_f32_e32 v66, 1.0, v66
	v_rcp_f32_e32 v66, v66
	s_nop 0
	v_mul_f32_e32 v65, v65, v66
	v_mov_b32_e32 v66, v71
	v_mul_f32_e32 v70, v64, v65
	v_pk_fma_f32 v[64:65], v[200:201], v[114:115], v[66:67] op_sel_hi:[0,1,1] neg_lo:[1,0,0] neg_hi:[1,0,0]
	v_pk_fma_f32 v[64:65], v[202:203], v[64:65], v[118:119] op_sel_hi:[0,1,1]
	v_mul_f32_e32 v66, 0xbfb8aa3b, v65
	v_exp_f32_e32 v66, v66
	s_nop 0
	v_add_f32_e32 v66, 1.0, v66
	v_rcp_f32_e32 v66, v66
	s_nop 0
	v_mul_f32_e32 v65, v65, v66
	v_mul_f32_e32 v67, v64, v65
	v_cvt_pk_bf16_f32 v66, v72, v73
	v_cvt_pk_bf16_f32 v67, v70, v67
	v_cvt_pk_bf16_f32 v64, v76, v77
	v_cvt_pk_bf16_f32 v65, v78, v74
	global_store_dwordx4 v[68:69], v[64:67], off
	s_nop 1
	v_mov_b32_e32 v66, v60
	v_mov_b32_e32 v67, v56
	v_pk_fma_f32 v[66:67], v[194:195], v[206:207], v[66:67] op_sel_hi:[0,1,1] neg_lo:[1,0,0] neg_hi:[1,0,0]
	v_pk_fma_f32 v[66:67], v[198:199], v[66:67], v[192:193] op_sel_hi:[0,1,1]
	v_mul_f32_e32 v56, 0xbfb8aa3b, v67
	v_exp_f32_e32 v56, v56
	v_lshl_add_u64 v[64:65], s[44:45], 0, v[204:205]
	v_lshlrev_b64 v[64:65], 7, v[64:65]
	v_lshl_add_u64 v[64:65], s[6:7], 0, v[64:65]
	v_add_f32_e32 v56, 1.0, v56
	v_rcp_f32_e32 v56, v56
	s_nop 0
	v_mul_f32_e32 v56, v67, v56
	v_mul_f32_e32 v60, v66, v56
	v_mov_b32_e32 v56, v61
	v_pk_fma_f32 v[56:57], v[194:195], v[208:209], v[56:57] op_sel_hi:[0,1,1] neg_lo:[1,0,0] neg_hi:[1,0,0]
	v_pk_fma_f32 v[56:57], v[198:199], v[56:57], v[132:133] op_sel_hi:[0,1,1]
	v_mul_f32_e32 v61, 0xbfb8aa3b, v57
	v_exp_f32_e32 v61, v61
	s_nop 0
	v_add_f32_e32 v61, 1.0, v61
	v_rcp_f32_e32 v61, v61
	s_nop 0
	v_mul_f32_e32 v57, v57, v61
	v_mul_f32_e32 v61, v56, v57
	v_mov_b32_e32 v56, v62
	v_mov_b32_e32 v57, v58
	v_pk_fma_f32 v[56:57], v[194:195], v[156:157], v[56:57] op_sel_hi:[0,1,1] neg_lo:[1,0,0] neg_hi:[1,0,0]
	v_pk_fma_f32 v[56:57], v[198:199], v[56:57], v[140:141] op_sel_hi:[0,1,1]
	v_mul_f32_e32 v58, 0xbfb8aa3b, v57
	v_exp_f32_e32 v58, v58
	s_nop 0
	v_add_f32_e32 v58, 1.0, v58
	v_rcp_f32_e32 v58, v58
	s_nop 0
	v_mul_f32_e32 v57, v57, v58
	v_mov_b32_e32 v58, v63
	v_mul_f32_e32 v62, v56, v57
	v_pk_fma_f32 v[56:57], v[194:195], v[210:211], v[58:59] op_sel_hi:[0,1,1] neg_lo:[1,0,0] neg_hi:[1,0,0]
	v_pk_fma_f32 v[56:57], v[198:199], v[56:57], v[134:135] op_sel_hi:[0,1,1]
	v_mul_f32_e32 v58, 0xbfb8aa3b, v57
	v_exp_f32_e32 v58, v58
	s_nop 0
	v_add_f32_e32 v58, 1.0, v58
	v_rcp_f32_e32 v58, v58
	s_nop 0
	v_mul_f32_e32 v57, v57, v58
	v_mul_f32_e32 v58, v56, v57
	v_mov_b32_e32 v56, v52
	v_mov_b32_e32 v57, v48
	v_pk_fma_f32 v[56:57], v[194:195], v[142:143], v[56:57] op_sel_hi:[0,1,1] neg_lo:[1,0,0] neg_hi:[1,0,0]
	v_pk_fma_f32 v[56:57], v[198:199], v[56:57], v[144:145] op_sel_hi:[0,1,1]
	v_mul_f32_e32 v48, 0xbfb8aa3b, v57
	v_exp_f32_e32 v48, v48
	s_nop 0
	v_add_f32_e32 v48, 1.0, v48
	v_rcp_f32_e32 v48, v48
	s_nop 0
	v_mul_f32_e32 v48, v57, v48
	v_mul_f32_e32 v56, v56, v48
	v_mov_b32_e32 v48, v53
	v_pk_fma_f32 v[48:49], v[194:195], v[112:113], v[48:49] op_sel_hi:[0,1,1] neg_lo:[1,0,0] neg_hi:[1,0,0]
	v_pk_fma_f32 v[48:49], v[198:199], v[48:49], v[116:117] op_sel_hi:[0,1,1]
	v_mul_f32_e32 v52, 0xbfb8aa3b, v49
	v_exp_f32_e32 v52, v52
	s_nop 0
	v_add_f32_e32 v52, 1.0, v52
	v_rcp_f32_e32 v52, v52
	s_nop 0
	v_mul_f32_e32 v49, v49, v52
	v_mul_f32_e32 v57, v48, v49
	v_mov_b32_e32 v48, v54
	v_mov_b32_e32 v49, v50
	v_pk_fma_f32 v[48:49], v[194:195], v[120:121], v[48:49] op_sel_hi:[0,1,1] neg_lo:[1,0,0] neg_hi:[1,0,0]
	v_pk_fma_f32 v[48:49], v[198:199], v[48:49], v[124:125] op_sel_hi:[0,1,1]
	v_mul_f32_e32 v50, 0xbfb8aa3b, v49
	v_exp_f32_e32 v50, v50
	v_lshl_add_u64 v[52:53], v[64:65], 0, v[122:123]
	v_add_f32_e32 v50, 1.0, v50
	v_rcp_f32_e32 v50, v50
	s_nop 0
	v_mul_f32_e32 v49, v49, v50
	v_mov_b32_e32 v50, v55
	v_mul_f32_e32 v54, v48, v49
	v_pk_fma_f32 v[48:49], v[194:195], v[114:115], v[50:51] op_sel_hi:[0,1,1] neg_lo:[1,0,0] neg_hi:[1,0,0]
	v_pk_fma_f32 v[48:49], v[198:199], v[48:49], v[118:119] op_sel_hi:[0,1,1]
; __device__ __forceinline__ unsigned cvt_pk_bf16(float lo, float hi) { unsigned r; asm("v_cvt_pk_bf16_f32 %0, %1, %2" : "=v"(r) : "v"(lo), "v"(hi)); return r; }
; __device__ __forceinline__ float fast_sigmoid(float v) { return __builtin_amdgcn_rcpf(1.0f + __builtin_amdgcn_exp2f(-1.4426950408889634f * v)); }
; __device__ __forceinline__ f32x4 ln_fix(const f32x4& a, float mu, float rs, const f32x4& cs, const f32x4& cb) { return (a - cs * mu) * rs + cb; }
;     __device__ __forceinline__ void operator()(const f32x4 (&acc)[2][2][4][2], const Unit& u, int wr, int wc, int fr_in, int fq_in) const {
;     ...
;         for (int ai = 0; ai < 2; ++ai)
; #pragma unroll
;             for (int m = 0; m < 4; ++m) { bf16_t* rowp = H + ((size_t)kt * mrows + (row0 + ai * HALF + m * 16)) * 64 + cin;
;                 float h[8];
; #pragma unroll
;                 for (int n = 0; n < 2; ++n) { f32x4 g = acc[ai][0][m][n], uu = acc[ai][1][m][n];
;                     if constexpr (LN) { g = ln_fix(g, rst.mu[ai][m], rst.rs[ai][m], csv[0][n], cbv[0][n]); uu = ln_fix(uu, rst.mu[ai][m], rst.rs[ai][m], csv[1][n], cbv[1][n]); }
; #pragma unroll
;                     for (int j = 0; j < 4; ++j) h[4 * n + j] = g[j] * fast_sigmoid(g[j]) * uu[j]; }
;                 u32x4 w; w.x = cvt_pk_bf16(h[0], h[1]); w.y = cvt_pk_bf16(h[2], h[3]); w.z = cvt_pk_bf16(h[4], h[5]); w.w = cvt_pk_bf16(h[6], h[7]);
;                 *(u32x4*)rowp = w; }
	v_mul_f32_e32 v50, 0xbfb8aa3b, v49
	v_exp_f32_e32 v50, v50
	s_nop 0
	v_add_f32_e32 v50, 1.0, v50
	v_rcp_f32_e32 v50, v50
	s_nop 0
	v_mul_f32_e32 v49, v49, v50
	v_mul_f32_e32 v51, v48, v49
	v_cvt_pk_bf16_f32 v50, v56, v57
	v_cvt_pk_bf16_f32 v51, v54, v51
	v_cvt_pk_bf16_f32 v48, v60, v61
	v_cvt_pk_bf16_f32 v49, v62, v58
	global_store_dwordx4 v[52:53], v[48:51], off
	s_nop 1
	v_mov_b32_e32 v50, v44
	v_mov_b32_e32 v51, v40
	v_pk_fma_f32 v[50:51], v[186:187], v[206:207], v[50:51] op_sel_hi:[0,1,1] neg_lo:[1,0,0] neg_hi:[1,0,0]
	v_pk_fma_f32 v[50:51], v[190:191], v[50:51], v[192:193] op_sel_hi:[0,1,1]
	v_mul_f32_e32 v40, 0xbfb8aa3b, v51
	v_exp_f32_e32 v40, v40
	v_lshl_add_u64 v[48:49], s[44:45], 0, v[196:197]
	v_lshlrev_b64 v[48:49], 7, v[48:49]
	v_lshl_add_u64 v[48:49], s[6:7], 0, v[48:49]
	v_add_f32_e32 v40, 1.0, v40
	v_rcp_f32_e32 v40, v40
	s_nop 0
	v_mul_f32_e32 v40, v51, v40
	v_mul_f32_e32 v44, v50, v40
	v_mov_b32_e32 v40, v45
	v_pk_fma_f32 v[40:41], v[186:187], v[208:209], v[40:41] op_sel_hi:[0,1,1] neg_lo:[1,0,0] neg_hi:[1,0,0]
	v_pk_fma_f32 v[40:41], v[190:191], v[40:41], v[132:133] op_sel_hi:[0,1,1]
	v_mul_f32_e32 v45, 0xbfb8aa3b, v41
	v_exp_f32_e32 v45, v45
	s_nop 0
	v_add_f32_e32 v45, 1.0, v45
	v_rcp_f32_e32 v45, v45
	s_nop 0
	v_mul_f32_e32 v41, v41, v45
	v_mul_f32_e32 v45, v40, v41
	v_mov_b32_e32 v40, v46
	v_mov_b32_e32 v41, v42
	v_pk_fma_f32 v[40:41], v[186:187], v[156:157], v[40:41] op_sel_hi:[0,1,1] neg_lo:[1,0,0] neg_hi:[1,0,0]
	v_pk_fma_f32 v[40:41], v[190:191], v[40:41], v[140:141] op_sel_hi:[0,1,1]
	v_mul_f32_e32 v42, 0xbfb8aa3b, v41
	v_exp_f32_e32 v42, v42
	s_nop 0
	v_add_f32_e32 v42, 1.0, v42
	v_rcp_f32_e32 v42, v42
	s_nop 0
	v_mul_f32_e32 v41, v41, v42
	v_mov_b32_e32 v42, v47
	v_mul_f32_e32 v46, v40, v41
	v_pk_fma_f32 v[40:41], v[186:187], v[210:211], v[42:43] op_sel_hi:[0,1,1] neg_lo:[1,0,0] neg_hi:[1,0,0]
	v_pk_fma_f32 v[40:41], v[190:191], v[40:41], v[134:135] op_sel_hi:[0,1,1]
	v_mul_f32_e32 v42, 0xbfb8aa3b, v41
	v_exp_f32_e32 v42, v42
	s_nop 0
	v_add_f32_e32 v42, 1.0, v42
	v_rcp_f32_e32 v42, v42
	s_nop 0
	v_mul_f32_e32 v41, v41, v42
	v_mul_f32_e32 v42, v40, v41
	v_mov_b32_e32 v40, v36
	v_mov_b32_e32 v41, v32
	v_pk_fma_f32 v[40:41], v[186:187], v[142:143], v[40:41] op_sel_hi:[0,1,1] neg_lo:[1,0,0] neg_hi:[1,0,0]
	v_pk_fma_f32 v[40:41], v[190:191], v[40:41], v[144:145] op_sel_hi:[0,1,1]
	v_mul_f32_e32 v32, 0xbfb8aa3b, v41
	v_exp_f32_e32 v32, v32
	s_nop 0
	v_add_f32_e32 v32, 1.0, v32
	v_rcp_f32_e32 v32, v32
	s_nop 0
	v_mul_f32_e32 v32, v41, v32
	v_mul_f32_e32 v40, v40, v32
	v_mov_b32_e32 v32, v37
	v_pk_fma_f32 v[32:33], v[186:187], v[112:113], v[32:33] op_sel_hi:[0,1,1] neg_lo:[1,0,0] neg_hi:[1,0,0]
	v_pk_fma_f32 v[32:33], v[190:191], v[32:33], v[116:117] op_sel_hi:[0,1,1]
	v_mul_f32_e32 v36, 0xbfb8aa3b, v33
	v_exp_f32_e32 v36, v36
	s_nop 0
	v_add_f32_e32 v36, 1.0, v36
	v_rcp_f32_e32 v36, v36
	s_nop 0
	v_mul_f32_e32 v33, v33, v36
	v_mul_f32_e32 v41, v32, v33
	v_mov_b32_e32 v32, v38
	v_mov_b32_e32 v33, v34
	v_pk_fma_f32 v[32:33], v[186:187], v[120:121], v[32:33] op_sel_hi:[0,1,1] neg_lo:[1,0,0] neg_hi:[1,0,0]
	v_pk_fma_f32 v[32:33], v[190:191], v[32:33], v[124:125] op_sel_hi:[0,1,1]
	v_mul_f32_e32 v34, 0xbfb8aa3b, v33
	v_exp_f32_e32 v34, v34
	v_lshl_add_u64 v[36:37], v[48:49], 0, v[122:123]
	v_add_f32_e32 v34, 1.0, v34
	v_rcp_f32_e32 v34, v34
	s_nop 0
	v_mul_f32_e32 v33, v33, v34
	v_mov_b32_e32 v34, v39
	v_mul_f32_e32 v38, v32, v33
	v_pk_fma_f32 v[32:33], v[186:187], v[114:115], v[34:35] op_sel_hi:[0,1,1] neg_lo:[1,0,0] neg_hi:[1,0,0]
	v_pk_fma_f32 v[32:33], v[190:191], v[32:33], v[118:119] op_sel_hi:[0,1,1]
	v_mul_f32_e32 v34, 0xbfb8aa3b, v33
	v_exp_f32_e32 v34, v34
	s_nop 0
	v_add_f32_e32 v34, 1.0, v34
	v_rcp_f32_e32 v34, v34
	s_nop 0
	v_mul_f32_e32 v33, v33, v34
	v_mul_f32_e32 v35, v32, v33
	v_cvt_pk_bf16_f32 v34, v40, v41
	v_cvt_pk_bf16_f32 v35, v38, v35
	v_cvt_pk_bf16_f32 v32, v44, v45
	v_cvt_pk_bf16_f32 v33, v46, v42
	global_store_dwordx4 v[36:37], v[32:35], off
	s_nop 1
	v_mov_b32_e32 v34, v28
	v_mov_b32_e32 v35, v24
	v_pk_fma_f32 v[34:35], v[180:181], v[206:207], v[34:35] op_sel_hi:[0,1,1] neg_lo:[1,0,0] neg_hi:[1,0,0]
	v_pk_fma_f32 v[34:35], v[184:185], v[34:35], v[192:193] op_sel_hi:[0,1,1]
	v_mul_f32_e32 v24, 0xbfb8aa3b, v35
	v_exp_f32_e32 v24, v24
	v_lshl_add_u64 v[32:33], s[44:45], 0, v[188:189]
	v_lshlrev_b64 v[32:33], 7, v[32:33]
	v_lshl_add_u64 v[32:33], s[6:7], 0, v[32:33]
	v_add_f32_e32 v24, 1.0, v24
	v_rcp_f32_e32 v24, v24
	s_nop 0
	v_mul_f32_e32 v24, v35, v24
	v_mul_f32_e32 v28, v34, v24
	v_mov_b32_e32 v24, v29
	v_pk_fma_f32 v[24:25], v[180:181], v[208:209], v[24:25] op_sel_hi:[0,1,1] neg_lo:[1,0,0] neg_hi:[1,0,0]
	v_pk_fma_f32 v[24:25], v[184:185], v[24:25], v[132:133] op_sel_hi:[0,1,1]
	v_mul_f32_e32 v29, 0xbfb8aa3b, v25
	v_exp_f32_e32 v29, v29
	s_nop 0
	v_add_f32_e32 v29, 1.0, v29
	v_rcp_f32_e32 v29, v29
	s_nop 0
	v_mul_f32_e32 v25, v25, v29
	v_mul_f32_e32 v29, v24, v25
	v_mov_b32_e32 v24, v30
	v_mov_b32_e32 v25, v26
	v_pk_fma_f32 v[24:25], v[180:181], v[156:157], v[24:25] op_sel_hi:[0,1,1] neg_lo:[1,0,0] neg_hi:[1,0,0]
	v_pk_fma_f32 v[24:25], v[184:185], v[24:25], v[140:141] op_sel_hi:[0,1,1]
	v_mul_f32_e32 v26, 0xbfb8aa3b, v25
	v_exp_f32_e32 v26, v26
	s_nop 0
	v_add_f32_e32 v26, 1.0, v26
	v_rcp_f32_e32 v26, v26
	s_nop 0
	v_mul_f32_e32 v25, v25, v26
	v_mov_b32_e32 v26, v31
	v_mul_f32_e32 v30, v24, v25
	v_pk_fma_f32 v[24:25], v[180:181], v[210:211], v[26:27] op_sel_hi:[0,1,1] neg_lo:[1,0,0] neg_hi:[1,0,0]
	v_pk_fma_f32 v[24:25], v[184:185], v[24:25], v[134:135] op_sel_hi:[0,1,1]
	v_mul_f32_e32 v26, 0xbfb8aa3b, v25
	v_exp_f32_e32 v26, v26
	s_nop 0
	v_add_f32_e32 v26, 1.0, v26
	v_rcp_f32_e32 v26, v26
; __device__ __forceinline__ unsigned cvt_pk_bf16(float lo, float hi) { unsigned r; asm("v_cvt_pk_bf16_f32 %0, %1, %2" : "=v"(r) : "v"(lo), "v"(hi)); return r; }
; __device__ __forceinline__ float fast_sigmoid(float v) { return __builtin_amdgcn_rcpf(1.0f + __builtin_amdgcn_exp2f(-1.4426950408889634f * v)); }
; __device__ __forceinline__ f32x4 ln_fix(const f32x4& a, float mu, float rs, const f32x4& cs, const f32x4& cb) { return (a - cs * mu) * rs + cb; }
; #define PG8_BAR __builtin_amdgcn_s_barrier()
;     __device__ __forceinline__ void operator()(const f32x4 (&acc)[2][2][4][2], const Unit& u, int wr, int wc, int fr_in, int fq_in) const {
;     ...
;         for (int ai = 0; ai < 2; ++ai)
; #pragma unroll
;             for (int m = 0; m < 4; ++m) { bf16_t* rowp = H + ((size_t)kt * mrows + (row0 + ai * HALF + m * 16)) * 64 + cin;
;                 float h[8];
; #pragma unroll
;                 for (int n = 0; n < 2; ++n) { f32x4 g = acc[ai][0][m][n], uu = acc[ai][1][m][n];
;                     if constexpr (LN) { g = ln_fix(g, rst.mu[ai][m], rst.rs[ai][m], csv[0][n], cbv[0][n]); uu = ln_fix(uu, rst.mu[ai][m], rst.rs[ai][m], csv[1][n], cbv[1][n]); }
; #pragma unroll
;                     for (int j = 0; j < 4; ++j) h[4 * n + j] = g[j] * fast_sigmoid(g[j]) * uu[j]; }
;                 u32x4 w; w.x = cvt_pk_bf16(h[0], h[1]); w.y = cvt_pk_bf16(h[2], h[3]); w.z = cvt_pk_bf16(h[4], h[5]); w.w = cvt_pk_bf16(h[6], h[7]);
;                 *(u32x4*)rowp = w; }
; template <class Epi, class Sched, bool ALIGN_EPI = false, bool SP2 = false>
; __device__ __forceinline__ void gemm_phase(PG8_LAS unsigned char* lds, const Gemm g, const Sched& S, const Epi& E) {
;     ...
;         if constexpr (ALIGN_EPI) { if (wr == 0) PG8_BAR; }
;         if constexpr (!Epi::AFTER_DRAIN) { E(acc, cur, wr, wc, fr, fq); S.done(cur); }
;         if (!has_next) break;
; #pragma unroll
;         for (int a = 0; a < 2; ++a)
; #pragma unroll
;             for (int b = 0; b < 2; ++b)
; #pragma unroll
;                 for (int m = 0; m < 4; ++m)
; #pragma unroll
;                     for (int n = 0; n < 2; ++n) acc[a][b][m][n] = (f32x4){0.f, 0.f, 0.f, 0.f};
;         cur = nxt; cA = nA; cB = nB; ++ui;
;         if constexpr (ALIGN_EPI) { if (wr == 1) PG8_BAR; }
	s_nop 0
	v_mul_f32_e32 v25, v25, v26
	v_mul_f32_e32 v26, v24, v25
	v_mov_b32_e32 v24, v20
	v_mov_b32_e32 v25, v16
	v_pk_fma_f32 v[24:25], v[180:181], v[142:143], v[24:25] op_sel_hi:[0,1,1] neg_lo:[1,0,0] neg_hi:[1,0,0]
	v_pk_fma_f32 v[24:25], v[184:185], v[24:25], v[144:145] op_sel_hi:[0,1,1]
	v_mul_f32_e32 v16, 0xbfb8aa3b, v25
	v_exp_f32_e32 v16, v16
	s_nop 0
	v_add_f32_e32 v16, 1.0, v16
	v_rcp_f32_e32 v16, v16
	s_nop 0
	v_mul_f32_e32 v16, v25, v16
	v_mul_f32_e32 v24, v24, v16
	v_mov_b32_e32 v16, v21
	v_pk_fma_f32 v[16:17], v[180:181], v[112:113], v[16:17] op_sel_hi:[0,1,1] neg_lo:[1,0,0] neg_hi:[1,0,0]
	v_pk_fma_f32 v[16:17], v[184:185], v[16:17], v[116:117] op_sel_hi:[0,1,1]
	v_mul_f32_e32 v20, 0xbfb8aa3b, v17
	v_exp_f32_e32 v20, v20
	s_nop 0
	v_add_f32_e32 v20, 1.0, v20
	v_rcp_f32_e32 v20, v20
	s_nop 0
	v_mul_f32_e32 v17, v17, v20
	v_mul_f32_e32 v25, v16, v17
	v_mov_b32_e32 v16, v22
	v_mov_b32_e32 v17, v18
	v_pk_fma_f32 v[16:17], v[180:181], v[120:121], v[16:17] op_sel_hi:[0,1,1] neg_lo:[1,0,0] neg_hi:[1,0,0]
	v_pk_fma_f32 v[16:17], v[184:185], v[16:17], v[124:125] op_sel_hi:[0,1,1]
	v_mul_f32_e32 v18, 0xbfb8aa3b, v17
	v_exp_f32_e32 v18, v18
	v_lshl_add_u64 v[20:21], v[32:33], 0, v[122:123]
	v_add_f32_e32 v18, 1.0, v18
	v_rcp_f32_e32 v18, v18
	s_nop 0
	v_mul_f32_e32 v17, v17, v18
	v_mov_b32_e32 v18, v23
	v_mul_f32_e32 v22, v16, v17
	v_pk_fma_f32 v[16:17], v[180:181], v[114:115], v[18:19] op_sel_hi:[0,1,1] neg_lo:[1,0,0] neg_hi:[1,0,0]
	v_pk_fma_f32 v[16:17], v[184:185], v[16:17], v[118:119] op_sel_hi:[0,1,1]
	v_mul_f32_e32 v18, 0xbfb8aa3b, v17
	v_exp_f32_e32 v18, v18
	v_mov_b32_e32 v23, v8
	v_add_f32_e32 v18, 1.0, v18
	v_rcp_f32_e32 v18, v18
	s_nop 0
	v_mul_f32_e32 v17, v17, v18
	v_mul_f32_e32 v19, v16, v17
	v_cvt_pk_bf16_f32 v18, v24, v25
	v_cvt_pk_bf16_f32 v19, v22, v19
	v_cvt_pk_bf16_f32 v16, v28, v29
	v_cvt_pk_bf16_f32 v17, v30, v26
	global_store_dwordx4 v[20:21], v[16:19], off
	v_mov_b32_e32 v20, v136
	v_mov_b32_e32 v21, v176
	v_mov_b32_e32 v18, v176
	v_mov_b32_e32 v19, v128
	v_mov_b32_e32 v22, v12
	v_pk_fma_f32 v[18:19], v[18:19], v[20:21], v[22:23] neg_lo:[1,0,0] neg_hi:[1,0,0]
	v_mov_b32_e32 v128, v176
	v_pk_fma_f32 v[18:19], v[18:19], v[178:179], v[192:193] op_sel_hi:[1,0,1]
	v_lshl_add_u64 v[16:17], s[44:45], 0, v[182:183]
	v_mul_f32_e32 v8, 0xbfb8aa3b, v19
	v_exp_f32_e32 v8, v8
	v_lshlrev_b64 v[16:17], 7, v[16:17]
	v_lshl_add_u64 v[16:17], s[6:7], 0, v[16:17]
	s_mov_b64 s[44:45], -1
	v_add_f32_e32 v8, 1.0, v8
	v_rcp_f32_e32 v8, v8
	s_nop 0
	v_mul_f32_e32 v8, v19, v8
	v_mul_f32_e32 v20, v18, v8
	v_pk_mov_b32 v[18:19], v[136:137], v[176:177] op_sel:[1,0]
	v_mov_b32_e32 v8, v13
	v_pk_fma_f32 v[8:9], v[128:129], v[18:19], v[8:9] neg_lo:[1,0,0] neg_hi:[1,0,0]
	v_mov_b32_e32 v13, v176
	v_pk_fma_f32 v[8:9], v[8:9], v[178:179], v[132:133] op_sel_hi:[1,0,1]
	v_mov_b32_e32 v18, v14
	v_mul_f32_e32 v12, 0xbfb8aa3b, v9
	v_exp_f32_e32 v12, v12
	v_mov_b32_e32 v19, v10
	v_add_f32_e32 v12, 1.0, v12
	v_rcp_f32_e32 v12, v12
	s_nop 0
	v_mul_f32_e32 v9, v9, v12
	v_mul_f32_e32 v21, v8, v9
	v_mov_b32_e32 v8, v176
	v_mov_b32_e32 v9, v130
	v_mov_b32_e32 v12, v138
	v_pk_fma_f32 v[8:9], v[8:9], v[12:13], v[18:19] neg_lo:[1,0,0] neg_hi:[1,0,0]
	v_mov_b32_e32 v130, v176
	v_pk_fma_f32 v[8:9], v[8:9], v[178:179], v[140:141] op_sel_hi:[1,0,1]
	s_nop 0
	v_mul_f32_e32 v10, 0xbfb8aa3b, v9
	v_exp_f32_e32 v10, v10
	s_nop 0
	v_add_f32_e32 v10, 1.0, v10
	v_rcp_f32_e32 v10, v10
	s_nop 0
	v_mul_f32_e32 v9, v9, v10
	v_mul_f32_e32 v12, v8, v9
	v_pk_mov_b32 v[8:9], v[138:139], v[176:177] op_sel:[1,0]
	v_mov_b32_e32 v10, v15
	v_pk_fma_f32 v[8:9], v[130:131], v[8:9], v[10:11] neg_lo:[1,0,0] neg_hi:[1,0,0]
	s_nop 0
	v_pk_fma_f32 v[8:9], v[8:9], v[178:179], v[134:135] op_sel_hi:[1,0,1]
	s_nop 0
	v_mul_f32_e32 v10, 0xbfb8aa3b, v9
	v_exp_f32_e32 v10, v10
	s_nop 0
	v_add_f32_e32 v10, 1.0, v10
	v_rcp_f32_e32 v10, v10
	s_nop 0
	v_mul_f32_e32 v9, v9, v10
	v_mul_f32_e32 v10, v8, v9
	v_mov_b32_e32 v8, v0
	v_mov_b32_e32 v9, v4
	v_pk_fma_f32 v[8:9], v[176:177], v[142:143], v[8:9] op_sel_hi:[0,1,1] neg_lo:[1,0,0] neg_hi:[1,0,0]
	v_pk_fma_f32 v[8:9], v[178:179], v[8:9], v[144:145] op_sel_hi:[0,1,1]
	v_mul_f32_e32 v0, 0xbfb8aa3b, v9
	v_exp_f32_e32 v0, v0
	v_mov_b32_e32 v4, v1
	v_add_f32_e32 v0, 1.0, v0
	v_rcp_f32_e32 v0, v0
	s_nop 0
	v_mul_f32_e32 v0, v9, v0
	v_mul_f32_e32 v8, v8, v0
	v_pk_fma_f32 v[0:1], v[176:177], v[112:113], v[4:5] op_sel_hi:[0,1,1] neg_lo:[1,0,0] neg_hi:[1,0,0]
	v_pk_fma_f32 v[0:1], v[178:179], v[0:1], v[116:117] op_sel_hi:[0,1,1]
	v_mul_f32_e32 v4, 0xbfb8aa3b, v1
	v_exp_f32_e32 v4, v4
	s_nop 0
	v_add_f32_e32 v4, 1.0, v4
	v_rcp_f32_e32 v4, v4
	s_nop 0
	v_mul_f32_e32 v1, v1, v4
	v_mul_f32_e32 v9, v0, v1
	v_mov_b32_e32 v0, v2
	v_mov_b32_e32 v1, v6
	v_pk_fma_f32 v[0:1], v[176:177], v[120:121], v[0:1] op_sel_hi:[0,1,1] neg_lo:[1,0,0] neg_hi:[1,0,0]
	v_pk_fma_f32 v[0:1], v[178:179], v[0:1], v[124:125] op_sel_hi:[0,1,1]
	v_mul_f32_e32 v2, 0xbfb8aa3b, v1
	v_exp_f32_e32 v2, v2
	v_mov_b32_e32 v6, v3
	v_lshl_add_u64 v[4:5], v[16:17], 0, v[122:123]
	v_add_f32_e32 v2, 1.0, v2
	v_rcp_f32_e32 v2, v2
	s_nop 0
	v_mul_f32_e32 v1, v1, v2
	v_mul_f32_e32 v11, v0, v1
	v_pk_fma_f32 v[0:1], v[176:177], v[114:115], v[6:7] op_sel_hi:[0,1,1] neg_lo:[1,0,0] neg_hi:[1,0,0]
	v_pk_fma_f32 v[0:1], v[178:179], v[0:1], v[118:119] op_sel_hi:[0,1,1]
	v_mul_f32_e32 v2, 0xbfb8aa3b, v1
	v_exp_f32_e32 v2, v2
	s_nop 0
	v_add_f32_e32 v2, 1.0, v2
	v_rcp_f32_e32 v2, v2
	s_nop 0
	v_mul_f32_e32 v1, v1, v2
	v_mul_f32_e32 v3, v0, v1
	v_cvt_pk_bf16_f32 v0, v20, v21
	v_cvt_pk_bf16_f32 v1, v12, v10
	v_cvt_pk_bf16_f32 v2, v8, v9
	v_cvt_pk_bf16_f32 v3, v11, v3
	global_store_dwordx4 v[4:5], v[0:3], off
	s_cbranch_vccnz .LBB0_1987
	s_andn2_b64 vcc, exec, s[4:5]
	s_cbranch_vccnz .LBB0_1986
	s_barrier
	s_branch .LBB0_1986

; __device__ __forceinline__ void load_row_stats(const float* sp, int row0, RowStats& r) {
; #pragma unroll
;     for (int ai = 0; ai < 2; ++ai) { asm volatile("" ::: "memory");
; #pragma unroll
;         for (int m = 0; m < 4; ++m) { const float* p = sp + (size_t)(row0 + ai * HALF + m * 16) * 8; const f32x4 a = *(const f32x4*)p, b = *(const f32x4*)(p + 4);
;             const float s1 = (a[0] + a[2]) + (b[0] + b[2]), s2 = (a[1] + a[3]) + (b[1] + b[3]); const float mu = s1 * (1.f / 1024.f); const float var = s2 * (1.f / 1024.f) - mu * mu;
;             r.mu[ai][m] = mu; r.rs[ai][m] = __builtin_amdgcn_rsqf(__builtin_fmaxf(var, 0.f) + 1e-5f); } }
;     __device__ __forceinline__ void operator()(const f32x4 (&acc)[2][2][4][2], const Unit& u, int wr, int wc, int fr_in, int fq_in) const {
;     ...
;         if constexpr (BASE == 1) load_row_stats(sp_old, row0, rst);
.LBB0_2100:
	s_lshl_b32 s11, s46, 8
	v_mov_b32_e32 v203, v177
	v_mov_b32_e32 v199, v175
	s_add_i32 s8, s11, s60
	v_mov_b32_e32 v174, 0.5
	v_add_u32_e32 v146, s8, v199
	v_ashrrev_i32_e32 v147, 31, v146
	v_mov_b32_e32 v176, 0x3fb504f3
	s_cselect_b32 s99, 1, 0
	v_readfirstlane_b32 s98, v254
	v_and_b32_e32 v128, 0xffffff00, v146
	s_nop 0
	s_cmpk_lt_u32 s98, 0x100
	s_cbranch_scc0 .Lrs10_skip
	v_add_u32_e32 v128, v128, v254
	v_mov_b32_e32 v129, 0
	v_lshlrev_b64 v[128:129], 5, v[128:129]
	v_lshl_add_u64 v[132:133], s[22:23], 0, v[128:129]
	global_load_dwordx4 v[128:131], v[132:133], off offset:16
	s_nop 0
	global_load_dwordx4 v[132:135], v[132:133], off
	s_waitcnt vmcnt(0)
	v_pk_add_f32 v[128:129], v[128:129], v[130:131]
	v_pk_add_f32 v[132:133], v[132:133], v[134:135]
	s_nop 0
	v_pk_add_f32 v[128:129], v[132:133], v[128:129]
	s_nop 0
	v_pk_mul_f32 v[128:129], v[128:129], s[34:35] op_sel_hi:[1,0]
	v_lshlrev_b32_e32 v130, 3, v254
	v_add_u32_e32 v130, 0x22400, v130
	ds_write_b64 v130, v[128:129]

; __device__ __forceinline__ void load_row_stats(const float* sp, int row0, RowStats& r) {
; #pragma unroll
;     for (int ai = 0; ai < 2; ++ai) { asm volatile("" ::: "memory");
; #pragma unroll
;         for (int m = 0; m < 4; ++m) { const float* p = sp + (size_t)(row0 + ai * HALF + m * 16) * 8; const f32x4 a = *(const f32x4*)p, b = *(const f32x4*)(p + 4);
;             const float s1 = (a[0] + a[2]) + (b[0] + b[2]), s2 = (a[1] + a[3]) + (b[1] + b[3]); const float mu = s1 * (1.f / 1024.f); const float var = s2 * (1.f / 1024.f) - mu * mu;
;             r.mu[ai][m] = mu; r.rs[ai][m] = __builtin_amdgcn_rsqf(__builtin_fmaxf(var, 0.f) + 1e-5f); } }
;     __device__ __forceinline__ void operator()(const f32x4 (&acc)[2][2][4][2], const Unit& u, int wr, int wc, int fr_in, int fq_in) const {
;     ...
;         RowStats rst; load_row_stats(sp, row0, rst);
; #pragma unroll
;         for (int bj = 0; bj < 2; ++bj) { f32x4 csv[2], cbv[2], gv[2], bv[2];
; #pragma unroll
;             for (int n = 0; n < 2; ++n) { csv[n] = *(const f32x4*)(cs + col0 + bj * HALF + 4 * n); cbv[n] = *(const f32x4*)(cb + col0 + bj * HALF + 4 * n); gv[n] = *(const f32x4*)(lg + col0 + bj * HALF + 4 * n); bv[n] = *(const f32x4*)(lb + col0 + bj * HALF + 4 * n); }
.LBB0_2193:
	s_lshl_b32 s10, s10, 8
	v_mov_b32_e32 v112, v183
	v_mov_b32_e32 v113, v187
	s_add_i32 s10, s10, s59
	s_andn2_b64 vcc, exec, s[0:1]
	v_add_u32_e32 v160, s10, v112
	s_lshl_b32 s10, s11, 8
	s_or_b32 s10, s10, s60
	v_ashrrev_i32_e32 v161, 31, v160
	v_lshl_add_u32 v212, v113, 3, s10
	s_cselect_b32 s99, 1, 0
	v_readfirstlane_b32 s98, v254
	v_and_b32_e32 v112, 0xffffff00, v160
	s_nop 0
	s_cmpk_lt_u32 s98, 0x100
	s_cbranch_scc0 .Lrs11_skip
	v_add_u32_e32 v112, v112, v254
	v_mov_b32_e32 v113, 0
	v_lshlrev_b64 v[112:113], 5, v[112:113]
	v_lshl_add_u64 v[116:117], s[28:29], 0, v[112:113]
	global_load_dwordx4 v[112:115], v[116:117], off offset:16
	s_nop 0
	global_load_dwordx4 v[116:119], v[116:117], off
	s_waitcnt vmcnt(0)
	v_pk_add_f32 v[112:113], v[112:113], v[114:115]
	v_pk_add_f32 v[116:117], v[116:117], v[118:119]
	s_nop 0
	v_pk_add_f32 v[112:113], v[116:117], v[112:113]
	s_nop 0
	v_pk_mul_f32 v[112:113], v[112:113], s[46:47] op_sel_hi:[1,0]
	v_lshlrev_b32_e32 v114, 3, v254
	v_add_u32_e32 v114, 0x22400, v114
	ds_write_b64 v114, v[112:113]
.Lrs11_skip:
	s_waitcnt vmcnt(0) lgkmcnt(0)
	s_barrier
	v_and_b32_e32 v114, 0xff, v160
	v_lshlrev_b32_e32 v114, 3, v114
	v_add_u32_e32 v114, 0x22400, v114
	ds_read_b64 v[208:209], v114
	ds_read_b64 v[204:205], v114 offset:128
	ds_read_b64 v[200:201], v114 offset:256
	ds_read_b64 v[196:197], v114 offset:384
	ds_read_b64 v[192:193], v114 offset:1024
	ds_read_b64 v[188:189], v114 offset:1152
	ds_read_b64 v[184:185], v114 offset:1280
	ds_read_b64 v[180:181], v114 offset:1408
	s_cmp_lg_u32 s99, 0
	s_waitcnt lgkmcnt(0)
	v_add_u32_e32 v236, 16, v160
	v_ashrrev_i32_e32 v237, 31, v236
	v_add_u32_e32 v234, 32, v160
	v_ashrrev_i32_e32 v235, 31, v234
	v_add_u32_e32 v232, 48, v160
	v_ashrrev_i32_e32 v233, 31, v232
	v_add_u32_e32 v230, 0x80, v160
	v_ashrrev_i32_e32 v231, 31, v230
	v_add_u32_e32 v228, 0x90, v160
	v_ashrrev_i32_e32 v229, 31, v228
	v_add_u32_e32 v226, 0xa0, v160
	v_ashrrev_i32_e32 v227, 31, v226
	v_add_u32_e32 v224, 0xb0, v160
	v_ashrrev_i32_e32 v225, 31, v224
	v_ashrrev_i32_e32 v213, 31, v212
	v_lshlrev_b64 v[222:223], 10, v[160:161]
	v_lshl_add_u64 v[238:239], v[222:223], 0, v[212:213]
	v_lshlrev_b64 v[240:241], 1, v[238:239]
	v_lshl_add_u64 v[160:161], s[26:27], 0, v[240:241]
	v_lshl_add_u64 v[240:241], s[22:23], 0, v[240:241]
	s_mov_b64 s[10:11], -1
	s_nop 0
	v_fma_f32 v112, -v208, v208, v209
	v_max_f32_e32 v112, 0, v112
	v_add_f32_e32 v112, 0x3727c5ac, v112
	v_rsq_f32_e32 v210, v112
	s_nop 0
	v_fma_f32 v112, -v204, v204, v205
	v_max_f32_e32 v112, 0, v112
	v_add_f32_e32 v112, 0x3727c5ac, v112
	v_rsq_f32_e32 v206, v112
	s_nop 0
	v_fma_f32 v112, -v200, v200, v201
	v_max_f32_e32 v112, 0, v112
	v_add_f32_e32 v112, 0x3727c5ac, v112
	v_rsq_f32_e32 v202, v112
	s_nop 0
	v_fma_f32 v112, -v196, v196, v197
	v_max_f32_e32 v112, 0, v112
	v_add_f32_e32 v112, 0x3727c5ac, v112
	v_rsq_f32_e32 v198, v112
	s_nop 0
	v_fma_f32 v112, -v192, v192, v193
	v_max_f32_e32 v112, 0, v112
	v_add_f32_e32 v112, 0x3727c5ac, v112
	v_rsq_f32_e32 v194, v112
	s_nop 0
	v_fma_f32 v112, -v188, v188, v189
	v_max_f32_e32 v112, 0, v112
	v_add_f32_e32 v112, 0x3727c5ac, v112
	v_rsq_f32_e32 v190, v112
	s_nop 0
	v_fma_f32 v112, -v184, v184, v185
	v_max_f32_e32 v112, 0, v112
	v_add_f32_e32 v112, 0x3727c5ac, v112
	v_rsq_f32_e32 v186, v112
	s_nop 0
	v_fma_f32 v112, -v180, v180, v181
	v_max_f32_e32 v112, 0, v112
	v_add_f32_e32 v112, 0x3727c5ac, v112
	v_rsq_f32_e32 v182, v112
	v_lshlrev_b64 v[112:113], 2, v[212:213]
	v_lshl_add_u64 v[220:221], s[30:31], 0, v[112:113]
	v_lshl_add_u64 v[218:219], s[6:7], 0, v[112:113]
	v_lshl_add_u64 v[216:217], s[34:35], 0, v[112:113]
	v_lshl_add_u64 v[214:215], s[38:39], 0, v[112:113]
	global_load_dwordx4 v[116:119], v[220:221], off offset:16
	global_load_dwordx4 v[124:127], v[220:221], off
	global_load_dwordx4 v[112:115], v[218:219], off offset:16
	global_load_dwordx4 v[120:123], v[218:219], off
	global_load_dwordx4 v[128:131], v[216:217], off offset:16
	global_load_dwordx4 v[136:139], v[216:217], off
	global_load_dwordx4 v[132:135], v[214:215], off offset:16
	global_load_dwordx4 v[140:143], v[214:215], off
	s_waitcnt vmcnt(0)
	v_pk_fma_f32 v[152:153], v[208:209], v[116:117], v[152:153] op_sel_hi:[0,1,1] neg_lo:[1,0,0] neg_hi:[1,0,0]
	global_load_dwordx4 v[160:163], v[160:161], off
	v_pk_fma_f32 v[156:157], v[208:209], v[124:125], v[156:157] op_sel_hi:[0,1,1] neg_lo:[1,0,0] neg_hi:[1,0,0]
	global_load_dwordx4 v[240:243], v[240:241], off
	v_pk_fma_f32 v[158:159], v[208:209], v[126:127], v[158:159] op_sel_hi:[0,1,1] neg_lo:[1,0,0] neg_hi:[1,0,0]
	v_pk_fma_f32 v[154:155], v[208:209], v[118:119], v[154:155] op_sel_hi:[0,1,1] neg_lo:[1,0,0] neg_hi:[1,0,0]
	v_pk_fma_f32 v[148:149], v[204:205], v[124:125], v[148:149] op_sel_hi:[0,1,1] neg_lo:[1,0,0] neg_hi:[1,0,0]
	v_pk_fma_f32 v[146:147], v[204:205], v[118:119], v[146:147] op_sel_hi:[0,1,1] neg_lo:[1,0,0] neg_hi:[1,0,0]
	v_pk_fma_f32 v[150:151], v[204:205], v[126:127], v[150:151] op_sel_hi:[0,1,1] neg_lo:[1,0,0] neg_hi:[1,0,0]
	v_pk_fma_f32 v[144:145], v[204:205], v[116:117], v[144:145] op_sel_hi:[0,1,1] neg_lo:[1,0,0] neg_hi:[1,0,0]
	v_pk_fma_f32 v[108:109], v[200:201], v[124:125], v[108:109] op_sel_hi:[0,1,1] neg_lo:[1,0,0] neg_hi:[1,0,0]
	v_pk_fma_f32 v[108:109], v[202:203], v[108:109], v[120:121] op_sel_hi:[0,1,1]
	v_pk_fma_f32 v[106:107], v[200:201], v[118:119], v[106:107] op_sel_hi:[0,1,1] neg_lo:[1,0,0] neg_hi:[1,0,0]
	v_pk_fma_f32 v[110:111], v[200:201], v[126:127], v[110:111] op_sel_hi:[0,1,1] neg_lo:[1,0,0] neg_hi:[1,0,0]
	v_pk_fma_f32 v[110:111], v[202:203], v[110:111], v[122:123] op_sel_hi:[0,1,1]
	v_pk_fma_f32 v[104:105], v[200:201], v[116:117], v[104:105] op_sel_hi:[0,1,1] neg_lo:[1,0,0] neg_hi:[1,0,0]
; __device__ __forceinline__ unsigned cvt_pk_bf16(float lo, float hi) { unsigned r; asm("v_cvt_pk_bf16_f32 %0, %1, %2" : "=v"(r) : "v"(lo), "v"(hi)); return r; }
; __device__ __forceinline__ float fast_sigmoid(float v) { return __builtin_amdgcn_rcpf(1.0f + __builtin_amdgcn_exp2f(-1.4426950408889634f * v)); }
;     __device__ __forceinline__ void operator()(const f32x4 (&acc)[2][2][4][2], const Unit& u, int wr, int wc, int fr_in, int fq_in) const {
;     ...
;             for (int am = 0; am < (FINAL ? 8 : 4); ++am) { constexpr int GR = FINAL ? 1 : 2; const int ai = (am * GR) >> 2; u32x4 ppw[4], pzw[4];
; #pragma unroll
;                 for (int m = (am * GR) & 3; m < ((am * GR) & 3) + GR; ++m) { const size_t off = (size_t)(row0 + ai * HALF + m * 16) * 1024 + col0 + bj * HALF; ppw[m] = *(const u32x4*)(pexb + off); pzw[m] = *(const u32x4*)(zb + off); }
;                 asm volatile("" ::: "memory");
; #pragma unroll
;                 for (int m = (am * GR) & 3; m < ((am * GR) & 3) + GR; ++m) { const size_t off = (size_t)(row0 + ai * HALF + m * 16) * 1024 + col0 + bj * HALF; const float mu = rst.mu[ai][m], rs = rst.rs[ai][m];
;                     const u32x4 pw = ppw[m]; const u32x4 zw = pzw[m];
;                     const f32x4 x0 = ((f32x4){bf_lo(zw.x), bf_hi(zw.x), bf_lo(zw.y), bf_hi(zw.y)} - mu) * rs * gv[0] + bv[0], x1 = ((f32x4){bf_lo(zw.z), bf_hi(zw.z), bf_lo(zw.w), bf_hi(zw.w)} - mu) * rs * gv[1] + bv[1];
;                     const f32x4 a0 = ln_fix(acc[ai][bj][m][0], mu, rs, csv[0], cbv[0]), a1 = ln_fix(acc[ai][bj][m][1], mu, rs, csv[1], cbv[1]); f32x4 o0, o1;
;                     o0[0] = x0[0] + fast_sigmoid(a0[0]) * bf_lo(pw.x); o0[1] = x0[1] + fast_sigmoid(a0[1]) * bf_hi(pw.x);
;                     o0[2] = x0[2] + fast_sigmoid(a0[2]) * bf_lo(pw.y); o0[3] = x0[3] + fast_sigmoid(a0[3]) * bf_hi(pw.y);
;                     o1[0] = x1[0] + fast_sigmoid(a1[0]) * bf_lo(pw.z); o1[1] = x1[1] + fast_sigmoid(a1[1]) * bf_hi(pw.z);
;                     o1[2] = x1[2] + fast_sigmoid(a1[2]) * bf_lo(pw.w); o1[3] = x1[3] + fast_sigmoid(a1[3]) * bf_hi(pw.w);
;                     if constexpr (FINAL) { *(f32x4*)(outf + off) = o0; *(f32x4*)(outf + off + 4) = o1; }
;                     else { u32x4 w; w.x = cvt_pk_bf16(o0[0], o0[1]); w.y = cvt_pk_bf16(o0[2], o0[3]); w.z = cvt_pk_bf16(o1[0], o1[1]); w.w = cvt_pk_bf16(o1[2], o1[3]); *(u32x4*)(pexb + off) = w; } } } }
	v_pk_fma_f32 v[104:105], v[202:203], v[104:105], v[112:113] op_sel_hi:[0,1,1]
	v_mul_f32_e32 v104, 0xbfb8aa3b, v104
	v_mul_f32_e32 v105, 0xbfb8aa3b, v105
	v_exp_f32_e32 v104, v104
	v_exp_f32_e32 v105, v105
	v_pk_fma_f32 v[100:101], v[196:197], v[124:125], v[100:101] op_sel_hi:[0,1,1] neg_lo:[1,0,0] neg_hi:[1,0,0]
	v_pk_fma_f32 v[100:101], v[198:199], v[100:101], v[120:121] op_sel_hi:[0,1,1]
	v_add_f32_e32 v104, 1.0, v104
	v_add_f32_e32 v105, 1.0, v105
	v_rcp_f32_e32 v104, v104
	v_rcp_f32_e32 v105, v105
	v_pk_fma_f32 v[98:99], v[196:197], v[118:119], v[98:99] op_sel_hi:[0,1,1] neg_lo:[1,0,0] neg_hi:[1,0,0]
	v_pk_fma_f32 v[102:103], v[196:197], v[126:127], v[102:103] op_sel_hi:[0,1,1] neg_lo:[1,0,0] neg_hi:[1,0,0]
	v_pk_fma_f32 v[102:103], v[198:199], v[102:103], v[122:123] op_sel_hi:[0,1,1]
	v_pk_fma_f32 v[96:97], v[196:197], v[116:117], v[96:97] op_sel_hi:[0,1,1] neg_lo:[1,0,0] neg_hi:[1,0,0]
	v_pk_fma_f32 v[96:97], v[198:199], v[96:97], v[112:113] op_sel_hi:[0,1,1]
	v_mul_f32_e32 v96, 0xbfb8aa3b, v96
	v_mul_f32_e32 v97, 0xbfb8aa3b, v97
	v_exp_f32_e32 v96, v96
	v_exp_f32_e32 v97, v97
	v_pk_fma_f32 v[92:93], v[192:193], v[124:125], v[92:93] op_sel_hi:[0,1,1] neg_lo:[1,0,0] neg_hi:[1,0,0]
	v_pk_fma_f32 v[92:93], v[92:93], v[194:195], v[120:121] op_sel_hi:[1,0,1]
	v_add_f32_e32 v96, 1.0, v96
	v_add_f32_e32 v97, 1.0, v97
	v_rcp_f32_e32 v96, v96
	v_rcp_f32_e32 v97, v97
	v_pk_fma_f32 v[88:89], v[192:193], v[116:117], v[88:89] op_sel_hi:[0,1,1] neg_lo:[1,0,0] neg_hi:[1,0,0]
	v_pk_fma_f32 v[94:95], v[192:193], v[126:127], v[94:95] op_sel_hi:[0,1,1] neg_lo:[1,0,0] neg_hi:[1,0,0]
	v_pk_fma_f32 v[90:91], v[192:193], v[118:119], v[90:91] op_sel_hi:[0,1,1] neg_lo:[1,0,0] neg_hi:[1,0,0]
	v_pk_fma_f32 v[94:95], v[94:95], v[194:195], v[122:123] op_sel_hi:[1,0,1]
	v_pk_fma_f32 v[80:81], v[188:189], v[116:117], v[80:81] op_sel_hi:[0,1,1] neg_lo:[1,0,0] neg_hi:[1,0,0]
	v_pk_fma_f32 v[82:83], v[188:189], v[118:119], v[82:83] op_sel_hi:[0,1,1] neg_lo:[1,0,0] neg_hi:[1,0,0]
	v_pk_fma_f32 v[76:77], v[124:125], v[184:185], v[76:77] op_sel_hi:[1,0,1] neg_lo:[1,0,0] neg_hi:[1,0,0]
	v_pk_fma_f32 v[72:73], v[184:185], v[116:117], v[72:73] op_sel_hi:[0,1,1] neg_lo:[1,0,0] neg_hi:[1,0,0]
	v_pk_fma_f32 v[76:77], v[76:77], v[186:187], v[120:121] op_sel_hi:[1,0,1]
	v_pk_fma_f32 v[74:75], v[184:185], v[118:119], v[74:75] op_sel_hi:[0,1,1] neg_lo:[1,0,0] neg_hi:[1,0,0]
	v_pk_fma_f32 v[68:69], v[124:125], v[180:181], v[68:69] op_sel_hi:[1,0,1] neg_lo:[1,0,0] neg_hi:[1,0,0]
	v_pk_fma_f32 v[64:65], v[116:117], v[180:181], v[64:65] op_sel_hi:[1,0,1] neg_lo:[1,0,0] neg_hi:[1,0,0]
	v_pk_fma_f32 v[68:69], v[68:69], v[182:183], v[120:121] op_sel_hi:[1,0,1]
	s_waitcnt vmcnt(0)
	v_lshlrev_b32_e32 v207, 16, v240
	v_and_b32_e32 v211, 0xffff0000, v240
	v_lshlrev_b32_e32 v240, 16, v241
	v_and_b32_e32 v241, 0xffff0000, v241
	v_sub_f32_e32 v241, v241, v208
	v_sub_f32_e32 v240, v240, v208
	v_sub_f32_e32 v245, v211, v208
	v_sub_f32_e32 v244, v207, v208
	v_pk_mul_f32 v[244:245], v[210:211], v[244:245] op_sel_hi:[0,1]
	v_pk_mul_f32 v[240:241], v[210:211], v[240:241] op_sel_hi:[0,1]
	v_and_b32_e32 v211, 0xffff0000, v242
	v_pk_fma_f32 v[156:157], v[210:211], v[156:157], v[120:121] op_sel_hi:[0,1,1]
	v_pk_fma_f32 v[250:251], v[210:211], v[152:153], v[112:113] op_sel_hi:[0,1,1]
	v_mul_f32_e32 v152, 0xbfb8aa3b, v156
	v_mul_f32_e32 v153, 0xbfb8aa3b, v157
	v_exp_f32_e32 v152, v152
	v_exp_f32_e32 v153, v153
	v_pk_fma_f32 v[244:245], v[136:137], v[244:245], v[140:141]
	v_pk_fma_f32 v[158:159], v[210:211], v[158:159], v[122:123] op_sel_hi:[0,1,1]
	v_add_f32_e32 v152, 1.0, v152
	v_add_f32_e32 v153, 1.0, v153
	v_rcp_f32_e32 v152, v152
	v_rcp_f32_e32 v153, v153
	v_pk_fma_f32 v[248:249], v[210:211], v[154:155], v[114:115] op_sel_hi:[0,1,1]
	v_lshlrev_b32_e32 v154, 16, v160
	v_and_b32_e32 v155, 0xffff0000, v160
	v_pk_fma_f32 v[152:153], v[152:153], v[154:155], v[244:245]
	v_mul_f32_e32 v154, 0xbfb8aa3b, v158
	v_mul_f32_e32 v155, 0xbfb8aa3b, v159
	v_exp_f32_e32 v154, v154
	v_exp_f32_e32 v155, v155
	v_pk_fma_f32 v[246:247], v[138:139], v[240:241], v[142:143]
	v_lshlrev_b32_e32 v156, 16, v161
	v_add_f32_e32 v154, 1.0, v154
	v_add_f32_e32 v155, 1.0, v155
	v_rcp_f32_e32 v154, v154
	v_rcp_f32_e32 v155, v155
	v_and_b32_e32 v157, 0xffff0000, v161
	v_lshlrev_b32_e32 v207, 16, v242
	v_lshlrev_b32_e32 v240, 16, v243
	v_pk_fma_f32 v[154:155], v[154:155], v[156:157], v[246:247]
	v_mul_f32_e32 v156, 0xbfb8aa3b, v250
	v_mul_f32_e32 v157, 0xbfb8aa3b, v251
	v_exp_f32_e32 v156, v156
	v_exp_f32_e32 v157, v157
	v_and_b32_e32 v241, 0xffff0000, v243
	v_sub_f32_e32 v243, v211, v208
	v_add_f32_e32 v156, 1.0, v156
	v_add_f32_e32 v157, 1.0, v157
	v_rcp_f32_e32 v156, v156
	v_rcp_f32_e32 v157, v157
	v_sub_f32_e32 v242, v207, v208
	v_pk_mul_f32 v[242:243], v[210:211], v[242:243] op_sel_hi:[0,1]
	v_pk_fma_f32 v[242:243], v[128:129], v[242:243], v[132:133]
	v_lshlrev_b32_e32 v158, 16, v162
	v_and_b32_e32 v159, 0xffff0000, v162
	v_pk_fma_f32 v[158:159], v[156:157], v[158:159], v[242:243]
	v_mul_f32_e32 v156, 0xbfb8aa3b, v248
	v_mul_f32_e32 v157, 0xbfb8aa3b, v249
	v_exp_f32_e32 v156, v156
	v_exp_f32_e32 v157, v157
	v_sub_f32_e32 v241, v241, v208
	v_sub_f32_e32 v240, v240, v208
	v_add_f32_e32 v156, 1.0, v156
	v_add_f32_e32 v157, 1.0, v157
	v_rcp_f32_e32 v156, v156
	v_rcp_f32_e32 v157, v157
	v_pk_mul_f32 v[240:241], v[210:211], v[240:241] op_sel_hi:[0,1]
	v_pk_fma_f32 v[240:241], v[130:131], v[240:241], v[134:135]
	v_lshlrev_b32_e32 v160, 16, v163
	v_and_b32_e32 v161, 0xffff0000, v163
	v_pk_fma_f32 v[160:161], v[156:157], v[160:161], v[240:241]
	v_lshl_add_u64 v[156:157], v[238:239], 2, s[4:5]
	global_store_dwordx4 v[156:157], v[152:155], off
	global_store_dwordx4 v[156:157], v[158:161], off offset:16
	s_nop 1
	v_lshlrev_b64 v[158:159], 10, v[236:237]
	v_lshl_add_u64 v[160:161], v[158:159], 0, v[212:213]
	v_lshlrev_b64 v[162:163], 1, v[160:161]
	v_lshl_add_u64 v[152:153], s[26:27], 0, v[162:163]
	v_lshl_add_u64 v[162:163], s[22:23], 0, v[162:163]
	global_load_dwordx4 v[152:155], v[152:153], off
	s_nop 0
	global_load_dwordx4 v[238:241], v[162:163], off
	s_waitcnt vmcnt(0)
; __device__ __forceinline__ unsigned cvt_pk_bf16(float lo, float hi) { unsigned r; asm("v_cvt_pk_bf16_f32 %0, %1, %2" : "=v"(r) : "v"(lo), "v"(hi)); return r; }
; __device__ __forceinline__ float fast_sigmoid(float v) { return __builtin_amdgcn_rcpf(1.0f + __builtin_amdgcn_exp2f(-1.4426950408889634f * v)); }
;     __device__ __forceinline__ void operator()(const f32x4 (&acc)[2][2][4][2], const Unit& u, int wr, int wc, int fr_in, int fq_in) const {
;     ...
;             for (int am = 0; am < (FINAL ? 8 : 4); ++am) { constexpr int GR = FINAL ? 1 : 2; const int ai = (am * GR) >> 2; u32x4 ppw[4], pzw[4];
; #pragma unroll
;                 for (int m = (am * GR) & 3; m < ((am * GR) & 3) + GR; ++m) { const size_t off = (size_t)(row0 + ai * HALF + m * 16) * 1024 + col0 + bj * HALF; ppw[m] = *(const u32x4*)(pexb + off); pzw[m] = *(const u32x4*)(zb + off); }
;                 asm volatile("" ::: "memory");
; #pragma unroll
;                 for (int m = (am * GR) & 3; m < ((am * GR) & 3) + GR; ++m) { const size_t off = (size_t)(row0 + ai * HALF + m * 16) * 1024 + col0 + bj * HALF; const float mu = rst.mu[ai][m], rs = rst.rs[ai][m];
;                     const u32x4 pw = ppw[m]; const u32x4 zw = pzw[m];
;                     const f32x4 x0 = ((f32x4){bf_lo(zw.x), bf_hi(zw.x), bf_lo(zw.y), bf_hi(zw.y)} - mu) * rs * gv[0] + bv[0], x1 = ((f32x4){bf_lo(zw.z), bf_hi(zw.z), bf_lo(zw.w), bf_hi(zw.w)} - mu) * rs * gv[1] + bv[1];
;                     const f32x4 a0 = ln_fix(acc[ai][bj][m][0], mu, rs, csv[0], cbv[0]), a1 = ln_fix(acc[ai][bj][m][1], mu, rs, csv[1], cbv[1]); f32x4 o0, o1;
;                     o0[0] = x0[0] + fast_sigmoid(a0[0]) * bf_lo(pw.x); o0[1] = x0[1] + fast_sigmoid(a0[1]) * bf_hi(pw.x);
;                     o0[2] = x0[2] + fast_sigmoid(a0[2]) * bf_lo(pw.y); o0[3] = x0[3] + fast_sigmoid(a0[3]) * bf_hi(pw.y);
;                     o1[0] = x1[0] + fast_sigmoid(a1[0]) * bf_lo(pw.z); o1[1] = x1[1] + fast_sigmoid(a1[1]) * bf_hi(pw.z);
;                     o1[2] = x1[2] + fast_sigmoid(a1[2]) * bf_lo(pw.w); o1[3] = x1[3] + fast_sigmoid(a1[3]) * bf_hi(pw.w);
;                     if constexpr (FINAL) { *(f32x4*)(outf + off) = o0; *(f32x4*)(outf + off + 4) = o1; }
;                     else { u32x4 w; w.x = cvt_pk_bf16(o0[0], o0[1]); w.y = cvt_pk_bf16(o0[2], o0[3]); w.z = cvt_pk_bf16(o1[0], o1[1]); w.w = cvt_pk_bf16(o1[2], o1[3]); *(u32x4*)(pexb + off) = w; } } } }
	v_lshlrev_b32_e32 v207, 16, v238
	v_and_b32_e32 v211, 0xffff0000, v238
	v_lshlrev_b32_e32 v162, 16, v239
	v_and_b32_e32 v163, 0xffff0000, v239
	v_sub_f32_e32 v163, v163, v204
	v_sub_f32_e32 v162, v162, v204
	v_sub_f32_e32 v237, v211, v204
	v_sub_f32_e32 v236, v207, v204
	v_pk_mul_f32 v[236:237], v[206:207], v[236:237] op_sel_hi:[0,1]
	v_pk_mul_f32 v[162:163], v[206:207], v[162:163] op_sel_hi:[0,1]
	v_lshlrev_b32_e32 v207, 16, v240
	v_pk_fma_f32 v[148:149], v[206:207], v[148:149], v[120:121] op_sel_hi:[0,1,1]
	v_pk_fma_f32 v[238:239], v[138:139], v[162:163], v[142:143]
	v_and_b32_e32 v211, 0xffff0000, v240
	v_lshlrev_b32_e32 v162, 16, v241
	v_and_b32_e32 v163, 0xffff0000, v241
	v_pk_fma_f32 v[240:241], v[206:207], v[146:147], v[114:115] op_sel_hi:[0,1,1]
	v_mul_f32_e32 v146, 0xbfb8aa3b, v148
	v_mul_f32_e32 v147, 0xbfb8aa3b, v149
	v_exp_f32_e32 v146, v146
	v_exp_f32_e32 v147, v147
	v_pk_fma_f32 v[242:243], v[136:137], v[236:237], v[140:141]
	v_pk_fma_f32 v[150:151], v[206:207], v[150:151], v[122:123] op_sel_hi:[0,1,1]
	v_add_f32_e32 v146, 1.0, v146
	v_add_f32_e32 v147, 1.0, v147
	v_rcp_f32_e32 v146, v146
	v_rcp_f32_e32 v147, v147
	v_lshlrev_b32_e32 v148, 16, v152
	v_and_b32_e32 v149, 0xffff0000, v152
	v_pk_fma_f32 v[144:145], v[206:207], v[144:145], v[112:113] op_sel_hi:[0,1,1]
	v_pk_fma_f32 v[146:147], v[146:147], v[148:149], v[242:243]
	v_mul_f32_e32 v148, 0xbfb8aa3b, v150
	v_mul_f32_e32 v149, 0xbfb8aa3b, v151
	v_exp_f32_e32 v148, v148
	v_exp_f32_e32 v149, v149
	v_mul_f32_e32 v144, 0xbfb8aa3b, v144
	v_mul_f32_e32 v145, 0xbfb8aa3b, v145
	v_exp_f32_e32 v144, v144
	v_exp_f32_e32 v145, v145
	v_add_f32_e32 v148, 1.0, v148
	v_add_f32_e32 v149, 1.0, v149
	v_rcp_f32_e32 v148, v148
	v_rcp_f32_e32 v149, v149
	v_add_f32_e32 v144, 1.0, v144
	v_add_f32_e32 v145, 1.0, v145
	v_rcp_f32_e32 v144, v144
	v_rcp_f32_e32 v145, v145
	v_sub_f32_e32 v237, v211, v204
	v_sub_f32_e32 v236, v207, v204
	v_pk_mul_f32 v[236:237], v[206:207], v[236:237] op_sel_hi:[0,1]
	v_lshlrev_b32_e32 v150, 16, v153
	v_and_b32_e32 v151, 0xffff0000, v153
	v_pk_fma_f32 v[236:237], v[128:129], v[236:237], v[132:133]
	v_pk_fma_f32 v[148:149], v[148:149], v[150:151], v[238:239]
	v_lshlrev_b32_e32 v150, 16, v154
	v_and_b32_e32 v151, 0xffff0000, v154
	v_pk_fma_f32 v[150:151], v[144:145], v[150:151], v[236:237]
	v_mul_f32_e32 v144, 0xbfb8aa3b, v240
	v_mul_f32_e32 v145, 0xbfb8aa3b, v241
	v_exp_f32_e32 v144, v144
	v_exp_f32_e32 v145, v145
	v_sub_f32_e32 v163, v163, v204
	v_sub_f32_e32 v162, v162, v204
	v_add_f32_e32 v144, 1.0, v144
	v_add_f32_e32 v145, 1.0, v145
	v_rcp_f32_e32 v144, v144
	v_rcp_f32_e32 v145, v145
	v_pk_mul_f32 v[162:163], v[206:207], v[162:163] op_sel_hi:[0,1]
	v_pk_fma_f32 v[162:163], v[130:131], v[162:163], v[134:135]
	v_lshlrev_b32_e32 v152, 16, v155
	v_and_b32_e32 v153, 0xffff0000, v155
	v_pk_fma_f32 v[152:153], v[144:145], v[152:153], v[162:163]
	v_lshl_add_u64 v[144:145], v[160:161], 2, s[4:5]
	global_store_dwordx4 v[144:145], v[146:149], off
	global_store_dwordx4 v[144:145], v[150:153], off offset:16
	v_pk_fma_f32 v[236:237], v[202:203], v[106:107], v[114:115] op_sel_hi:[0,1,1]
	v_lshlrev_b64 v[146:147], 10, v[234:235]
	v_lshl_add_u64 v[160:161], v[146:147], 0, v[212:213]
	v_lshlrev_b64 v[152:153], 1, v[160:161]
	v_lshl_add_u64 v[148:149], s[26:27], 0, v[152:153]
	v_lshl_add_u64 v[152:153], s[22:23], 0, v[152:153]
	global_load_dwordx4 v[148:151], v[148:149], off
	v_mul_f32_e32 v106, 0xbfb8aa3b, v108
	global_load_dwordx4 v[152:155], v[152:153], off
	v_mul_f32_e32 v107, 0xbfb8aa3b, v109
	v_exp_f32_e32 v106, v106
	v_exp_f32_e32 v107, v107
	v_add_f32_e32 v106, 1.0, v106
	v_add_f32_e32 v107, 1.0, v107
	v_rcp_f32_e32 v106, v106
	v_rcp_f32_e32 v107, v107
	s_waitcnt vmcnt(0)
	v_lshlrev_b32_e32 v108, 16, v148
	v_and_b32_e32 v109, 0xffff0000, v148
	v_lshlrev_b32_e32 v162, 16, v152
	v_and_b32_e32 v163, 0xffff0000, v152
	v_sub_f32_e32 v163, v163, v200
	v_sub_f32_e32 v162, v162, v200
	v_pk_mul_f32 v[162:163], v[202:203], v[162:163] op_sel_hi:[0,1]
	v_pk_fma_f32 v[162:163], v[136:137], v[162:163], v[140:141]
	v_lshlrev_b32_e32 v152, 16, v153
	v_pk_fma_f32 v[106:107], v[106:107], v[108:109], v[162:163]
	v_mul_f32_e32 v108, 0xbfb8aa3b, v110
	v_mul_f32_e32 v109, 0xbfb8aa3b, v111
	v_exp_f32_e32 v108, v108
	v_exp_f32_e32 v109, v109
	v_and_b32_e32 v153, 0xffff0000, v153
	v_sub_f32_e32 v153, v153, v200
	v_add_f32_e32 v108, 1.0, v108
	v_add_f32_e32 v109, 1.0, v109
	v_rcp_f32_e32 v108, v108
	v_rcp_f32_e32 v109, v109
	v_sub_f32_e32 v152, v152, v200
	v_lshlrev_b32_e32 v207, 16, v154
	v_and_b32_e32 v211, 0xffff0000, v154
	v_pk_mul_f32 v[152:153], v[202:203], v[152:153] op_sel_hi:[0,1]
	v_sub_f32_e32 v235, v211, v200
	v_sub_f32_e32 v234, v207, v200
	v_pk_fma_f32 v[152:153], v[138:139], v[152:153], v[142:143]
	v_pk_mul_f32 v[234:235], v[202:203], v[234:235] op_sel_hi:[0,1]
	v_lshlrev_b32_e32 v110, 16, v149
	v_and_b32_e32 v111, 0xffff0000, v149
	v_pk_fma_f32 v[234:235], v[128:129], v[234:235], v[132:133]
	v_pk_fma_f32 v[108:109], v[108:109], v[110:111], v[152:153]
	v_lshlrev_b32_e32 v110, 16, v150
	v_and_b32_e32 v111, 0xffff0000, v150
	v_pk_fma_f32 v[148:149], v[104:105], v[110:111], v[234:235]
	v_mul_f32_e32 v104, 0xbfb8aa3b, v236
	v_mul_f32_e32 v105, 0xbfb8aa3b, v237
	v_exp_f32_e32 v104, v104
	v_exp_f32_e32 v105, v105
	v_lshlrev_b32_e32 v154, 16, v155
	v_and_b32_e32 v155, 0xffff0000, v155
	v_add_f32_e32 v104, 1.0, v104
	v_add_f32_e32 v105, 1.0, v105
	v_rcp_f32_e32 v104, v104
	v_rcp_f32_e32 v105, v105
	v_sub_f32_e32 v155, v155, v200
	v_sub_f32_e32 v154, v154, v200
	v_pk_mul_f32 v[154:155], v[202:203], v[154:155] op_sel_hi:[0,1]
	v_pk_fma_f32 v[154:155], v[130:131], v[154:155], v[134:135]
	v_lshlrev_b32_e32 v110, 16, v151
	v_and_b32_e32 v111, 0xffff0000, v151
	v_pk_fma_f32 v[150:151], v[104:105], v[110:111], v[154:155]
	v_lshl_add_u64 v[104:105], v[160:161], 2, s[4:5]
	global_store_dwordx4 v[104:105], v[106:109], off
	global_store_dwordx4 v[104:105], v[148:151], off offset:16
	v_pk_fma_f32 v[162:163], v[198:199], v[98:99], v[114:115] op_sel_hi:[0,1,1]
	v_lshlrev_b64 v[106:107], 10, v[232:233]
	v_lshl_add_u64 v[152:153], v[106:107], 0, v[212:213]
	v_lshlrev_b64 v[148:149], 1, v[152:153]
	v_lshl_add_u64 v[108:109], s[26:27], 0, v[148:149]
	v_lshl_add_u64 v[148:149], s[22:23], 0, v[148:149]
	global_load_dwordx4 v[108:111], v[108:109], off
	v_mul_f32_e32 v98, 0xbfb8aa3b, v100
	global_load_dwordx4 v[148:151], v[148:149], off
	v_mul_f32_e32 v99, 0xbfb8aa3b, v101
	v_exp_f32_e32 v98, v98
	v_exp_f32_e32 v99, v99
	v_add_f32_e32 v98, 1.0, v98
	v_add_f32_e32 v99, 1.0, v99
	v_rcp_f32_e32 v98, v98
	v_rcp_f32_e32 v99, v99
	s_waitcnt vmcnt(0)
; __device__ __forceinline__ unsigned cvt_pk_bf16(float lo, float hi) { unsigned r; asm("v_cvt_pk_bf16_f32 %0, %1, %2" : "=v"(r) : "v"(lo), "v"(hi)); return r; }
; __device__ __forceinline__ float fast_sigmoid(float v) { return __builtin_amdgcn_rcpf(1.0f + __builtin_amdgcn_exp2f(-1.4426950408889634f * v)); }
;     __device__ __forceinline__ void operator()(const f32x4 (&acc)[2][2][4][2], const Unit& u, int wr, int wc, int fr_in, int fq_in) const {
;     ...
;             for (int am = 0; am < (FINAL ? 8 : 4); ++am) { constexpr int GR = FINAL ? 1 : 2; const int ai = (am * GR) >> 2; u32x4 ppw[4], pzw[4];
; #pragma unroll
;                 for (int m = (am * GR) & 3; m < ((am * GR) & 3) + GR; ++m) { const size_t off = (size_t)(row0 + ai * HALF + m * 16) * 1024 + col0 + bj * HALF; ppw[m] = *(const u32x4*)(pexb + off); pzw[m] = *(const u32x4*)(zb + off); }
;                 asm volatile("" ::: "memory");
; #pragma unroll
;                 for (int m = (am * GR) & 3; m < ((am * GR) & 3) + GR; ++m) { const size_t off = (size_t)(row0 + ai * HALF + m * 16) * 1024 + col0 + bj * HALF; const float mu = rst.mu[ai][m], rs = rst.rs[ai][m];
;                     const u32x4 pw = ppw[m]; const u32x4 zw = pzw[m];
;                     const f32x4 x0 = ((f32x4){bf_lo(zw.x), bf_hi(zw.x), bf_lo(zw.y), bf_hi(zw.y)} - mu) * rs * gv[0] + bv[0], x1 = ((f32x4){bf_lo(zw.z), bf_hi(zw.z), bf_lo(zw.w), bf_hi(zw.w)} - mu) * rs * gv[1] + bv[1];
;                     const f32x4 a0 = ln_fix(acc[ai][bj][m][0], mu, rs, csv[0], cbv[0]), a1 = ln_fix(acc[ai][bj][m][1], mu, rs, csv[1], cbv[1]); f32x4 o0, o1;
;                     o0[0] = x0[0] + fast_sigmoid(a0[0]) * bf_lo(pw.x); o0[1] = x0[1] + fast_sigmoid(a0[1]) * bf_hi(pw.x);
;                     o0[2] = x0[2] + fast_sigmoid(a0[2]) * bf_lo(pw.y); o0[3] = x0[3] + fast_sigmoid(a0[3]) * bf_hi(pw.y);
;                     o1[0] = x1[0] + fast_sigmoid(a1[0]) * bf_lo(pw.z); o1[1] = x1[1] + fast_sigmoid(a1[1]) * bf_hi(pw.z);
;                     o1[2] = x1[2] + fast_sigmoid(a1[2]) * bf_lo(pw.w); o1[3] = x1[3] + fast_sigmoid(a1[3]) * bf_hi(pw.w);
;                     if constexpr (FINAL) { *(f32x4*)(outf + off) = o0; *(f32x4*)(outf + off + 4) = o1; }
;                     else { u32x4 w; w.x = cvt_pk_bf16(o0[0], o0[1]); w.y = cvt_pk_bf16(o0[2], o0[3]); w.z = cvt_pk_bf16(o1[0], o1[1]); w.w = cvt_pk_bf16(o1[2], o1[3]); *(u32x4*)(pexb + off) = w; } } } }
	v_lshlrev_b32_e32 v100, 16, v108
	v_and_b32_e32 v101, 0xffff0000, v108
	v_lshlrev_b32_e32 v154, 16, v148
	v_and_b32_e32 v155, 0xffff0000, v148
	v_sub_f32_e32 v155, v155, v196
	v_sub_f32_e32 v154, v154, v196
	v_pk_mul_f32 v[154:155], v[198:199], v[154:155] op_sel_hi:[0,1]
	v_pk_fma_f32 v[154:155], v[136:137], v[154:155], v[140:141]
	v_lshlrev_b32_e32 v148, 16, v149
	v_pk_fma_f32 v[98:99], v[98:99], v[100:101], v[154:155]
	v_mul_f32_e32 v100, 0xbfb8aa3b, v102
	v_mul_f32_e32 v101, 0xbfb8aa3b, v103
	v_exp_f32_e32 v100, v100
	v_exp_f32_e32 v101, v101
	v_and_b32_e32 v149, 0xffff0000, v149
	v_sub_f32_e32 v149, v149, v196
	v_add_f32_e32 v100, 1.0, v100
	v_add_f32_e32 v101, 1.0, v101
	v_rcp_f32_e32 v100, v100
	v_rcp_f32_e32 v101, v101
	v_sub_f32_e32 v148, v148, v196
	v_lshlrev_b32_e32 v160, 16, v150
	v_and_b32_e32 v161, 0xffff0000, v150
	v_pk_mul_f32 v[148:149], v[198:199], v[148:149] op_sel_hi:[0,1]
	v_sub_f32_e32 v161, v161, v196
	v_sub_f32_e32 v160, v160, v196
	v_pk_fma_f32 v[148:149], v[138:139], v[148:149], v[142:143]
	v_pk_mul_f32 v[160:161], v[198:199], v[160:161] op_sel_hi:[0,1]
	v_lshlrev_b32_e32 v102, 16, v109
	v_and_b32_e32 v103, 0xffff0000, v109
	v_pk_fma_f32 v[160:161], v[128:129], v[160:161], v[132:133]
	v_pk_fma_f32 v[100:101], v[100:101], v[102:103], v[148:149]
	v_lshlrev_b32_e32 v102, 16, v110
	v_and_b32_e32 v103, 0xffff0000, v110
	v_pk_fma_f32 v[108:109], v[96:97], v[102:103], v[160:161]
	v_mul_f32_e32 v96, 0xbfb8aa3b, v162
	v_mul_f32_e32 v97, 0xbfb8aa3b, v163
	v_exp_f32_e32 v96, v96
	v_exp_f32_e32 v97, v97
	v_lshlrev_b32_e32 v150, 16, v151
	v_and_b32_e32 v151, 0xffff0000, v151
	v_add_f32_e32 v96, 1.0, v96
	v_add_f32_e32 v97, 1.0, v97
	v_rcp_f32_e32 v96, v96
	v_rcp_f32_e32 v97, v97
	v_sub_f32_e32 v151, v151, v196
	v_sub_f32_e32 v150, v150, v196
	v_pk_mul_f32 v[150:151], v[198:199], v[150:151] op_sel_hi:[0,1]
	v_pk_fma_f32 v[150:151], v[130:131], v[150:151], v[134:135]
	v_lshlrev_b32_e32 v102, 16, v111
	v_and_b32_e32 v103, 0xffff0000, v111
	v_pk_fma_f32 v[110:111], v[96:97], v[102:103], v[150:151]
	v_lshl_add_u64 v[96:97], v[152:153], 2, s[4:5]
	global_store_dwordx4 v[96:97], v[98:101], off
	global_store_dwordx4 v[96:97], v[108:111], off offset:16
	v_pk_fma_f32 v[160:161], v[194:195], v[88:89], v[112:113] op_sel_hi:[0,1,1]
	v_lshlrev_b64 v[98:99], 10, v[230:231]
	v_lshl_add_u64 v[148:149], v[98:99], 0, v[212:213]
	v_lshlrev_b64 v[108:109], 1, v[148:149]
	v_lshl_add_u64 v[100:101], s[26:27], 0, v[108:109]
	v_lshl_add_u64 v[108:109], s[22:23], 0, v[108:109]
	global_load_dwordx4 v[100:103], v[100:101], off
	v_mul_f32_e32 v88, 0xbfb8aa3b, v92
	global_load_dwordx4 v[108:111], v[108:109], off
	v_mul_f32_e32 v89, 0xbfb8aa3b, v93
	v_exp_f32_e32 v88, v88
	v_exp_f32_e32 v89, v89
	v_pk_fma_f32 v[154:155], v[194:195], v[90:91], v[114:115] op_sel_hi:[0,1,1]
	v_add_f32_e32 v88, 1.0, v88
	v_add_f32_e32 v89, 1.0, v89
	v_rcp_f32_e32 v88, v88
	v_rcp_f32_e32 v89, v89
	s_waitcnt vmcnt(0)
	v_lshlrev_b32_e32 v90, 16, v100
	v_and_b32_e32 v91, 0xffff0000, v100
	v_lshlrev_b32_e32 v150, 16, v108
	v_and_b32_e32 v151, 0xffff0000, v108
	v_sub_f32_e32 v151, v151, v192
	v_sub_f32_e32 v150, v150, v192
	v_pk_mul_f32 v[150:151], v[194:195], v[150:151] op_sel_hi:[0,1]
	v_pk_fma_f32 v[150:151], v[136:137], v[150:151], v[140:141]
	v_lshlrev_b32_e32 v108, 16, v109
	v_pk_fma_f32 v[88:89], v[88:89], v[90:91], v[150:151]
	v_mul_f32_e32 v90, 0xbfb8aa3b, v94
	v_mul_f32_e32 v91, 0xbfb8aa3b, v95
	v_exp_f32_e32 v90, v90
	v_exp_f32_e32 v91, v91
	v_and_b32_e32 v109, 0xffff0000, v109
	v_sub_f32_e32 v109, v109, v192
	v_add_f32_e32 v90, 1.0, v90
	v_add_f32_e32 v91, 1.0, v91
	v_rcp_f32_e32 v90, v90
	v_rcp_f32_e32 v91, v91
	v_sub_f32_e32 v108, v108, v192
	v_pk_mul_f32 v[108:109], v[194:195], v[108:109] op_sel_hi:[0,1]
	v_pk_fma_f32 v[108:109], v[138:139], v[108:109], v[142:143]
	v_lshlrev_b32_e32 v92, 16, v101
	v_and_b32_e32 v93, 0xffff0000, v101
	v_pk_fma_f32 v[90:91], v[90:91], v[92:93], v[108:109]
	v_mul_f32_e32 v92, 0xbfb8aa3b, v160
	v_mul_f32_e32 v93, 0xbfb8aa3b, v161
	v_exp_f32_e32 v92, v92
	v_exp_f32_e32 v93, v93
	v_lshlrev_b32_e32 v152, 16, v110
	v_and_b32_e32 v153, 0xffff0000, v110
	v_add_f32_e32 v92, 1.0, v92
	v_add_f32_e32 v93, 1.0, v93
	v_rcp_f32_e32 v92, v92
	v_rcp_f32_e32 v93, v93
	v_sub_f32_e32 v153, v153, v192
	v_sub_f32_e32 v152, v152, v192
	v_pk_mul_f32 v[152:153], v[194:195], v[152:153] op_sel_hi:[0,1]
	v_pk_fma_f32 v[152:153], v[128:129], v[152:153], v[132:133]
	v_lshlrev_b32_e32 v94, 16, v102
	v_and_b32_e32 v95, 0xffff0000, v102
	v_pk_fma_f32 v[92:93], v[92:93], v[94:95], v[152:153]
	v_mul_f32_e32 v94, 0xbfb8aa3b, v154
	v_mul_f32_e32 v95, 0xbfb8aa3b, v155
	v_exp_f32_e32 v94, v94
	v_exp_f32_e32 v95, v95
	v_lshlrev_b32_e32 v110, 16, v111
	v_and_b32_e32 v111, 0xffff0000, v111
	v_add_f32_e32 v94, 1.0, v94
	v_add_f32_e32 v95, 1.0, v95
	v_rcp_f32_e32 v94, v94
	v_rcp_f32_e32 v95, v95
	v_sub_f32_e32 v111, v111, v192
	v_sub_f32_e32 v110, v110, v192
	v_pk_mul_f32 v[110:111], v[194:195], v[110:111] op_sel_hi:[0,1]
	v_pk_fma_f32 v[110:111], v[130:131], v[110:111], v[134:135]
	v_lshlrev_b32_e32 v100, 16, v103
	v_and_b32_e32 v101, 0xffff0000, v103
	v_lshlrev_b64 v[102:103], 10, v[228:229]
	v_pk_fma_f32 v[94:95], v[94:95], v[100:101], v[110:111]
	v_lshl_add_u64 v[100:101], v[148:149], 2, s[4:5]
	v_lshl_add_u64 v[108:109], v[102:103], 0, v[212:213]
	global_store_dwordx4 v[100:101], v[88:91], off
	global_store_dwordx4 v[100:101], v[92:95], off offset:16
	v_pk_fma_f32 v[150:151], v[124:125], v[188:189], v[84:85] op_sel_hi:[1,0,1] neg_lo:[1,0,0] neg_hi:[1,0,0]
	v_xor_b32_e32 v85, 0x80000000, v127
	v_lshlrev_b64 v[92:93], 1, v[108:109]
	v_lshl_add_u64 v[88:89], s[26:27], 0, v[92:93]
; __device__ __forceinline__ unsigned cvt_pk_bf16(float lo, float hi) { unsigned r; asm("v_cvt_pk_bf16_f32 %0, %1, %2" : "=v"(r) : "v"(lo), "v"(hi)); return r; }
; __device__ __forceinline__ float fast_sigmoid(float v) { return __builtin_amdgcn_rcpf(1.0f + __builtin_amdgcn_exp2f(-1.4426950408889634f * v)); }
;     __device__ __forceinline__ void operator()(const f32x4 (&acc)[2][2][4][2], const Unit& u, int wr, int wc, int fr_in, int fq_in) const {
;     ...
;             for (int am = 0; am < (FINAL ? 8 : 4); ++am) { constexpr int GR = FINAL ? 1 : 2; const int ai = (am * GR) >> 2; u32x4 ppw[4], pzw[4];
; #pragma unroll
;                 for (int m = (am * GR) & 3; m < ((am * GR) & 3) + GR; ++m) { const size_t off = (size_t)(row0 + ai * HALF + m * 16) * 1024 + col0 + bj * HALF; ppw[m] = *(const u32x4*)(pexb + off); pzw[m] = *(const u32x4*)(zb + off); }
;                 asm volatile("" ::: "memory");
; #pragma unroll
;                 for (int m = (am * GR) & 3; m < ((am * GR) & 3) + GR; ++m) { const size_t off = (size_t)(row0 + ai * HALF + m * 16) * 1024 + col0 + bj * HALF; const float mu = rst.mu[ai][m], rs = rst.rs[ai][m];
;                     const u32x4 pw = ppw[m]; const u32x4 zw = pzw[m];
;                     const f32x4 x0 = ((f32x4){bf_lo(zw.x), bf_hi(zw.x), bf_lo(zw.y), bf_hi(zw.y)} - mu) * rs * gv[0] + bv[0], x1 = ((f32x4){bf_lo(zw.z), bf_hi(zw.z), bf_lo(zw.w), bf_hi(zw.w)} - mu) * rs * gv[1] + bv[1];
;                     const f32x4 a0 = ln_fix(acc[ai][bj][m][0], mu, rs, csv[0], cbv[0]), a1 = ln_fix(acc[ai][bj][m][1], mu, rs, csv[1], cbv[1]); f32x4 o0, o1;
;                     o0[0] = x0[0] + fast_sigmoid(a0[0]) * bf_lo(pw.x); o0[1] = x0[1] + fast_sigmoid(a0[1]) * bf_hi(pw.x);
;                     o0[2] = x0[2] + fast_sigmoid(a0[2]) * bf_lo(pw.y); o0[3] = x0[3] + fast_sigmoid(a0[3]) * bf_hi(pw.y);
;                     o1[0] = x1[0] + fast_sigmoid(a1[0]) * bf_lo(pw.z); o1[1] = x1[1] + fast_sigmoid(a1[1]) * bf_hi(pw.z);
;                     o1[2] = x1[2] + fast_sigmoid(a1[2]) * bf_lo(pw.w); o1[3] = x1[3] + fast_sigmoid(a1[3]) * bf_hi(pw.w);
;                     if constexpr (FINAL) { *(f32x4*)(outf + off) = o0; *(f32x4*)(outf + off + 4) = o1; }
;                     else { u32x4 w; w.x = cvt_pk_bf16(o0[0], o0[1]); w.y = cvt_pk_bf16(o0[2], o0[3]); w.z = cvt_pk_bf16(o1[0], o1[1]); w.w = cvt_pk_bf16(o1[2], o1[3]); *(u32x4*)(pexb + off) = w; } } } }
	v_lshl_add_u64 v[92:93], s[22:23], 0, v[92:93]
	global_load_dwordx4 v[88:91], v[88:89], off
	v_xor_b32_e32 v84, 0x80000000, v126
	global_load_dwordx4 v[92:95], v[92:93], off
	v_pk_fma_f32 v[126:127], v[150:151], v[190:191], v[120:121] op_sel_hi:[1,0,1]
	v_pk_fma_f32 v[152:153], v[190:191], v[80:81], v[112:113] op_sel_hi:[0,1,1]
	v_mul_f32_e32 v80, 0xbfb8aa3b, v126
	v_mul_f32_e32 v81, 0xbfb8aa3b, v127
	v_exp_f32_e32 v80, v80
	v_exp_f32_e32 v81, v81
	v_pk_fma_f32 v[86:87], v[84:85], v[188:189], v[86:87] op_sel_hi:[1,0,1]
	v_pk_fma_f32 v[150:151], v[190:191], v[82:83], v[114:115] op_sel_hi:[0,1,1]
	v_add_f32_e32 v80, 1.0, v80
	v_add_f32_e32 v81, 1.0, v81
	v_rcp_f32_e32 v80, v80
	v_rcp_f32_e32 v81, v81
	v_pk_fma_f32 v[86:87], v[86:87], v[190:191], v[122:123] op_sel_hi:[1,0,1]
	v_lshl_add_u64 v[108:109], v[108:109], 2, s[4:5]
	v_pk_fma_f32 v[78:79], v[84:85], v[184:185], v[78:79] op_sel_hi:[1,0,1]
	v_pk_fma_f32 v[126:127], v[74:75], v[186:187], v[114:115] op_sel_hi:[1,0,1]
	v_pk_fma_f32 v[78:79], v[78:79], v[186:187], v[122:123] op_sel_hi:[1,0,1]
	v_pk_fma_f32 v[70:71], v[84:85], v[180:181], v[70:71] op_sel_hi:[1,0,1]
	v_xor_b32_e32 v85, 0x80000000, v119
	v_xor_b32_e32 v84, 0x80000000, v118
	v_pk_fma_f32 v[66:67], v[84:85], v[180:181], v[66:67] op_sel_hi:[1,0,1]
	v_pk_fma_f32 v[70:71], v[70:71], v[182:183], v[122:123] op_sel_hi:[1,0,1]
	v_pk_fma_f32 v[84:85], v[66:67], v[182:183], v[114:115] op_sel_hi:[1,0,1]
	v_lshl_add_u64 v[114:115], v[212:213], 0, s[40:41]
	v_lshl_add_u64 v[116:117], v[114:115], 0, v[222:223]
	v_lshlrev_b64 v[120:121], 1, v[116:117]
	v_lshl_add_u64 v[116:117], s[26:27], 0, v[120:121]
	v_lshl_add_u64 v[120:121], s[22:23], 0, v[120:121]
	s_waitcnt vmcnt(0)
	v_lshlrev_b32_e32 v82, 16, v88
	v_and_b32_e32 v83, 0xffff0000, v88
	v_lshlrev_b32_e32 v110, 16, v92
	v_and_b32_e32 v111, 0xffff0000, v92
	v_sub_f32_e32 v111, v111, v188
	v_sub_f32_e32 v110, v110, v188
	v_pk_mul_f32 v[110:111], v[190:191], v[110:111] op_sel_hi:[0,1]
	v_pk_fma_f32 v[110:111], v[136:137], v[110:111], v[140:141]
	v_lshlrev_b32_e32 v92, 16, v93
	v_pk_fma_f32 v[80:81], v[80:81], v[82:83], v[110:111]
	v_mul_f32_e32 v82, 0xbfb8aa3b, v86
	v_mul_f32_e32 v83, 0xbfb8aa3b, v87
	v_exp_f32_e32 v82, v82
	v_exp_f32_e32 v83, v83
	v_and_b32_e32 v93, 0xffff0000, v93
	v_sub_f32_e32 v93, v93, v188
	v_add_f32_e32 v82, 1.0, v82
	v_add_f32_e32 v83, 1.0, v83
	v_rcp_f32_e32 v82, v82
	v_rcp_f32_e32 v83, v83
	v_sub_f32_e32 v92, v92, v188
	v_pk_mul_f32 v[92:93], v[190:191], v[92:93] op_sel_hi:[0,1]
	v_pk_fma_f32 v[92:93], v[138:139], v[92:93], v[142:143]
	v_lshlrev_b32_e32 v86, 16, v89
	v_and_b32_e32 v87, 0xffff0000, v89
	v_pk_fma_f32 v[82:83], v[82:83], v[86:87], v[92:93]
	v_mul_f32_e32 v86, 0xbfb8aa3b, v152
	v_mul_f32_e32 v87, 0xbfb8aa3b, v153
	v_exp_f32_e32 v86, v86
	v_exp_f32_e32 v87, v87
	v_lshlrev_b32_e32 v148, 16, v94
	v_and_b32_e32 v149, 0xffff0000, v94
	v_add_f32_e32 v86, 1.0, v86
	v_add_f32_e32 v87, 1.0, v87
	v_rcp_f32_e32 v86, v86
	v_rcp_f32_e32 v87, v87
	v_sub_f32_e32 v149, v149, v188
	v_sub_f32_e32 v148, v148, v188
	v_pk_mul_f32 v[148:149], v[190:191], v[148:149] op_sel_hi:[0,1]
	v_pk_fma_f32 v[148:149], v[128:129], v[148:149], v[132:133]
	v_lshlrev_b32_e32 v88, 16, v90
	v_and_b32_e32 v89, 0xffff0000, v90
	v_pk_fma_f32 v[86:87], v[86:87], v[88:89], v[148:149]
	v_mul_f32_e32 v88, 0xbfb8aa3b, v150
	v_mul_f32_e32 v89, 0xbfb8aa3b, v151
	v_exp_f32_e32 v88, v88
	v_exp_f32_e32 v89, v89
	v_lshlrev_b32_e32 v94, 16, v95
	v_and_b32_e32 v95, 0xffff0000, v95
	v_add_f32_e32 v88, 1.0, v88
	v_add_f32_e32 v89, 1.0, v89
	v_rcp_f32_e32 v88, v88
	v_rcp_f32_e32 v89, v89
	v_sub_f32_e32 v95, v95, v188
	v_sub_f32_e32 v94, v94, v188
	v_pk_mul_f32 v[94:95], v[190:191], v[94:95] op_sel_hi:[0,1]
	v_pk_fma_f32 v[94:95], v[130:131], v[94:95], v[134:135]
	v_lshlrev_b32_e32 v90, 16, v91
	v_and_b32_e32 v91, 0xffff0000, v91
	v_lshlrev_b64 v[110:111], 10, v[226:227]
	v_pk_fma_f32 v[88:89], v[88:89], v[90:91], v[94:95]
	v_lshl_add_u64 v[90:91], v[110:111], 0, v[212:213]
	global_store_dwordx4 v[108:109], v[80:83], off
	global_store_dwordx4 v[108:109], v[86:89], off offset:16
	v_pk_fma_f32 v[148:149], v[72:73], v[186:187], v[112:113] op_sel_hi:[1,0,1]
	v_mul_f32_e32 v72, 0xbfb8aa3b, v76
	v_lshlrev_b64 v[86:87], 1, v[90:91]
	v_lshl_add_u64 v[80:81], s[26:27], 0, v[86:87]
	v_lshl_add_u64 v[86:87], s[22:23], 0, v[86:87]
	global_load_dwordx4 v[80:83], v[80:81], off
	v_mul_f32_e32 v73, 0xbfb8aa3b, v77
	global_load_dwordx4 v[86:89], v[86:87], off
	v_exp_f32_e32 v72, v72
	v_exp_f32_e32 v73, v73
	v_add_f32_e32 v72, 1.0, v72
	v_add_f32_e32 v73, 1.0, v73
	v_rcp_f32_e32 v72, v72
	v_rcp_f32_e32 v73, v73
	s_waitcnt vmcnt(0)
; __device__ __forceinline__ float bf_lo(unsigned w) { return __uint_as_float(w << 16); }
;     __device__ __forceinline__ void operator()(const f32x4 (&acc)[2][2][4][2], const Unit& u, int wr, int wc, int fr_in, int fq_in) const {
;     ...
;         for (int bj = 0; bj < 2; ++bj) { f32x4 csv[2], cbv[2], gv[2], bv[2];
; #pragma unroll
;             for (int n = 0; n < 2; ++n) { csv[n] = *(const f32x4*)(cs + col0 + bj * HALF + 4 * n); cbv[n] = *(const f32x4*)(cb + col0 + bj * HALF + 4 * n); gv[n] = *(const f32x4*)(lg + col0 + bj * HALF + 4 * n); bv[n] = *(const f32x4*)(lb + col0 + bj * HALF + 4 * n); }
; #pragma unroll
;             for (int am = 0; am < (FINAL ? 8 : 4); ++am) { constexpr int GR = FINAL ? 1 : 2; const int ai = (am * GR) >> 2; u32x4 ppw[4], pzw[4];
; #pragma unroll
;                 for (int m = (am * GR) & 3; m < ((am * GR) & 3) + GR; ++m) { const size_t off = (size_t)(row0 + ai * HALF + m * 16) * 1024 + col0 + bj * HALF; ppw[m] = *(const u32x4*)(pexb + off); pzw[m] = *(const u32x4*)(zb + off); }
;                 asm volatile("" ::: "memory");
; #pragma unroll
;                 for (int m = (am * GR) & 3; m < ((am * GR) & 3) + GR; ++m) { const size_t off = (size_t)(row0 + ai * HALF + m * 16) * 1024 + col0 + bj * HALF; const float mu = rst.mu[ai][m], rs = rst.rs[ai][m];
;                     const u32x4 pw = ppw[m]; const u32x4 zw = pzw[m];
;                     const f32x4 x0 = ((f32x4){bf_lo(zw.x), bf_hi(zw.x), bf_lo(zw.y), bf_hi(zw.y)} - mu) * rs * gv[0] + bv[0], x1 = ((f32x4){bf_lo(zw.z), bf_hi(zw.z), bf_lo(zw.w), bf_hi(zw.w)} - mu) * rs * gv[1] + bv[1];
;                     const f32x4 a0 = ln_fix(acc[ai][bj][m][0], mu, rs, csv[0], cbv[0]), a1 = ln_fix(acc[ai][bj][m][1], mu, rs, csv[1], cbv[1]); f32x4 o0, o1;
;                     o0[0] = x0[0] + fast_sigmoid(a0[0]) * bf_lo(pw.x); o0[1] = x0[1] + fast_sigmoid(a0[1]) * bf_hi(pw.x);
;                     o0[2] = x0[2] + fast_sigmoid(a0[2]) * bf_lo(pw.y); o0[3] = x0[3] + fast_sigmoid(a0[3]) * bf_hi(pw.y);
;                     o1[0] = x1[0] + fast_sigmoid(a1[0]) * bf_lo(pw.z); o1[1] = x1[1] + fast_sigmoid(a1[1]) * bf_hi(pw.z);
;                     o1[2] = x1[2] + fast_sigmoid(a1[2]) * bf_lo(pw.w); o1[3] = x1[3] + fast_sigmoid(a1[3]) * bf_hi(pw.w);
;                     if constexpr (FINAL) { *(f32x4*)(outf + off) = o0; *(f32x4*)(outf + off + 4) = o1; }
	v_lshlrev_b32_e32 v74, 16, v80
	v_and_b32_e32 v75, 0xffff0000, v80
	v_lshlrev_b32_e32 v92, 16, v86
	v_and_b32_e32 v93, 0xffff0000, v86
	v_sub_f32_e32 v93, v93, v184
	v_sub_f32_e32 v92, v92, v184
	v_pk_mul_f32 v[92:93], v[186:187], v[92:93] op_sel_hi:[0,1]
	v_pk_fma_f32 v[92:93], v[136:137], v[92:93], v[140:141]
	v_lshlrev_b32_e32 v86, 16, v87
	v_pk_fma_f32 v[72:73], v[72:73], v[74:75], v[92:93]
	v_mul_f32_e32 v74, 0xbfb8aa3b, v78
	v_mul_f32_e32 v75, 0xbfb8aa3b, v79
	v_exp_f32_e32 v74, v74
	v_exp_f32_e32 v75, v75
	v_and_b32_e32 v87, 0xffff0000, v87
	v_sub_f32_e32 v87, v87, v184
	v_add_f32_e32 v74, 1.0, v74
	v_add_f32_e32 v75, 1.0, v75
	v_rcp_f32_e32 v74, v74
	v_rcp_f32_e32 v75, v75
	v_sub_f32_e32 v86, v86, v184
	v_pk_mul_f32 v[86:87], v[186:187], v[86:87] op_sel_hi:[0,1]
	v_pk_fma_f32 v[86:87], v[138:139], v[86:87], v[142:143]
	v_lshlrev_b32_e32 v76, 16, v81
	v_and_b32_e32 v77, 0xffff0000, v81
	v_pk_fma_f32 v[74:75], v[74:75], v[76:77], v[86:87]
	v_mul_f32_e32 v76, 0xbfb8aa3b, v148
	v_mul_f32_e32 v77, 0xbfb8aa3b, v149
	v_exp_f32_e32 v76, v76
	v_exp_f32_e32 v77, v77
	v_lshlrev_b32_e32 v94, 16, v88
	v_and_b32_e32 v95, 0xffff0000, v88
	v_add_f32_e32 v76, 1.0, v76
	v_add_f32_e32 v77, 1.0, v77
	v_rcp_f32_e32 v76, v76
	v_rcp_f32_e32 v77, v77
	v_sub_f32_e32 v95, v95, v184
	v_sub_f32_e32 v94, v94, v184
	v_pk_mul_f32 v[94:95], v[186:187], v[94:95] op_sel_hi:[0,1]
	v_pk_fma_f32 v[94:95], v[128:129], v[94:95], v[132:133]
	v_lshlrev_b32_e32 v78, 16, v82
	v_and_b32_e32 v79, 0xffff0000, v82
	v_pk_fma_f32 v[76:77], v[76:77], v[78:79], v[94:95]
	v_mul_f32_e32 v78, 0xbfb8aa3b, v126
	v_mul_f32_e32 v79, 0xbfb8aa3b, v127
	v_exp_f32_e32 v78, v78
	v_exp_f32_e32 v79, v79
	v_lshlrev_b32_e32 v88, 16, v89
	v_and_b32_e32 v89, 0xffff0000, v89
	v_add_f32_e32 v78, 1.0, v78
	v_add_f32_e32 v79, 1.0, v79
	v_rcp_f32_e32 v78, v78
	v_rcp_f32_e32 v79, v79
	v_sub_f32_e32 v89, v89, v184
	v_sub_f32_e32 v88, v88, v184
	v_pk_mul_f32 v[88:89], v[186:187], v[88:89] op_sel_hi:[0,1]
	v_pk_fma_f32 v[88:89], v[130:131], v[88:89], v[134:135]
	v_lshlrev_b32_e32 v80, 16, v83
	v_and_b32_e32 v81, 0xffff0000, v83
	v_lshlrev_b64 v[148:149], 10, v[224:225]
	v_pk_fma_f32 v[78:79], v[78:79], v[80:81], v[88:89]
	v_lshl_add_u64 v[126:127], v[90:91], 2, s[4:5]
	v_lshl_add_u64 v[80:81], v[148:149], 0, v[212:213]
	global_store_dwordx4 v[126:127], v[72:75], off
	global_store_dwordx4 v[126:127], v[76:79], off offset:16
	v_pk_fma_f32 v[88:89], v[64:65], v[182:183], v[112:113] op_sel_hi:[1,0,1]
	v_mul_f32_e32 v64, 0xbfb8aa3b, v68
	v_lshlrev_b64 v[76:77], 1, v[80:81]
	v_lshl_add_u64 v[72:73], s[26:27], 0, v[76:77]
	v_lshl_add_u64 v[76:77], s[22:23], 0, v[76:77]
	global_load_dwordx4 v[72:75], v[72:73], off
	v_mul_f32_e32 v65, 0xbfb8aa3b, v69
	global_load_dwordx4 v[76:79], v[76:77], off
	v_exp_f32_e32 v64, v64
	v_exp_f32_e32 v65, v65
	v_lshl_add_u64 v[112:113], v[80:81], 2, s[4:5]
	v_add_f32_e32 v64, 1.0, v64
	v_add_f32_e32 v65, 1.0, v65
	v_rcp_f32_e32 v64, v64
	v_rcp_f32_e32 v65, v65
	s_waitcnt vmcnt(0)
	v_lshlrev_b32_e32 v66, 16, v72
	v_and_b32_e32 v67, 0xffff0000, v72
	v_lshlrev_b32_e32 v82, 16, v76
	v_and_b32_e32 v83, 0xffff0000, v76
	v_sub_f32_e32 v83, v83, v180
	v_sub_f32_e32 v82, v82, v180
	v_pk_mul_f32 v[82:83], v[182:183], v[82:83] op_sel_hi:[0,1]
	v_pk_fma_f32 v[82:83], v[136:137], v[82:83], v[140:141]
	v_lshlrev_b32_e32 v76, 16, v77
	v_pk_fma_f32 v[64:65], v[64:65], v[66:67], v[82:83]
	v_mul_f32_e32 v66, 0xbfb8aa3b, v70
	v_mul_f32_e32 v67, 0xbfb8aa3b, v71
	v_exp_f32_e32 v66, v66
	v_exp_f32_e32 v67, v67
	v_and_b32_e32 v77, 0xffff0000, v77
	v_sub_f32_e32 v77, v77, v180
	v_add_f32_e32 v66, 1.0, v66
	v_add_f32_e32 v67, 1.0, v67
	v_rcp_f32_e32 v66, v66
	v_rcp_f32_e32 v67, v67
	v_sub_f32_e32 v76, v76, v180
	v_pk_mul_f32 v[76:77], v[182:183], v[76:77] op_sel_hi:[0,1]
	v_pk_fma_f32 v[76:77], v[138:139], v[76:77], v[142:143]
	v_lshlrev_b32_e32 v68, 16, v73
	v_and_b32_e32 v69, 0xffff0000, v73
	v_pk_fma_f32 v[66:67], v[66:67], v[68:69], v[76:77]
	v_mul_f32_e32 v68, 0xbfb8aa3b, v88
	v_mul_f32_e32 v69, 0xbfb8aa3b, v89
	v_exp_f32_e32 v68, v68
	v_exp_f32_e32 v69, v69
	v_lshlrev_b32_e32 v86, 16, v78
	v_and_b32_e32 v87, 0xffff0000, v78
	v_add_f32_e32 v68, 1.0, v68
	v_add_f32_e32 v69, 1.0, v69
	v_rcp_f32_e32 v68, v68
	v_rcp_f32_e32 v69, v69
	v_sub_f32_e32 v87, v87, v180
	v_sub_f32_e32 v86, v86, v180
	v_pk_mul_f32 v[86:87], v[182:183], v[86:87] op_sel_hi:[0,1]
	v_pk_fma_f32 v[86:87], v[128:129], v[86:87], v[132:133]
	v_lshlrev_b32_e32 v70, 16, v74
	v_and_b32_e32 v71, 0xffff0000, v74
	v_pk_fma_f32 v[68:69], v[68:69], v[70:71], v[86:87]
	v_mul_f32_e32 v70, 0xbfb8aa3b, v84
	v_mul_f32_e32 v71, 0xbfb8aa3b, v85
	v_exp_f32_e32 v70, v70
	v_exp_f32_e32 v71, v71
	v_lshlrev_b32_e32 v78, 16, v79
	v_and_b32_e32 v79, 0xffff0000, v79
	v_add_f32_e32 v70, 1.0, v70
	v_add_f32_e32 v71, 1.0, v71
	v_rcp_f32_e32 v70, v70
	v_rcp_f32_e32 v71, v71
	v_sub_f32_e32 v79, v79, v180
	v_sub_f32_e32 v78, v78, v180
	v_pk_mul_f32 v[78:79], v[182:183], v[78:79] op_sel_hi:[0,1]
	v_pk_fma_f32 v[78:79], v[130:131], v[78:79], v[134:135]
	v_lshlrev_b32_e32 v72, 16, v75
	v_and_b32_e32 v73, 0xffff0000, v75
	v_pk_fma_f32 v[70:71], v[70:71], v[72:73], v[78:79]
	global_store_dwordx4 v[112:113], v[64:67], off
	global_store_dwordx4 v[112:113], v[68:71], off offset:16
	global_load_dwordx4 v[64:67], v[220:221], off offset:528
	s_nop 0
	global_load_dwordx4 v[72:75], v[220:221], off offset:512
	global_load_dwordx4 v[68:71], v[218:219], off offset:528
	global_load_dwordx4 v[76:79], v[218:219], off offset:512
	global_load_dwordx4 v[80:83], v[216:217], off offset:528
	global_load_dwordx4 v[88:91], v[216:217], off offset:512
	global_load_dwordx4 v[84:87], v[214:215], off offset:528
	global_load_dwordx4 v[92:95], v[214:215], off offset:512
	s_waitcnt vmcnt(0)
; __device__ __forceinline__ f32x4 ln_fix(const f32x4& a, float mu, float rs, const f32x4& cs, const f32x4& cb) { return (a - cs * mu) * rs + cb; }
; __device__ __forceinline__ float bf_lo(unsigned w) { return __uint_as_float(w << 16); }
; __device__ __forceinline__ float bf_hi(unsigned w) { return __uint_as_float(w & 0xffff0000u); }
;     __device__ __forceinline__ void operator()(const f32x4 (&acc)[2][2][4][2], const Unit& u, int wr, int wc, int fr_in, int fq_in) const {
;     ...
;             for (int am = 0; am < (FINAL ? 8 : 4); ++am) { constexpr int GR = FINAL ? 1 : 2; const int ai = (am * GR) >> 2; u32x4 ppw[4], pzw[4];
; #pragma unroll
;                 for (int m = (am * GR) & 3; m < ((am * GR) & 3) + GR; ++m) { const size_t off = (size_t)(row0 + ai * HALF + m * 16) * 1024 + col0 + bj * HALF; ppw[m] = *(const u32x4*)(pexb + off); pzw[m] = *(const u32x4*)(zb + off); }
;                 asm volatile("" ::: "memory");
; #pragma unroll
;                 for (int m = (am * GR) & 3; m < ((am * GR) & 3) + GR; ++m) { const size_t off = (size_t)(row0 + ai * HALF + m * 16) * 1024 + col0 + bj * HALF; const float mu = rst.mu[ai][m], rs = rst.rs[ai][m];
;                     const u32x4 pw = ppw[m]; const u32x4 zw = pzw[m];
;                     const f32x4 x0 = ((f32x4){bf_lo(zw.x), bf_hi(zw.x), bf_lo(zw.y), bf_hi(zw.y)} - mu) * rs * gv[0] + bv[0], x1 = ((f32x4){bf_lo(zw.z), bf_hi(zw.z), bf_lo(zw.w), bf_hi(zw.w)} - mu) * rs * gv[1] + bv[1];
;                     const f32x4 a0 = ln_fix(acc[ai][bj][m][0], mu, rs, csv[0], cbv[0]), a1 = ln_fix(acc[ai][bj][m][1], mu, rs, csv[1], cbv[1]); f32x4 o0, o1;
	v_pk_fma_f32 v[56:57], v[208:209], v[64:65], v[56:57] op_sel_hi:[0,1,1] neg_lo:[1,0,0] neg_hi:[1,0,0]
	global_load_dwordx4 v[116:119], v[116:117], off
	v_pk_fma_f32 v[60:61], v[208:209], v[72:73], v[60:61] op_sel_hi:[0,1,1] neg_lo:[1,0,0] neg_hi:[1,0,0]
	global_load_dwordx4 v[120:123], v[120:121], off
	v_pk_fma_f32 v[60:61], v[210:211], v[60:61], v[76:77] op_sel_hi:[0,1,1]
	v_pk_fma_f32 v[132:133], v[210:211], v[56:57], v[68:69] op_sel_hi:[0,1,1]
	v_mul_f32_e32 v56, 0xbfb8aa3b, v60
	v_mul_f32_e32 v57, 0xbfb8aa3b, v61
	v_exp_f32_e32 v56, v56
	v_exp_f32_e32 v57, v57
	v_pk_fma_f32 v[62:63], v[208:209], v[74:75], v[62:63] op_sel_hi:[0,1,1] neg_lo:[1,0,0] neg_hi:[1,0,0]
	v_pk_fma_f32 v[58:59], v[208:209], v[66:67], v[58:59] op_sel_hi:[0,1,1] neg_lo:[1,0,0] neg_hi:[1,0,0]
	v_add_f32_e32 v56, 1.0, v56
	v_add_f32_e32 v57, 1.0, v57
	v_rcp_f32_e32 v56, v56
	v_rcp_f32_e32 v57, v57
	v_pk_fma_f32 v[62:63], v[210:211], v[62:63], v[78:79] op_sel_hi:[0,1,1]
	v_pk_fma_f32 v[130:131], v[210:211], v[58:59], v[70:71] op_sel_hi:[0,1,1]
	v_pk_fma_f32 v[52:53], v[204:205], v[72:73], v[52:53] op_sel_hi:[0,1,1] neg_lo:[1,0,0] neg_hi:[1,0,0]
	v_pk_fma_f32 v[52:53], v[206:207], v[52:53], v[76:77] op_sel_hi:[0,1,1]
	v_pk_fma_f32 v[48:49], v[204:205], v[64:65], v[48:49] op_sel_hi:[0,1,1] neg_lo:[1,0,0] neg_hi:[1,0,0]
	v_pk_fma_f32 v[54:55], v[204:205], v[74:75], v[54:55] op_sel_hi:[0,1,1] neg_lo:[1,0,0] neg_hi:[1,0,0]
	v_pk_fma_f32 v[50:51], v[204:205], v[66:67], v[50:51] op_sel_hi:[0,1,1] neg_lo:[1,0,0] neg_hi:[1,0,0]
	v_pk_fma_f32 v[54:55], v[206:207], v[54:55], v[78:79] op_sel_hi:[0,1,1]
	v_pk_fma_f32 v[44:45], v[200:201], v[72:73], v[44:45] op_sel_hi:[0,1,1] neg_lo:[1,0,0] neg_hi:[1,0,0]
	v_pk_fma_f32 v[44:45], v[202:203], v[44:45], v[76:77] op_sel_hi:[0,1,1]
	v_pk_fma_f32 v[40:41], v[200:201], v[64:65], v[40:41] op_sel_hi:[0,1,1] neg_lo:[1,0,0] neg_hi:[1,0,0]
	v_pk_fma_f32 v[46:47], v[200:201], v[74:75], v[46:47] op_sel_hi:[0,1,1] neg_lo:[1,0,0] neg_hi:[1,0,0]
	v_pk_fma_f32 v[42:43], v[200:201], v[66:67], v[42:43] op_sel_hi:[0,1,1] neg_lo:[1,0,0] neg_hi:[1,0,0]
	v_pk_fma_f32 v[46:47], v[202:203], v[46:47], v[78:79] op_sel_hi:[0,1,1]
	v_pk_fma_f32 v[36:37], v[196:197], v[72:73], v[36:37] op_sel_hi:[0,1,1] neg_lo:[1,0,0] neg_hi:[1,0,0]
	v_pk_fma_f32 v[36:37], v[198:199], v[36:37], v[76:77] op_sel_hi:[0,1,1]
	v_pk_fma_f32 v[32:33], v[196:197], v[64:65], v[32:33] op_sel_hi:[0,1,1] neg_lo:[1,0,0] neg_hi:[1,0,0]
	v_pk_fma_f32 v[38:39], v[196:197], v[74:75], v[38:39] op_sel_hi:[0,1,1] neg_lo:[1,0,0] neg_hi:[1,0,0]
	v_pk_fma_f32 v[34:35], v[196:197], v[66:67], v[34:35] op_sel_hi:[0,1,1] neg_lo:[1,0,0] neg_hi:[1,0,0]
	v_pk_fma_f32 v[38:39], v[198:199], v[38:39], v[78:79] op_sel_hi:[0,1,1]
	v_pk_fma_f32 v[28:29], v[192:193], v[72:73], v[28:29] op_sel_hi:[0,1,1] neg_lo:[1,0,0] neg_hi:[1,0,0]
	v_pk_fma_f32 v[28:29], v[194:195], v[28:29], v[76:77] op_sel_hi:[0,1,1]
	v_pk_fma_f32 v[24:25], v[192:193], v[64:65], v[24:25] op_sel_hi:[0,1,1] neg_lo:[1,0,0] neg_hi:[1,0,0]
	v_pk_fma_f32 v[30:31], v[192:193], v[74:75], v[30:31] op_sel_hi:[0,1,1] neg_lo:[1,0,0] neg_hi:[1,0,0]
	v_pk_fma_f32 v[26:27], v[192:193], v[66:67], v[26:27] op_sel_hi:[0,1,1] neg_lo:[1,0,0] neg_hi:[1,0,0]
	v_pk_fma_f32 v[30:31], v[194:195], v[30:31], v[78:79] op_sel_hi:[0,1,1]
	v_pk_fma_f32 v[20:21], v[188:189], v[72:73], v[20:21] op_sel_hi:[0,1,1] neg_lo:[1,0,0] neg_hi:[1,0,0]
	v_pk_fma_f32 v[20:21], v[190:191], v[20:21], v[76:77] op_sel_hi:[0,1,1]
	v_pk_fma_f32 v[16:17], v[188:189], v[64:65], v[16:17] op_sel_hi:[0,1,1] neg_lo:[1,0,0] neg_hi:[1,0,0]
	v_pk_fma_f32 v[22:23], v[188:189], v[74:75], v[22:23] op_sel_hi:[0,1,1] neg_lo:[1,0,0] neg_hi:[1,0,0]
	v_pk_fma_f32 v[18:19], v[188:189], v[66:67], v[18:19] op_sel_hi:[0,1,1] neg_lo:[1,0,0] neg_hi:[1,0,0]
	v_pk_fma_f32 v[22:23], v[190:191], v[22:23], v[78:79] op_sel_hi:[0,1,1]
	v_pk_fma_f32 v[12:13], v[184:185], v[72:73], v[12:13] op_sel_hi:[0,1,1] neg_lo:[1,0,0] neg_hi:[1,0,0]
	v_pk_fma_f32 v[12:13], v[186:187], v[12:13], v[76:77] op_sel_hi:[0,1,1]
	v_pk_fma_f32 v[8:9], v[184:185], v[64:65], v[8:9] op_sel_hi:[0,1,1] neg_lo:[1,0,0] neg_hi:[1,0,0]
	v_pk_fma_f32 v[14:15], v[184:185], v[74:75], v[14:15] op_sel_hi:[0,1,1] neg_lo:[1,0,0] neg_hi:[1,0,0]
	v_pk_fma_f32 v[10:11], v[184:185], v[66:67], v[10:11] op_sel_hi:[0,1,1] neg_lo:[1,0,0] neg_hi:[1,0,0]
	v_pk_fma_f32 v[14:15], v[186:187], v[14:15], v[78:79] op_sel_hi:[0,1,1]
	v_pk_fma_f32 v[4:5], v[180:181], v[72:73], v[4:5] op_sel_hi:[0,1,1] neg_lo:[1,0,0] neg_hi:[1,0,0]
	v_pk_fma_f32 v[4:5], v[182:183], v[4:5], v[76:77] op_sel_hi:[0,1,1]
	v_pk_fma_f32 v[0:1], v[180:181], v[64:65], v[0:1] op_sel_hi:[0,1,1] neg_lo:[1,0,0] neg_hi:[1,0,0]
	v_pk_fma_f32 v[6:7], v[180:181], v[74:75], v[6:7] op_sel_hi:[0,1,1] neg_lo:[1,0,0] neg_hi:[1,0,0]
	v_pk_fma_f32 v[2:3], v[180:181], v[66:67], v[2:3] op_sel_hi:[0,1,1] neg_lo:[1,0,0] neg_hi:[1,0,0]
	v_pk_fma_f32 v[6:7], v[182:183], v[6:7], v[78:79] op_sel_hi:[0,1,1]
	s_waitcnt vmcnt(0)
; __device__ __forceinline__ unsigned cvt_pk_bf16(float lo, float hi) { unsigned r; asm("v_cvt_pk_bf16_f32 %0, %1, %2" : "=v"(r) : "v"(lo), "v"(hi)); return r; }
; __device__ __forceinline__ float fast_sigmoid(float v) { return __builtin_amdgcn_rcpf(1.0f + __builtin_amdgcn_exp2f(-1.4426950408889634f * v)); }
; __device__ __forceinline__ f32x4 ln_fix(const f32x4& a, float mu, float rs, const f32x4& cs, const f32x4& cb) { return (a - cs * mu) * rs + cb; }
; __device__ __forceinline__ float bf_lo(unsigned w) { return __uint_as_float(w << 16); }
; __device__ __forceinline__ float bf_hi(unsigned w) { return __uint_as_float(w & 0xffff0000u); }
;     __device__ __forceinline__ void operator()(const f32x4 (&acc)[2][2][4][2], const Unit& u, int wr, int wc, int fr_in, int fq_in) const {
;     ...
;                 for (int m = (am * GR) & 3; m < ((am * GR) & 3) + GR; ++m) { const size_t off = (size_t)(row0 + ai * HALF + m * 16) * 1024 + col0 + bj * HALF; const float mu = rst.mu[ai][m], rs = rst.rs[ai][m];
;                     const u32x4 pw = ppw[m]; const u32x4 zw = pzw[m];
;                     const f32x4 x0 = ((f32x4){bf_lo(zw.x), bf_hi(zw.x), bf_lo(zw.y), bf_hi(zw.y)} - mu) * rs * gv[0] + bv[0], x1 = ((f32x4){bf_lo(zw.z), bf_hi(zw.z), bf_lo(zw.w), bf_hi(zw.w)} - mu) * rs * gv[1] + bv[1];
;                     const f32x4 a0 = ln_fix(acc[ai][bj][m][0], mu, rs, csv[0], cbv[0]), a1 = ln_fix(acc[ai][bj][m][1], mu, rs, csv[1], cbv[1]); f32x4 o0, o1;
;                     o0[0] = x0[0] + fast_sigmoid(a0[0]) * bf_lo(pw.x); o0[1] = x0[1] + fast_sigmoid(a0[1]) * bf_hi(pw.x);
;                     o0[2] = x0[2] + fast_sigmoid(a0[2]) * bf_lo(pw.y); o0[3] = x0[3] + fast_sigmoid(a0[3]) * bf_hi(pw.y);
;                     o1[0] = x1[0] + fast_sigmoid(a1[0]) * bf_lo(pw.z); o1[1] = x1[1] + fast_sigmoid(a1[1]) * bf_hi(pw.z);
;                     o1[2] = x1[2] + fast_sigmoid(a1[2]) * bf_lo(pw.w); o1[3] = x1[3] + fast_sigmoid(a1[3]) * bf_hi(pw.w);
;                     if constexpr (FINAL) { *(f32x4*)(outf + off) = o0; *(f32x4*)(outf + off + 4) = o1; }
;                     else { u32x4 w; w.x = cvt_pk_bf16(o0[0], o0[1]); w.y = cvt_pk_bf16(o0[2], o0[3]); w.z = cvt_pk_bf16(o1[0], o1[1]); w.w = cvt_pk_bf16(o1[2], o1[3]); *(u32x4*)(pexb + off) = w; } } } }
	v_lshlrev_b32_e32 v58, 16, v116
	v_and_b32_e32 v59, 0xffff0000, v116
	v_lshlrev_b32_e32 v124, 16, v120
	v_and_b32_e32 v125, 0xffff0000, v120
	v_sub_f32_e32 v125, v125, v208
	v_sub_f32_e32 v124, v124, v208
	v_pk_mul_f32 v[124:125], v[210:211], v[124:125] op_sel_hi:[0,1]
	v_pk_fma_f32 v[124:125], v[88:89], v[124:125], v[92:93]
	v_lshlrev_b32_e32 v120, 16, v121
	v_pk_fma_f32 v[56:57], v[56:57], v[58:59], v[124:125]
	v_mul_f32_e32 v58, 0xbfb8aa3b, v62
	v_mul_f32_e32 v59, 0xbfb8aa3b, v63
	v_exp_f32_e32 v58, v58
	v_exp_f32_e32 v59, v59
	v_and_b32_e32 v121, 0xffff0000, v121
	v_sub_f32_e32 v121, v121, v208
	v_add_f32_e32 v58, 1.0, v58
	v_add_f32_e32 v59, 1.0, v59
	v_rcp_f32_e32 v58, v58
	v_rcp_f32_e32 v59, v59
	v_sub_f32_e32 v120, v120, v208
	v_pk_mul_f32 v[120:121], v[210:211], v[120:121] op_sel_hi:[0,1]
	v_pk_fma_f32 v[120:121], v[90:91], v[120:121], v[94:95]
	v_lshlrev_b32_e32 v60, 16, v117
	v_and_b32_e32 v61, 0xffff0000, v117
	v_pk_fma_f32 v[58:59], v[58:59], v[60:61], v[120:121]
	v_mul_f32_e32 v60, 0xbfb8aa3b, v132
	v_mul_f32_e32 v61, 0xbfb8aa3b, v133
	v_exp_f32_e32 v60, v60
	v_exp_f32_e32 v61, v61
	v_lshlrev_b32_e32 v128, 16, v122
	v_and_b32_e32 v129, 0xffff0000, v122
	v_add_f32_e32 v60, 1.0, v60
	v_add_f32_e32 v61, 1.0, v61
	v_rcp_f32_e32 v60, v60
	v_rcp_f32_e32 v61, v61
	v_sub_f32_e32 v129, v129, v208
	v_sub_f32_e32 v128, v128, v208
	v_pk_mul_f32 v[128:129], v[210:211], v[128:129] op_sel_hi:[0,1]
	v_pk_fma_f32 v[128:129], v[80:81], v[128:129], v[84:85]
	v_lshlrev_b32_e32 v62, 16, v118
	v_and_b32_e32 v63, 0xffff0000, v118
	v_pk_fma_f32 v[60:61], v[60:61], v[62:63], v[128:129]
	v_mul_f32_e32 v62, 0xbfb8aa3b, v130
	v_mul_f32_e32 v63, 0xbfb8aa3b, v131
	v_exp_f32_e32 v62, v62
	v_exp_f32_e32 v63, v63
	v_lshlrev_b32_e32 v122, 16, v123
	v_and_b32_e32 v123, 0xffff0000, v123
	v_add_f32_e32 v62, 1.0, v62
	v_add_f32_e32 v63, 1.0, v63
	v_rcp_f32_e32 v62, v62
	v_rcp_f32_e32 v63, v63
	v_sub_f32_e32 v123, v123, v208
	v_sub_f32_e32 v122, v122, v208
	v_pk_mul_f32 v[122:123], v[210:211], v[122:123] op_sel_hi:[0,1]
	v_pk_fma_f32 v[122:123], v[82:83], v[122:123], v[86:87]
	v_lshlrev_b32_e32 v116, 16, v119
	v_and_b32_e32 v117, 0xffff0000, v119
	v_pk_fma_f32 v[62:63], v[62:63], v[116:117], v[122:123]
	global_store_dwordx4 v[156:157], v[56:59], off offset:512
	global_store_dwordx4 v[156:157], v[60:63], off offset:528
	v_pk_fma_f32 v[122:123], v[206:207], v[48:49], v[68:69] op_sel_hi:[0,1,1]
	v_lshl_add_u64 v[56:57], v[114:115], 0, v[158:159]
	v_lshlrev_b64 v[60:61], 1, v[56:57]
	v_lshl_add_u64 v[56:57], s[26:27], 0, v[60:61]
	v_lshl_add_u64 v[60:61], s[22:23], 0, v[60:61]
	global_load_dwordx4 v[56:59], v[56:57], off
	v_mul_f32_e32 v48, 0xbfb8aa3b, v52
	global_load_dwordx4 v[60:63], v[60:61], off
	v_mul_f32_e32 v49, 0xbfb8aa3b, v53
	v_exp_f32_e32 v48, v48
	v_exp_f32_e32 v49, v49
	v_pk_fma_f32 v[120:121], v[206:207], v[50:51], v[70:71] op_sel_hi:[0,1,1]
	v_add_f32_e32 v48, 1.0, v48
	v_add_f32_e32 v49, 1.0, v49
	v_rcp_f32_e32 v48, v48
	v_rcp_f32_e32 v49, v49
	s_waitcnt vmcnt(0)
	v_lshlrev_b32_e32 v50, 16, v56
	v_and_b32_e32 v51, 0xffff0000, v56
	v_lshlrev_b32_e32 v116, 16, v60
	v_and_b32_e32 v117, 0xffff0000, v60
	v_sub_f32_e32 v117, v117, v204
	v_sub_f32_e32 v116, v116, v204
	v_pk_mul_f32 v[116:117], v[206:207], v[116:117] op_sel_hi:[0,1]
	v_pk_fma_f32 v[116:117], v[88:89], v[116:117], v[92:93]
	v_lshlrev_b32_e32 v60, 16, v61
	v_pk_fma_f32 v[48:49], v[48:49], v[50:51], v[116:117]
	v_mul_f32_e32 v50, 0xbfb8aa3b, v54
	v_mul_f32_e32 v51, 0xbfb8aa3b, v55
	v_exp_f32_e32 v50, v50
	v_exp_f32_e32 v51, v51
	v_and_b32_e32 v61, 0xffff0000, v61
	v_sub_f32_e32 v61, v61, v204
	v_add_f32_e32 v50, 1.0, v50
	v_add_f32_e32 v51, 1.0, v51
	v_rcp_f32_e32 v50, v50
	v_rcp_f32_e32 v51, v51
	v_sub_f32_e32 v60, v60, v204
	v_pk_mul_f32 v[60:61], v[206:207], v[60:61] op_sel_hi:[0,1]
	v_pk_fma_f32 v[60:61], v[90:91], v[60:61], v[94:95]
	v_lshlrev_b32_e32 v52, 16, v57
	v_and_b32_e32 v53, 0xffff0000, v57
	v_pk_fma_f32 v[50:51], v[50:51], v[52:53], v[60:61]
	v_mul_f32_e32 v52, 0xbfb8aa3b, v122
	v_mul_f32_e32 v53, 0xbfb8aa3b, v123
	v_exp_f32_e32 v52, v52
	v_exp_f32_e32 v53, v53
	v_lshlrev_b32_e32 v118, 16, v62
	v_and_b32_e32 v119, 0xffff0000, v62
	v_add_f32_e32 v52, 1.0, v52
	v_add_f32_e32 v53, 1.0, v53
	v_rcp_f32_e32 v52, v52
	v_rcp_f32_e32 v53, v53
	v_sub_f32_e32 v119, v119, v204
	v_sub_f32_e32 v118, v118, v204
	v_pk_mul_f32 v[118:119], v[206:207], v[118:119] op_sel_hi:[0,1]
	v_pk_fma_f32 v[118:119], v[80:81], v[118:119], v[84:85]
	v_lshlrev_b32_e32 v54, 16, v58
	v_and_b32_e32 v55, 0xffff0000, v58
	v_pk_fma_f32 v[52:53], v[52:53], v[54:55], v[118:119]
	v_mul_f32_e32 v54, 0xbfb8aa3b, v120
	v_mul_f32_e32 v55, 0xbfb8aa3b, v121
	v_exp_f32_e32 v54, v54
	v_exp_f32_e32 v55, v55
	v_lshlrev_b32_e32 v62, 16, v63
	v_and_b32_e32 v63, 0xffff0000, v63
	v_add_f32_e32 v54, 1.0, v54
	v_add_f32_e32 v55, 1.0, v55
	v_rcp_f32_e32 v54, v54
	v_rcp_f32_e32 v55, v55
	v_sub_f32_e32 v63, v63, v204
	v_sub_f32_e32 v62, v62, v204
	v_pk_mul_f32 v[62:63], v[206:207], v[62:63] op_sel_hi:[0,1]
	v_pk_fma_f32 v[62:63], v[82:83], v[62:63], v[86:87]
	v_lshlrev_b32_e32 v56, 16, v59
	v_and_b32_e32 v57, 0xffff0000, v59
	v_pk_fma_f32 v[54:55], v[54:55], v[56:57], v[62:63]
	global_store_dwordx4 v[144:145], v[48:51], off offset:512
	global_store_dwordx4 v[144:145], v[52:55], off offset:528
	v_pk_fma_f32 v[62:63], v[202:203], v[40:41], v[68:69] op_sel_hi:[0,1,1]
	v_lshl_add_u64 v[48:49], v[114:115], 0, v[146:147]
	v_lshlrev_b64 v[52:53], 1, v[48:49]
	v_lshl_add_u64 v[48:49], s[26:27], 0, v[52:53]
	v_lshl_add_u64 v[52:53], s[22:23], 0, v[52:53]
	global_load_dwordx4 v[48:51], v[48:49], off
	v_mul_f32_e32 v40, 0xbfb8aa3b, v44
	global_load_dwordx4 v[52:55], v[52:53], off
	v_mul_f32_e32 v41, 0xbfb8aa3b, v45
	v_exp_f32_e32 v40, v40
	v_exp_f32_e32 v41, v41
	v_pk_fma_f32 v[60:61], v[202:203], v[42:43], v[70:71] op_sel_hi:[0,1,1]
	v_add_f32_e32 v40, 1.0, v40
	v_add_f32_e32 v41, 1.0, v41
	v_rcp_f32_e32 v40, v40
	v_rcp_f32_e32 v41, v41
	s_waitcnt vmcnt(0)
; __device__ __forceinline__ unsigned cvt_pk_bf16(float lo, float hi) { unsigned r; asm("v_cvt_pk_bf16_f32 %0, %1, %2" : "=v"(r) : "v"(lo), "v"(hi)); return r; }
; __device__ __forceinline__ float fast_sigmoid(float v) { return __builtin_amdgcn_rcpf(1.0f + __builtin_amdgcn_exp2f(-1.4426950408889634f * v)); }
; __device__ __forceinline__ f32x4 ln_fix(const f32x4& a, float mu, float rs, const f32x4& cs, const f32x4& cb) { return (a - cs * mu) * rs + cb; }
; __device__ __forceinline__ float bf_lo(unsigned w) { return __uint_as_float(w << 16); }
; __device__ __forceinline__ float bf_hi(unsigned w) { return __uint_as_float(w & 0xffff0000u); }
;     __device__ __forceinline__ void operator()(const f32x4 (&acc)[2][2][4][2], const Unit& u, int wr, int wc, int fr_in, int fq_in) const {
;     ...
;                 for (int m = (am * GR) & 3; m < ((am * GR) & 3) + GR; ++m) { const size_t off = (size_t)(row0 + ai * HALF + m * 16) * 1024 + col0 + bj * HALF; const float mu = rst.mu[ai][m], rs = rst.rs[ai][m];
;                     const u32x4 pw = ppw[m]; const u32x4 zw = pzw[m];
;                     const f32x4 x0 = ((f32x4){bf_lo(zw.x), bf_hi(zw.x), bf_lo(zw.y), bf_hi(zw.y)} - mu) * rs * gv[0] + bv[0], x1 = ((f32x4){bf_lo(zw.z), bf_hi(zw.z), bf_lo(zw.w), bf_hi(zw.w)} - mu) * rs * gv[1] + bv[1];
;                     const f32x4 a0 = ln_fix(acc[ai][bj][m][0], mu, rs, csv[0], cbv[0]), a1 = ln_fix(acc[ai][bj][m][1], mu, rs, csv[1], cbv[1]); f32x4 o0, o1;
;                     o0[0] = x0[0] + fast_sigmoid(a0[0]) * bf_lo(pw.x); o0[1] = x0[1] + fast_sigmoid(a0[1]) * bf_hi(pw.x);
;                     o0[2] = x0[2] + fast_sigmoid(a0[2]) * bf_lo(pw.y); o0[3] = x0[3] + fast_sigmoid(a0[3]) * bf_hi(pw.y);
;                     o1[0] = x1[0] + fast_sigmoid(a1[0]) * bf_lo(pw.z); o1[1] = x1[1] + fast_sigmoid(a1[1]) * bf_hi(pw.z);
;                     o1[2] = x1[2] + fast_sigmoid(a1[2]) * bf_lo(pw.w); o1[3] = x1[3] + fast_sigmoid(a1[3]) * bf_hi(pw.w);
;                     if constexpr (FINAL) { *(f32x4*)(outf + off) = o0; *(f32x4*)(outf + off + 4) = o1; }
;                     else { u32x4 w; w.x = cvt_pk_bf16(o0[0], o0[1]); w.y = cvt_pk_bf16(o0[2], o0[3]); w.z = cvt_pk_bf16(o1[0], o1[1]); w.w = cvt_pk_bf16(o1[2], o1[3]); *(u32x4*)(pexb + off) = w; } } } }
	v_lshlrev_b32_e32 v42, 16, v48
	v_and_b32_e32 v43, 0xffff0000, v48
	v_lshlrev_b32_e32 v56, 16, v52
	v_and_b32_e32 v57, 0xffff0000, v52
	v_sub_f32_e32 v57, v57, v200
	v_sub_f32_e32 v56, v56, v200
	v_pk_mul_f32 v[56:57], v[202:203], v[56:57] op_sel_hi:[0,1]
	v_pk_fma_f32 v[56:57], v[88:89], v[56:57], v[92:93]
	v_lshlrev_b32_e32 v52, 16, v53
	v_pk_fma_f32 v[40:41], v[40:41], v[42:43], v[56:57]
	v_mul_f32_e32 v42, 0xbfb8aa3b, v46
	v_mul_f32_e32 v43, 0xbfb8aa3b, v47
	v_exp_f32_e32 v42, v42
	v_exp_f32_e32 v43, v43
	v_and_b32_e32 v53, 0xffff0000, v53
	v_sub_f32_e32 v53, v53, v200
	v_add_f32_e32 v42, 1.0, v42
	v_add_f32_e32 v43, 1.0, v43
	v_rcp_f32_e32 v42, v42
	v_rcp_f32_e32 v43, v43
	v_sub_f32_e32 v52, v52, v200
	v_pk_mul_f32 v[52:53], v[202:203], v[52:53] op_sel_hi:[0,1]
	v_pk_fma_f32 v[52:53], v[90:91], v[52:53], v[94:95]
	v_lshlrev_b32_e32 v44, 16, v49
	v_and_b32_e32 v45, 0xffff0000, v49
	v_pk_fma_f32 v[42:43], v[42:43], v[44:45], v[52:53]
	v_mul_f32_e32 v44, 0xbfb8aa3b, v62
	v_mul_f32_e32 v45, 0xbfb8aa3b, v63
	v_exp_f32_e32 v44, v44
	v_exp_f32_e32 v45, v45
	v_lshlrev_b32_e32 v58, 16, v54
	v_and_b32_e32 v59, 0xffff0000, v54
	v_add_f32_e32 v44, 1.0, v44
	v_add_f32_e32 v45, 1.0, v45
	v_rcp_f32_e32 v44, v44
	v_rcp_f32_e32 v45, v45
	v_sub_f32_e32 v59, v59, v200
	v_sub_f32_e32 v58, v58, v200
	v_pk_mul_f32 v[58:59], v[202:203], v[58:59] op_sel_hi:[0,1]
	v_pk_fma_f32 v[58:59], v[80:81], v[58:59], v[84:85]
	v_lshlrev_b32_e32 v46, 16, v50
	v_and_b32_e32 v47, 0xffff0000, v50
	v_pk_fma_f32 v[44:45], v[44:45], v[46:47], v[58:59]
	v_mul_f32_e32 v46, 0xbfb8aa3b, v60
	v_mul_f32_e32 v47, 0xbfb8aa3b, v61
	v_exp_f32_e32 v46, v46
	v_exp_f32_e32 v47, v47
	v_lshlrev_b32_e32 v54, 16, v55
	v_and_b32_e32 v55, 0xffff0000, v55
	v_add_f32_e32 v46, 1.0, v46
	v_add_f32_e32 v47, 1.0, v47
	v_rcp_f32_e32 v46, v46
	v_rcp_f32_e32 v47, v47
	v_sub_f32_e32 v55, v55, v200
	v_sub_f32_e32 v54, v54, v200
	v_pk_mul_f32 v[54:55], v[202:203], v[54:55] op_sel_hi:[0,1]
	v_pk_fma_f32 v[54:55], v[82:83], v[54:55], v[86:87]
	v_lshlrev_b32_e32 v48, 16, v51
	v_and_b32_e32 v49, 0xffff0000, v51
	v_pk_fma_f32 v[46:47], v[46:47], v[48:49], v[54:55]
	global_store_dwordx4 v[104:105], v[40:43], off offset:512
	global_store_dwordx4 v[104:105], v[44:47], off offset:528
	v_pk_fma_f32 v[54:55], v[198:199], v[32:33], v[68:69] op_sel_hi:[0,1,1]
	v_lshl_add_u64 v[40:41], v[114:115], 0, v[106:107]
	v_lshlrev_b64 v[44:45], 1, v[40:41]
	v_lshl_add_u64 v[40:41], s[26:27], 0, v[44:45]
	v_lshl_add_u64 v[44:45], s[22:23], 0, v[44:45]
	global_load_dwordx4 v[40:43], v[40:41], off
	v_mul_f32_e32 v32, 0xbfb8aa3b, v36
	global_load_dwordx4 v[44:47], v[44:45], off
	v_mul_f32_e32 v33, 0xbfb8aa3b, v37
	v_exp_f32_e32 v32, v32
	v_exp_f32_e32 v33, v33
	v_pk_fma_f32 v[52:53], v[198:199], v[34:35], v[70:71] op_sel_hi:[0,1,1]
	v_add_f32_e32 v32, 1.0, v32
	v_add_f32_e32 v33, 1.0, v33
	v_rcp_f32_e32 v32, v32
	v_rcp_f32_e32 v33, v33
	s_waitcnt vmcnt(0)
	v_lshlrev_b32_e32 v34, 16, v40
	v_and_b32_e32 v35, 0xffff0000, v40
	v_lshlrev_b32_e32 v48, 16, v44
	v_and_b32_e32 v49, 0xffff0000, v44
	v_sub_f32_e32 v49, v49, v196
	v_sub_f32_e32 v48, v48, v196
	v_pk_mul_f32 v[48:49], v[198:199], v[48:49] op_sel_hi:[0,1]
	v_pk_fma_f32 v[48:49], v[88:89], v[48:49], v[92:93]
	v_lshlrev_b32_e32 v44, 16, v45
	v_pk_fma_f32 v[32:33], v[32:33], v[34:35], v[48:49]
	v_mul_f32_e32 v34, 0xbfb8aa3b, v38
	v_mul_f32_e32 v35, 0xbfb8aa3b, v39
	v_exp_f32_e32 v34, v34
	v_exp_f32_e32 v35, v35
	v_and_b32_e32 v45, 0xffff0000, v45
	v_sub_f32_e32 v45, v45, v196
	v_add_f32_e32 v34, 1.0, v34
	v_add_f32_e32 v35, 1.0, v35
	v_rcp_f32_e32 v34, v34
	v_rcp_f32_e32 v35, v35
	v_sub_f32_e32 v44, v44, v196
	v_pk_mul_f32 v[44:45], v[198:199], v[44:45] op_sel_hi:[0,1]
	v_pk_fma_f32 v[44:45], v[90:91], v[44:45], v[94:95]
	v_lshlrev_b32_e32 v36, 16, v41
	v_and_b32_e32 v37, 0xffff0000, v41
	v_pk_fma_f32 v[34:35], v[34:35], v[36:37], v[44:45]
	v_mul_f32_e32 v36, 0xbfb8aa3b, v54
	v_mul_f32_e32 v37, 0xbfb8aa3b, v55
	v_exp_f32_e32 v36, v36
	v_exp_f32_e32 v37, v37
	v_lshlrev_b32_e32 v50, 16, v46
	v_and_b32_e32 v51, 0xffff0000, v46
	v_add_f32_e32 v36, 1.0, v36
	v_add_f32_e32 v37, 1.0, v37
	v_rcp_f32_e32 v36, v36
	v_rcp_f32_e32 v37, v37
	v_sub_f32_e32 v51, v51, v196
	v_sub_f32_e32 v50, v50, v196
	v_pk_mul_f32 v[50:51], v[198:199], v[50:51] op_sel_hi:[0,1]
	v_pk_fma_f32 v[50:51], v[80:81], v[50:51], v[84:85]
	v_lshlrev_b32_e32 v38, 16, v42
	v_and_b32_e32 v39, 0xffff0000, v42
	v_pk_fma_f32 v[36:37], v[36:37], v[38:39], v[50:51]
	v_mul_f32_e32 v38, 0xbfb8aa3b, v52
	v_mul_f32_e32 v39, 0xbfb8aa3b, v53
	v_exp_f32_e32 v38, v38
	v_exp_f32_e32 v39, v39
	v_lshlrev_b32_e32 v46, 16, v47
	v_and_b32_e32 v47, 0xffff0000, v47
	v_add_f32_e32 v38, 1.0, v38
	v_add_f32_e32 v39, 1.0, v39
	v_rcp_f32_e32 v38, v38
	v_rcp_f32_e32 v39, v39
	v_sub_f32_e32 v47, v47, v196
	v_sub_f32_e32 v46, v46, v196
	v_pk_mul_f32 v[46:47], v[198:199], v[46:47] op_sel_hi:[0,1]
	v_pk_fma_f32 v[46:47], v[82:83], v[46:47], v[86:87]
	v_lshlrev_b32_e32 v40, 16, v43
	v_and_b32_e32 v41, 0xffff0000, v43
	v_pk_fma_f32 v[38:39], v[38:39], v[40:41], v[46:47]
	global_store_dwordx4 v[96:97], v[32:35], off offset:512
	global_store_dwordx4 v[96:97], v[36:39], off offset:528
	v_pk_fma_f32 v[46:47], v[194:195], v[24:25], v[68:69] op_sel_hi:[0,1,1]
	v_lshl_add_u64 v[32:33], v[114:115], 0, v[98:99]
	v_lshlrev_b64 v[36:37], 1, v[32:33]
	v_lshl_add_u64 v[32:33], s[26:27], 0, v[36:37]
	v_lshl_add_u64 v[36:37], s[22:23], 0, v[36:37]
	global_load_dwordx4 v[32:35], v[32:33], off
	v_mul_f32_e32 v24, 0xbfb8aa3b, v28
	global_load_dwordx4 v[36:39], v[36:37], off
	v_mul_f32_e32 v25, 0xbfb8aa3b, v29
	v_exp_f32_e32 v24, v24
	v_exp_f32_e32 v25, v25
	v_pk_fma_f32 v[44:45], v[194:195], v[26:27], v[70:71] op_sel_hi:[0,1,1]
	v_add_f32_e32 v24, 1.0, v24
	v_add_f32_e32 v25, 1.0, v25
	v_rcp_f32_e32 v24, v24
	v_rcp_f32_e32 v25, v25
	s_waitcnt vmcnt(0)
; __device__ __forceinline__ unsigned cvt_pk_bf16(float lo, float hi) { unsigned r; asm("v_cvt_pk_bf16_f32 %0, %1, %2" : "=v"(r) : "v"(lo), "v"(hi)); return r; }
; __device__ __forceinline__ float fast_sigmoid(float v) { return __builtin_amdgcn_rcpf(1.0f + __builtin_amdgcn_exp2f(-1.4426950408889634f * v)); }
; __device__ __forceinline__ f32x4 ln_fix(const f32x4& a, float mu, float rs, const f32x4& cs, const f32x4& cb) { return (a - cs * mu) * rs + cb; }
; __device__ __forceinline__ float bf_lo(unsigned w) { return __uint_as_float(w << 16); }
; __device__ __forceinline__ float bf_hi(unsigned w) { return __uint_as_float(w & 0xffff0000u); }
;     __device__ __forceinline__ void operator()(const f32x4 (&acc)[2][2][4][2], const Unit& u, int wr, int wc, int fr_in, int fq_in) const {
;     ...
;                 for (int m = (am * GR) & 3; m < ((am * GR) & 3) + GR; ++m) { const size_t off = (size_t)(row0 + ai * HALF + m * 16) * 1024 + col0 + bj * HALF; const float mu = rst.mu[ai][m], rs = rst.rs[ai][m];
;                     const u32x4 pw = ppw[m]; const u32x4 zw = pzw[m];
;                     const f32x4 x0 = ((f32x4){bf_lo(zw.x), bf_hi(zw.x), bf_lo(zw.y), bf_hi(zw.y)} - mu) * rs * gv[0] + bv[0], x1 = ((f32x4){bf_lo(zw.z), bf_hi(zw.z), bf_lo(zw.w), bf_hi(zw.w)} - mu) * rs * gv[1] + bv[1];
;                     const f32x4 a0 = ln_fix(acc[ai][bj][m][0], mu, rs, csv[0], cbv[0]), a1 = ln_fix(acc[ai][bj][m][1], mu, rs, csv[1], cbv[1]); f32x4 o0, o1;
;                     o0[0] = x0[0] + fast_sigmoid(a0[0]) * bf_lo(pw.x); o0[1] = x0[1] + fast_sigmoid(a0[1]) * bf_hi(pw.x);
;                     o0[2] = x0[2] + fast_sigmoid(a0[2]) * bf_lo(pw.y); o0[3] = x0[3] + fast_sigmoid(a0[3]) * bf_hi(pw.y);
;                     o1[0] = x1[0] + fast_sigmoid(a1[0]) * bf_lo(pw.z); o1[1] = x1[1] + fast_sigmoid(a1[1]) * bf_hi(pw.z);
;                     o1[2] = x1[2] + fast_sigmoid(a1[2]) * bf_lo(pw.w); o1[3] = x1[3] + fast_sigmoid(a1[3]) * bf_hi(pw.w);
;                     if constexpr (FINAL) { *(f32x4*)(outf + off) = o0; *(f32x4*)(outf + off + 4) = o1; }
;                     else { u32x4 w; w.x = cvt_pk_bf16(o0[0], o0[1]); w.y = cvt_pk_bf16(o0[2], o0[3]); w.z = cvt_pk_bf16(o1[0], o1[1]); w.w = cvt_pk_bf16(o1[2], o1[3]); *(u32x4*)(pexb + off) = w; } } } }
	v_lshlrev_b32_e32 v26, 16, v32
	v_and_b32_e32 v27, 0xffff0000, v32
	v_lshlrev_b32_e32 v40, 16, v36
	v_and_b32_e32 v41, 0xffff0000, v36
	v_sub_f32_e32 v41, v41, v192
	v_sub_f32_e32 v40, v40, v192
	v_pk_mul_f32 v[40:41], v[194:195], v[40:41] op_sel_hi:[0,1]
	v_pk_fma_f32 v[40:41], v[88:89], v[40:41], v[92:93]
	v_lshlrev_b32_e32 v36, 16, v37
	v_pk_fma_f32 v[24:25], v[24:25], v[26:27], v[40:41]
	v_mul_f32_e32 v26, 0xbfb8aa3b, v30
	v_mul_f32_e32 v27, 0xbfb8aa3b, v31
	v_exp_f32_e32 v26, v26
	v_exp_f32_e32 v27, v27
	v_and_b32_e32 v37, 0xffff0000, v37
	v_sub_f32_e32 v37, v37, v192
	v_add_f32_e32 v26, 1.0, v26
	v_add_f32_e32 v27, 1.0, v27
	v_rcp_f32_e32 v26, v26
	v_rcp_f32_e32 v27, v27
	v_sub_f32_e32 v36, v36, v192
	v_pk_mul_f32 v[36:37], v[194:195], v[36:37] op_sel_hi:[0,1]
	v_pk_fma_f32 v[36:37], v[90:91], v[36:37], v[94:95]
	v_lshlrev_b32_e32 v28, 16, v33
	v_and_b32_e32 v29, 0xffff0000, v33
	v_pk_fma_f32 v[26:27], v[26:27], v[28:29], v[36:37]
	v_mul_f32_e32 v28, 0xbfb8aa3b, v46
	v_mul_f32_e32 v29, 0xbfb8aa3b, v47
	v_exp_f32_e32 v28, v28
	v_exp_f32_e32 v29, v29
	v_lshlrev_b32_e32 v42, 16, v38
	v_and_b32_e32 v43, 0xffff0000, v38
	v_add_f32_e32 v28, 1.0, v28
	v_add_f32_e32 v29, 1.0, v29
	v_rcp_f32_e32 v28, v28
	v_rcp_f32_e32 v29, v29
	v_sub_f32_e32 v43, v43, v192
	v_sub_f32_e32 v42, v42, v192
	v_pk_mul_f32 v[42:43], v[194:195], v[42:43] op_sel_hi:[0,1]
	v_pk_fma_f32 v[42:43], v[80:81], v[42:43], v[84:85]
	v_lshlrev_b32_e32 v30, 16, v34
	v_and_b32_e32 v31, 0xffff0000, v34
	v_pk_fma_f32 v[28:29], v[28:29], v[30:31], v[42:43]
	v_mul_f32_e32 v30, 0xbfb8aa3b, v44
	v_mul_f32_e32 v31, 0xbfb8aa3b, v45
	v_exp_f32_e32 v30, v30
	v_exp_f32_e32 v31, v31
	v_lshlrev_b32_e32 v38, 16, v39
	v_and_b32_e32 v39, 0xffff0000, v39
	v_add_f32_e32 v30, 1.0, v30
	v_add_f32_e32 v31, 1.0, v31
	v_rcp_f32_e32 v30, v30
	v_rcp_f32_e32 v31, v31
	v_sub_f32_e32 v39, v39, v192
	v_sub_f32_e32 v38, v38, v192
	v_pk_mul_f32 v[38:39], v[194:195], v[38:39] op_sel_hi:[0,1]
	v_pk_fma_f32 v[38:39], v[82:83], v[38:39], v[86:87]
	v_lshlrev_b32_e32 v32, 16, v35
	v_and_b32_e32 v33, 0xffff0000, v35
	v_pk_fma_f32 v[30:31], v[30:31], v[32:33], v[38:39]
	global_store_dwordx4 v[100:101], v[24:27], off offset:512
	global_store_dwordx4 v[100:101], v[28:31], off offset:528
	v_pk_fma_f32 v[38:39], v[190:191], v[16:17], v[68:69] op_sel_hi:[0,1,1]
	v_lshl_add_u64 v[24:25], v[114:115], 0, v[102:103]
	v_lshlrev_b64 v[28:29], 1, v[24:25]
	v_lshl_add_u64 v[24:25], s[26:27], 0, v[28:29]
	v_lshl_add_u64 v[28:29], s[22:23], 0, v[28:29]
	global_load_dwordx4 v[24:27], v[24:25], off
	v_mul_f32_e32 v16, 0xbfb8aa3b, v20
	global_load_dwordx4 v[28:31], v[28:29], off
	v_mul_f32_e32 v17, 0xbfb8aa3b, v21
	v_exp_f32_e32 v16, v16
	v_exp_f32_e32 v17, v17
	v_pk_fma_f32 v[36:37], v[190:191], v[18:19], v[70:71] op_sel_hi:[0,1,1]
	v_add_f32_e32 v16, 1.0, v16
	v_add_f32_e32 v17, 1.0, v17
	v_rcp_f32_e32 v16, v16
	v_rcp_f32_e32 v17, v17
	s_waitcnt vmcnt(0)
	v_lshlrev_b32_e32 v18, 16, v24
	v_and_b32_e32 v19, 0xffff0000, v24
	v_lshlrev_b32_e32 v32, 16, v28
	v_and_b32_e32 v33, 0xffff0000, v28
	v_sub_f32_e32 v33, v33, v188
	v_sub_f32_e32 v32, v32, v188
	v_pk_mul_f32 v[32:33], v[190:191], v[32:33] op_sel_hi:[0,1]
	v_pk_fma_f32 v[32:33], v[88:89], v[32:33], v[92:93]
	v_lshlrev_b32_e32 v28, 16, v29
	v_pk_fma_f32 v[16:17], v[16:17], v[18:19], v[32:33]
	v_mul_f32_e32 v18, 0xbfb8aa3b, v22
	v_mul_f32_e32 v19, 0xbfb8aa3b, v23
	v_exp_f32_e32 v18, v18
	v_exp_f32_e32 v19, v19
	v_and_b32_e32 v29, 0xffff0000, v29
	v_sub_f32_e32 v29, v29, v188
	v_add_f32_e32 v18, 1.0, v18
	v_add_f32_e32 v19, 1.0, v19
	v_rcp_f32_e32 v18, v18
	v_rcp_f32_e32 v19, v19
	v_sub_f32_e32 v28, v28, v188
	v_pk_mul_f32 v[28:29], v[190:191], v[28:29] op_sel_hi:[0,1]
	v_pk_fma_f32 v[28:29], v[90:91], v[28:29], v[94:95]
	v_lshlrev_b32_e32 v20, 16, v25
	v_and_b32_e32 v21, 0xffff0000, v25
	v_pk_fma_f32 v[18:19], v[18:19], v[20:21], v[28:29]
	v_mul_f32_e32 v20, 0xbfb8aa3b, v38
	v_mul_f32_e32 v21, 0xbfb8aa3b, v39
	v_exp_f32_e32 v20, v20
	v_exp_f32_e32 v21, v21
	v_lshlrev_b32_e32 v34, 16, v30
	v_and_b32_e32 v35, 0xffff0000, v30
	v_add_f32_e32 v20, 1.0, v20
	v_add_f32_e32 v21, 1.0, v21
	v_rcp_f32_e32 v20, v20
	v_rcp_f32_e32 v21, v21
	v_sub_f32_e32 v35, v35, v188
	v_sub_f32_e32 v34, v34, v188
	v_pk_mul_f32 v[34:35], v[190:191], v[34:35] op_sel_hi:[0,1]
	v_pk_fma_f32 v[34:35], v[80:81], v[34:35], v[84:85]
	v_lshlrev_b32_e32 v22, 16, v26
	v_and_b32_e32 v23, 0xffff0000, v26
	v_pk_fma_f32 v[20:21], v[20:21], v[22:23], v[34:35]
	v_mul_f32_e32 v22, 0xbfb8aa3b, v36
	v_mul_f32_e32 v23, 0xbfb8aa3b, v37
	v_exp_f32_e32 v22, v22
	v_exp_f32_e32 v23, v23
	v_lshlrev_b32_e32 v30, 16, v31
	v_and_b32_e32 v31, 0xffff0000, v31
	v_add_f32_e32 v22, 1.0, v22
	v_add_f32_e32 v23, 1.0, v23
	v_rcp_f32_e32 v22, v22
	v_rcp_f32_e32 v23, v23
	v_sub_f32_e32 v31, v31, v188
	v_sub_f32_e32 v30, v30, v188
	v_pk_mul_f32 v[30:31], v[190:191], v[30:31] op_sel_hi:[0,1]
	v_pk_fma_f32 v[30:31], v[82:83], v[30:31], v[86:87]
	v_lshlrev_b32_e32 v24, 16, v27
	v_and_b32_e32 v25, 0xffff0000, v27
	v_pk_fma_f32 v[22:23], v[22:23], v[24:25], v[30:31]
	global_store_dwordx4 v[108:109], v[16:19], off offset:512
	global_store_dwordx4 v[108:109], v[20:23], off offset:528
	v_pk_fma_f32 v[30:31], v[186:187], v[8:9], v[68:69] op_sel_hi:[0,1,1]
	v_lshl_add_u64 v[16:17], v[114:115], 0, v[110:111]
	v_lshlrev_b64 v[20:21], 1, v[16:17]
	v_lshl_add_u64 v[16:17], s[26:27], 0, v[20:21]
	v_lshl_add_u64 v[20:21], s[22:23], 0, v[20:21]
	global_load_dwordx4 v[16:19], v[16:17], off
	v_mul_f32_e32 v8, 0xbfb8aa3b, v12
	global_load_dwordx4 v[20:23], v[20:21], off
	v_mul_f32_e32 v9, 0xbfb8aa3b, v13
	v_exp_f32_e32 v8, v8
	v_exp_f32_e32 v9, v9
	v_pk_fma_f32 v[28:29], v[186:187], v[10:11], v[70:71] op_sel_hi:[0,1,1]
	v_add_f32_e32 v8, 1.0, v8
	v_add_f32_e32 v9, 1.0, v9
	v_rcp_f32_e32 v8, v8
	v_rcp_f32_e32 v9, v9
	s_waitcnt vmcnt(0)
;     __device__ __forceinline__ void operator()(const f32x4 (&acc)[2][2][4][2], const Unit& u, int wr, int wc, int fr_in, int fq_in) const {
;     ...
;                 for (int m = (am * GR) & 3; m < ((am * GR) & 3) + GR; ++m) { const size_t off = (size_t)(row0 + ai * HALF + m * 16) * 1024 + col0 + bj * HALF; const float mu = rst.mu[ai][m], rs = rst.rs[ai][m];
;                     const u32x4 pw = ppw[m]; const u32x4 zw = pzw[m];
;                     const f32x4 x0 = ((f32x4){bf_lo(zw.x), bf_hi(zw.x), bf_lo(zw.y), bf_hi(zw.y)} - mu) * rs * gv[0] + bv[0], x1 = ((f32x4){bf_lo(zw.z), bf_hi(zw.z), bf_lo(zw.w), bf_hi(zw.w)} - mu) * rs * gv[1] + bv[1];
;                     const f32x4 a0 = ln_fix(acc[ai][bj][m][0], mu, rs, csv[0], cbv[0]), a1 = ln_fix(acc[ai][bj][m][1], mu, rs, csv[1], cbv[1]); f32x4 o0, o1;
;                     o0[0] = x0[0] + fast_sigmoid(a0[0]) * bf_lo(pw.x); o0[1] = x0[1] + fast_sigmoid(a0[1]) * bf_hi(pw.x);
;                     o0[2] = x0[2] + fast_sigmoid(a0[2]) * bf_lo(pw.y); o0[3] = x0[3] + fast_sigmoid(a0[3]) * bf_hi(pw.y);
;                     o1[0] = x1[0] + fast_sigmoid(a1[0]) * bf_lo(pw.z); o1[1] = x1[1] + fast_sigmoid(a1[1]) * bf_hi(pw.z);
;                     o1[2] = x1[2] + fast_sigmoid(a1[2]) * bf_lo(pw.w); o1[3] = x1[3] + fast_sigmoid(a1[3]) * bf_hi(pw.w);
;                     if constexpr (FINAL) { *(f32x4*)(outf + off) = o0; *(f32x4*)(outf + off + 4) = o1; }
;                     else { u32x4 w; w.x = cvt_pk_bf16(o0[0], o0[1]); w.y = cvt_pk_bf16(o0[2], o0[3]); w.z = cvt_pk_bf16(o1[0], o1[1]); w.w = cvt_pk_bf16(o1[2], o1[3]); *(u32x4*)(pexb + off) = w; } } } }
; template <class Epi, class Sched, bool ALIGN_EPI = false, bool SP2 = false>
; __device__ __forceinline__ void gemm_phase(PG8_LAS unsigned char* lds, const Gemm g, const Sched& S, const Epi& E) {
;     ...
;         if constexpr (ALIGN_EPI) { if (wr == 0) PG8_BAR; }
;         if constexpr (!Epi::AFTER_DRAIN) { E(acc, cur, wr, wc, fr, fq); S.done(cur); }
;         if (!has_next) break;
; #pragma unroll
;         for (int a = 0; a < 2; ++a)
; #pragma unroll
;             for (int b = 0; b < 2; ++b)
; #pragma unroll
;                 for (int m = 0; m < 4; ++m)
; #pragma unroll
;                     for (int n = 0; n < 2; ++n) acc[a][b][m][n] = (f32x4){0.f, 0.f, 0.f, 0.f};
;         cur = nxt; cA = nA; cB = nB; ++ui;
;         if constexpr (ALIGN_EPI) { if (wr == 1) PG8_BAR; }
	v_lshlrev_b32_e32 v10, 16, v16
	v_and_b32_e32 v11, 0xffff0000, v16
	v_lshlrev_b32_e32 v24, 16, v20
	v_and_b32_e32 v25, 0xffff0000, v20
	v_sub_f32_e32 v25, v25, v184
	v_sub_f32_e32 v24, v24, v184
	v_pk_mul_f32 v[24:25], v[186:187], v[24:25] op_sel_hi:[0,1]
	v_pk_fma_f32 v[24:25], v[88:89], v[24:25], v[92:93]
	v_lshlrev_b32_e32 v20, 16, v21
	v_pk_fma_f32 v[8:9], v[8:9], v[10:11], v[24:25]
	v_mul_f32_e32 v10, 0xbfb8aa3b, v14
	v_mul_f32_e32 v11, 0xbfb8aa3b, v15
	v_exp_f32_e32 v10, v10
	v_exp_f32_e32 v11, v11
	v_and_b32_e32 v21, 0xffff0000, v21
	v_sub_f32_e32 v21, v21, v184
	v_add_f32_e32 v10, 1.0, v10
	v_add_f32_e32 v11, 1.0, v11
	v_rcp_f32_e32 v10, v10
	v_rcp_f32_e32 v11, v11
	v_sub_f32_e32 v20, v20, v184
	v_pk_mul_f32 v[20:21], v[186:187], v[20:21] op_sel_hi:[0,1]
	v_pk_fma_f32 v[20:21], v[90:91], v[20:21], v[94:95]
	v_lshlrev_b32_e32 v12, 16, v17
	v_and_b32_e32 v13, 0xffff0000, v17
	v_pk_fma_f32 v[10:11], v[10:11], v[12:13], v[20:21]
	v_mul_f32_e32 v12, 0xbfb8aa3b, v30
	v_mul_f32_e32 v13, 0xbfb8aa3b, v31
	v_exp_f32_e32 v12, v12
	v_exp_f32_e32 v13, v13
	v_lshlrev_b32_e32 v26, 16, v22
	v_and_b32_e32 v27, 0xffff0000, v22
	v_add_f32_e32 v12, 1.0, v12
	v_add_f32_e32 v13, 1.0, v13
	v_rcp_f32_e32 v12, v12
	v_rcp_f32_e32 v13, v13
	v_sub_f32_e32 v27, v27, v184
	v_sub_f32_e32 v26, v26, v184
	v_pk_mul_f32 v[26:27], v[186:187], v[26:27] op_sel_hi:[0,1]
	v_pk_fma_f32 v[26:27], v[80:81], v[26:27], v[84:85]
	v_lshlrev_b32_e32 v14, 16, v18
	v_and_b32_e32 v15, 0xffff0000, v18
	v_pk_fma_f32 v[12:13], v[12:13], v[14:15], v[26:27]
	v_mul_f32_e32 v14, 0xbfb8aa3b, v28
	v_mul_f32_e32 v15, 0xbfb8aa3b, v29
	v_exp_f32_e32 v14, v14
	v_exp_f32_e32 v15, v15
	v_lshlrev_b32_e32 v22, 16, v23
	v_and_b32_e32 v23, 0xffff0000, v23
	v_add_f32_e32 v14, 1.0, v14
	v_add_f32_e32 v15, 1.0, v15
	v_rcp_f32_e32 v14, v14
	v_rcp_f32_e32 v15, v15
	v_sub_f32_e32 v23, v23, v184
	v_sub_f32_e32 v22, v22, v184
	v_pk_mul_f32 v[22:23], v[186:187], v[22:23] op_sel_hi:[0,1]
	v_pk_fma_f32 v[22:23], v[82:83], v[22:23], v[86:87]
	v_lshlrev_b32_e32 v16, 16, v19
	v_and_b32_e32 v17, 0xffff0000, v19
	v_pk_fma_f32 v[14:15], v[14:15], v[16:17], v[22:23]
	global_store_dwordx4 v[126:127], v[8:11], off offset:512
	global_store_dwordx4 v[126:127], v[12:15], off offset:528
	v_pk_fma_f32 v[22:23], v[182:183], v[0:1], v[68:69] op_sel_hi:[0,1,1]
	v_lshl_add_u64 v[8:9], v[114:115], 0, v[148:149]
	v_lshlrev_b64 v[12:13], 1, v[8:9]
	v_lshl_add_u64 v[8:9], s[26:27], 0, v[12:13]
	v_lshl_add_u64 v[12:13], s[22:23], 0, v[12:13]
	global_load_dwordx4 v[8:11], v[8:9], off
	v_mul_f32_e32 v0, 0xbfb8aa3b, v4
	global_load_dwordx4 v[12:15], v[12:13], off
	v_mul_f32_e32 v1, 0xbfb8aa3b, v5
	v_exp_f32_e32 v0, v0
	v_exp_f32_e32 v1, v1
	v_pk_fma_f32 v[20:21], v[182:183], v[2:3], v[70:71] op_sel_hi:[0,1,1]
	v_add_f32_e32 v0, 1.0, v0
	v_add_f32_e32 v1, 1.0, v1
	v_rcp_f32_e32 v0, v0
	v_rcp_f32_e32 v1, v1
	s_waitcnt vmcnt(0)
	v_lshlrev_b32_e32 v2, 16, v8
	v_and_b32_e32 v3, 0xffff0000, v8
	v_lshlrev_b32_e32 v16, 16, v12
	v_and_b32_e32 v17, 0xffff0000, v12
	v_sub_f32_e32 v17, v17, v180
	v_sub_f32_e32 v16, v16, v180
	v_pk_mul_f32 v[16:17], v[182:183], v[16:17] op_sel_hi:[0,1]
	v_pk_fma_f32 v[16:17], v[88:89], v[16:17], v[92:93]
	v_lshlrev_b32_e32 v12, 16, v13
	v_pk_fma_f32 v[0:1], v[0:1], v[2:3], v[16:17]
	v_mul_f32_e32 v2, 0xbfb8aa3b, v6
	v_mul_f32_e32 v3, 0xbfb8aa3b, v7
	v_exp_f32_e32 v2, v2
	v_exp_f32_e32 v3, v3
	v_and_b32_e32 v13, 0xffff0000, v13
	v_sub_f32_e32 v13, v13, v180
	v_add_f32_e32 v2, 1.0, v2
	v_add_f32_e32 v3, 1.0, v3
	v_rcp_f32_e32 v2, v2
	v_rcp_f32_e32 v3, v3
	v_sub_f32_e32 v12, v12, v180
	v_pk_mul_f32 v[12:13], v[182:183], v[12:13] op_sel_hi:[0,1]
	v_pk_fma_f32 v[12:13], v[90:91], v[12:13], v[94:95]
	v_lshlrev_b32_e32 v4, 16, v9
	v_and_b32_e32 v5, 0xffff0000, v9
	v_pk_fma_f32 v[2:3], v[2:3], v[4:5], v[12:13]
	v_mul_f32_e32 v4, 0xbfb8aa3b, v22
	v_mul_f32_e32 v5, 0xbfb8aa3b, v23
	v_exp_f32_e32 v4, v4
	v_exp_f32_e32 v5, v5
	v_lshlrev_b32_e32 v18, 16, v14
	v_and_b32_e32 v19, 0xffff0000, v14
	v_add_f32_e32 v4, 1.0, v4
	v_add_f32_e32 v5, 1.0, v5
	v_rcp_f32_e32 v4, v4
	v_rcp_f32_e32 v5, v5
	v_sub_f32_e32 v19, v19, v180
	v_sub_f32_e32 v18, v18, v180
	v_pk_mul_f32 v[18:19], v[182:183], v[18:19] op_sel_hi:[0,1]
	v_pk_fma_f32 v[18:19], v[80:81], v[18:19], v[84:85]
	v_lshlrev_b32_e32 v6, 16, v10
	v_and_b32_e32 v7, 0xffff0000, v10
	v_pk_fma_f32 v[4:5], v[4:5], v[6:7], v[18:19]
	v_mul_f32_e32 v6, 0xbfb8aa3b, v20
	v_mul_f32_e32 v7, 0xbfb8aa3b, v21
	v_exp_f32_e32 v6, v6
	v_exp_f32_e32 v7, v7
	v_lshlrev_b32_e32 v14, 16, v15
	v_and_b32_e32 v15, 0xffff0000, v15
	v_add_f32_e32 v6, 1.0, v6
	v_add_f32_e32 v7, 1.0, v7
	v_rcp_f32_e32 v6, v6
	v_rcp_f32_e32 v7, v7
	v_sub_f32_e32 v15, v15, v180
	v_sub_f32_e32 v14, v14, v180
	v_pk_mul_f32 v[14:15], v[182:183], v[14:15] op_sel_hi:[0,1]
	v_pk_fma_f32 v[14:15], v[82:83], v[14:15], v[86:87]
	v_lshlrev_b32_e32 v8, 16, v11
	v_and_b32_e32 v9, 0xffff0000, v11
	v_pk_fma_f32 v[6:7], v[6:7], v[8:9], v[14:15]
	global_store_dwordx4 v[112:113], v[0:3], off offset:512
	global_store_dwordx4 v[112:113], v[4:7], off offset:528
	s_cbranch_vccnz .LBB0_2181
	s_andn2_b64 vcc, exec, s[24:25]
	s_cbranch_vccnz .LBB0_2180
	s_barrier
	s_branch .LBB0_2180

; #define LAS __attribute__((address_space(3)))
; __global__ void __launch_bounds__(NWAVES * 64, 2) mega_fwd(Args a0) {
;     extern __shared__ __attribute__((aligned(16))) unsigned char lds[];
;     LAS unsigned char* L = (LAS unsigned char*)lds;
;     const int tid = threadIdx.x, lane = tid & 63, wave = __builtin_amdgcn_readfirstlane(tid >> 6);
	.amdhsa_kernel _Z8mega_fwd4Args
		.amdhsa_group_segment_fixed_size 0
		.amdhsa_private_segment_fixed_size 0
		.amdhsa_kernarg_size 440
		.amdhsa_user_sgpr_count 2
		.amdhsa_user_sgpr_dispatch_ptr 0
		.amdhsa_user_sgpr_queue_ptr 0
		.amdhsa_user_sgpr_kernarg_segment_ptr 1
		.amdhsa_user_sgpr_dispatch_id 0
		.amdhsa_user_sgpr_kernarg_preload_length 0
		.amdhsa_user_sgpr_kernarg_preload_offset 0
		.amdhsa_user_sgpr_private_segment_size 0
		.amdhsa_uses_dynamic_stack 0
		.amdhsa_enable_private_segment 0
		.amdhsa_system_sgpr_workgroup_id_x 1
		.amdhsa_system_sgpr_workgroup_id_y 0
		.amdhsa_system_sgpr_workgroup_id_z 0
		.amdhsa_system_sgpr_workgroup_info 0
		.amdhsa_system_vgpr_workitem_id 2
		.amdhsa_next_free_vgpr 256
		.amdhsa_next_free_sgpr 100
		.amdhsa_accum_offset 256
		.amdhsa_reserve_vcc 1
		.amdhsa_float_round_mode_32 0
		.amdhsa_float_round_mode_16_64 0
		.amdhsa_float_denorm_mode_32 3
		.amdhsa_float_denorm_mode_16_64 3
		.amdhsa_dx10_clamp 1
		.amdhsa_ieee_mode 1
		.amdhsa_fp16_overflow 0
		.amdhsa_tg_split 0
		.amdhsa_exception_fp_ieee_invalid_op 0
		.amdhsa_exception_fp_denorm_src 0
		.amdhsa_exception_fp_ieee_div_zero 0
		.amdhsa_exception_fp_ieee_overflow 0
		.amdhsa_exception_fp_ieee_underflow 0
		.amdhsa_exception_fp_ieee_inexact 0
		.amdhsa_exception_int_div_zero 0
	.end_amdhsa_kernel

; #define LAS __attribute__((address_space(3)))
; __global__ void __launch_bounds__(NWAVES * 64, 2) mega_fwd(Args a0) {
;     extern __shared__ __attribute__((aligned(16))) unsigned char lds[];
;     LAS unsigned char* L = (LAS unsigned char*)lds;
;     const int tid = threadIdx.x, lane = tid & 63, wave = __builtin_amdgcn_readfirstlane(tid >> 6);
amdhsa.kernels:
  - .agpr_count:     0
    .args:
      - .offset:         0
        .size:           184
        .value_kind:     by_value
      - .offset:         184
        .size:           4
        .value_kind:     hidden_block_count_x
      - .offset:         188
        .size:           4
        .value_kind:     hidden_block_count_y
      - .offset:         192
        .size:           4
        .value_kind:     hidden_block_count_z
      - .offset:         196
        .size:           2
        .value_kind:     hidden_group_size_x
      - .offset:         198
        .size:           2
        .value_kind:     hidden_group_size_y
      - .offset:         200
        .size:           2
        .value_kind:     hidden_group_size_z
      - .offset:         202
        .size:           2
        .value_kind:     hidden_remainder_x
      - .offset:         204
        .size:           2
        .value_kind:     hidden_remainder_y
      - .offset:         206
        .size:           2
        .value_kind:     hidden_remainder_z
      - .offset:         224
        .size:           8
        .value_kind:     hidden_global_offset_x
      - .offset:         232
        .size:           8
        .value_kind:     hidden_global_offset_y
      - .offset:         240
        .size:           8
        .value_kind:     hidden_global_offset_z
      - .offset:         248
        .size:           2
        .value_kind:     hidden_grid_dims
      - .offset:         272
        .size:           8
        .value_kind:     hidden_multigrid_sync_arg
      - .offset:         304
        .size:           4
        .value_kind:     hidden_dynamic_lds_size
    .group_segment_fixed_size: 0
    .kernarg_segment_align: 8
    .kernarg_segment_size: 440
    .language:       OpenCL C
    .language_version:
      - 2
      - 0
    .max_flat_workgroup_size: 512
    .name:           _Z8mega_fwd4Args
    .private_segment_fixed_size: 0
    .sgpr_count:     106
    .sgpr_spill_count: 54
    .symbol:         _Z8mega_fwd4Args.kd
    .uniform_work_group_size: 1
    .uses_dynamic_stack: false
    .vgpr_count:     256
    .vgpr_spill_count: 0
    .wavefront_size: 64
